# lean row loops with non-temporal hints on last-use streams (D loads; P13 XN loads and output stores)
# speedup vs baseline: 1.0015x; 1.0008x over previous
; __device__ __forceinline__ const float* xrow_ptr(const Ctx& C, int row) { return row < MPROMPT ? C.in(0) + (size_t)row * DM : C.in(1) + (size_t)(row - MPROMPT) * DM; }
; __device__ __forceinline__ v4f ld4_bf16(const bf16* p) { const v2u w = *(const v2u*)p; return (v4f){bf_lo(w.x), bf_hi(w.x), bf_lo(w.y), bf_hi(w.y)}; }
; __device__ __forceinline__ float ssq4(v4f v) { return (v.x * v.x + v.y * v.y) + (v.z * v.z + v.w * v.w); }
; template <int R, bool BASE_F32, bool OUT_F32>
; __device__ __forceinline__ void rows_res(const Ctx& C, int m0, int stride, int mx, const float* gpost, float scale, int lane) {
;     v4f d[R][4], b[R][4]; int mr[R]; bool ok[R]; float r1[R];
;     const bf16* D = C.D(); bf16* XN = C.XN();
; #pragma unroll
;     for (int r = 0; r < R; ++r) { mr[r] = (r == 4) ? mx : m0 + r * stride; ok[r] = (r == 4) ? (mx < M) : (mr[r] < MPROMPT); const int mm = ok[r] ? mr[r] : 0;
; #pragma unroll
;         for (int j = 0; j < 4; ++j) d[r][j] = ld4_bf16(D + (size_t)mm * DM + 4 * lane + 256 * j);
;         if (BASE_F32) { const float* x = xrow_ptr(C, mm);
; #pragma unroll
;             for (int j = 0; j < 4; ++j) b[r][j] = ld4_f32(x + 4 * lane + 256 * j);
;         } else { const float inv = C.RS()[mm];
; #pragma unroll
;             for (int j = 0; j < 4; ++j) b[r][j] = ld4_bf16(XN + (size_t)mm * DM + 4 * lane + 256 * j) * inv;
;         } }
; #pragma unroll
;     for (int r = 0; r < R; ++r) { float s = 0.f;
; #pragma unroll
;         for (int j = 0; j < 4; ++j) s += ssq4(d[r][j]);
;         r1[r] = s; }
; __global__ void __launch_bounds__(NTHREADS, 2) fwd_kernel(Args args) {
;     ...
;       for (int it = 0; it < nit - 1; ++it) rows_res<4, false, false>(C, gw_ + 4 * it * ngw_, ngw_, M, gp, 0.5f, LANE);
.LBB0_366:
	s_or_b64 exec, exec, s[6:7]
	s_waitcnt lgkmcnt(0)
	v_mov_b32_e32 v0, v182
	s_mov_b64 s[0:1], s[80:81]
	s_barrier
	s_load_dwordx2 s[14:15], s[0:1], 0x40
	v_readfirstlane_b32 s0, v0
	s_ashr_i32 s47, s0, 6
	v_readlane_b32 s0, v232, 0
	s_add_i32 s42, s47, s0
	v_readlane_b32 s0, v232, 1
	v_and_b32_e32 v189, 63, v0
	v_readlane_b32 s1, v232, 2
	v_lshlrev_b32_e32 v0, 2, v189
	v_mov_b32_e32 v1, 0
	v_cndmask_b32_e64 v2, 0, 1, s[0:1]
	v_cmp_ne_u32_e64 s[6:7], 1, v2
	s_andn2_b64 vcc, exec, s[0:1]
	v_lshlrev_b32_e32 v2, 2, v0
	v_cmp_ne_u32_e64 s[8:9], 0, v189
	v_lshlrev_b32_e32 v0, 1, v0
	s_load_dwordx2 s[98:99], s[80:81], 0x110
	s_load_dwordx2 s[100:101], s[80:81], 0x40
	v_and_b32_e32 v176, 63, v182
	v_lshlrev_b32_e32 v170, 3, v176
	s_lshl_b32 vcc_lo, s42, 11
	v_add_u32_e32 v170, vcc_lo, v170
	v_add_u32_e32 v171, 0x3000000, v170
	v_add_u32_e32 v170, 0x7100000, v170
	v_mov_b32_e32 v173, v171
	s_lshl_b32 vcc_lo, s42, 2
	v_mov_b32_e32 v172, 0x2a80000
	v_add_u32_e32 v172, vcc_lo, v172
	v_mov_b32_e32 v174, v172
	v_lshlrev_b32_e32 v176, 4, v176
	v_mov_b32_e32 v138, 0x358637bd
	s_waitcnt lgkmcnt(0)
	global_load_dwordx4 v[192:195], v176, s[100:101]
	global_load_dwordx4 v[196:199], v176, s[100:101] offset:1024
	global_load_dwordx4 v[200:203], v176, s[100:101] offset:2048
	global_load_dwordx4 v[204:207], v176, s[100:101] offset:3072
	global_load_dword v52, v172, s[98:99]
	global_load_dwordx2 v[20:21], v170, s[98:99] nt
	global_load_dwordx2 v[22:23], v170, s[98:99] offset:512 nt
	global_load_dwordx2 v[24:25], v170, s[98:99] offset:1024 nt
	global_load_dwordx2 v[26:27], v170, s[98:99] offset:1536 nt
	global_load_dwordx2 v[36:37], v171, s[98:99]
	global_load_dwordx2 v[38:39], v171, s[98:99] offset:512
	global_load_dwordx2 v[40:41], v171, s[98:99] offset:1024
	global_load_dwordx2 v[42:43], v171, s[98:99] offset:1536
	v_add_u32_e32 v170, 0x400000, v170
	v_add_u32_e32 v171, 0x400000, v171
	v_add_u32_e32 v172, 0x2000, v172
	global_load_dword v54, v172, s[98:99]
	global_load_dwordx2 v[28:29], v170, s[98:99] nt
	global_load_dwordx2 v[30:31], v170, s[98:99] offset:512 nt
	global_load_dwordx2 v[32:33], v170, s[98:99] offset:1024 nt
	global_load_dwordx2 v[34:35], v170, s[98:99] offset:1536 nt
	global_load_dwordx2 v[44:45], v171, s[98:99]
	global_load_dwordx2 v[46:47], v171, s[98:99] offset:512
	global_load_dwordx2 v[48:49], v171, s[98:99] offset:1024
	global_load_dwordx2 v[50:51], v171, s[98:99] offset:1536
	v_add_u32_e32 v170, 0x400000, v170
	v_add_u32_e32 v171, 0x400000, v171
	v_add_u32_e32 v172, 0x2000, v172
	global_load_dword v88, v172, s[98:99]
	global_load_dwordx2 v[56:57], v170, s[98:99] nt
	global_load_dwordx2 v[58:59], v170, s[98:99] offset:512 nt
	global_load_dwordx2 v[60:61], v170, s[98:99] offset:1024 nt
	global_load_dwordx2 v[62:63], v170, s[98:99] offset:1536 nt
	global_load_dwordx2 v[72:73], v171, s[98:99]
	global_load_dwordx2 v[74:75], v171, s[98:99] offset:512
	global_load_dwordx2 v[76:77], v171, s[98:99] offset:1024
	global_load_dwordx2 v[78:79], v171, s[98:99] offset:1536
	v_add_u32_e32 v170, 0x400000, v170
	v_add_u32_e32 v171, 0x400000, v171
	v_add_u32_e32 v172, 0x2000, v172
	global_load_dword v90, v172, s[98:99]
	global_load_dwordx2 v[64:65], v170, s[98:99] nt
	global_load_dwordx2 v[66:67], v170, s[98:99] offset:512 nt
	global_load_dwordx2 v[68:69], v170, s[98:99] offset:1024 nt
	global_load_dwordx2 v[70:71], v170, s[98:99] offset:1536 nt
	global_load_dwordx2 v[80:81], v171, s[98:99]
	global_load_dwordx2 v[82:83], v171, s[98:99] offset:512
	global_load_dwordx2 v[84:85], v171, s[98:99] offset:1024
	global_load_dwordx2 v[86:87], v171, s[98:99] offset:1536
	v_add_u32_e32 v170, 0x400000, v170
	v_add_u32_e32 v171, 0x400000, v171
	v_add_u32_e32 v172, 0x2000, v172
	s_waitcnt vmcnt(31)
	v_lshlrev_b32_e32 v96, 16, v20
	v_and_b32_e32 v97, 0xffff0000, v20
	v_lshlrev_b32_e32 v98, 16, v21
	v_and_b32_e32 v99, 0xffff0000, v21
	v_lshlrev_b32_e32 v100, 16, v22
	v_and_b32_e32 v101, 0xffff0000, v22
	v_lshlrev_b32_e32 v102, 16, v23
	v_and_b32_e32 v103, 0xffff0000, v23
	v_lshlrev_b32_e32 v104, 16, v24
	v_and_b32_e32 v105, 0xffff0000, v24
	v_lshlrev_b32_e32 v106, 16, v25
	v_and_b32_e32 v107, 0xffff0000, v25
	v_lshlrev_b32_e32 v108, 16, v26
	v_and_b32_e32 v109, 0xffff0000, v26
	v_lshlrev_b32_e32 v110, 16, v27
	v_and_b32_e32 v111, 0xffff0000, v27
	v_pk_mul_f32 v[128:129], v[96:97], v[96:97]
	v_pk_fma_f32 v[128:129], v[98:99], v[98:99], v[128:129]
	v_pk_fma_f32 v[128:129], v[100:101], v[100:101], v[128:129]
	v_pk_fma_f32 v[128:129], v[102:103], v[102:103], v[128:129]
	v_pk_fma_f32 v[128:129], v[104:105], v[104:105], v[128:129]
	v_pk_fma_f32 v[128:129], v[106:107], v[106:107], v[128:129]
	v_pk_fma_f32 v[128:129], v[108:109], v[108:109], v[128:129]
	v_pk_fma_f32 v[128:129], v[110:111], v[110:111], v[128:129]
	s_nop 0
	v_add_f32_e32 v128, v128, v129
	s_waitcnt vmcnt(22)
;     __device__ __forceinline__ float* out() const { return (float*)karg_in(33); }
; __device__ __forceinline__ float ssq4(v4f v) { return (v.x * v.x + v.y * v.y) + (v.z * v.z + v.w * v.w); }
; template <int R, bool BASE_F32, bool OUT_F32>
; __device__ __forceinline__ void rows_res(const Ctx& C, int m0, int stride, int mx, const float* gpost, float scale, int lane) {
;     ...
;     for (int r = 0; r < R; ++r) { float s = 0.f;
; #pragma unroll
;         for (int j = 0; j < 4; ++j) s += ssq4(d[r][j]);
;         r1[r] = s; }
; #pragma unroll
;     for (int r = 0; r < R; ++r) r1[r] = rsqrtf(wave_sum(r1[r]) * (1.f / DM) + EPS) * scale;
; #pragma unroll
;     for (int j = 0; j < 4; ++j) { const v4f gp = ld4_f32(gpost + 4 * lane + 256 * j);
; #pragma unroll
;         for (int r = 0; r < R; ++r) d[r][j] = b[r][j] + d[r][j] * r1[r] * gp; }
;     if (OUT_F32) { float* Y = C.out();
; #pragma unroll
;         for (int r = 0; r < R; ++r)
; #pragma unroll
;             for (int j = 0; j < 4; ++j) if (ok[r]) *(v4f*)(Y + (size_t)mr[r] * DM + 4 * lane + 256 * j) = d[r][j];
;     } else { float* rs = C.RS(); float t[R];
; #pragma unroll
;         for (int r = 0; r < R; ++r) { float s = 0.f;
; #pragma unroll
;             for (int j = 0; j < 4; ++j) s += ssq4(d[r][j]);
;             t[r] = s; }
	v_lshlrev_b32_e32 v112, 16, v28
	v_and_b32_e32 v113, 0xffff0000, v28
	v_lshlrev_b32_e32 v114, 16, v29
	v_and_b32_e32 v115, 0xffff0000, v29
	v_lshlrev_b32_e32 v116, 16, v30
	v_and_b32_e32 v117, 0xffff0000, v30
	v_lshlrev_b32_e32 v118, 16, v31
	v_and_b32_e32 v119, 0xffff0000, v31
	v_lshlrev_b32_e32 v120, 16, v32
	v_and_b32_e32 v121, 0xffff0000, v32
	v_lshlrev_b32_e32 v122, 16, v33
	v_and_b32_e32 v123, 0xffff0000, v33
	v_lshlrev_b32_e32 v124, 16, v34
	v_and_b32_e32 v125, 0xffff0000, v34
	v_lshlrev_b32_e32 v126, 16, v35
	v_and_b32_e32 v127, 0xffff0000, v35
	v_pk_mul_f32 v[130:131], v[112:113], v[112:113]
	v_pk_fma_f32 v[130:131], v[114:115], v[114:115], v[130:131]
	v_pk_fma_f32 v[130:131], v[116:117], v[116:117], v[130:131]
	v_pk_fma_f32 v[130:131], v[118:119], v[118:119], v[130:131]
	v_pk_fma_f32 v[130:131], v[120:121], v[120:121], v[130:131]
	v_pk_fma_f32 v[130:131], v[122:123], v[122:123], v[130:131]
	v_pk_fma_f32 v[130:131], v[124:125], v[124:125], v[130:131]
	v_pk_fma_f32 v[130:131], v[126:127], v[126:127], v[130:131]
	s_nop 0
	v_add_f32_e32 v130, v130, v131
	s_nop 1
	v_add_f32_dpp v128, v128, v128 quad_perm:[1,0,3,2] row_mask:0xf bank_mask:0xf
	v_add_f32_dpp v130, v130, v130 quad_perm:[1,0,3,2] row_mask:0xf bank_mask:0xf
	s_nop 0
	v_add_f32_dpp v128, v128, v128 quad_perm:[2,3,0,1] row_mask:0xf bank_mask:0xf
	v_add_f32_dpp v130, v130, v130 quad_perm:[2,3,0,1] row_mask:0xf bank_mask:0xf
	s_nop 0
	v_add_f32_dpp v128, v128, v128 row_half_mirror row_mask:0xf bank_mask:0xf
	v_add_f32_dpp v130, v130, v130 row_half_mirror row_mask:0xf bank_mask:0xf
	s_nop 0
	v_add_f32_dpp v128, v128, v128 row_mirror row_mask:0xf bank_mask:0xf
	v_add_f32_dpp v130, v130, v130 row_mirror row_mask:0xf bank_mask:0xf
	s_nop 0
	ds_bpermute_b32 v136, v187, v128
	ds_bpermute_b32 v137, v187, v130
	s_waitcnt lgkmcnt(0)
	v_add_f32_e32 v128, v128, v136
	v_add_f32_e32 v130, v130, v137
	ds_bpermute_b32 v136, v188, v128
	ds_bpermute_b32 v137, v188, v130
	s_waitcnt lgkmcnt(0)
	v_add_f32_e32 v128, v128, v136
	v_add_f32_e32 v130, v130, v137
	v_fmamk_f32 v128, v128, 0x3a800000, v138
	v_fmamk_f32 v130, v130, 0x3a800000, v138
	s_nop 0
	v_rsq_f32_e32 v128, v128
	v_rsq_f32_e32 v130, v130
	s_nop 1
	v_mul_f32_e32 v128, 0.5, v128
	v_mul_f32_e32 v130, 0.5, v130
	s_waitcnt vmcnt(18)
	v_pk_mul_f32 v[96:97], v[128:129], v[96:97] op_sel_hi:[0,1]
	v_pk_mul_f32 v[98:99], v[128:129], v[98:99] op_sel_hi:[0,1]
	v_pk_mul_f32 v[100:101], v[128:129], v[100:101] op_sel_hi:[0,1]
	v_pk_mul_f32 v[102:103], v[128:129], v[102:103] op_sel_hi:[0,1]
	v_pk_mul_f32 v[104:105], v[128:129], v[104:105] op_sel_hi:[0,1]
	v_pk_mul_f32 v[106:107], v[128:129], v[106:107] op_sel_hi:[0,1]
	v_pk_mul_f32 v[108:109], v[128:129], v[108:109] op_sel_hi:[0,1]
	v_pk_mul_f32 v[110:111], v[128:129], v[110:111] op_sel_hi:[0,1]
	v_pk_mul_f32 v[96:97], v[96:97], v[192:193]
	v_pk_mul_f32 v[98:99], v[98:99], v[194:195]
	v_pk_mul_f32 v[100:101], v[100:101], v[196:197]
	v_pk_mul_f32 v[102:103], v[102:103], v[198:199]
	v_pk_mul_f32 v[104:105], v[104:105], v[200:201]
	v_pk_mul_f32 v[106:107], v[106:107], v[202:203]
	v_pk_mul_f32 v[108:109], v[108:109], v[204:205]
	v_pk_mul_f32 v[110:111], v[110:111], v[206:207]
	v_lshlrev_b32_e32 v20, 16, v36
	v_and_b32_e32 v21, 0xffff0000, v36
	v_lshlrev_b32_e32 v22, 16, v37
	v_and_b32_e32 v23, 0xffff0000, v37
	v_lshlrev_b32_e32 v24, 16, v38
	v_and_b32_e32 v25, 0xffff0000, v38
	v_lshlrev_b32_e32 v26, 16, v39
	v_and_b32_e32 v27, 0xffff0000, v39
	v_pk_fma_f32 v[96:97], v[52:53], v[20:21], v[96:97] op_sel_hi:[0,1,1]
	v_pk_fma_f32 v[98:99], v[52:53], v[22:23], v[98:99] op_sel_hi:[0,1,1]
	v_pk_fma_f32 v[100:101], v[52:53], v[24:25], v[100:101] op_sel_hi:[0,1,1]
	v_pk_fma_f32 v[102:103], v[52:53], v[26:27], v[102:103] op_sel_hi:[0,1,1]
	v_lshlrev_b32_e32 v20, 16, v40
	v_and_b32_e32 v21, 0xffff0000, v40
	v_lshlrev_b32_e32 v22, 16, v41
	v_and_b32_e32 v23, 0xffff0000, v41
	v_lshlrev_b32_e32 v24, 16, v42
	v_and_b32_e32 v25, 0xffff0000, v42
	v_lshlrev_b32_e32 v26, 16, v43
	v_and_b32_e32 v27, 0xffff0000, v43
	v_pk_fma_f32 v[104:105], v[52:53], v[20:21], v[104:105] op_sel_hi:[0,1,1]
	v_pk_fma_f32 v[106:107], v[52:53], v[22:23], v[106:107] op_sel_hi:[0,1,1]
	v_pk_fma_f32 v[108:109], v[52:53], v[24:25], v[108:109] op_sel_hi:[0,1,1]
	v_pk_fma_f32 v[110:111], v[52:53], v[26:27], v[110:111] op_sel_hi:[0,1,1]
	v_pk_mul_f32 v[132:133], v[96:97], v[96:97]
	v_pk_fma_f32 v[132:133], v[98:99], v[98:99], v[132:133]
	v_pk_fma_f32 v[132:133], v[100:101], v[100:101], v[132:133]
	v_pk_fma_f32 v[132:133], v[102:103], v[102:103], v[132:133]
	v_pk_fma_f32 v[132:133], v[104:105], v[104:105], v[132:133]
	v_pk_fma_f32 v[132:133], v[106:107], v[106:107], v[132:133]
	v_pk_fma_f32 v[132:133], v[108:109], v[108:109], v[132:133]
	v_pk_fma_f32 v[132:133], v[110:111], v[110:111], v[132:133]
	s_nop 0
	v_add_f32_e32 v132, v132, v133
	v_pk_mul_f32 v[112:113], v[130:131], v[112:113] op_sel_hi:[0,1]
	v_pk_mul_f32 v[114:115], v[130:131], v[114:115] op_sel_hi:[0,1]
	v_pk_mul_f32 v[116:117], v[130:131], v[116:117] op_sel_hi:[0,1]
	v_pk_mul_f32 v[118:119], v[130:131], v[118:119] op_sel_hi:[0,1]
	v_pk_mul_f32 v[120:121], v[130:131], v[120:121] op_sel_hi:[0,1]
	v_pk_mul_f32 v[122:123], v[130:131], v[122:123] op_sel_hi:[0,1]
	v_pk_mul_f32 v[124:125], v[130:131], v[124:125] op_sel_hi:[0,1]
	v_pk_mul_f32 v[126:127], v[130:131], v[126:127] op_sel_hi:[0,1]
	v_pk_mul_f32 v[112:113], v[112:113], v[192:193]
	v_pk_mul_f32 v[114:115], v[114:115], v[194:195]
	v_pk_mul_f32 v[116:117], v[116:117], v[196:197]
	v_pk_mul_f32 v[118:119], v[118:119], v[198:199]
	v_pk_mul_f32 v[120:121], v[120:121], v[200:201]
	v_pk_mul_f32 v[122:123], v[122:123], v[202:203]
;     __device__ __forceinline__ float* out() const { return (float*)karg_in(33); }
; __device__ __forceinline__ const float* xrow_ptr(const Ctx& C, int row) { return row < MPROMPT ? C.in(0) + (size_t)row * DM : C.in(1) + (size_t)(row - MPROMPT) * DM; }
; __device__ __forceinline__ v4f ld4_bf16(const bf16* p) { const v2u w = *(const v2u*)p; return (v4f){bf_lo(w.x), bf_hi(w.x), bf_lo(w.y), bf_hi(w.y)}; }
; __device__ __forceinline__ void st4_bf16(bf16* p, v4f o) { v2u w; w.x = cvt_pk_nv(o.x, o.y); w.y = cvt_pk_nv(o.z, o.w); *(v2u*)p = w; }
; __device__ __forceinline__ float ssq4(v4f v) { return (v.x * v.x + v.y * v.y) + (v.z * v.z + v.w * v.w); }
; template <int R, bool BASE_F32, bool OUT_F32>
; __device__ __forceinline__ void rows_res(const Ctx& C, int m0, int stride, int mx, const float* gpost, float scale, int lane) {
;     ...
;     for (int r = 0; r < R; ++r) { mr[r] = (r == 4) ? mx : m0 + r * stride; ok[r] = (r == 4) ? (mx < M) : (mr[r] < MPROMPT); const int mm = ok[r] ? mr[r] : 0;
; #pragma unroll
;         for (int j = 0; j < 4; ++j) d[r][j] = ld4_bf16(D + (size_t)mm * DM + 4 * lane + 256 * j);
;         if (BASE_F32) { const float* x = xrow_ptr(C, mm);
; #pragma unroll
;             for (int j = 0; j < 4; ++j) b[r][j] = ld4_f32(x + 4 * lane + 256 * j);
;         } else { const float inv = C.RS()[mm];
; #pragma unroll
;             for (int j = 0; j < 4; ++j) b[r][j] = ld4_bf16(XN + (size_t)mm * DM + 4 * lane + 256 * j) * inv;
;         } }
;     ...
;         for (int r = 0; r < R; ++r) d[r][j] = b[r][j] + d[r][j] * r1[r] * gp; }
;     if (OUT_F32) { float* Y = C.out();
; #pragma unroll
;         for (int r = 0; r < R; ++r)
; #pragma unroll
;             for (int j = 0; j < 4; ++j) if (ok[r]) *(v4f*)(Y + (size_t)mr[r] * DM + 4 * lane + 256 * j) = d[r][j];
;     } else { float* rs = C.RS(); float t[R];
; #pragma unroll
;         for (int r = 0; r < R; ++r) { float s = 0.f;
; #pragma unroll
;             for (int j = 0; j < 4; ++j) s += ssq4(d[r][j]);
;             t[r] = s; }
; #pragma unroll
;         for (int r = 0; r < R; ++r) t[r] = wave_sum(t[r]) * (1.f / DM) + EPS;
; #pragma unroll
;         for (int r = 0; r < R; ++r) { const float rstd = rsqrtf(t[r]);
; #pragma unroll
;             for (int j = 0; j < 4; ++j) if (ok[r]) st4_bf16(XN + (size_t)mr[r] * DM + 4 * lane + 256 * j, d[r][j] * rstd);
;             if (lane == 0 && ok[r]) rs[mr[r]] = sqrtf(t[r]); }
	v_pk_mul_f32 v[124:125], v[124:125], v[204:205]
	v_pk_mul_f32 v[126:127], v[126:127], v[206:207]
	v_lshlrev_b32_e32 v28, 16, v44
	v_and_b32_e32 v29, 0xffff0000, v44
	v_lshlrev_b32_e32 v30, 16, v45
	v_and_b32_e32 v31, 0xffff0000, v45
	v_lshlrev_b32_e32 v32, 16, v46
	v_and_b32_e32 v33, 0xffff0000, v46
	v_lshlrev_b32_e32 v34, 16, v47
	v_and_b32_e32 v35, 0xffff0000, v47
	v_pk_fma_f32 v[112:113], v[54:55], v[28:29], v[112:113] op_sel_hi:[0,1,1]
	v_pk_fma_f32 v[114:115], v[54:55], v[30:31], v[114:115] op_sel_hi:[0,1,1]
	v_pk_fma_f32 v[116:117], v[54:55], v[32:33], v[116:117] op_sel_hi:[0,1,1]
	v_pk_fma_f32 v[118:119], v[54:55], v[34:35], v[118:119] op_sel_hi:[0,1,1]
	v_lshlrev_b32_e32 v28, 16, v48
	v_and_b32_e32 v29, 0xffff0000, v48
	v_lshlrev_b32_e32 v30, 16, v49
	v_and_b32_e32 v31, 0xffff0000, v49
	v_lshlrev_b32_e32 v32, 16, v50
	v_and_b32_e32 v33, 0xffff0000, v50
	v_lshlrev_b32_e32 v34, 16, v51
	v_and_b32_e32 v35, 0xffff0000, v51
	v_pk_fma_f32 v[120:121], v[54:55], v[28:29], v[120:121] op_sel_hi:[0,1,1]
	v_pk_fma_f32 v[122:123], v[54:55], v[30:31], v[122:123] op_sel_hi:[0,1,1]
	v_pk_fma_f32 v[124:125], v[54:55], v[32:33], v[124:125] op_sel_hi:[0,1,1]
	v_pk_fma_f32 v[126:127], v[54:55], v[34:35], v[126:127] op_sel_hi:[0,1,1]
	v_pk_mul_f32 v[134:135], v[112:113], v[112:113]
	v_pk_fma_f32 v[134:135], v[114:115], v[114:115], v[134:135]
	v_pk_fma_f32 v[134:135], v[116:117], v[116:117], v[134:135]
	v_pk_fma_f32 v[134:135], v[118:119], v[118:119], v[134:135]
	v_pk_fma_f32 v[134:135], v[120:121], v[120:121], v[134:135]
	v_pk_fma_f32 v[134:135], v[122:123], v[122:123], v[134:135]
	v_pk_fma_f32 v[134:135], v[124:125], v[124:125], v[134:135]
	v_pk_fma_f32 v[134:135], v[126:127], v[126:127], v[134:135]
	s_nop 0
	v_add_f32_e32 v134, v134, v135
	s_nop 1
	v_add_f32_dpp v132, v132, v132 quad_perm:[1,0,3,2] row_mask:0xf bank_mask:0xf
	v_add_f32_dpp v134, v134, v134 quad_perm:[1,0,3,2] row_mask:0xf bank_mask:0xf
	s_nop 0
	v_add_f32_dpp v132, v132, v132 quad_perm:[2,3,0,1] row_mask:0xf bank_mask:0xf
	v_add_f32_dpp v134, v134, v134 quad_perm:[2,3,0,1] row_mask:0xf bank_mask:0xf
	s_nop 0
	v_add_f32_dpp v132, v132, v132 row_half_mirror row_mask:0xf bank_mask:0xf
	v_add_f32_dpp v134, v134, v134 row_half_mirror row_mask:0xf bank_mask:0xf
	s_nop 0
	v_add_f32_dpp v132, v132, v132 row_mirror row_mask:0xf bank_mask:0xf
	v_add_f32_dpp v134, v134, v134 row_mirror row_mask:0xf bank_mask:0xf
	s_nop 0
	ds_bpermute_b32 v136, v187, v132
	ds_bpermute_b32 v137, v187, v134
	s_waitcnt lgkmcnt(0)
	v_add_f32_e32 v132, v132, v136
	v_add_f32_e32 v134, v134, v137
	ds_bpermute_b32 v136, v188, v132
	ds_bpermute_b32 v137, v188, v134
	s_waitcnt lgkmcnt(0)
	v_add_f32_e32 v132, v132, v136
	v_add_f32_e32 v134, v134, v137
	v_fmamk_f32 v164, v132, 0x3a800000, v138
	v_fmamk_f32 v167, v134, 0x3a800000, v138
	s_nop 0
	v_rsq_f32_e32 v132, v164
	v_rsq_f32_e32 v134, v167
	v_sqrt_f32_e32 v165, v164
	v_sqrt_f32_e32 v168, v167
	s_nop 1
	v_pk_mul_f32 v[140:141], v[96:97], v[132:133] op_sel_hi:[1,0]
	v_cvt_pk_bf16_f32 v148, v140, v141
	v_pk_mul_f32 v[142:143], v[98:99], v[132:133] op_sel_hi:[1,0]
	v_cvt_pk_bf16_f32 v149, v142, v143
	v_pk_mul_f32 v[144:145], v[100:101], v[132:133] op_sel_hi:[1,0]
	v_cvt_pk_bf16_f32 v150, v144, v145
	v_pk_mul_f32 v[146:147], v[102:103], v[132:133] op_sel_hi:[1,0]
	v_cvt_pk_bf16_f32 v151, v146, v147
	v_pk_mul_f32 v[140:141], v[104:105], v[132:133] op_sel_hi:[1,0]
	v_cvt_pk_bf16_f32 v152, v140, v141
	v_pk_mul_f32 v[142:143], v[106:107], v[132:133] op_sel_hi:[1,0]
	v_cvt_pk_bf16_f32 v153, v142, v143
	v_pk_mul_f32 v[144:145], v[108:109], v[132:133] op_sel_hi:[1,0]
	v_cvt_pk_bf16_f32 v154, v144, v145
	v_pk_mul_f32 v[146:147], v[110:111], v[132:133] op_sel_hi:[1,0]
	v_cvt_pk_bf16_f32 v155, v146, v147
	global_store_dwordx2 v173, v[148:149], s[98:99]
	global_store_dwordx2 v173, v[150:151], s[98:99] offset:512
	global_store_dwordx2 v173, v[152:153], s[98:99] offset:1024
	global_store_dwordx2 v173, v[154:155], s[98:99] offset:1536
	v_add_u32_e32 v173, 0x400000, v173
	v_pk_mul_f32 v[140:141], v[112:113], v[134:135] op_sel_hi:[1,0]
	v_cvt_pk_bf16_f32 v156, v140, v141
	v_pk_mul_f32 v[142:143], v[114:115], v[134:135] op_sel_hi:[1,0]
	v_cvt_pk_bf16_f32 v157, v142, v143
	v_pk_mul_f32 v[144:145], v[116:117], v[134:135] op_sel_hi:[1,0]
	v_cvt_pk_bf16_f32 v158, v144, v145
	v_pk_mul_f32 v[146:147], v[118:119], v[134:135] op_sel_hi:[1,0]
	v_cvt_pk_bf16_f32 v159, v146, v147
	v_pk_mul_f32 v[140:141], v[120:121], v[134:135] op_sel_hi:[1,0]
	v_cvt_pk_bf16_f32 v160, v140, v141
	v_pk_mul_f32 v[142:143], v[122:123], v[134:135] op_sel_hi:[1,0]
	v_cvt_pk_bf16_f32 v161, v142, v143
	v_pk_mul_f32 v[144:145], v[124:125], v[134:135] op_sel_hi:[1,0]
	v_cvt_pk_bf16_f32 v162, v144, v145
	v_pk_mul_f32 v[146:147], v[126:127], v[134:135] op_sel_hi:[1,0]
	v_cvt_pk_bf16_f32 v163, v146, v147
	global_store_dwordx2 v173, v[156:157], s[98:99]
	global_store_dwordx2 v173, v[158:159], s[98:99] offset:512
	global_store_dwordx2 v173, v[160:161], s[98:99] offset:1024
	global_store_dwordx2 v173, v[162:163], s[98:99] offset:1536
	v_add_u32_e32 v173, 0x400000, v173
	v_add_u32_e32 v166, -1, v165
	v_fma_f32 v140, -v166, v165, v164
	v_cmp_ge_f32_e32 vcc, 0, v140
	v_add_u32_e32 v141, 1, v165
	v_cndmask_b32_e32 v166, v165, v166, vcc
	v_fma_f32 v140, -v141, v165, v164
	v_cmp_lt_f32_e32 vcc, 0, v140
	s_nop 1
	v_cndmask_b32_e32 v165, v166, v141, vcc
	v_add_u32_e32 v169, -1, v168
	v_fma_f32 v142, -v169, v168, v167
	v_cmp_ge_f32_e32 vcc, 0, v142
	v_add_u32_e32 v143, 1, v168
	v_cndmask_b32_e32 v169, v168, v169, vcc
	v_fma_f32 v142, -v143, v168, v167
	v_cmp_lt_f32_e32 vcc, 0, v142
	s_nop 1
	v_cndmask_b32_e32 v168, v169, v143, vcc
	s_mov_b64 exec, 1
	global_store_dword v174, v165, s[98:99]
	v_add_u32_e32 v174, 0x2000, v174
	global_store_dword v174, v168, s[98:99]
	v_add_u32_e32 v174, 0x2000, v174
	s_mov_b64 exec, -1
	global_load_dword v52, v172, s[98:99]
	global_load_dwordx2 v[20:21], v170, s[98:99] nt
	global_load_dwordx2 v[22:23], v170, s[98:99] offset:512 nt
	global_load_dwordx2 v[24:25], v170, s[98:99] offset:1024 nt
	global_load_dwordx2 v[26:27], v170, s[98:99] offset:1536 nt
	global_load_dwordx2 v[36:37], v171, s[98:99]
	global_load_dwordx2 v[38:39], v171, s[98:99] offset:512
	global_load_dwordx2 v[40:41], v171, s[98:99] offset:1024
	global_load_dwordx2 v[42:43], v171, s[98:99] offset:1536
	v_add_u32_e32 v170, 0x400000, v170
	v_add_u32_e32 v171, 0x400000, v171
	v_add_u32_e32 v172, 0x2000, v172
	global_load_dword v54, v172, s[98:99]
	global_load_dwordx2 v[28:29], v170, s[98:99] nt
	global_load_dwordx2 v[30:31], v170, s[98:99] offset:512 nt
	global_load_dwordx2 v[32:33], v170, s[98:99] offset:1024 nt
	global_load_dwordx2 v[34:35], v170, s[98:99] offset:1536 nt
	global_load_dwordx2 v[44:45], v171, s[98:99]
	global_load_dwordx2 v[46:47], v171, s[98:99] offset:512
	global_load_dwordx2 v[48:49], v171, s[98:99] offset:1024
	global_load_dwordx2 v[50:51], v171, s[98:99] offset:1536
	v_add_u32_e32 v170, 0x400000, v170
	v_add_u32_e32 v171, 0x400000, v171
	v_add_u32_e32 v172, 0x2000, v172
	s_waitcnt vmcnt(41)
; __device__ __forceinline__ float ssq4(v4f v) { return (v.x * v.x + v.y * v.y) + (v.z * v.z + v.w * v.w); }
; template <int R, bool BASE_F32, bool OUT_F32>
; __device__ __forceinline__ void rows_res(const Ctx& C, int m0, int stride, int mx, const float* gpost, float scale, int lane) {
;     ...
;     for (int r = 0; r < R; ++r) { float s = 0.f;
; #pragma unroll
;         for (int j = 0; j < 4; ++j) s += ssq4(d[r][j]);
;         r1[r] = s; }
; #pragma unroll
;     for (int r = 0; r < R; ++r) r1[r] = rsqrtf(wave_sum(r1[r]) * (1.f / DM) + EPS) * scale;
; #pragma unroll
;     for (int j = 0; j < 4; ++j) { const v4f gp = ld4_f32(gpost + 4 * lane + 256 * j);
; #pragma unroll
;         for (int r = 0; r < R; ++r) d[r][j] = b[r][j] + d[r][j] * r1[r] * gp; }
	v_lshlrev_b32_e32 v96, 16, v56
	v_and_b32_e32 v97, 0xffff0000, v56
	v_lshlrev_b32_e32 v98, 16, v57
	v_and_b32_e32 v99, 0xffff0000, v57
	v_lshlrev_b32_e32 v100, 16, v58
	v_and_b32_e32 v101, 0xffff0000, v58
	v_lshlrev_b32_e32 v102, 16, v59
	v_and_b32_e32 v103, 0xffff0000, v59
	v_lshlrev_b32_e32 v104, 16, v60
	v_and_b32_e32 v105, 0xffff0000, v60
	v_lshlrev_b32_e32 v106, 16, v61
	v_and_b32_e32 v107, 0xffff0000, v61
	v_lshlrev_b32_e32 v108, 16, v62
	v_and_b32_e32 v109, 0xffff0000, v62
	v_lshlrev_b32_e32 v110, 16, v63
	v_and_b32_e32 v111, 0xffff0000, v63
	v_pk_mul_f32 v[128:129], v[96:97], v[96:97]
	v_pk_fma_f32 v[128:129], v[98:99], v[98:99], v[128:129]
	v_pk_fma_f32 v[128:129], v[100:101], v[100:101], v[128:129]
	v_pk_fma_f32 v[128:129], v[102:103], v[102:103], v[128:129]
	v_pk_fma_f32 v[128:129], v[104:105], v[104:105], v[128:129]
	v_pk_fma_f32 v[128:129], v[106:107], v[106:107], v[128:129]
	v_pk_fma_f32 v[128:129], v[108:109], v[108:109], v[128:129]
	v_pk_fma_f32 v[128:129], v[110:111], v[110:111], v[128:129]
	s_nop 0
	v_add_f32_e32 v128, v128, v129
	s_waitcnt vmcnt(32)
	v_lshlrev_b32_e32 v112, 16, v64
	v_and_b32_e32 v113, 0xffff0000, v64
	v_lshlrev_b32_e32 v114, 16, v65
	v_and_b32_e32 v115, 0xffff0000, v65
	v_lshlrev_b32_e32 v116, 16, v66
	v_and_b32_e32 v117, 0xffff0000, v66
	v_lshlrev_b32_e32 v118, 16, v67
	v_and_b32_e32 v119, 0xffff0000, v67
	v_lshlrev_b32_e32 v120, 16, v68
	v_and_b32_e32 v121, 0xffff0000, v68
	v_lshlrev_b32_e32 v122, 16, v69
	v_and_b32_e32 v123, 0xffff0000, v69
	v_lshlrev_b32_e32 v124, 16, v70
	v_and_b32_e32 v125, 0xffff0000, v70
	v_lshlrev_b32_e32 v126, 16, v71
	v_and_b32_e32 v127, 0xffff0000, v71
	v_pk_mul_f32 v[130:131], v[112:113], v[112:113]
	v_pk_fma_f32 v[130:131], v[114:115], v[114:115], v[130:131]
	v_pk_fma_f32 v[130:131], v[116:117], v[116:117], v[130:131]
	v_pk_fma_f32 v[130:131], v[118:119], v[118:119], v[130:131]
	v_pk_fma_f32 v[130:131], v[120:121], v[120:121], v[130:131]
	v_pk_fma_f32 v[130:131], v[122:123], v[122:123], v[130:131]
	v_pk_fma_f32 v[130:131], v[124:125], v[124:125], v[130:131]
	v_pk_fma_f32 v[130:131], v[126:127], v[126:127], v[130:131]
	s_nop 0
	v_add_f32_e32 v130, v130, v131
	s_nop 1
	v_add_f32_dpp v128, v128, v128 quad_perm:[1,0,3,2] row_mask:0xf bank_mask:0xf
	v_add_f32_dpp v130, v130, v130 quad_perm:[1,0,3,2] row_mask:0xf bank_mask:0xf
	s_nop 0
	v_add_f32_dpp v128, v128, v128 quad_perm:[2,3,0,1] row_mask:0xf bank_mask:0xf
	v_add_f32_dpp v130, v130, v130 quad_perm:[2,3,0,1] row_mask:0xf bank_mask:0xf
	s_nop 0
	v_add_f32_dpp v128, v128, v128 row_half_mirror row_mask:0xf bank_mask:0xf
	v_add_f32_dpp v130, v130, v130 row_half_mirror row_mask:0xf bank_mask:0xf
	s_nop 0
	v_add_f32_dpp v128, v128, v128 row_mirror row_mask:0xf bank_mask:0xf
	v_add_f32_dpp v130, v130, v130 row_mirror row_mask:0xf bank_mask:0xf
	s_nop 0
	ds_bpermute_b32 v136, v187, v128
	ds_bpermute_b32 v137, v187, v130
	s_waitcnt lgkmcnt(0)
	v_add_f32_e32 v128, v128, v136
	v_add_f32_e32 v130, v130, v137
	ds_bpermute_b32 v136, v188, v128
	ds_bpermute_b32 v137, v188, v130
	s_waitcnt lgkmcnt(0)
	v_add_f32_e32 v128, v128, v136
	v_add_f32_e32 v130, v130, v137
	v_fmamk_f32 v128, v128, 0x3a800000, v138
	v_fmamk_f32 v130, v130, 0x3a800000, v138
	s_nop 0
	v_rsq_f32_e32 v128, v128
	v_rsq_f32_e32 v130, v130
	s_nop 1
	v_mul_f32_e32 v128, 0.5, v128
	v_mul_f32_e32 v130, 0.5, v130
	s_waitcnt vmcnt(28)
	v_pk_mul_f32 v[96:97], v[128:129], v[96:97] op_sel_hi:[0,1]
	v_pk_mul_f32 v[98:99], v[128:129], v[98:99] op_sel_hi:[0,1]
	v_pk_mul_f32 v[100:101], v[128:129], v[100:101] op_sel_hi:[0,1]
	v_pk_mul_f32 v[102:103], v[128:129], v[102:103] op_sel_hi:[0,1]
	v_pk_mul_f32 v[104:105], v[128:129], v[104:105] op_sel_hi:[0,1]
	v_pk_mul_f32 v[106:107], v[128:129], v[106:107] op_sel_hi:[0,1]
	v_pk_mul_f32 v[108:109], v[128:129], v[108:109] op_sel_hi:[0,1]
	v_pk_mul_f32 v[110:111], v[128:129], v[110:111] op_sel_hi:[0,1]
	v_pk_mul_f32 v[96:97], v[96:97], v[192:193]
	v_pk_mul_f32 v[98:99], v[98:99], v[194:195]
	v_pk_mul_f32 v[100:101], v[100:101], v[196:197]
	v_pk_mul_f32 v[102:103], v[102:103], v[198:199]
	v_pk_mul_f32 v[104:105], v[104:105], v[200:201]
	v_pk_mul_f32 v[106:107], v[106:107], v[202:203]
	v_pk_mul_f32 v[108:109], v[108:109], v[204:205]
	v_pk_mul_f32 v[110:111], v[110:111], v[206:207]
	v_lshlrev_b32_e32 v56, 16, v72
	v_and_b32_e32 v57, 0xffff0000, v72
	v_lshlrev_b32_e32 v58, 16, v73
	v_and_b32_e32 v59, 0xffff0000, v73
	v_lshlrev_b32_e32 v60, 16, v74
	v_and_b32_e32 v61, 0xffff0000, v74
	v_lshlrev_b32_e32 v62, 16, v75
	v_and_b32_e32 v63, 0xffff0000, v75
	v_pk_fma_f32 v[96:97], v[88:89], v[56:57], v[96:97] op_sel_hi:[0,1,1]
	v_pk_fma_f32 v[98:99], v[88:89], v[58:59], v[98:99] op_sel_hi:[0,1,1]
	v_pk_fma_f32 v[100:101], v[88:89], v[60:61], v[100:101] op_sel_hi:[0,1,1]
	v_pk_fma_f32 v[102:103], v[88:89], v[62:63], v[102:103] op_sel_hi:[0,1,1]
	v_lshlrev_b32_e32 v56, 16, v76
	v_and_b32_e32 v57, 0xffff0000, v76
	v_lshlrev_b32_e32 v58, 16, v77
	v_and_b32_e32 v59, 0xffff0000, v77
	v_lshlrev_b32_e32 v60, 16, v78
	v_and_b32_e32 v61, 0xffff0000, v78
	v_lshlrev_b32_e32 v62, 16, v79
	v_and_b32_e32 v63, 0xffff0000, v79
	v_pk_fma_f32 v[104:105], v[88:89], v[56:57], v[104:105] op_sel_hi:[0,1,1]
	v_pk_fma_f32 v[106:107], v[88:89], v[58:59], v[106:107] op_sel_hi:[0,1,1]
	v_pk_fma_f32 v[108:109], v[88:89], v[60:61], v[108:109] op_sel_hi:[0,1,1]
	v_pk_fma_f32 v[110:111], v[88:89], v[62:63], v[110:111] op_sel_hi:[0,1,1]
	v_pk_mul_f32 v[132:133], v[96:97], v[96:97]
	v_pk_fma_f32 v[132:133], v[98:99], v[98:99], v[132:133]
	v_pk_fma_f32 v[132:133], v[100:101], v[100:101], v[132:133]
	v_pk_fma_f32 v[132:133], v[102:103], v[102:103], v[132:133]
;     __device__ __forceinline__ float* out() const { return (float*)karg_in(33); }
; __device__ __forceinline__ void st4_bf16(bf16* p, v4f o) { v2u w; w.x = cvt_pk_nv(o.x, o.y); w.y = cvt_pk_nv(o.z, o.w); *(v2u*)p = w; }
; __device__ __forceinline__ float ssq4(v4f v) { return (v.x * v.x + v.y * v.y) + (v.z * v.z + v.w * v.w); }
; template <int R, bool BASE_F32, bool OUT_F32>
; __device__ __forceinline__ void rows_res(const Ctx& C, int m0, int stride, int mx, const float* gpost, float scale, int lane) {
;     ...
;         for (int r = 0; r < R; ++r) d[r][j] = b[r][j] + d[r][j] * r1[r] * gp; }
;     if (OUT_F32) { float* Y = C.out();
; #pragma unroll
;         for (int r = 0; r < R; ++r)
; #pragma unroll
;             for (int j = 0; j < 4; ++j) if (ok[r]) *(v4f*)(Y + (size_t)mr[r] * DM + 4 * lane + 256 * j) = d[r][j];
;     } else { float* rs = C.RS(); float t[R];
; #pragma unroll
;         for (int r = 0; r < R; ++r) { float s = 0.f;
; #pragma unroll
;             for (int j = 0; j < 4; ++j) s += ssq4(d[r][j]);
;             t[r] = s; }
; #pragma unroll
;         for (int r = 0; r < R; ++r) t[r] = wave_sum(t[r]) * (1.f / DM) + EPS;
; #pragma unroll
;         for (int r = 0; r < R; ++r) { const float rstd = rsqrtf(t[r]);
; #pragma unroll
;             for (int j = 0; j < 4; ++j) if (ok[r]) st4_bf16(XN + (size_t)mr[r] * DM + 4 * lane + 256 * j, d[r][j] * rstd);
;             if (lane == 0 && ok[r]) rs[mr[r]] = sqrtf(t[r]); }
	v_pk_fma_f32 v[132:133], v[104:105], v[104:105], v[132:133]
	v_pk_fma_f32 v[132:133], v[106:107], v[106:107], v[132:133]
	v_pk_fma_f32 v[132:133], v[108:109], v[108:109], v[132:133]
	v_pk_fma_f32 v[132:133], v[110:111], v[110:111], v[132:133]
	s_nop 0
	v_add_f32_e32 v132, v132, v133
	v_pk_mul_f32 v[112:113], v[130:131], v[112:113] op_sel_hi:[0,1]
	v_pk_mul_f32 v[114:115], v[130:131], v[114:115] op_sel_hi:[0,1]
	v_pk_mul_f32 v[116:117], v[130:131], v[116:117] op_sel_hi:[0,1]
	v_pk_mul_f32 v[118:119], v[130:131], v[118:119] op_sel_hi:[0,1]
	v_pk_mul_f32 v[120:121], v[130:131], v[120:121] op_sel_hi:[0,1]
	v_pk_mul_f32 v[122:123], v[130:131], v[122:123] op_sel_hi:[0,1]
	v_pk_mul_f32 v[124:125], v[130:131], v[124:125] op_sel_hi:[0,1]
	v_pk_mul_f32 v[126:127], v[130:131], v[126:127] op_sel_hi:[0,1]
	v_pk_mul_f32 v[112:113], v[112:113], v[192:193]
	v_pk_mul_f32 v[114:115], v[114:115], v[194:195]
	v_pk_mul_f32 v[116:117], v[116:117], v[196:197]
	v_pk_mul_f32 v[118:119], v[118:119], v[198:199]
	v_pk_mul_f32 v[120:121], v[120:121], v[200:201]
	v_pk_mul_f32 v[122:123], v[122:123], v[202:203]
	v_pk_mul_f32 v[124:125], v[124:125], v[204:205]
	v_pk_mul_f32 v[126:127], v[126:127], v[206:207]
	v_lshlrev_b32_e32 v64, 16, v80
	v_and_b32_e32 v65, 0xffff0000, v80
	v_lshlrev_b32_e32 v66, 16, v81
	v_and_b32_e32 v67, 0xffff0000, v81
	v_lshlrev_b32_e32 v68, 16, v82
	v_and_b32_e32 v69, 0xffff0000, v82
	v_lshlrev_b32_e32 v70, 16, v83
	v_and_b32_e32 v71, 0xffff0000, v83
	v_pk_fma_f32 v[112:113], v[90:91], v[64:65], v[112:113] op_sel_hi:[0,1,1]
	v_pk_fma_f32 v[114:115], v[90:91], v[66:67], v[114:115] op_sel_hi:[0,1,1]
	v_pk_fma_f32 v[116:117], v[90:91], v[68:69], v[116:117] op_sel_hi:[0,1,1]
	v_pk_fma_f32 v[118:119], v[90:91], v[70:71], v[118:119] op_sel_hi:[0,1,1]
	v_lshlrev_b32_e32 v64, 16, v84
	v_and_b32_e32 v65, 0xffff0000, v84
	v_lshlrev_b32_e32 v66, 16, v85
	v_and_b32_e32 v67, 0xffff0000, v85
	v_lshlrev_b32_e32 v68, 16, v86
	v_and_b32_e32 v69, 0xffff0000, v86
	v_lshlrev_b32_e32 v70, 16, v87
	v_and_b32_e32 v71, 0xffff0000, v87
	v_pk_fma_f32 v[120:121], v[90:91], v[64:65], v[120:121] op_sel_hi:[0,1,1]
	v_pk_fma_f32 v[122:123], v[90:91], v[66:67], v[122:123] op_sel_hi:[0,1,1]
	v_pk_fma_f32 v[124:125], v[90:91], v[68:69], v[124:125] op_sel_hi:[0,1,1]
	v_pk_fma_f32 v[126:127], v[90:91], v[70:71], v[126:127] op_sel_hi:[0,1,1]
	v_pk_mul_f32 v[134:135], v[112:113], v[112:113]
	v_pk_fma_f32 v[134:135], v[114:115], v[114:115], v[134:135]
	v_pk_fma_f32 v[134:135], v[116:117], v[116:117], v[134:135]
	v_pk_fma_f32 v[134:135], v[118:119], v[118:119], v[134:135]
	v_pk_fma_f32 v[134:135], v[120:121], v[120:121], v[134:135]
	v_pk_fma_f32 v[134:135], v[122:123], v[122:123], v[134:135]
	v_pk_fma_f32 v[134:135], v[124:125], v[124:125], v[134:135]
	v_pk_fma_f32 v[134:135], v[126:127], v[126:127], v[134:135]
	s_nop 0
	v_add_f32_e32 v134, v134, v135
	s_nop 1
	v_add_f32_dpp v132, v132, v132 quad_perm:[1,0,3,2] row_mask:0xf bank_mask:0xf
	v_add_f32_dpp v134, v134, v134 quad_perm:[1,0,3,2] row_mask:0xf bank_mask:0xf
	s_nop 0
	v_add_f32_dpp v132, v132, v132 quad_perm:[2,3,0,1] row_mask:0xf bank_mask:0xf
	v_add_f32_dpp v134, v134, v134 quad_perm:[2,3,0,1] row_mask:0xf bank_mask:0xf
	s_nop 0
	v_add_f32_dpp v132, v132, v132 row_half_mirror row_mask:0xf bank_mask:0xf
	v_add_f32_dpp v134, v134, v134 row_half_mirror row_mask:0xf bank_mask:0xf
	s_nop 0
	v_add_f32_dpp v132, v132, v132 row_mirror row_mask:0xf bank_mask:0xf
	v_add_f32_dpp v134, v134, v134 row_mirror row_mask:0xf bank_mask:0xf
	s_nop 0
	ds_bpermute_b32 v136, v187, v132
	ds_bpermute_b32 v137, v187, v134
	s_waitcnt lgkmcnt(0)
	v_add_f32_e32 v132, v132, v136
	v_add_f32_e32 v134, v134, v137
	ds_bpermute_b32 v136, v188, v132
	ds_bpermute_b32 v137, v188, v134
	s_waitcnt lgkmcnt(0)
	v_add_f32_e32 v132, v132, v136
	v_add_f32_e32 v134, v134, v137
	v_fmamk_f32 v164, v132, 0x3a800000, v138
	v_fmamk_f32 v167, v134, 0x3a800000, v138
	s_nop 0
	v_rsq_f32_e32 v132, v164
	v_rsq_f32_e32 v134, v167
	v_sqrt_f32_e32 v165, v164
	v_sqrt_f32_e32 v168, v167
	s_nop 1
	v_pk_mul_f32 v[140:141], v[96:97], v[132:133] op_sel_hi:[1,0]
	v_cvt_pk_bf16_f32 v148, v140, v141
	v_pk_mul_f32 v[142:143], v[98:99], v[132:133] op_sel_hi:[1,0]
	v_cvt_pk_bf16_f32 v149, v142, v143
	v_pk_mul_f32 v[144:145], v[100:101], v[132:133] op_sel_hi:[1,0]
	v_cvt_pk_bf16_f32 v150, v144, v145
	v_pk_mul_f32 v[146:147], v[102:103], v[132:133] op_sel_hi:[1,0]
	v_cvt_pk_bf16_f32 v151, v146, v147
	v_pk_mul_f32 v[140:141], v[104:105], v[132:133] op_sel_hi:[1,0]
	v_cvt_pk_bf16_f32 v152, v140, v141
	v_pk_mul_f32 v[142:143], v[106:107], v[132:133] op_sel_hi:[1,0]
	v_cvt_pk_bf16_f32 v153, v142, v143
	v_pk_mul_f32 v[144:145], v[108:109], v[132:133] op_sel_hi:[1,0]
	v_cvt_pk_bf16_f32 v154, v144, v145
	v_pk_mul_f32 v[146:147], v[110:111], v[132:133] op_sel_hi:[1,0]
	v_cvt_pk_bf16_f32 v155, v146, v147
	global_store_dwordx2 v173, v[148:149], s[98:99]
	global_store_dwordx2 v173, v[150:151], s[98:99] offset:512
	global_store_dwordx2 v173, v[152:153], s[98:99] offset:1024
	global_store_dwordx2 v173, v[154:155], s[98:99] offset:1536
	v_add_u32_e32 v173, 0x400000, v173
	v_pk_mul_f32 v[140:141], v[112:113], v[134:135] op_sel_hi:[1,0]
	v_cvt_pk_bf16_f32 v156, v140, v141
	v_pk_mul_f32 v[142:143], v[114:115], v[134:135] op_sel_hi:[1,0]
	v_cvt_pk_bf16_f32 v157, v142, v143
	v_pk_mul_f32 v[144:145], v[116:117], v[134:135] op_sel_hi:[1,0]
	v_cvt_pk_bf16_f32 v158, v144, v145
	v_pk_mul_f32 v[146:147], v[118:119], v[134:135] op_sel_hi:[1,0]
	v_cvt_pk_bf16_f32 v159, v146, v147
	v_pk_mul_f32 v[140:141], v[120:121], v[134:135] op_sel_hi:[1,0]
	v_cvt_pk_bf16_f32 v160, v140, v141
	v_pk_mul_f32 v[142:143], v[122:123], v[134:135] op_sel_hi:[1,0]
; __device__ __forceinline__ const float* xrow_ptr(const Ctx& C, int row) { return row < MPROMPT ? C.in(0) + (size_t)row * DM : C.in(1) + (size_t)(row - MPROMPT) * DM; }
; __device__ __forceinline__ v4f ld4_bf16(const bf16* p) { const v2u w = *(const v2u*)p; return (v4f){bf_lo(w.x), bf_hi(w.x), bf_lo(w.y), bf_hi(w.y)}; }
; __device__ __forceinline__ void st4_bf16(bf16* p, v4f o) { v2u w; w.x = cvt_pk_nv(o.x, o.y); w.y = cvt_pk_nv(o.z, o.w); *(v2u*)p = w; }
; __device__ __forceinline__ float ssq4(v4f v) { return (v.x * v.x + v.y * v.y) + (v.z * v.z + v.w * v.w); }
; template <int R, bool BASE_F32, bool OUT_F32>
; __device__ __forceinline__ void rows_res(const Ctx& C, int m0, int stride, int mx, const float* gpost, float scale, int lane) {
;     ...
;     for (int r = 0; r < R; ++r) { mr[r] = (r == 4) ? mx : m0 + r * stride; ok[r] = (r == 4) ? (mx < M) : (mr[r] < MPROMPT); const int mm = ok[r] ? mr[r] : 0;
; #pragma unroll
;         for (int j = 0; j < 4; ++j) d[r][j] = ld4_bf16(D + (size_t)mm * DM + 4 * lane + 256 * j);
;         if (BASE_F32) { const float* x = xrow_ptr(C, mm);
; #pragma unroll
;             for (int j = 0; j < 4; ++j) b[r][j] = ld4_f32(x + 4 * lane + 256 * j);
;         } else { const float inv = C.RS()[mm];
; #pragma unroll
;             for (int j = 0; j < 4; ++j) b[r][j] = ld4_bf16(XN + (size_t)mm * DM + 4 * lane + 256 * j) * inv;
;         } }
; #pragma unroll
;     for (int r = 0; r < R; ++r) { float s = 0.f;
; #pragma unroll
;         for (int j = 0; j < 4; ++j) s += ssq4(d[r][j]);
;         r1[r] = s; }
; #pragma unroll
;     for (int r = 0; r < R; ++r) r1[r] = rsqrtf(wave_sum(r1[r]) * (1.f / DM) + EPS) * scale;
;     ...
;         for (int r = 0; r < R; ++r) { const float rstd = rsqrtf(t[r]);
; #pragma unroll
;             for (int j = 0; j < 4; ++j) if (ok[r]) st4_bf16(XN + (size_t)mr[r] * DM + 4 * lane + 256 * j, d[r][j] * rstd);
;             if (lane == 0 && ok[r]) rs[mr[r]] = sqrtf(t[r]); }
	v_cvt_pk_bf16_f32 v161, v142, v143
	v_pk_mul_f32 v[144:145], v[124:125], v[134:135] op_sel_hi:[1,0]
	v_cvt_pk_bf16_f32 v162, v144, v145
	v_pk_mul_f32 v[146:147], v[126:127], v[134:135] op_sel_hi:[1,0]
	v_cvt_pk_bf16_f32 v163, v146, v147
	global_store_dwordx2 v173, v[156:157], s[98:99]
	global_store_dwordx2 v173, v[158:159], s[98:99] offset:512
	global_store_dwordx2 v173, v[160:161], s[98:99] offset:1024
	global_store_dwordx2 v173, v[162:163], s[98:99] offset:1536
	v_add_u32_e32 v173, 0x400000, v173
	v_add_u32_e32 v166, -1, v165
	v_fma_f32 v140, -v166, v165, v164
	v_cmp_ge_f32_e32 vcc, 0, v140
	v_add_u32_e32 v141, 1, v165
	v_cndmask_b32_e32 v166, v165, v166, vcc
	v_fma_f32 v140, -v141, v165, v164
	v_cmp_lt_f32_e32 vcc, 0, v140
	s_nop 1
	v_cndmask_b32_e32 v165, v166, v141, vcc
	v_add_u32_e32 v169, -1, v168
	v_fma_f32 v142, -v169, v168, v167
	v_cmp_ge_f32_e32 vcc, 0, v142
	v_add_u32_e32 v143, 1, v168
	v_cndmask_b32_e32 v169, v168, v169, vcc
	v_fma_f32 v142, -v143, v168, v167
	v_cmp_lt_f32_e32 vcc, 0, v142
	s_nop 1
	v_cndmask_b32_e32 v168, v169, v143, vcc
	s_mov_b64 exec, 1
	global_store_dword v174, v165, s[98:99]
	v_add_u32_e32 v174, 0x2000, v174
	global_store_dword v174, v168, s[98:99]
	v_add_u32_e32 v174, 0x2000, v174
	s_mov_b64 exec, -1
	global_load_dword v88, v172, s[98:99]
	global_load_dwordx2 v[56:57], v170, s[98:99] nt
	global_load_dwordx2 v[58:59], v170, s[98:99] offset:512 nt
	global_load_dwordx2 v[60:61], v170, s[98:99] offset:1024 nt
	global_load_dwordx2 v[62:63], v170, s[98:99] offset:1536 nt
	global_load_dwordx2 v[72:73], v171, s[98:99]
	global_load_dwordx2 v[74:75], v171, s[98:99] offset:512
	global_load_dwordx2 v[76:77], v171, s[98:99] offset:1024
	global_load_dwordx2 v[78:79], v171, s[98:99] offset:1536
	v_add_u32_e32 v170, 0x400000, v170
	v_add_u32_e32 v171, 0x400000, v171
	v_add_u32_e32 v172, 0x2000, v172
	global_load_dword v90, v172, s[98:99]
	global_load_dwordx2 v[64:65], v170, s[98:99] nt
	global_load_dwordx2 v[66:67], v170, s[98:99] offset:512 nt
	global_load_dwordx2 v[68:69], v170, s[98:99] offset:1024 nt
	global_load_dwordx2 v[70:71], v170, s[98:99] offset:1536 nt
	global_load_dwordx2 v[80:81], v171, s[98:99]
	global_load_dwordx2 v[82:83], v171, s[98:99] offset:512
	global_load_dwordx2 v[84:85], v171, s[98:99] offset:1024
	global_load_dwordx2 v[86:87], v171, s[98:99] offset:1536
	v_add_u32_e32 v170, 0x400000, v170
	v_add_u32_e32 v171, 0x400000, v171
	v_add_u32_e32 v172, 0x2000, v172
	s_waitcnt vmcnt(41)
	v_lshlrev_b32_e32 v96, 16, v20
	v_and_b32_e32 v97, 0xffff0000, v20
	v_lshlrev_b32_e32 v98, 16, v21
	v_and_b32_e32 v99, 0xffff0000, v21
	v_lshlrev_b32_e32 v100, 16, v22
	v_and_b32_e32 v101, 0xffff0000, v22
	v_lshlrev_b32_e32 v102, 16, v23
	v_and_b32_e32 v103, 0xffff0000, v23
	v_lshlrev_b32_e32 v104, 16, v24
	v_and_b32_e32 v105, 0xffff0000, v24
	v_lshlrev_b32_e32 v106, 16, v25
	v_and_b32_e32 v107, 0xffff0000, v25
	v_lshlrev_b32_e32 v108, 16, v26
	v_and_b32_e32 v109, 0xffff0000, v26
	v_lshlrev_b32_e32 v110, 16, v27
	v_and_b32_e32 v111, 0xffff0000, v27
	v_pk_mul_f32 v[128:129], v[96:97], v[96:97]
	v_pk_fma_f32 v[128:129], v[98:99], v[98:99], v[128:129]
	v_pk_fma_f32 v[128:129], v[100:101], v[100:101], v[128:129]
	v_pk_fma_f32 v[128:129], v[102:103], v[102:103], v[128:129]
	v_pk_fma_f32 v[128:129], v[104:105], v[104:105], v[128:129]
	v_pk_fma_f32 v[128:129], v[106:107], v[106:107], v[128:129]
	v_pk_fma_f32 v[128:129], v[108:109], v[108:109], v[128:129]
	v_pk_fma_f32 v[128:129], v[110:111], v[110:111], v[128:129]
	s_nop 0
	v_add_f32_e32 v128, v128, v129
	s_waitcnt vmcnt(32)
	v_lshlrev_b32_e32 v112, 16, v28
	v_and_b32_e32 v113, 0xffff0000, v28
	v_lshlrev_b32_e32 v114, 16, v29
	v_and_b32_e32 v115, 0xffff0000, v29
	v_lshlrev_b32_e32 v116, 16, v30
	v_and_b32_e32 v117, 0xffff0000, v30
	v_lshlrev_b32_e32 v118, 16, v31
	v_and_b32_e32 v119, 0xffff0000, v31
	v_lshlrev_b32_e32 v120, 16, v32
	v_and_b32_e32 v121, 0xffff0000, v32
	v_lshlrev_b32_e32 v122, 16, v33
	v_and_b32_e32 v123, 0xffff0000, v33
	v_lshlrev_b32_e32 v124, 16, v34
	v_and_b32_e32 v125, 0xffff0000, v34
	v_lshlrev_b32_e32 v126, 16, v35
	v_and_b32_e32 v127, 0xffff0000, v35
	v_pk_mul_f32 v[130:131], v[112:113], v[112:113]
	v_pk_fma_f32 v[130:131], v[114:115], v[114:115], v[130:131]
	v_pk_fma_f32 v[130:131], v[116:117], v[116:117], v[130:131]
	v_pk_fma_f32 v[130:131], v[118:119], v[118:119], v[130:131]
	v_pk_fma_f32 v[130:131], v[120:121], v[120:121], v[130:131]
	v_pk_fma_f32 v[130:131], v[122:123], v[122:123], v[130:131]
	v_pk_fma_f32 v[130:131], v[124:125], v[124:125], v[130:131]
	v_pk_fma_f32 v[130:131], v[126:127], v[126:127], v[130:131]
	s_nop 0
	v_add_f32_e32 v130, v130, v131
	s_nop 1
	v_add_f32_dpp v128, v128, v128 quad_perm:[1,0,3,2] row_mask:0xf bank_mask:0xf
	v_add_f32_dpp v130, v130, v130 quad_perm:[1,0,3,2] row_mask:0xf bank_mask:0xf
	s_nop 0
	v_add_f32_dpp v128, v128, v128 quad_perm:[2,3,0,1] row_mask:0xf bank_mask:0xf
	v_add_f32_dpp v130, v130, v130 quad_perm:[2,3,0,1] row_mask:0xf bank_mask:0xf
	s_nop 0
	v_add_f32_dpp v128, v128, v128 row_half_mirror row_mask:0xf bank_mask:0xf
	v_add_f32_dpp v130, v130, v130 row_half_mirror row_mask:0xf bank_mask:0xf
	s_nop 0
	v_add_f32_dpp v128, v128, v128 row_mirror row_mask:0xf bank_mask:0xf
	v_add_f32_dpp v130, v130, v130 row_mirror row_mask:0xf bank_mask:0xf
	s_nop 0
	ds_bpermute_b32 v136, v187, v128
	ds_bpermute_b32 v137, v187, v130
	s_waitcnt lgkmcnt(0)
	v_add_f32_e32 v128, v128, v136
	v_add_f32_e32 v130, v130, v137
	ds_bpermute_b32 v136, v188, v128
	ds_bpermute_b32 v137, v188, v130
	s_waitcnt lgkmcnt(0)
;     __device__ __forceinline__ float* out() const { return (float*)karg_in(33); }
; __device__ __forceinline__ float ssq4(v4f v) { return (v.x * v.x + v.y * v.y) + (v.z * v.z + v.w * v.w); }
; template <int R, bool BASE_F32, bool OUT_F32>
; __device__ __forceinline__ void rows_res(const Ctx& C, int m0, int stride, int mx, const float* gpost, float scale, int lane) {
;     ...
;     for (int r = 0; r < R; ++r) r1[r] = rsqrtf(wave_sum(r1[r]) * (1.f / DM) + EPS) * scale;
; #pragma unroll
;     for (int j = 0; j < 4; ++j) { const v4f gp = ld4_f32(gpost + 4 * lane + 256 * j);
; #pragma unroll
;         for (int r = 0; r < R; ++r) d[r][j] = b[r][j] + d[r][j] * r1[r] * gp; }
;     if (OUT_F32) { float* Y = C.out();
; #pragma unroll
;         for (int r = 0; r < R; ++r)
; #pragma unroll
;             for (int j = 0; j < 4; ++j) if (ok[r]) *(v4f*)(Y + (size_t)mr[r] * DM + 4 * lane + 256 * j) = d[r][j];
;     } else { float* rs = C.RS(); float t[R];
; #pragma unroll
;         for (int r = 0; r < R; ++r) { float s = 0.f;
; #pragma unroll
;             for (int j = 0; j < 4; ++j) s += ssq4(d[r][j]);
;             t[r] = s; }
; #pragma unroll
;         for (int r = 0; r < R; ++r) t[r] = wave_sum(t[r]) * (1.f / DM) + EPS;
	v_add_f32_e32 v128, v128, v136
	v_add_f32_e32 v130, v130, v137
	v_fmamk_f32 v128, v128, 0x3a800000, v138
	v_fmamk_f32 v130, v130, 0x3a800000, v138
	s_nop 0
	v_rsq_f32_e32 v128, v128
	v_rsq_f32_e32 v130, v130
	s_nop 1
	v_mul_f32_e32 v128, 0.5, v128
	v_mul_f32_e32 v130, 0.5, v130
	s_waitcnt vmcnt(28)
	v_pk_mul_f32 v[96:97], v[128:129], v[96:97] op_sel_hi:[0,1]
	v_pk_mul_f32 v[98:99], v[128:129], v[98:99] op_sel_hi:[0,1]
	v_pk_mul_f32 v[100:101], v[128:129], v[100:101] op_sel_hi:[0,1]
	v_pk_mul_f32 v[102:103], v[128:129], v[102:103] op_sel_hi:[0,1]
	v_pk_mul_f32 v[104:105], v[128:129], v[104:105] op_sel_hi:[0,1]
	v_pk_mul_f32 v[106:107], v[128:129], v[106:107] op_sel_hi:[0,1]
	v_pk_mul_f32 v[108:109], v[128:129], v[108:109] op_sel_hi:[0,1]
	v_pk_mul_f32 v[110:111], v[128:129], v[110:111] op_sel_hi:[0,1]
	v_pk_mul_f32 v[96:97], v[96:97], v[192:193]
	v_pk_mul_f32 v[98:99], v[98:99], v[194:195]
	v_pk_mul_f32 v[100:101], v[100:101], v[196:197]
	v_pk_mul_f32 v[102:103], v[102:103], v[198:199]
	v_pk_mul_f32 v[104:105], v[104:105], v[200:201]
	v_pk_mul_f32 v[106:107], v[106:107], v[202:203]
	v_pk_mul_f32 v[108:109], v[108:109], v[204:205]
	v_pk_mul_f32 v[110:111], v[110:111], v[206:207]
	v_lshlrev_b32_e32 v20, 16, v36
	v_and_b32_e32 v21, 0xffff0000, v36
	v_lshlrev_b32_e32 v22, 16, v37
	v_and_b32_e32 v23, 0xffff0000, v37
	v_lshlrev_b32_e32 v24, 16, v38
	v_and_b32_e32 v25, 0xffff0000, v38
	v_lshlrev_b32_e32 v26, 16, v39
	v_and_b32_e32 v27, 0xffff0000, v39
	v_pk_fma_f32 v[96:97], v[52:53], v[20:21], v[96:97] op_sel_hi:[0,1,1]
	v_pk_fma_f32 v[98:99], v[52:53], v[22:23], v[98:99] op_sel_hi:[0,1,1]
	v_pk_fma_f32 v[100:101], v[52:53], v[24:25], v[100:101] op_sel_hi:[0,1,1]
	v_pk_fma_f32 v[102:103], v[52:53], v[26:27], v[102:103] op_sel_hi:[0,1,1]
	v_lshlrev_b32_e32 v20, 16, v40
	v_and_b32_e32 v21, 0xffff0000, v40
	v_lshlrev_b32_e32 v22, 16, v41
	v_and_b32_e32 v23, 0xffff0000, v41
	v_lshlrev_b32_e32 v24, 16, v42
	v_and_b32_e32 v25, 0xffff0000, v42
	v_lshlrev_b32_e32 v26, 16, v43
	v_and_b32_e32 v27, 0xffff0000, v43
	v_pk_fma_f32 v[104:105], v[52:53], v[20:21], v[104:105] op_sel_hi:[0,1,1]
	v_pk_fma_f32 v[106:107], v[52:53], v[22:23], v[106:107] op_sel_hi:[0,1,1]
	v_pk_fma_f32 v[108:109], v[52:53], v[24:25], v[108:109] op_sel_hi:[0,1,1]
	v_pk_fma_f32 v[110:111], v[52:53], v[26:27], v[110:111] op_sel_hi:[0,1,1]
	v_pk_mul_f32 v[132:133], v[96:97], v[96:97]
	v_pk_fma_f32 v[132:133], v[98:99], v[98:99], v[132:133]
	v_pk_fma_f32 v[132:133], v[100:101], v[100:101], v[132:133]
	v_pk_fma_f32 v[132:133], v[102:103], v[102:103], v[132:133]
	v_pk_fma_f32 v[132:133], v[104:105], v[104:105], v[132:133]
	v_pk_fma_f32 v[132:133], v[106:107], v[106:107], v[132:133]
	v_pk_fma_f32 v[132:133], v[108:109], v[108:109], v[132:133]
	v_pk_fma_f32 v[132:133], v[110:111], v[110:111], v[132:133]
	s_nop 0
	v_add_f32_e32 v132, v132, v133
	v_pk_mul_f32 v[112:113], v[130:131], v[112:113] op_sel_hi:[0,1]
	v_pk_mul_f32 v[114:115], v[130:131], v[114:115] op_sel_hi:[0,1]
	v_pk_mul_f32 v[116:117], v[130:131], v[116:117] op_sel_hi:[0,1]
	v_pk_mul_f32 v[118:119], v[130:131], v[118:119] op_sel_hi:[0,1]
	v_pk_mul_f32 v[120:121], v[130:131], v[120:121] op_sel_hi:[0,1]
	v_pk_mul_f32 v[122:123], v[130:131], v[122:123] op_sel_hi:[0,1]
	v_pk_mul_f32 v[124:125], v[130:131], v[124:125] op_sel_hi:[0,1]
	v_pk_mul_f32 v[126:127], v[130:131], v[126:127] op_sel_hi:[0,1]
	v_pk_mul_f32 v[112:113], v[112:113], v[192:193]
	v_pk_mul_f32 v[114:115], v[114:115], v[194:195]
	v_pk_mul_f32 v[116:117], v[116:117], v[196:197]
	v_pk_mul_f32 v[118:119], v[118:119], v[198:199]
	v_pk_mul_f32 v[120:121], v[120:121], v[200:201]
	v_pk_mul_f32 v[122:123], v[122:123], v[202:203]
	v_pk_mul_f32 v[124:125], v[124:125], v[204:205]
	v_pk_mul_f32 v[126:127], v[126:127], v[206:207]
	v_lshlrev_b32_e32 v28, 16, v44
	v_and_b32_e32 v29, 0xffff0000, v44
	v_lshlrev_b32_e32 v30, 16, v45
	v_and_b32_e32 v31, 0xffff0000, v45
	v_lshlrev_b32_e32 v32, 16, v46
	v_and_b32_e32 v33, 0xffff0000, v46
	v_lshlrev_b32_e32 v34, 16, v47
	v_and_b32_e32 v35, 0xffff0000, v47
	v_pk_fma_f32 v[112:113], v[54:55], v[28:29], v[112:113] op_sel_hi:[0,1,1]
	v_pk_fma_f32 v[114:115], v[54:55], v[30:31], v[114:115] op_sel_hi:[0,1,1]
	v_pk_fma_f32 v[116:117], v[54:55], v[32:33], v[116:117] op_sel_hi:[0,1,1]
	v_pk_fma_f32 v[118:119], v[54:55], v[34:35], v[118:119] op_sel_hi:[0,1,1]
	v_lshlrev_b32_e32 v28, 16, v48
	v_and_b32_e32 v29, 0xffff0000, v48
	v_lshlrev_b32_e32 v30, 16, v49
	v_and_b32_e32 v31, 0xffff0000, v49
	v_lshlrev_b32_e32 v32, 16, v50
	v_and_b32_e32 v33, 0xffff0000, v50
	v_lshlrev_b32_e32 v34, 16, v51
	v_and_b32_e32 v35, 0xffff0000, v51
	v_pk_fma_f32 v[120:121], v[54:55], v[28:29], v[120:121] op_sel_hi:[0,1,1]
	v_pk_fma_f32 v[122:123], v[54:55], v[30:31], v[122:123] op_sel_hi:[0,1,1]
	v_pk_fma_f32 v[124:125], v[54:55], v[32:33], v[124:125] op_sel_hi:[0,1,1]
	v_pk_fma_f32 v[126:127], v[54:55], v[34:35], v[126:127] op_sel_hi:[0,1,1]
	v_pk_mul_f32 v[134:135], v[112:113], v[112:113]
	v_pk_fma_f32 v[134:135], v[114:115], v[114:115], v[134:135]
	v_pk_fma_f32 v[134:135], v[116:117], v[116:117], v[134:135]
	v_pk_fma_f32 v[134:135], v[118:119], v[118:119], v[134:135]
	v_pk_fma_f32 v[134:135], v[120:121], v[120:121], v[134:135]
	v_pk_fma_f32 v[134:135], v[122:123], v[122:123], v[134:135]
	v_pk_fma_f32 v[134:135], v[124:125], v[124:125], v[134:135]
	v_pk_fma_f32 v[134:135], v[126:127], v[126:127], v[134:135]
	s_nop 0
	v_add_f32_e32 v134, v134, v135
	s_nop 1
	v_add_f32_dpp v132, v132, v132 quad_perm:[1,0,3,2] row_mask:0xf bank_mask:0xf
	v_add_f32_dpp v134, v134, v134 quad_perm:[1,0,3,2] row_mask:0xf bank_mask:0xf
	s_nop 0
	v_add_f32_dpp v132, v132, v132 quad_perm:[2,3,0,1] row_mask:0xf bank_mask:0xf
	v_add_f32_dpp v134, v134, v134 quad_perm:[2,3,0,1] row_mask:0xf bank_mask:0xf
	s_nop 0
	v_add_f32_dpp v132, v132, v132 row_half_mirror row_mask:0xf bank_mask:0xf
	v_add_f32_dpp v134, v134, v134 row_half_mirror row_mask:0xf bank_mask:0xf
	s_nop 0
	v_add_f32_dpp v132, v132, v132 row_mirror row_mask:0xf bank_mask:0xf
	v_add_f32_dpp v134, v134, v134 row_mirror row_mask:0xf bank_mask:0xf
	s_nop 0
	ds_bpermute_b32 v136, v187, v132
	ds_bpermute_b32 v137, v187, v134
	s_waitcnt lgkmcnt(0)
; __device__ __forceinline__ const float* xrow_ptr(const Ctx& C, int row) { return row < MPROMPT ? C.in(0) + (size_t)row * DM : C.in(1) + (size_t)(row - MPROMPT) * DM; }
; __device__ __forceinline__ v4f ld4_bf16(const bf16* p) { const v2u w = *(const v2u*)p; return (v4f){bf_lo(w.x), bf_hi(w.x), bf_lo(w.y), bf_hi(w.y)}; }
; __device__ __forceinline__ void st4_bf16(bf16* p, v4f o) { v2u w; w.x = cvt_pk_nv(o.x, o.y); w.y = cvt_pk_nv(o.z, o.w); *(v2u*)p = w; }
; __device__ __forceinline__ float ssq4(v4f v) { return (v.x * v.x + v.y * v.y) + (v.z * v.z + v.w * v.w); }
; template <int R, bool BASE_F32, bool OUT_F32>
; __device__ __forceinline__ void rows_res(const Ctx& C, int m0, int stride, int mx, const float* gpost, float scale, int lane) {
;     ...
;     for (int r = 0; r < R; ++r) { mr[r] = (r == 4) ? mx : m0 + r * stride; ok[r] = (r == 4) ? (mx < M) : (mr[r] < MPROMPT); const int mm = ok[r] ? mr[r] : 0;
; #pragma unroll
;         for (int j = 0; j < 4; ++j) d[r][j] = ld4_bf16(D + (size_t)mm * DM + 4 * lane + 256 * j);
;         if (BASE_F32) { const float* x = xrow_ptr(C, mm);
; #pragma unroll
;             for (int j = 0; j < 4; ++j) b[r][j] = ld4_f32(x + 4 * lane + 256 * j);
;         } else { const float inv = C.RS()[mm];
; #pragma unroll
;             for (int j = 0; j < 4; ++j) b[r][j] = ld4_bf16(XN + (size_t)mm * DM + 4 * lane + 256 * j) * inv;
;         } }
; #pragma unroll
;     for (int r = 0; r < R; ++r) { float s = 0.f;
; #pragma unroll
;         for (int j = 0; j < 4; ++j) s += ssq4(d[r][j]);
;         r1[r] = s; }
;     ...
;             for (int j = 0; j < 4; ++j) s += ssq4(d[r][j]);
;             t[r] = s; }
; #pragma unroll
;         for (int r = 0; r < R; ++r) t[r] = wave_sum(t[r]) * (1.f / DM) + EPS;
; #pragma unroll
;         for (int r = 0; r < R; ++r) { const float rstd = rsqrtf(t[r]);
; #pragma unroll
;             for (int j = 0; j < 4; ++j) if (ok[r]) st4_bf16(XN + (size_t)mr[r] * DM + 4 * lane + 256 * j, d[r][j] * rstd);
;             if (lane == 0 && ok[r]) rs[mr[r]] = sqrtf(t[r]); }
	v_add_f32_e32 v132, v132, v136
	v_add_f32_e32 v134, v134, v137
	ds_bpermute_b32 v136, v188, v132
	ds_bpermute_b32 v137, v188, v134
	s_waitcnt lgkmcnt(0)
	v_add_f32_e32 v132, v132, v136
	v_add_f32_e32 v134, v134, v137
	v_fmamk_f32 v164, v132, 0x3a800000, v138
	v_fmamk_f32 v167, v134, 0x3a800000, v138
	s_nop 0
	v_rsq_f32_e32 v132, v164
	v_rsq_f32_e32 v134, v167
	v_sqrt_f32_e32 v165, v164
	v_sqrt_f32_e32 v168, v167
	s_nop 1
	v_pk_mul_f32 v[140:141], v[96:97], v[132:133] op_sel_hi:[1,0]
	v_cvt_pk_bf16_f32 v148, v140, v141
	v_pk_mul_f32 v[142:143], v[98:99], v[132:133] op_sel_hi:[1,0]
	v_cvt_pk_bf16_f32 v149, v142, v143
	v_pk_mul_f32 v[144:145], v[100:101], v[132:133] op_sel_hi:[1,0]
	v_cvt_pk_bf16_f32 v150, v144, v145
	v_pk_mul_f32 v[146:147], v[102:103], v[132:133] op_sel_hi:[1,0]
	v_cvt_pk_bf16_f32 v151, v146, v147
	v_pk_mul_f32 v[140:141], v[104:105], v[132:133] op_sel_hi:[1,0]
	v_cvt_pk_bf16_f32 v152, v140, v141
	v_pk_mul_f32 v[142:143], v[106:107], v[132:133] op_sel_hi:[1,0]
	v_cvt_pk_bf16_f32 v153, v142, v143
	v_pk_mul_f32 v[144:145], v[108:109], v[132:133] op_sel_hi:[1,0]
	v_cvt_pk_bf16_f32 v154, v144, v145
	v_pk_mul_f32 v[146:147], v[110:111], v[132:133] op_sel_hi:[1,0]
	v_cvt_pk_bf16_f32 v155, v146, v147
	global_store_dwordx2 v173, v[148:149], s[98:99]
	global_store_dwordx2 v173, v[150:151], s[98:99] offset:512
	global_store_dwordx2 v173, v[152:153], s[98:99] offset:1024
	global_store_dwordx2 v173, v[154:155], s[98:99] offset:1536
	v_add_u32_e32 v173, 0x400000, v173
	v_pk_mul_f32 v[140:141], v[112:113], v[134:135] op_sel_hi:[1,0]
	v_cvt_pk_bf16_f32 v156, v140, v141
	v_pk_mul_f32 v[142:143], v[114:115], v[134:135] op_sel_hi:[1,0]
	v_cvt_pk_bf16_f32 v157, v142, v143
	v_pk_mul_f32 v[144:145], v[116:117], v[134:135] op_sel_hi:[1,0]
	v_cvt_pk_bf16_f32 v158, v144, v145
	v_pk_mul_f32 v[146:147], v[118:119], v[134:135] op_sel_hi:[1,0]
	v_cvt_pk_bf16_f32 v159, v146, v147
	v_pk_mul_f32 v[140:141], v[120:121], v[134:135] op_sel_hi:[1,0]
	v_cvt_pk_bf16_f32 v160, v140, v141
	v_pk_mul_f32 v[142:143], v[122:123], v[134:135] op_sel_hi:[1,0]
	v_cvt_pk_bf16_f32 v161, v142, v143
	v_pk_mul_f32 v[144:145], v[124:125], v[134:135] op_sel_hi:[1,0]
	v_cvt_pk_bf16_f32 v162, v144, v145
	v_pk_mul_f32 v[146:147], v[126:127], v[134:135] op_sel_hi:[1,0]
	v_cvt_pk_bf16_f32 v163, v146, v147
	global_store_dwordx2 v173, v[156:157], s[98:99]
	global_store_dwordx2 v173, v[158:159], s[98:99] offset:512
	global_store_dwordx2 v173, v[160:161], s[98:99] offset:1024
	global_store_dwordx2 v173, v[162:163], s[98:99] offset:1536
	v_add_u32_e32 v173, 0x400000, v173
	v_add_u32_e32 v166, -1, v165
	v_fma_f32 v140, -v166, v165, v164
	v_cmp_ge_f32_e32 vcc, 0, v140
	v_add_u32_e32 v141, 1, v165
	v_cndmask_b32_e32 v166, v165, v166, vcc
	v_fma_f32 v140, -v141, v165, v164
	v_cmp_lt_f32_e32 vcc, 0, v140
	s_nop 1
	v_cndmask_b32_e32 v165, v166, v141, vcc
	v_add_u32_e32 v169, -1, v168
	v_fma_f32 v142, -v169, v168, v167
	v_cmp_ge_f32_e32 vcc, 0, v142
	v_add_u32_e32 v143, 1, v168
	v_cndmask_b32_e32 v169, v168, v169, vcc
	v_fma_f32 v142, -v143, v168, v167
	v_cmp_lt_f32_e32 vcc, 0, v142
	s_nop 1
	v_cndmask_b32_e32 v168, v169, v143, vcc
	s_mov_b64 exec, 1
	global_store_dword v174, v165, s[98:99]
	v_add_u32_e32 v174, 0x2000, v174
	global_store_dword v174, v168, s[98:99]
	v_add_u32_e32 v174, 0x2000, v174
	s_mov_b64 exec, -1
	global_load_dword v52, v172, s[98:99]
	global_load_dwordx2 v[20:21], v170, s[98:99] nt
	global_load_dwordx2 v[22:23], v170, s[98:99] offset:512 nt
	global_load_dwordx2 v[24:25], v170, s[98:99] offset:1024 nt
	global_load_dwordx2 v[26:27], v170, s[98:99] offset:1536 nt
	global_load_dwordx2 v[36:37], v171, s[98:99]
	global_load_dwordx2 v[38:39], v171, s[98:99] offset:512
	global_load_dwordx2 v[40:41], v171, s[98:99] offset:1024
	global_load_dwordx2 v[42:43], v171, s[98:99] offset:1536
	v_add_u32_e32 v170, 0x400000, v170
	v_add_u32_e32 v171, 0x400000, v171
	v_add_u32_e32 v172, 0x2000, v172
	global_load_dword v54, v172, s[98:99]
	global_load_dwordx2 v[28:29], v170, s[98:99] nt
	global_load_dwordx2 v[30:31], v170, s[98:99] offset:512 nt
	global_load_dwordx2 v[32:33], v170, s[98:99] offset:1024 nt
	global_load_dwordx2 v[34:35], v170, s[98:99] offset:1536 nt
	global_load_dwordx2 v[44:45], v171, s[98:99]
	global_load_dwordx2 v[46:47], v171, s[98:99] offset:512
	global_load_dwordx2 v[48:49], v171, s[98:99] offset:1024
	global_load_dwordx2 v[50:51], v171, s[98:99] offset:1536
	v_add_u32_e32 v170, 0x400000, v170
	v_add_u32_e32 v171, 0x400000, v171
	v_add_u32_e32 v172, 0x2000, v172
	s_waitcnt vmcnt(41)
	v_lshlrev_b32_e32 v96, 16, v56
	v_and_b32_e32 v97, 0xffff0000, v56
	v_lshlrev_b32_e32 v98, 16, v57
	v_and_b32_e32 v99, 0xffff0000, v57
	v_lshlrev_b32_e32 v100, 16, v58
	v_and_b32_e32 v101, 0xffff0000, v58
	v_lshlrev_b32_e32 v102, 16, v59
	v_and_b32_e32 v103, 0xffff0000, v59
	v_lshlrev_b32_e32 v104, 16, v60
	v_and_b32_e32 v105, 0xffff0000, v60
	v_lshlrev_b32_e32 v106, 16, v61
	v_and_b32_e32 v107, 0xffff0000, v61
	v_lshlrev_b32_e32 v108, 16, v62
	v_and_b32_e32 v109, 0xffff0000, v62
	v_lshlrev_b32_e32 v110, 16, v63
	v_and_b32_e32 v111, 0xffff0000, v63
	v_pk_mul_f32 v[128:129], v[96:97], v[96:97]
	v_pk_fma_f32 v[128:129], v[98:99], v[98:99], v[128:129]
	v_pk_fma_f32 v[128:129], v[100:101], v[100:101], v[128:129]
	v_pk_fma_f32 v[128:129], v[102:103], v[102:103], v[128:129]
	v_pk_fma_f32 v[128:129], v[104:105], v[104:105], v[128:129]
	v_pk_fma_f32 v[128:129], v[106:107], v[106:107], v[128:129]
	v_pk_fma_f32 v[128:129], v[108:109], v[108:109], v[128:129]
	v_pk_fma_f32 v[128:129], v[110:111], v[110:111], v[128:129]
	s_nop 0
	v_add_f32_e32 v128, v128, v129
	s_waitcnt vmcnt(32)
; __device__ __forceinline__ float ssq4(v4f v) { return (v.x * v.x + v.y * v.y) + (v.z * v.z + v.w * v.w); }
; template <int R, bool BASE_F32, bool OUT_F32>
; __device__ __forceinline__ void rows_res(const Ctx& C, int m0, int stride, int mx, const float* gpost, float scale, int lane) {
;     ...
;     for (int r = 0; r < R; ++r) { float s = 0.f;
; #pragma unroll
;         for (int j = 0; j < 4; ++j) s += ssq4(d[r][j]);
;         r1[r] = s; }
; #pragma unroll
;     for (int r = 0; r < R; ++r) r1[r] = rsqrtf(wave_sum(r1[r]) * (1.f / DM) + EPS) * scale;
; #pragma unroll
;     for (int j = 0; j < 4; ++j) { const v4f gp = ld4_f32(gpost + 4 * lane + 256 * j);
; #pragma unroll
;         for (int r = 0; r < R; ++r) d[r][j] = b[r][j] + d[r][j] * r1[r] * gp; }
	v_lshlrev_b32_e32 v112, 16, v64
	v_and_b32_e32 v113, 0xffff0000, v64
	v_lshlrev_b32_e32 v114, 16, v65
	v_and_b32_e32 v115, 0xffff0000, v65
	v_lshlrev_b32_e32 v116, 16, v66
	v_and_b32_e32 v117, 0xffff0000, v66
	v_lshlrev_b32_e32 v118, 16, v67
	v_and_b32_e32 v119, 0xffff0000, v67
	v_lshlrev_b32_e32 v120, 16, v68
	v_and_b32_e32 v121, 0xffff0000, v68
	v_lshlrev_b32_e32 v122, 16, v69
	v_and_b32_e32 v123, 0xffff0000, v69
	v_lshlrev_b32_e32 v124, 16, v70
	v_and_b32_e32 v125, 0xffff0000, v70
	v_lshlrev_b32_e32 v126, 16, v71
	v_and_b32_e32 v127, 0xffff0000, v71
	v_pk_mul_f32 v[130:131], v[112:113], v[112:113]
	v_pk_fma_f32 v[130:131], v[114:115], v[114:115], v[130:131]
	v_pk_fma_f32 v[130:131], v[116:117], v[116:117], v[130:131]
	v_pk_fma_f32 v[130:131], v[118:119], v[118:119], v[130:131]
	v_pk_fma_f32 v[130:131], v[120:121], v[120:121], v[130:131]
	v_pk_fma_f32 v[130:131], v[122:123], v[122:123], v[130:131]
	v_pk_fma_f32 v[130:131], v[124:125], v[124:125], v[130:131]
	v_pk_fma_f32 v[130:131], v[126:127], v[126:127], v[130:131]
	s_nop 0
	v_add_f32_e32 v130, v130, v131
	s_nop 1
	v_add_f32_dpp v128, v128, v128 quad_perm:[1,0,3,2] row_mask:0xf bank_mask:0xf
	v_add_f32_dpp v130, v130, v130 quad_perm:[1,0,3,2] row_mask:0xf bank_mask:0xf
	s_nop 0
	v_add_f32_dpp v128, v128, v128 quad_perm:[2,3,0,1] row_mask:0xf bank_mask:0xf
	v_add_f32_dpp v130, v130, v130 quad_perm:[2,3,0,1] row_mask:0xf bank_mask:0xf
	s_nop 0
	v_add_f32_dpp v128, v128, v128 row_half_mirror row_mask:0xf bank_mask:0xf
	v_add_f32_dpp v130, v130, v130 row_half_mirror row_mask:0xf bank_mask:0xf
	s_nop 0
	v_add_f32_dpp v128, v128, v128 row_mirror row_mask:0xf bank_mask:0xf
	v_add_f32_dpp v130, v130, v130 row_mirror row_mask:0xf bank_mask:0xf
	s_nop 0
	ds_bpermute_b32 v136, v187, v128
	ds_bpermute_b32 v137, v187, v130
	s_waitcnt lgkmcnt(0)
	v_add_f32_e32 v128, v128, v136
	v_add_f32_e32 v130, v130, v137
	ds_bpermute_b32 v136, v188, v128
	ds_bpermute_b32 v137, v188, v130
	s_waitcnt lgkmcnt(0)
	v_add_f32_e32 v128, v128, v136
	v_add_f32_e32 v130, v130, v137
	v_fmamk_f32 v128, v128, 0x3a800000, v138
	v_fmamk_f32 v130, v130, 0x3a800000, v138
	s_nop 0
	v_rsq_f32_e32 v128, v128
	v_rsq_f32_e32 v130, v130
	s_nop 1
	v_mul_f32_e32 v128, 0.5, v128
	v_mul_f32_e32 v130, 0.5, v130
	s_waitcnt vmcnt(28)
	v_pk_mul_f32 v[96:97], v[128:129], v[96:97] op_sel_hi:[0,1]
	v_pk_mul_f32 v[98:99], v[128:129], v[98:99] op_sel_hi:[0,1]
	v_pk_mul_f32 v[100:101], v[128:129], v[100:101] op_sel_hi:[0,1]
	v_pk_mul_f32 v[102:103], v[128:129], v[102:103] op_sel_hi:[0,1]
	v_pk_mul_f32 v[104:105], v[128:129], v[104:105] op_sel_hi:[0,1]
	v_pk_mul_f32 v[106:107], v[128:129], v[106:107] op_sel_hi:[0,1]
	v_pk_mul_f32 v[108:109], v[128:129], v[108:109] op_sel_hi:[0,1]
	v_pk_mul_f32 v[110:111], v[128:129], v[110:111] op_sel_hi:[0,1]
	v_pk_mul_f32 v[96:97], v[96:97], v[192:193]
	v_pk_mul_f32 v[98:99], v[98:99], v[194:195]
	v_pk_mul_f32 v[100:101], v[100:101], v[196:197]
	v_pk_mul_f32 v[102:103], v[102:103], v[198:199]
	v_pk_mul_f32 v[104:105], v[104:105], v[200:201]
	v_pk_mul_f32 v[106:107], v[106:107], v[202:203]
	v_pk_mul_f32 v[108:109], v[108:109], v[204:205]
	v_pk_mul_f32 v[110:111], v[110:111], v[206:207]
	v_lshlrev_b32_e32 v56, 16, v72
	v_and_b32_e32 v57, 0xffff0000, v72
	v_lshlrev_b32_e32 v58, 16, v73
	v_and_b32_e32 v59, 0xffff0000, v73
	v_lshlrev_b32_e32 v60, 16, v74
	v_and_b32_e32 v61, 0xffff0000, v74
	v_lshlrev_b32_e32 v62, 16, v75
	v_and_b32_e32 v63, 0xffff0000, v75
	v_pk_fma_f32 v[96:97], v[88:89], v[56:57], v[96:97] op_sel_hi:[0,1,1]
	v_pk_fma_f32 v[98:99], v[88:89], v[58:59], v[98:99] op_sel_hi:[0,1,1]
	v_pk_fma_f32 v[100:101], v[88:89], v[60:61], v[100:101] op_sel_hi:[0,1,1]
	v_pk_fma_f32 v[102:103], v[88:89], v[62:63], v[102:103] op_sel_hi:[0,1,1]
	v_lshlrev_b32_e32 v56, 16, v76
	v_and_b32_e32 v57, 0xffff0000, v76
	v_lshlrev_b32_e32 v58, 16, v77
	v_and_b32_e32 v59, 0xffff0000, v77
	v_lshlrev_b32_e32 v60, 16, v78
	v_and_b32_e32 v61, 0xffff0000, v78
	v_lshlrev_b32_e32 v62, 16, v79
	v_and_b32_e32 v63, 0xffff0000, v79
	v_pk_fma_f32 v[104:105], v[88:89], v[56:57], v[104:105] op_sel_hi:[0,1,1]
	v_pk_fma_f32 v[106:107], v[88:89], v[58:59], v[106:107] op_sel_hi:[0,1,1]
	v_pk_fma_f32 v[108:109], v[88:89], v[60:61], v[108:109] op_sel_hi:[0,1,1]
	v_pk_fma_f32 v[110:111], v[88:89], v[62:63], v[110:111] op_sel_hi:[0,1,1]
	v_pk_mul_f32 v[132:133], v[96:97], v[96:97]
	v_pk_fma_f32 v[132:133], v[98:99], v[98:99], v[132:133]
	v_pk_fma_f32 v[132:133], v[100:101], v[100:101], v[132:133]
	v_pk_fma_f32 v[132:133], v[102:103], v[102:103], v[132:133]
	v_pk_fma_f32 v[132:133], v[104:105], v[104:105], v[132:133]
	v_pk_fma_f32 v[132:133], v[106:107], v[106:107], v[132:133]
	v_pk_fma_f32 v[132:133], v[108:109], v[108:109], v[132:133]
	v_pk_fma_f32 v[132:133], v[110:111], v[110:111], v[132:133]
	s_nop 0
	v_add_f32_e32 v132, v132, v133
	v_pk_mul_f32 v[112:113], v[130:131], v[112:113] op_sel_hi:[0,1]
	v_pk_mul_f32 v[114:115], v[130:131], v[114:115] op_sel_hi:[0,1]
	v_pk_mul_f32 v[116:117], v[130:131], v[116:117] op_sel_hi:[0,1]
	v_pk_mul_f32 v[118:119], v[130:131], v[118:119] op_sel_hi:[0,1]
	v_pk_mul_f32 v[120:121], v[130:131], v[120:121] op_sel_hi:[0,1]
	v_pk_mul_f32 v[122:123], v[130:131], v[122:123] op_sel_hi:[0,1]
	v_pk_mul_f32 v[124:125], v[130:131], v[124:125] op_sel_hi:[0,1]
	v_pk_mul_f32 v[126:127], v[130:131], v[126:127] op_sel_hi:[0,1]
	v_pk_mul_f32 v[112:113], v[112:113], v[192:193]
	v_pk_mul_f32 v[114:115], v[114:115], v[194:195]
	v_pk_mul_f32 v[116:117], v[116:117], v[196:197]
	v_pk_mul_f32 v[118:119], v[118:119], v[198:199]
	v_pk_mul_f32 v[120:121], v[120:121], v[200:201]
	v_pk_mul_f32 v[122:123], v[122:123], v[202:203]
;     __device__ __forceinline__ float* out() const { return (float*)karg_in(33); }
; __device__ __forceinline__ const float* xrow_ptr(const Ctx& C, int row) { return row < MPROMPT ? C.in(0) + (size_t)row * DM : C.in(1) + (size_t)(row - MPROMPT) * DM; }
; __device__ __forceinline__ v4f ld4_bf16(const bf16* p) { const v2u w = *(const v2u*)p; return (v4f){bf_lo(w.x), bf_hi(w.x), bf_lo(w.y), bf_hi(w.y)}; }
; __device__ __forceinline__ void st4_bf16(bf16* p, v4f o) { v2u w; w.x = cvt_pk_nv(o.x, o.y); w.y = cvt_pk_nv(o.z, o.w); *(v2u*)p = w; }
; __device__ __forceinline__ float ssq4(v4f v) { return (v.x * v.x + v.y * v.y) + (v.z * v.z + v.w * v.w); }
; template <int R, bool BASE_F32, bool OUT_F32>
; __device__ __forceinline__ void rows_res(const Ctx& C, int m0, int stride, int mx, const float* gpost, float scale, int lane) {
;     ...
;     for (int r = 0; r < R; ++r) { mr[r] = (r == 4) ? mx : m0 + r * stride; ok[r] = (r == 4) ? (mx < M) : (mr[r] < MPROMPT); const int mm = ok[r] ? mr[r] : 0;
; #pragma unroll
;         for (int j = 0; j < 4; ++j) d[r][j] = ld4_bf16(D + (size_t)mm * DM + 4 * lane + 256 * j);
;         if (BASE_F32) { const float* x = xrow_ptr(C, mm);
; #pragma unroll
;             for (int j = 0; j < 4; ++j) b[r][j] = ld4_f32(x + 4 * lane + 256 * j);
;         } else { const float inv = C.RS()[mm];
; #pragma unroll
;             for (int j = 0; j < 4; ++j) b[r][j] = ld4_bf16(XN + (size_t)mm * DM + 4 * lane + 256 * j) * inv;
;         } }
;     ...
;         for (int r = 0; r < R; ++r) d[r][j] = b[r][j] + d[r][j] * r1[r] * gp; }
;     if (OUT_F32) { float* Y = C.out();
; #pragma unroll
;         for (int r = 0; r < R; ++r)
; #pragma unroll
;             for (int j = 0; j < 4; ++j) if (ok[r]) *(v4f*)(Y + (size_t)mr[r] * DM + 4 * lane + 256 * j) = d[r][j];
;     } else { float* rs = C.RS(); float t[R];
; #pragma unroll
;         for (int r = 0; r < R; ++r) { float s = 0.f;
; #pragma unroll
;             for (int j = 0; j < 4; ++j) s += ssq4(d[r][j]);
;             t[r] = s; }
; #pragma unroll
;         for (int r = 0; r < R; ++r) t[r] = wave_sum(t[r]) * (1.f / DM) + EPS;
; #pragma unroll
;         for (int r = 0; r < R; ++r) { const float rstd = rsqrtf(t[r]);
; #pragma unroll
;             for (int j = 0; j < 4; ++j) if (ok[r]) st4_bf16(XN + (size_t)mr[r] * DM + 4 * lane + 256 * j, d[r][j] * rstd);
;             if (lane == 0 && ok[r]) rs[mr[r]] = sqrtf(t[r]); }
	v_pk_mul_f32 v[124:125], v[124:125], v[204:205]
	v_pk_mul_f32 v[126:127], v[126:127], v[206:207]
	v_lshlrev_b32_e32 v64, 16, v80
	v_and_b32_e32 v65, 0xffff0000, v80
	v_lshlrev_b32_e32 v66, 16, v81
	v_and_b32_e32 v67, 0xffff0000, v81
	v_lshlrev_b32_e32 v68, 16, v82
	v_and_b32_e32 v69, 0xffff0000, v82
	v_lshlrev_b32_e32 v70, 16, v83
	v_and_b32_e32 v71, 0xffff0000, v83
	v_pk_fma_f32 v[112:113], v[90:91], v[64:65], v[112:113] op_sel_hi:[0,1,1]
	v_pk_fma_f32 v[114:115], v[90:91], v[66:67], v[114:115] op_sel_hi:[0,1,1]
	v_pk_fma_f32 v[116:117], v[90:91], v[68:69], v[116:117] op_sel_hi:[0,1,1]
	v_pk_fma_f32 v[118:119], v[90:91], v[70:71], v[118:119] op_sel_hi:[0,1,1]
	v_lshlrev_b32_e32 v64, 16, v84
	v_and_b32_e32 v65, 0xffff0000, v84
	v_lshlrev_b32_e32 v66, 16, v85
	v_and_b32_e32 v67, 0xffff0000, v85
	v_lshlrev_b32_e32 v68, 16, v86
	v_and_b32_e32 v69, 0xffff0000, v86
	v_lshlrev_b32_e32 v70, 16, v87
	v_and_b32_e32 v71, 0xffff0000, v87
	v_pk_fma_f32 v[120:121], v[90:91], v[64:65], v[120:121] op_sel_hi:[0,1,1]
	v_pk_fma_f32 v[122:123], v[90:91], v[66:67], v[122:123] op_sel_hi:[0,1,1]
	v_pk_fma_f32 v[124:125], v[90:91], v[68:69], v[124:125] op_sel_hi:[0,1,1]
	v_pk_fma_f32 v[126:127], v[90:91], v[70:71], v[126:127] op_sel_hi:[0,1,1]
	v_pk_mul_f32 v[134:135], v[112:113], v[112:113]
	v_pk_fma_f32 v[134:135], v[114:115], v[114:115], v[134:135]
	v_pk_fma_f32 v[134:135], v[116:117], v[116:117], v[134:135]
	v_pk_fma_f32 v[134:135], v[118:119], v[118:119], v[134:135]
	v_pk_fma_f32 v[134:135], v[120:121], v[120:121], v[134:135]
	v_pk_fma_f32 v[134:135], v[122:123], v[122:123], v[134:135]
	v_pk_fma_f32 v[134:135], v[124:125], v[124:125], v[134:135]
	v_pk_fma_f32 v[134:135], v[126:127], v[126:127], v[134:135]
	s_nop 0
	v_add_f32_e32 v134, v134, v135
	s_nop 1
	v_add_f32_dpp v132, v132, v132 quad_perm:[1,0,3,2] row_mask:0xf bank_mask:0xf
	v_add_f32_dpp v134, v134, v134 quad_perm:[1,0,3,2] row_mask:0xf bank_mask:0xf
	s_nop 0
	v_add_f32_dpp v132, v132, v132 quad_perm:[2,3,0,1] row_mask:0xf bank_mask:0xf
	v_add_f32_dpp v134, v134, v134 quad_perm:[2,3,0,1] row_mask:0xf bank_mask:0xf
	s_nop 0
	v_add_f32_dpp v132, v132, v132 row_half_mirror row_mask:0xf bank_mask:0xf
	v_add_f32_dpp v134, v134, v134 row_half_mirror row_mask:0xf bank_mask:0xf
	s_nop 0
	v_add_f32_dpp v132, v132, v132 row_mirror row_mask:0xf bank_mask:0xf
	v_add_f32_dpp v134, v134, v134 row_mirror row_mask:0xf bank_mask:0xf
	s_nop 0
	ds_bpermute_b32 v136, v187, v132
	ds_bpermute_b32 v137, v187, v134
	s_waitcnt lgkmcnt(0)
	v_add_f32_e32 v132, v132, v136
	v_add_f32_e32 v134, v134, v137
	ds_bpermute_b32 v136, v188, v132
	ds_bpermute_b32 v137, v188, v134
	s_waitcnt lgkmcnt(0)
	v_add_f32_e32 v132, v132, v136
	v_add_f32_e32 v134, v134, v137
	v_fmamk_f32 v164, v132, 0x3a800000, v138
	v_fmamk_f32 v167, v134, 0x3a800000, v138
	s_nop 0
	v_rsq_f32_e32 v132, v164
	v_rsq_f32_e32 v134, v167
	v_sqrt_f32_e32 v165, v164
	v_sqrt_f32_e32 v168, v167
	s_nop 1
	v_pk_mul_f32 v[140:141], v[96:97], v[132:133] op_sel_hi:[1,0]
	v_cvt_pk_bf16_f32 v148, v140, v141
	v_pk_mul_f32 v[142:143], v[98:99], v[132:133] op_sel_hi:[1,0]
	v_cvt_pk_bf16_f32 v149, v142, v143
	v_pk_mul_f32 v[144:145], v[100:101], v[132:133] op_sel_hi:[1,0]
	v_cvt_pk_bf16_f32 v150, v144, v145
	v_pk_mul_f32 v[146:147], v[102:103], v[132:133] op_sel_hi:[1,0]
	v_cvt_pk_bf16_f32 v151, v146, v147
	v_pk_mul_f32 v[140:141], v[104:105], v[132:133] op_sel_hi:[1,0]
	v_cvt_pk_bf16_f32 v152, v140, v141
	v_pk_mul_f32 v[142:143], v[106:107], v[132:133] op_sel_hi:[1,0]
	v_cvt_pk_bf16_f32 v153, v142, v143
	v_pk_mul_f32 v[144:145], v[108:109], v[132:133] op_sel_hi:[1,0]
	v_cvt_pk_bf16_f32 v154, v144, v145
	v_pk_mul_f32 v[146:147], v[110:111], v[132:133] op_sel_hi:[1,0]
	v_cvt_pk_bf16_f32 v155, v146, v147
	global_store_dwordx2 v173, v[148:149], s[98:99]
	global_store_dwordx2 v173, v[150:151], s[98:99] offset:512
	global_store_dwordx2 v173, v[152:153], s[98:99] offset:1024
	global_store_dwordx2 v173, v[154:155], s[98:99] offset:1536
	v_add_u32_e32 v173, 0x400000, v173
	v_pk_mul_f32 v[140:141], v[112:113], v[134:135] op_sel_hi:[1,0]
	v_cvt_pk_bf16_f32 v156, v140, v141
	v_pk_mul_f32 v[142:143], v[114:115], v[134:135] op_sel_hi:[1,0]
	v_cvt_pk_bf16_f32 v157, v142, v143
	v_pk_mul_f32 v[144:145], v[116:117], v[134:135] op_sel_hi:[1,0]
	v_cvt_pk_bf16_f32 v158, v144, v145
	v_pk_mul_f32 v[146:147], v[118:119], v[134:135] op_sel_hi:[1,0]
	v_cvt_pk_bf16_f32 v159, v146, v147
	v_pk_mul_f32 v[140:141], v[120:121], v[134:135] op_sel_hi:[1,0]
	v_cvt_pk_bf16_f32 v160, v140, v141
	v_pk_mul_f32 v[142:143], v[122:123], v[134:135] op_sel_hi:[1,0]
	v_cvt_pk_bf16_f32 v161, v142, v143
	v_pk_mul_f32 v[144:145], v[124:125], v[134:135] op_sel_hi:[1,0]
	v_cvt_pk_bf16_f32 v162, v144, v145
	v_pk_mul_f32 v[146:147], v[126:127], v[134:135] op_sel_hi:[1,0]
	v_cvt_pk_bf16_f32 v163, v146, v147
	global_store_dwordx2 v173, v[156:157], s[98:99]
	global_store_dwordx2 v173, v[158:159], s[98:99] offset:512
	global_store_dwordx2 v173, v[160:161], s[98:99] offset:1024
	global_store_dwordx2 v173, v[162:163], s[98:99] offset:1536
	v_add_u32_e32 v173, 0x400000, v173
	v_add_u32_e32 v166, -1, v165
	v_fma_f32 v140, -v166, v165, v164
	v_cmp_ge_f32_e32 vcc, 0, v140
	v_add_u32_e32 v141, 1, v165
	v_cndmask_b32_e32 v166, v165, v166, vcc
	v_fma_f32 v140, -v141, v165, v164
	v_cmp_lt_f32_e32 vcc, 0, v140
	s_nop 1
	v_cndmask_b32_e32 v165, v166, v141, vcc
	v_add_u32_e32 v169, -1, v168
	v_fma_f32 v142, -v169, v168, v167
	v_cmp_ge_f32_e32 vcc, 0, v142
	v_add_u32_e32 v143, 1, v168
	v_cndmask_b32_e32 v169, v168, v169, vcc
	v_fma_f32 v142, -v143, v168, v167
	v_cmp_lt_f32_e32 vcc, 0, v142
	s_nop 1
	v_cndmask_b32_e32 v168, v169, v143, vcc
	s_mov_b64 exec, 1
	global_store_dword v174, v165, s[98:99]
	v_add_u32_e32 v174, 0x2000, v174
	global_store_dword v174, v168, s[98:99]
	v_add_u32_e32 v174, 0x2000, v174
	s_mov_b64 exec, -1
	global_load_dword v88, v172, s[98:99]
	global_load_dwordx2 v[56:57], v170, s[98:99] nt
	global_load_dwordx2 v[58:59], v170, s[98:99] offset:512 nt
	global_load_dwordx2 v[60:61], v170, s[98:99] offset:1024 nt
	global_load_dwordx2 v[62:63], v170, s[98:99] offset:1536 nt
	global_load_dwordx2 v[72:73], v171, s[98:99]
	global_load_dwordx2 v[74:75], v171, s[98:99] offset:512
	global_load_dwordx2 v[76:77], v171, s[98:99] offset:1024
	global_load_dwordx2 v[78:79], v171, s[98:99] offset:1536
	v_add_u32_e32 v170, 0x400000, v170
	v_add_u32_e32 v171, 0x400000, v171
	v_add_u32_e32 v172, 0x2000, v172
	global_load_dword v90, v172, s[98:99]
	global_load_dwordx2 v[64:65], v170, s[98:99] nt
	global_load_dwordx2 v[66:67], v170, s[98:99] offset:512 nt
	global_load_dwordx2 v[68:69], v170, s[98:99] offset:1024 nt
	global_load_dwordx2 v[70:71], v170, s[98:99] offset:1536 nt
	global_load_dwordx2 v[80:81], v171, s[98:99]
	global_load_dwordx2 v[82:83], v171, s[98:99] offset:512
	global_load_dwordx2 v[84:85], v171, s[98:99] offset:1024
	global_load_dwordx2 v[86:87], v171, s[98:99] offset:1536
	v_add_u32_e32 v170, 0x400000, v170
	v_add_u32_e32 v171, 0x400000, v171
	v_add_u32_e32 v172, 0x2000, v172
	s_waitcnt vmcnt(41)
; __device__ __forceinline__ float ssq4(v4f v) { return (v.x * v.x + v.y * v.y) + (v.z * v.z + v.w * v.w); }
; template <int R, bool BASE_F32, bool OUT_F32>
; __device__ __forceinline__ void rows_res(const Ctx& C, int m0, int stride, int mx, const float* gpost, float scale, int lane) {
;     ...
;     for (int r = 0; r < R; ++r) { float s = 0.f;
; #pragma unroll
;         for (int j = 0; j < 4; ++j) s += ssq4(d[r][j]);
;         r1[r] = s; }
; #pragma unroll
;     for (int r = 0; r < R; ++r) r1[r] = rsqrtf(wave_sum(r1[r]) * (1.f / DM) + EPS) * scale;
; #pragma unroll
;     for (int j = 0; j < 4; ++j) { const v4f gp = ld4_f32(gpost + 4 * lane + 256 * j);
; #pragma unroll
;         for (int r = 0; r < R; ++r) d[r][j] = b[r][j] + d[r][j] * r1[r] * gp; }
	v_lshlrev_b32_e32 v96, 16, v20
	v_and_b32_e32 v97, 0xffff0000, v20
	v_lshlrev_b32_e32 v98, 16, v21
	v_and_b32_e32 v99, 0xffff0000, v21
	v_lshlrev_b32_e32 v100, 16, v22
	v_and_b32_e32 v101, 0xffff0000, v22
	v_lshlrev_b32_e32 v102, 16, v23
	v_and_b32_e32 v103, 0xffff0000, v23
	v_lshlrev_b32_e32 v104, 16, v24
	v_and_b32_e32 v105, 0xffff0000, v24
	v_lshlrev_b32_e32 v106, 16, v25
	v_and_b32_e32 v107, 0xffff0000, v25
	v_lshlrev_b32_e32 v108, 16, v26
	v_and_b32_e32 v109, 0xffff0000, v26
	v_lshlrev_b32_e32 v110, 16, v27
	v_and_b32_e32 v111, 0xffff0000, v27
	v_pk_mul_f32 v[128:129], v[96:97], v[96:97]
	v_pk_fma_f32 v[128:129], v[98:99], v[98:99], v[128:129]
	v_pk_fma_f32 v[128:129], v[100:101], v[100:101], v[128:129]
	v_pk_fma_f32 v[128:129], v[102:103], v[102:103], v[128:129]
	v_pk_fma_f32 v[128:129], v[104:105], v[104:105], v[128:129]
	v_pk_fma_f32 v[128:129], v[106:107], v[106:107], v[128:129]
	v_pk_fma_f32 v[128:129], v[108:109], v[108:109], v[128:129]
	v_pk_fma_f32 v[128:129], v[110:111], v[110:111], v[128:129]
	s_nop 0
	v_add_f32_e32 v128, v128, v129
	s_waitcnt vmcnt(32)
	v_lshlrev_b32_e32 v112, 16, v28
	v_and_b32_e32 v113, 0xffff0000, v28
	v_lshlrev_b32_e32 v114, 16, v29
	v_and_b32_e32 v115, 0xffff0000, v29
	v_lshlrev_b32_e32 v116, 16, v30
	v_and_b32_e32 v117, 0xffff0000, v30
	v_lshlrev_b32_e32 v118, 16, v31
	v_and_b32_e32 v119, 0xffff0000, v31
	v_lshlrev_b32_e32 v120, 16, v32
	v_and_b32_e32 v121, 0xffff0000, v32
	v_lshlrev_b32_e32 v122, 16, v33
	v_and_b32_e32 v123, 0xffff0000, v33
	v_lshlrev_b32_e32 v124, 16, v34
	v_and_b32_e32 v125, 0xffff0000, v34
	v_lshlrev_b32_e32 v126, 16, v35
	v_and_b32_e32 v127, 0xffff0000, v35
	v_pk_mul_f32 v[130:131], v[112:113], v[112:113]
	v_pk_fma_f32 v[130:131], v[114:115], v[114:115], v[130:131]
	v_pk_fma_f32 v[130:131], v[116:117], v[116:117], v[130:131]
	v_pk_fma_f32 v[130:131], v[118:119], v[118:119], v[130:131]
	v_pk_fma_f32 v[130:131], v[120:121], v[120:121], v[130:131]
	v_pk_fma_f32 v[130:131], v[122:123], v[122:123], v[130:131]
	v_pk_fma_f32 v[130:131], v[124:125], v[124:125], v[130:131]
	v_pk_fma_f32 v[130:131], v[126:127], v[126:127], v[130:131]
	s_nop 0
	v_add_f32_e32 v130, v130, v131
	s_nop 1
	v_add_f32_dpp v128, v128, v128 quad_perm:[1,0,3,2] row_mask:0xf bank_mask:0xf
	v_add_f32_dpp v130, v130, v130 quad_perm:[1,0,3,2] row_mask:0xf bank_mask:0xf
	s_nop 0
	v_add_f32_dpp v128, v128, v128 quad_perm:[2,3,0,1] row_mask:0xf bank_mask:0xf
	v_add_f32_dpp v130, v130, v130 quad_perm:[2,3,0,1] row_mask:0xf bank_mask:0xf
	s_nop 0
	v_add_f32_dpp v128, v128, v128 row_half_mirror row_mask:0xf bank_mask:0xf
	v_add_f32_dpp v130, v130, v130 row_half_mirror row_mask:0xf bank_mask:0xf
	s_nop 0
	v_add_f32_dpp v128, v128, v128 row_mirror row_mask:0xf bank_mask:0xf
	v_add_f32_dpp v130, v130, v130 row_mirror row_mask:0xf bank_mask:0xf
	s_nop 0
	ds_bpermute_b32 v136, v187, v128
	ds_bpermute_b32 v137, v187, v130
	s_waitcnt lgkmcnt(0)
	v_add_f32_e32 v128, v128, v136
	v_add_f32_e32 v130, v130, v137
	ds_bpermute_b32 v136, v188, v128
	ds_bpermute_b32 v137, v188, v130
	s_waitcnt lgkmcnt(0)
	v_add_f32_e32 v128, v128, v136
	v_add_f32_e32 v130, v130, v137
	v_fmamk_f32 v128, v128, 0x3a800000, v138
	v_fmamk_f32 v130, v130, 0x3a800000, v138
	s_nop 0
	v_rsq_f32_e32 v128, v128
	v_rsq_f32_e32 v130, v130
	s_nop 1
	v_mul_f32_e32 v128, 0.5, v128
	v_mul_f32_e32 v130, 0.5, v130
	s_waitcnt vmcnt(28)
	v_pk_mul_f32 v[96:97], v[128:129], v[96:97] op_sel_hi:[0,1]
	v_pk_mul_f32 v[98:99], v[128:129], v[98:99] op_sel_hi:[0,1]
	v_pk_mul_f32 v[100:101], v[128:129], v[100:101] op_sel_hi:[0,1]
	v_pk_mul_f32 v[102:103], v[128:129], v[102:103] op_sel_hi:[0,1]
	v_pk_mul_f32 v[104:105], v[128:129], v[104:105] op_sel_hi:[0,1]
	v_pk_mul_f32 v[106:107], v[128:129], v[106:107] op_sel_hi:[0,1]
	v_pk_mul_f32 v[108:109], v[128:129], v[108:109] op_sel_hi:[0,1]
	v_pk_mul_f32 v[110:111], v[128:129], v[110:111] op_sel_hi:[0,1]
	v_pk_mul_f32 v[96:97], v[96:97], v[192:193]
	v_pk_mul_f32 v[98:99], v[98:99], v[194:195]
	v_pk_mul_f32 v[100:101], v[100:101], v[196:197]
	v_pk_mul_f32 v[102:103], v[102:103], v[198:199]
	v_pk_mul_f32 v[104:105], v[104:105], v[200:201]
	v_pk_mul_f32 v[106:107], v[106:107], v[202:203]
	v_pk_mul_f32 v[108:109], v[108:109], v[204:205]
	v_pk_mul_f32 v[110:111], v[110:111], v[206:207]
	v_lshlrev_b32_e32 v20, 16, v36
	v_and_b32_e32 v21, 0xffff0000, v36
	v_lshlrev_b32_e32 v22, 16, v37
	v_and_b32_e32 v23, 0xffff0000, v37
	v_lshlrev_b32_e32 v24, 16, v38
	v_and_b32_e32 v25, 0xffff0000, v38
	v_lshlrev_b32_e32 v26, 16, v39
	v_and_b32_e32 v27, 0xffff0000, v39
	v_pk_fma_f32 v[96:97], v[52:53], v[20:21], v[96:97] op_sel_hi:[0,1,1]
	v_pk_fma_f32 v[98:99], v[52:53], v[22:23], v[98:99] op_sel_hi:[0,1,1]
	v_pk_fma_f32 v[100:101], v[52:53], v[24:25], v[100:101] op_sel_hi:[0,1,1]
	v_pk_fma_f32 v[102:103], v[52:53], v[26:27], v[102:103] op_sel_hi:[0,1,1]
	v_lshlrev_b32_e32 v20, 16, v40
	v_and_b32_e32 v21, 0xffff0000, v40
	v_lshlrev_b32_e32 v22, 16, v41
	v_and_b32_e32 v23, 0xffff0000, v41
	v_lshlrev_b32_e32 v24, 16, v42
	v_and_b32_e32 v25, 0xffff0000, v42
	v_lshlrev_b32_e32 v26, 16, v43
	v_and_b32_e32 v27, 0xffff0000, v43
	v_pk_fma_f32 v[104:105], v[52:53], v[20:21], v[104:105] op_sel_hi:[0,1,1]
	v_pk_fma_f32 v[106:107], v[52:53], v[22:23], v[106:107] op_sel_hi:[0,1,1]
	v_pk_fma_f32 v[108:109], v[52:53], v[24:25], v[108:109] op_sel_hi:[0,1,1]
	v_pk_fma_f32 v[110:111], v[52:53], v[26:27], v[110:111] op_sel_hi:[0,1,1]
	v_pk_mul_f32 v[132:133], v[96:97], v[96:97]
	v_pk_fma_f32 v[132:133], v[98:99], v[98:99], v[132:133]
	v_pk_fma_f32 v[132:133], v[100:101], v[100:101], v[132:133]
	v_pk_fma_f32 v[132:133], v[102:103], v[102:103], v[132:133]
;     __device__ __forceinline__ float* out() const { return (float*)karg_in(33); }
; __device__ __forceinline__ void st4_bf16(bf16* p, v4f o) { v2u w; w.x = cvt_pk_nv(o.x, o.y); w.y = cvt_pk_nv(o.z, o.w); *(v2u*)p = w; }
; __device__ __forceinline__ float ssq4(v4f v) { return (v.x * v.x + v.y * v.y) + (v.z * v.z + v.w * v.w); }
; template <int R, bool BASE_F32, bool OUT_F32>
; __device__ __forceinline__ void rows_res(const Ctx& C, int m0, int stride, int mx, const float* gpost, float scale, int lane) {
;     ...
;         for (int r = 0; r < R; ++r) d[r][j] = b[r][j] + d[r][j] * r1[r] * gp; }
;     if (OUT_F32) { float* Y = C.out();
; #pragma unroll
;         for (int r = 0; r < R; ++r)
; #pragma unroll
;             for (int j = 0; j < 4; ++j) if (ok[r]) *(v4f*)(Y + (size_t)mr[r] * DM + 4 * lane + 256 * j) = d[r][j];
;     } else { float* rs = C.RS(); float t[R];
; #pragma unroll
;         for (int r = 0; r < R; ++r) { float s = 0.f;
; #pragma unroll
;             for (int j = 0; j < 4; ++j) s += ssq4(d[r][j]);
;             t[r] = s; }
; #pragma unroll
;         for (int r = 0; r < R; ++r) t[r] = wave_sum(t[r]) * (1.f / DM) + EPS;
; #pragma unroll
;         for (int r = 0; r < R; ++r) { const float rstd = rsqrtf(t[r]);
; #pragma unroll
;             for (int j = 0; j < 4; ++j) if (ok[r]) st4_bf16(XN + (size_t)mr[r] * DM + 4 * lane + 256 * j, d[r][j] * rstd);
;             if (lane == 0 && ok[r]) rs[mr[r]] = sqrtf(t[r]); }
	v_pk_fma_f32 v[132:133], v[104:105], v[104:105], v[132:133]
	v_pk_fma_f32 v[132:133], v[106:107], v[106:107], v[132:133]
	v_pk_fma_f32 v[132:133], v[108:109], v[108:109], v[132:133]
	v_pk_fma_f32 v[132:133], v[110:111], v[110:111], v[132:133]
	s_nop 0
	v_add_f32_e32 v132, v132, v133
	v_pk_mul_f32 v[112:113], v[130:131], v[112:113] op_sel_hi:[0,1]
	v_pk_mul_f32 v[114:115], v[130:131], v[114:115] op_sel_hi:[0,1]
	v_pk_mul_f32 v[116:117], v[130:131], v[116:117] op_sel_hi:[0,1]
	v_pk_mul_f32 v[118:119], v[130:131], v[118:119] op_sel_hi:[0,1]
	v_pk_mul_f32 v[120:121], v[130:131], v[120:121] op_sel_hi:[0,1]
	v_pk_mul_f32 v[122:123], v[130:131], v[122:123] op_sel_hi:[0,1]
	v_pk_mul_f32 v[124:125], v[130:131], v[124:125] op_sel_hi:[0,1]
	v_pk_mul_f32 v[126:127], v[130:131], v[126:127] op_sel_hi:[0,1]
	v_pk_mul_f32 v[112:113], v[112:113], v[192:193]
	v_pk_mul_f32 v[114:115], v[114:115], v[194:195]
	v_pk_mul_f32 v[116:117], v[116:117], v[196:197]
	v_pk_mul_f32 v[118:119], v[118:119], v[198:199]
	v_pk_mul_f32 v[120:121], v[120:121], v[200:201]
	v_pk_mul_f32 v[122:123], v[122:123], v[202:203]
	v_pk_mul_f32 v[124:125], v[124:125], v[204:205]
	v_pk_mul_f32 v[126:127], v[126:127], v[206:207]
	v_lshlrev_b32_e32 v28, 16, v44
	v_and_b32_e32 v29, 0xffff0000, v44
	v_lshlrev_b32_e32 v30, 16, v45
	v_and_b32_e32 v31, 0xffff0000, v45
	v_lshlrev_b32_e32 v32, 16, v46
	v_and_b32_e32 v33, 0xffff0000, v46
	v_lshlrev_b32_e32 v34, 16, v47
	v_and_b32_e32 v35, 0xffff0000, v47
	v_pk_fma_f32 v[112:113], v[54:55], v[28:29], v[112:113] op_sel_hi:[0,1,1]
	v_pk_fma_f32 v[114:115], v[54:55], v[30:31], v[114:115] op_sel_hi:[0,1,1]
	v_pk_fma_f32 v[116:117], v[54:55], v[32:33], v[116:117] op_sel_hi:[0,1,1]
	v_pk_fma_f32 v[118:119], v[54:55], v[34:35], v[118:119] op_sel_hi:[0,1,1]
	v_lshlrev_b32_e32 v28, 16, v48
	v_and_b32_e32 v29, 0xffff0000, v48
	v_lshlrev_b32_e32 v30, 16, v49
	v_and_b32_e32 v31, 0xffff0000, v49
	v_lshlrev_b32_e32 v32, 16, v50
	v_and_b32_e32 v33, 0xffff0000, v50
	v_lshlrev_b32_e32 v34, 16, v51
	v_and_b32_e32 v35, 0xffff0000, v51
	v_pk_fma_f32 v[120:121], v[54:55], v[28:29], v[120:121] op_sel_hi:[0,1,1]
	v_pk_fma_f32 v[122:123], v[54:55], v[30:31], v[122:123] op_sel_hi:[0,1,1]
	v_pk_fma_f32 v[124:125], v[54:55], v[32:33], v[124:125] op_sel_hi:[0,1,1]
	v_pk_fma_f32 v[126:127], v[54:55], v[34:35], v[126:127] op_sel_hi:[0,1,1]
	v_pk_mul_f32 v[134:135], v[112:113], v[112:113]
	v_pk_fma_f32 v[134:135], v[114:115], v[114:115], v[134:135]
	v_pk_fma_f32 v[134:135], v[116:117], v[116:117], v[134:135]
	v_pk_fma_f32 v[134:135], v[118:119], v[118:119], v[134:135]
	v_pk_fma_f32 v[134:135], v[120:121], v[120:121], v[134:135]
	v_pk_fma_f32 v[134:135], v[122:123], v[122:123], v[134:135]
	v_pk_fma_f32 v[134:135], v[124:125], v[124:125], v[134:135]
	v_pk_fma_f32 v[134:135], v[126:127], v[126:127], v[134:135]
	s_nop 0
	v_add_f32_e32 v134, v134, v135
	s_nop 1
	v_add_f32_dpp v132, v132, v132 quad_perm:[1,0,3,2] row_mask:0xf bank_mask:0xf
	v_add_f32_dpp v134, v134, v134 quad_perm:[1,0,3,2] row_mask:0xf bank_mask:0xf
	s_nop 0
	v_add_f32_dpp v132, v132, v132 quad_perm:[2,3,0,1] row_mask:0xf bank_mask:0xf
	v_add_f32_dpp v134, v134, v134 quad_perm:[2,3,0,1] row_mask:0xf bank_mask:0xf
	s_nop 0
	v_add_f32_dpp v132, v132, v132 row_half_mirror row_mask:0xf bank_mask:0xf
	v_add_f32_dpp v134, v134, v134 row_half_mirror row_mask:0xf bank_mask:0xf
	s_nop 0
	v_add_f32_dpp v132, v132, v132 row_mirror row_mask:0xf bank_mask:0xf
	v_add_f32_dpp v134, v134, v134 row_mirror row_mask:0xf bank_mask:0xf
	s_nop 0
	ds_bpermute_b32 v136, v187, v132
	ds_bpermute_b32 v137, v187, v134
	s_waitcnt lgkmcnt(0)
	v_add_f32_e32 v132, v132, v136
	v_add_f32_e32 v134, v134, v137
	ds_bpermute_b32 v136, v188, v132
	ds_bpermute_b32 v137, v188, v134
	s_waitcnt lgkmcnt(0)
	v_add_f32_e32 v132, v132, v136
	v_add_f32_e32 v134, v134, v137
	v_fmamk_f32 v164, v132, 0x3a800000, v138
	v_fmamk_f32 v167, v134, 0x3a800000, v138
	s_nop 0
	v_rsq_f32_e32 v132, v164
	v_rsq_f32_e32 v134, v167
	v_sqrt_f32_e32 v165, v164
	v_sqrt_f32_e32 v168, v167
	s_nop 1
	v_pk_mul_f32 v[140:141], v[96:97], v[132:133] op_sel_hi:[1,0]
	v_cvt_pk_bf16_f32 v148, v140, v141
	v_pk_mul_f32 v[142:143], v[98:99], v[132:133] op_sel_hi:[1,0]
	v_cvt_pk_bf16_f32 v149, v142, v143
	v_pk_mul_f32 v[144:145], v[100:101], v[132:133] op_sel_hi:[1,0]
	v_cvt_pk_bf16_f32 v150, v144, v145
	v_pk_mul_f32 v[146:147], v[102:103], v[132:133] op_sel_hi:[1,0]
	v_cvt_pk_bf16_f32 v151, v146, v147
	v_pk_mul_f32 v[140:141], v[104:105], v[132:133] op_sel_hi:[1,0]
	v_cvt_pk_bf16_f32 v152, v140, v141
	v_pk_mul_f32 v[142:143], v[106:107], v[132:133] op_sel_hi:[1,0]
	v_cvt_pk_bf16_f32 v153, v142, v143
	v_pk_mul_f32 v[144:145], v[108:109], v[132:133] op_sel_hi:[1,0]
	v_cvt_pk_bf16_f32 v154, v144, v145
	v_pk_mul_f32 v[146:147], v[110:111], v[132:133] op_sel_hi:[1,0]
	v_cvt_pk_bf16_f32 v155, v146, v147
	global_store_dwordx2 v173, v[148:149], s[98:99]
	global_store_dwordx2 v173, v[150:151], s[98:99] offset:512
	global_store_dwordx2 v173, v[152:153], s[98:99] offset:1024
	global_store_dwordx2 v173, v[154:155], s[98:99] offset:1536
	v_add_u32_e32 v173, 0x400000, v173
	v_pk_mul_f32 v[140:141], v[112:113], v[134:135] op_sel_hi:[1,0]
	v_cvt_pk_bf16_f32 v156, v140, v141
	v_pk_mul_f32 v[142:143], v[114:115], v[134:135] op_sel_hi:[1,0]
	v_cvt_pk_bf16_f32 v157, v142, v143
	v_pk_mul_f32 v[144:145], v[116:117], v[134:135] op_sel_hi:[1,0]
	v_cvt_pk_bf16_f32 v158, v144, v145
	v_pk_mul_f32 v[146:147], v[118:119], v[134:135] op_sel_hi:[1,0]
	v_cvt_pk_bf16_f32 v159, v146, v147
	v_pk_mul_f32 v[140:141], v[120:121], v[134:135] op_sel_hi:[1,0]
	v_cvt_pk_bf16_f32 v160, v140, v141
	v_pk_mul_f32 v[142:143], v[122:123], v[134:135] op_sel_hi:[1,0]
	v_cvt_pk_bf16_f32 v161, v142, v143
	v_pk_mul_f32 v[144:145], v[124:125], v[134:135] op_sel_hi:[1,0]
	v_cvt_pk_bf16_f32 v162, v144, v145
	v_pk_mul_f32 v[146:147], v[126:127], v[134:135] op_sel_hi:[1,0]
	v_cvt_pk_bf16_f32 v163, v146, v147
	global_store_dwordx2 v173, v[156:157], s[98:99]
	global_store_dwordx2 v173, v[158:159], s[98:99] offset:512
	global_store_dwordx2 v173, v[160:161], s[98:99] offset:1024
	global_store_dwordx2 v173, v[162:163], s[98:99] offset:1536
	v_add_u32_e32 v173, 0x400000, v173
	v_add_u32_e32 v166, -1, v165
	v_fma_f32 v140, -v166, v165, v164
	v_cmp_ge_f32_e32 vcc, 0, v140
	v_add_u32_e32 v141, 1, v165
	v_cndmask_b32_e32 v166, v165, v166, vcc
	v_fma_f32 v140, -v141, v165, v164
	v_cmp_lt_f32_e32 vcc, 0, v140
	s_nop 1
	v_cndmask_b32_e32 v165, v166, v141, vcc
	v_add_u32_e32 v169, -1, v168
	v_fma_f32 v142, -v169, v168, v167
	v_cmp_ge_f32_e32 vcc, 0, v142
	v_add_u32_e32 v143, 1, v168
	v_cndmask_b32_e32 v169, v168, v169, vcc
	v_fma_f32 v142, -v143, v168, v167
	v_cmp_lt_f32_e32 vcc, 0, v142
	s_nop 1
	v_cndmask_b32_e32 v168, v169, v143, vcc
	s_mov_b64 exec, 1
	global_store_dword v174, v165, s[98:99]
	v_add_u32_e32 v174, 0x2000, v174
	global_store_dword v174, v168, s[98:99]
	v_add_u32_e32 v174, 0x2000, v174
	s_mov_b64 exec, -1
	s_waitcnt vmcnt(23)
; __device__ __forceinline__ float ssq4(v4f v) { return (v.x * v.x + v.y * v.y) + (v.z * v.z + v.w * v.w); }
; template <int R, bool BASE_F32, bool OUT_F32>
; __device__ __forceinline__ void rows_res(const Ctx& C, int m0, int stride, int mx, const float* gpost, float scale, int lane) {
;     ...
;     for (int r = 0; r < R; ++r) { float s = 0.f;
; #pragma unroll
;         for (int j = 0; j < 4; ++j) s += ssq4(d[r][j]);
;         r1[r] = s; }
; #pragma unroll
;     for (int r = 0; r < R; ++r) r1[r] = rsqrtf(wave_sum(r1[r]) * (1.f / DM) + EPS) * scale;
; #pragma unroll
;     for (int j = 0; j < 4; ++j) { const v4f gp = ld4_f32(gpost + 4 * lane + 256 * j);
; #pragma unroll
;         for (int r = 0; r < R; ++r) d[r][j] = b[r][j] + d[r][j] * r1[r] * gp; }
	v_lshlrev_b32_e32 v96, 16, v56
	v_and_b32_e32 v97, 0xffff0000, v56
	v_lshlrev_b32_e32 v98, 16, v57
	v_and_b32_e32 v99, 0xffff0000, v57
	v_lshlrev_b32_e32 v100, 16, v58
	v_and_b32_e32 v101, 0xffff0000, v58
	v_lshlrev_b32_e32 v102, 16, v59
	v_and_b32_e32 v103, 0xffff0000, v59
	v_lshlrev_b32_e32 v104, 16, v60
	v_and_b32_e32 v105, 0xffff0000, v60
	v_lshlrev_b32_e32 v106, 16, v61
	v_and_b32_e32 v107, 0xffff0000, v61
	v_lshlrev_b32_e32 v108, 16, v62
	v_and_b32_e32 v109, 0xffff0000, v62
	v_lshlrev_b32_e32 v110, 16, v63
	v_and_b32_e32 v111, 0xffff0000, v63
	v_pk_mul_f32 v[128:129], v[96:97], v[96:97]
	v_pk_fma_f32 v[128:129], v[98:99], v[98:99], v[128:129]
	v_pk_fma_f32 v[128:129], v[100:101], v[100:101], v[128:129]
	v_pk_fma_f32 v[128:129], v[102:103], v[102:103], v[128:129]
	v_pk_fma_f32 v[128:129], v[104:105], v[104:105], v[128:129]
	v_pk_fma_f32 v[128:129], v[106:107], v[106:107], v[128:129]
	v_pk_fma_f32 v[128:129], v[108:109], v[108:109], v[128:129]
	v_pk_fma_f32 v[128:129], v[110:111], v[110:111], v[128:129]
	s_nop 0
	v_add_f32_e32 v128, v128, v129
	s_waitcnt vmcnt(14)
	v_lshlrev_b32_e32 v112, 16, v64
	v_and_b32_e32 v113, 0xffff0000, v64
	v_lshlrev_b32_e32 v114, 16, v65
	v_and_b32_e32 v115, 0xffff0000, v65
	v_lshlrev_b32_e32 v116, 16, v66
	v_and_b32_e32 v117, 0xffff0000, v66
	v_lshlrev_b32_e32 v118, 16, v67
	v_and_b32_e32 v119, 0xffff0000, v67
	v_lshlrev_b32_e32 v120, 16, v68
	v_and_b32_e32 v121, 0xffff0000, v68
	v_lshlrev_b32_e32 v122, 16, v69
	v_and_b32_e32 v123, 0xffff0000, v69
	v_lshlrev_b32_e32 v124, 16, v70
	v_and_b32_e32 v125, 0xffff0000, v70
	v_lshlrev_b32_e32 v126, 16, v71
	v_and_b32_e32 v127, 0xffff0000, v71
	v_pk_mul_f32 v[130:131], v[112:113], v[112:113]
	v_pk_fma_f32 v[130:131], v[114:115], v[114:115], v[130:131]
	v_pk_fma_f32 v[130:131], v[116:117], v[116:117], v[130:131]
	v_pk_fma_f32 v[130:131], v[118:119], v[118:119], v[130:131]
	v_pk_fma_f32 v[130:131], v[120:121], v[120:121], v[130:131]
	v_pk_fma_f32 v[130:131], v[122:123], v[122:123], v[130:131]
	v_pk_fma_f32 v[130:131], v[124:125], v[124:125], v[130:131]
	v_pk_fma_f32 v[130:131], v[126:127], v[126:127], v[130:131]
	s_nop 0
	v_add_f32_e32 v130, v130, v131
	s_nop 1
	v_add_f32_dpp v128, v128, v128 quad_perm:[1,0,3,2] row_mask:0xf bank_mask:0xf
	v_add_f32_dpp v130, v130, v130 quad_perm:[1,0,3,2] row_mask:0xf bank_mask:0xf
	s_nop 0
	v_add_f32_dpp v128, v128, v128 quad_perm:[2,3,0,1] row_mask:0xf bank_mask:0xf
	v_add_f32_dpp v130, v130, v130 quad_perm:[2,3,0,1] row_mask:0xf bank_mask:0xf
	s_nop 0
	v_add_f32_dpp v128, v128, v128 row_half_mirror row_mask:0xf bank_mask:0xf
	v_add_f32_dpp v130, v130, v130 row_half_mirror row_mask:0xf bank_mask:0xf
	s_nop 0
	v_add_f32_dpp v128, v128, v128 row_mirror row_mask:0xf bank_mask:0xf
	v_add_f32_dpp v130, v130, v130 row_mirror row_mask:0xf bank_mask:0xf
	s_nop 0
	ds_bpermute_b32 v136, v187, v128
	ds_bpermute_b32 v137, v187, v130
	s_waitcnt lgkmcnt(0)
	v_add_f32_e32 v128, v128, v136
	v_add_f32_e32 v130, v130, v137
	ds_bpermute_b32 v136, v188, v128
	ds_bpermute_b32 v137, v188, v130
	s_waitcnt lgkmcnt(0)
	v_add_f32_e32 v128, v128, v136
	v_add_f32_e32 v130, v130, v137
	v_fmamk_f32 v128, v128, 0x3a800000, v138
	v_fmamk_f32 v130, v130, 0x3a800000, v138
	s_nop 0
	v_rsq_f32_e32 v128, v128
	v_rsq_f32_e32 v130, v130
	s_nop 1
	v_mul_f32_e32 v128, 0.5, v128
	v_mul_f32_e32 v130, 0.5, v130
	s_waitcnt vmcnt(10)
	v_pk_mul_f32 v[96:97], v[128:129], v[96:97] op_sel_hi:[0,1]
	v_pk_mul_f32 v[98:99], v[128:129], v[98:99] op_sel_hi:[0,1]
	v_pk_mul_f32 v[100:101], v[128:129], v[100:101] op_sel_hi:[0,1]
	v_pk_mul_f32 v[102:103], v[128:129], v[102:103] op_sel_hi:[0,1]
	v_pk_mul_f32 v[104:105], v[128:129], v[104:105] op_sel_hi:[0,1]
	v_pk_mul_f32 v[106:107], v[128:129], v[106:107] op_sel_hi:[0,1]
	v_pk_mul_f32 v[108:109], v[128:129], v[108:109] op_sel_hi:[0,1]
	v_pk_mul_f32 v[110:111], v[128:129], v[110:111] op_sel_hi:[0,1]
	v_pk_mul_f32 v[96:97], v[96:97], v[192:193]
	v_pk_mul_f32 v[98:99], v[98:99], v[194:195]
	v_pk_mul_f32 v[100:101], v[100:101], v[196:197]
	v_pk_mul_f32 v[102:103], v[102:103], v[198:199]
	v_pk_mul_f32 v[104:105], v[104:105], v[200:201]
	v_pk_mul_f32 v[106:107], v[106:107], v[202:203]
	v_pk_mul_f32 v[108:109], v[108:109], v[204:205]
	v_pk_mul_f32 v[110:111], v[110:111], v[206:207]
	v_lshlrev_b32_e32 v56, 16, v72
	v_and_b32_e32 v57, 0xffff0000, v72
	v_lshlrev_b32_e32 v58, 16, v73
	v_and_b32_e32 v59, 0xffff0000, v73
	v_lshlrev_b32_e32 v60, 16, v74
	v_and_b32_e32 v61, 0xffff0000, v74
	v_lshlrev_b32_e32 v62, 16, v75
	v_and_b32_e32 v63, 0xffff0000, v75
	v_pk_fma_f32 v[96:97], v[88:89], v[56:57], v[96:97] op_sel_hi:[0,1,1]
	v_pk_fma_f32 v[98:99], v[88:89], v[58:59], v[98:99] op_sel_hi:[0,1,1]
	v_pk_fma_f32 v[100:101], v[88:89], v[60:61], v[100:101] op_sel_hi:[0,1,1]
	v_pk_fma_f32 v[102:103], v[88:89], v[62:63], v[102:103] op_sel_hi:[0,1,1]
	v_lshlrev_b32_e32 v56, 16, v76
	v_and_b32_e32 v57, 0xffff0000, v76
	v_lshlrev_b32_e32 v58, 16, v77
	v_and_b32_e32 v59, 0xffff0000, v77
	v_lshlrev_b32_e32 v60, 16, v78
	v_and_b32_e32 v61, 0xffff0000, v78
	v_lshlrev_b32_e32 v62, 16, v79
	v_and_b32_e32 v63, 0xffff0000, v79
	v_pk_fma_f32 v[104:105], v[88:89], v[56:57], v[104:105] op_sel_hi:[0,1,1]
	v_pk_fma_f32 v[106:107], v[88:89], v[58:59], v[106:107] op_sel_hi:[0,1,1]
	v_pk_fma_f32 v[108:109], v[88:89], v[60:61], v[108:109] op_sel_hi:[0,1,1]
	v_pk_fma_f32 v[110:111], v[88:89], v[62:63], v[110:111] op_sel_hi:[0,1,1]
	v_pk_mul_f32 v[132:133], v[96:97], v[96:97]
	v_pk_fma_f32 v[132:133], v[98:99], v[98:99], v[132:133]
	v_pk_fma_f32 v[132:133], v[100:101], v[100:101], v[132:133]
	v_pk_fma_f32 v[132:133], v[102:103], v[102:103], v[132:133]
;     __device__ __forceinline__ float* out() const { return (float*)karg_in(33); }
; __device__ __forceinline__ void st4_bf16(bf16* p, v4f o) { v2u w; w.x = cvt_pk_nv(o.x, o.y); w.y = cvt_pk_nv(o.z, o.w); *(v2u*)p = w; }
; __device__ __forceinline__ float ssq4(v4f v) { return (v.x * v.x + v.y * v.y) + (v.z * v.z + v.w * v.w); }
; template <int R, bool BASE_F32, bool OUT_F32>
; __device__ __forceinline__ void rows_res(const Ctx& C, int m0, int stride, int mx, const float* gpost, float scale, int lane) {
;     ...
;         for (int r = 0; r < R; ++r) d[r][j] = b[r][j] + d[r][j] * r1[r] * gp; }
;     if (OUT_F32) { float* Y = C.out();
; #pragma unroll
;         for (int r = 0; r < R; ++r)
; #pragma unroll
;             for (int j = 0; j < 4; ++j) if (ok[r]) *(v4f*)(Y + (size_t)mr[r] * DM + 4 * lane + 256 * j) = d[r][j];
;     } else { float* rs = C.RS(); float t[R];
; #pragma unroll
;         for (int r = 0; r < R; ++r) { float s = 0.f;
; #pragma unroll
;             for (int j = 0; j < 4; ++j) s += ssq4(d[r][j]);
;             t[r] = s; }
; #pragma unroll
;         for (int r = 0; r < R; ++r) t[r] = wave_sum(t[r]) * (1.f / DM) + EPS;
; #pragma unroll
;         for (int r = 0; r < R; ++r) { const float rstd = rsqrtf(t[r]);
; #pragma unroll
;             for (int j = 0; j < 4; ++j) if (ok[r]) st4_bf16(XN + (size_t)mr[r] * DM + 4 * lane + 256 * j, d[r][j] * rstd);
;             if (lane == 0 && ok[r]) rs[mr[r]] = sqrtf(t[r]); }
	v_pk_fma_f32 v[132:133], v[104:105], v[104:105], v[132:133]
	v_pk_fma_f32 v[132:133], v[106:107], v[106:107], v[132:133]
	v_pk_fma_f32 v[132:133], v[108:109], v[108:109], v[132:133]
	v_pk_fma_f32 v[132:133], v[110:111], v[110:111], v[132:133]
	s_nop 0
	v_add_f32_e32 v132, v132, v133
	v_pk_mul_f32 v[112:113], v[130:131], v[112:113] op_sel_hi:[0,1]
	v_pk_mul_f32 v[114:115], v[130:131], v[114:115] op_sel_hi:[0,1]
	v_pk_mul_f32 v[116:117], v[130:131], v[116:117] op_sel_hi:[0,1]
	v_pk_mul_f32 v[118:119], v[130:131], v[118:119] op_sel_hi:[0,1]
	v_pk_mul_f32 v[120:121], v[130:131], v[120:121] op_sel_hi:[0,1]
	v_pk_mul_f32 v[122:123], v[130:131], v[122:123] op_sel_hi:[0,1]
	v_pk_mul_f32 v[124:125], v[130:131], v[124:125] op_sel_hi:[0,1]
	v_pk_mul_f32 v[126:127], v[130:131], v[126:127] op_sel_hi:[0,1]
	v_pk_mul_f32 v[112:113], v[112:113], v[192:193]
	v_pk_mul_f32 v[114:115], v[114:115], v[194:195]
	v_pk_mul_f32 v[116:117], v[116:117], v[196:197]
	v_pk_mul_f32 v[118:119], v[118:119], v[198:199]
	v_pk_mul_f32 v[120:121], v[120:121], v[200:201]
	v_pk_mul_f32 v[122:123], v[122:123], v[202:203]
	v_pk_mul_f32 v[124:125], v[124:125], v[204:205]
	v_pk_mul_f32 v[126:127], v[126:127], v[206:207]
	v_lshlrev_b32_e32 v64, 16, v80
	v_and_b32_e32 v65, 0xffff0000, v80
	v_lshlrev_b32_e32 v66, 16, v81
	v_and_b32_e32 v67, 0xffff0000, v81
	v_lshlrev_b32_e32 v68, 16, v82
	v_and_b32_e32 v69, 0xffff0000, v82
	v_lshlrev_b32_e32 v70, 16, v83
	v_and_b32_e32 v71, 0xffff0000, v83
	v_pk_fma_f32 v[112:113], v[90:91], v[64:65], v[112:113] op_sel_hi:[0,1,1]
	v_pk_fma_f32 v[114:115], v[90:91], v[66:67], v[114:115] op_sel_hi:[0,1,1]
	v_pk_fma_f32 v[116:117], v[90:91], v[68:69], v[116:117] op_sel_hi:[0,1,1]
	v_pk_fma_f32 v[118:119], v[90:91], v[70:71], v[118:119] op_sel_hi:[0,1,1]
	v_lshlrev_b32_e32 v64, 16, v84
	v_and_b32_e32 v65, 0xffff0000, v84
	v_lshlrev_b32_e32 v66, 16, v85
	v_and_b32_e32 v67, 0xffff0000, v85
	v_lshlrev_b32_e32 v68, 16, v86
	v_and_b32_e32 v69, 0xffff0000, v86
	v_lshlrev_b32_e32 v70, 16, v87
	v_and_b32_e32 v71, 0xffff0000, v87
	v_pk_fma_f32 v[120:121], v[90:91], v[64:65], v[120:121] op_sel_hi:[0,1,1]
	v_pk_fma_f32 v[122:123], v[90:91], v[66:67], v[122:123] op_sel_hi:[0,1,1]
	v_pk_fma_f32 v[124:125], v[90:91], v[68:69], v[124:125] op_sel_hi:[0,1,1]
	v_pk_fma_f32 v[126:127], v[90:91], v[70:71], v[126:127] op_sel_hi:[0,1,1]
	v_pk_mul_f32 v[134:135], v[112:113], v[112:113]
	v_pk_fma_f32 v[134:135], v[114:115], v[114:115], v[134:135]
	v_pk_fma_f32 v[134:135], v[116:117], v[116:117], v[134:135]
	v_pk_fma_f32 v[134:135], v[118:119], v[118:119], v[134:135]
	v_pk_fma_f32 v[134:135], v[120:121], v[120:121], v[134:135]
	v_pk_fma_f32 v[134:135], v[122:123], v[122:123], v[134:135]
	v_pk_fma_f32 v[134:135], v[124:125], v[124:125], v[134:135]
	v_pk_fma_f32 v[134:135], v[126:127], v[126:127], v[134:135]
	s_nop 0
	v_add_f32_e32 v134, v134, v135
	s_nop 1
	v_add_f32_dpp v132, v132, v132 quad_perm:[1,0,3,2] row_mask:0xf bank_mask:0xf
	v_add_f32_dpp v134, v134, v134 quad_perm:[1,0,3,2] row_mask:0xf bank_mask:0xf
	s_nop 0
	v_add_f32_dpp v132, v132, v132 quad_perm:[2,3,0,1] row_mask:0xf bank_mask:0xf
	v_add_f32_dpp v134, v134, v134 quad_perm:[2,3,0,1] row_mask:0xf bank_mask:0xf
	s_nop 0
	v_add_f32_dpp v132, v132, v132 row_half_mirror row_mask:0xf bank_mask:0xf
	v_add_f32_dpp v134, v134, v134 row_half_mirror row_mask:0xf bank_mask:0xf
	s_nop 0
	v_add_f32_dpp v132, v132, v132 row_mirror row_mask:0xf bank_mask:0xf
	v_add_f32_dpp v134, v134, v134 row_mirror row_mask:0xf bank_mask:0xf
	s_nop 0
	ds_bpermute_b32 v136, v187, v132
	ds_bpermute_b32 v137, v187, v134
	s_waitcnt lgkmcnt(0)
	v_add_f32_e32 v132, v132, v136
	v_add_f32_e32 v134, v134, v137
	ds_bpermute_b32 v136, v188, v132
	ds_bpermute_b32 v137, v188, v134
	s_waitcnt lgkmcnt(0)
	v_add_f32_e32 v132, v132, v136
	v_add_f32_e32 v134, v134, v137
	v_fmamk_f32 v164, v132, 0x3a800000, v138
	v_fmamk_f32 v167, v134, 0x3a800000, v138
	s_nop 0
	v_rsq_f32_e32 v132, v164
	v_rsq_f32_e32 v134, v167
	v_sqrt_f32_e32 v165, v164
	v_sqrt_f32_e32 v168, v167
	s_nop 1
	v_pk_mul_f32 v[140:141], v[96:97], v[132:133] op_sel_hi:[1,0]
	v_cvt_pk_bf16_f32 v148, v140, v141
	v_pk_mul_f32 v[142:143], v[98:99], v[132:133] op_sel_hi:[1,0]
	v_cvt_pk_bf16_f32 v149, v142, v143
	v_pk_mul_f32 v[144:145], v[100:101], v[132:133] op_sel_hi:[1,0]
	v_cvt_pk_bf16_f32 v150, v144, v145
	v_pk_mul_f32 v[146:147], v[102:103], v[132:133] op_sel_hi:[1,0]
	v_cvt_pk_bf16_f32 v151, v146, v147
	v_pk_mul_f32 v[140:141], v[104:105], v[132:133] op_sel_hi:[1,0]
	v_cvt_pk_bf16_f32 v152, v140, v141
	v_pk_mul_f32 v[142:143], v[106:107], v[132:133] op_sel_hi:[1,0]
	v_cvt_pk_bf16_f32 v153, v142, v143
	v_pk_mul_f32 v[144:145], v[108:109], v[132:133] op_sel_hi:[1,0]
	v_cvt_pk_bf16_f32 v154, v144, v145
	v_pk_mul_f32 v[146:147], v[110:111], v[132:133] op_sel_hi:[1,0]
	v_cvt_pk_bf16_f32 v155, v146, v147
	global_store_dwordx2 v173, v[148:149], s[98:99]
	global_store_dwordx2 v173, v[150:151], s[98:99] offset:512
	global_store_dwordx2 v173, v[152:153], s[98:99] offset:1024
	global_store_dwordx2 v173, v[154:155], s[98:99] offset:1536
	v_add_u32_e32 v173, 0x400000, v173
	v_pk_mul_f32 v[140:141], v[112:113], v[134:135] op_sel_hi:[1,0]
	v_cvt_pk_bf16_f32 v156, v140, v141
	v_pk_mul_f32 v[142:143], v[114:115], v[134:135] op_sel_hi:[1,0]
	v_cvt_pk_bf16_f32 v157, v142, v143
	v_pk_mul_f32 v[144:145], v[116:117], v[134:135] op_sel_hi:[1,0]
	v_cvt_pk_bf16_f32 v158, v144, v145
	v_pk_mul_f32 v[146:147], v[118:119], v[134:135] op_sel_hi:[1,0]
	v_cvt_pk_bf16_f32 v159, v146, v147
	v_pk_mul_f32 v[140:141], v[120:121], v[134:135] op_sel_hi:[1,0]
	v_cvt_pk_bf16_f32 v160, v140, v141
	v_pk_mul_f32 v[142:143], v[122:123], v[134:135] op_sel_hi:[1,0]
	v_cvt_pk_bf16_f32 v161, v142, v143
	v_pk_mul_f32 v[144:145], v[124:125], v[134:135] op_sel_hi:[1,0]
	v_cvt_pk_bf16_f32 v162, v144, v145
	v_pk_mul_f32 v[146:147], v[126:127], v[134:135] op_sel_hi:[1,0]
	v_cvt_pk_bf16_f32 v163, v146, v147
	global_store_dwordx2 v173, v[156:157], s[98:99]
	global_store_dwordx2 v173, v[158:159], s[98:99] offset:512
	global_store_dwordx2 v173, v[160:161], s[98:99] offset:1024
	global_store_dwordx2 v173, v[162:163], s[98:99] offset:1536
	v_add_u32_e32 v173, 0x400000, v173
	v_add_u32_e32 v166, -1, v165
	v_fma_f32 v140, -v166, v165, v164
	v_cmp_ge_f32_e32 vcc, 0, v140
	v_add_u32_e32 v141, 1, v165
	v_cndmask_b32_e32 v166, v165, v166, vcc
	v_fma_f32 v140, -v141, v165, v164
	v_cmp_lt_f32_e32 vcc, 0, v140
	s_nop 1
	v_cndmask_b32_e32 v165, v166, v141, vcc
	v_add_u32_e32 v169, -1, v168
	v_fma_f32 v142, -v169, v168, v167
	v_cmp_ge_f32_e32 vcc, 0, v142
	v_add_u32_e32 v143, 1, v168
	v_cndmask_b32_e32 v169, v168, v169, vcc
	v_fma_f32 v142, -v143, v168, v167
	v_cmp_lt_f32_e32 vcc, 0, v142
	s_nop 1
	v_cndmask_b32_e32 v168, v169, v143, vcc
	s_mov_b64 exec, 1
	global_store_dword v174, v165, s[98:99]
	v_add_u32_e32 v174, 0x2000, v174
	global_store_dword v174, v168, s[98:99]
	v_add_u32_e32 v174, 0x2000, v174
	s_mov_b64 exec, -1
	s_branch .LBB0_385
;     __device__ __forceinline__ const float* in(int i) const { return karg_in(i); }
; #define FTID const int ftid_ = fresh_tid()
; __global__ void __launch_bounds__(NTHREADS, 2) fwd_kernel(Args args) {
;     ...
;     { FTID; const float* gp = C.in(8); { const int gw_ = GWV, ngw_ = NGWV, nit = (MPROMPT + 4 * ngw_ - 1) / (4 * ngw_);
;       for (int it = 0; it < nit - 1; ++it) rows_res<4, false, false>(C, gw_ + 4 * it * ngw_, ngw_, M, gp, 0.5f, LANE);
;       rows_res<5, false, false>(C, gw_ + 4 * (nit - 1) * ngw_, ngw_, MPROMPT + gw_, gp, 0.5f, LANE);
;       for (int ms = MPROMPT + gw_ + ngw_; ms < M; ms += ngw_) rows_res<5, false, false>(C, MPROMPT, ngw_, ms, gp, 0.5f, LANE); } }
	v_mov_b32_e32 v3, v1
	s_mov_b32 s0, 0x358637bd
	s_waitcnt lgkmcnt(0)
	v_lshl_add_u64 v[4:5], s[14:15], 0, v[2:3]
	s_mov_b64 s[12:13], 0x7100000
	s_mov_b64 s[16:17], 0x3000000
	v_mov_b32_e32 v3, 0x2a80000
	s_mov_b32 s18, 0x3a800000
	v_mov_b64_e32 v[6:7], s[0:1]
	s_mov_b32 s19, 0x800000
	v_mov_b32_e32 v37, 0x358637bd
	s_mov_b32 s43, 0xf800000
	v_mov_b32_e32 v148, 0x260
	s_mov_b32 s20, s42
	v_readlane_b32 s54, v232, 5
	s_branch .LBB0_369

;     __device__ __forceinline__ const float* in(int i) const { return karg_in(i); }
; __device__ __forceinline__ const float* xrow_ptr(const Ctx& C, int row) { return row < MPROMPT ? C.in(0) + (size_t)row * DM : C.in(1) + (size_t)(row - MPROMPT) * DM; }
; __device__ __forceinline__ v4f ld4_bf16(const bf16* p) { const v2u w = *(const v2u*)p; return (v4f){bf_lo(w.x), bf_hi(w.x), bf_lo(w.y), bf_hi(w.y)}; }
; __device__ __forceinline__ float ssq4(v4f v) { return (v.x * v.x + v.y * v.y) + (v.z * v.z + v.w * v.w); }
; #define FTID const int ftid_ = fresh_tid()
; template <int R, bool BASE_F32, bool OUT_F32>
; __device__ __forceinline__ void rows_res(const Ctx& C, int m0, int stride, int mx, const float* gpost, float scale, int lane) {
;     ...
;     for (int r = 0; r < R; ++r) { mr[r] = (r == 4) ? mx : m0 + r * stride; ok[r] = (r == 4) ? (mx < M) : (mr[r] < MPROMPT); const int mm = ok[r] ? mr[r] : 0;
; #pragma unroll
;         for (int j = 0; j < 4; ++j) d[r][j] = ld4_bf16(D + (size_t)mm * DM + 4 * lane + 256 * j);
;         if (BASE_F32) { const float* x = xrow_ptr(C, mm);
; #pragma unroll
;             for (int j = 0; j < 4; ++j) b[r][j] = ld4_f32(x + 4 * lane + 256 * j);
;         } else { const float inv = C.RS()[mm];
; #pragma unroll
;             for (int j = 0; j < 4; ++j) b[r][j] = ld4_bf16(XN + (size_t)mm * DM + 4 * lane + 256 * j) * inv;
;         } }
; #pragma unroll
;     for (int r = 0; r < R; ++r) { float s = 0.f;
; #pragma unroll
;         for (int j = 0; j < 4; ++j) s += ssq4(d[r][j]);
;         r1[r] = s; }
; #pragma unroll
;     for (int r = 0; r < R; ++r) r1[r] = rsqrtf(wave_sum(r1[r]) * (1.f / DM) + EPS) * scale;
; #pragma unroll
;     for (int j = 0; j < 4; ++j) { const v4f gp = ld4_f32(gpost + 4 * lane + 256 * j);
; __global__ void __launch_bounds__(NTHREADS, 2) fwd_kernel(Args args) {
;     ...
;     { FTID; const float* gp = C.in(27); { const int gw_ = GWV, ngw_ = NGWV, nit = (MPROMPT + 4 * ngw_ - 1) / (4 * ngw_);
;       for (int it = 0; it < nit - 1; ++it) rows_res<4, false, false>(C, gw_ + 4 * it * ngw_, ngw_, M, gp, 1.0f, LANE);
.LBB0_994:
	s_or_b64 exec, exec, s[10:11]
	s_waitcnt lgkmcnt(0)
	v_mov_b32_e32 v0, v182
	s_mov_b64 s[0:1], s[80:81]
	s_barrier
	s_load_dwordx2 s[16:17], s[0:1], 0xd8
	v_readfirstlane_b32 s0, v0
	v_and_b32_e32 v189, 63, v0
	s_ashr_i32 s47, s0, 6
	v_readlane_b32 s0, v232, 0
	v_lshlrev_b32_e32 v0, 2, v189
	s_add_i32 s23, s47, s0
	v_mov_b32_e32 v1, 0
	s_and_b64 vcc, exec, s[6:7]
	v_lshlrev_b32_e32 v2, 2, v0
	v_cmp_ne_u32_e64 s[10:11], 0, v189
	v_lshlrev_b32_e32 v0, 1, v0
	s_load_dwordx2 s[98:99], s[80:81], 0x110
	s_load_dwordx2 s[100:101], s[80:81], 0xd8
	v_and_b32_e32 v176, 63, v182
	v_lshlrev_b32_e32 v170, 3, v176
	s_lshl_b32 vcc_lo, s23, 11
	v_add_u32_e32 v170, vcc_lo, v170
	v_add_u32_e32 v171, 0x3000000, v170
	v_add_u32_e32 v170, 0x7100000, v170
	v_mov_b32_e32 v173, v171
	s_lshl_b32 vcc_lo, s23, 2
	v_mov_b32_e32 v172, 0x2a80000
	v_add_u32_e32 v172, vcc_lo, v172
	v_mov_b32_e32 v174, v172
	v_lshlrev_b32_e32 v176, 4, v176
	v_mov_b32_e32 v138, 0x358637bd
	s_waitcnt lgkmcnt(0)
	global_load_dwordx4 v[192:195], v176, s[100:101]
	global_load_dwordx4 v[196:199], v176, s[100:101] offset:1024
	global_load_dwordx4 v[200:203], v176, s[100:101] offset:2048
	global_load_dwordx4 v[204:207], v176, s[100:101] offset:3072
	global_load_dword v52, v172, s[98:99]
	global_load_dwordx2 v[20:21], v170, s[98:99] nt
	global_load_dwordx2 v[22:23], v170, s[98:99] offset:512 nt
	global_load_dwordx2 v[24:25], v170, s[98:99] offset:1024 nt
	global_load_dwordx2 v[26:27], v170, s[98:99] offset:1536 nt
	global_load_dwordx2 v[36:37], v171, s[98:99]
	global_load_dwordx2 v[38:39], v171, s[98:99] offset:512
	global_load_dwordx2 v[40:41], v171, s[98:99] offset:1024
	global_load_dwordx2 v[42:43], v171, s[98:99] offset:1536
	v_add_u32_e32 v170, 0x400000, v170
	v_add_u32_e32 v171, 0x400000, v171
	v_add_u32_e32 v172, 0x2000, v172
	global_load_dword v54, v172, s[98:99]
	global_load_dwordx2 v[28:29], v170, s[98:99] nt
	global_load_dwordx2 v[30:31], v170, s[98:99] offset:512 nt
	global_load_dwordx2 v[32:33], v170, s[98:99] offset:1024 nt
	global_load_dwordx2 v[34:35], v170, s[98:99] offset:1536 nt
	global_load_dwordx2 v[44:45], v171, s[98:99]
	global_load_dwordx2 v[46:47], v171, s[98:99] offset:512
	global_load_dwordx2 v[48:49], v171, s[98:99] offset:1024
	global_load_dwordx2 v[50:51], v171, s[98:99] offset:1536
	v_add_u32_e32 v170, 0x400000, v170
	v_add_u32_e32 v171, 0x400000, v171
	v_add_u32_e32 v172, 0x2000, v172
	global_load_dword v88, v172, s[98:99]
	global_load_dwordx2 v[56:57], v170, s[98:99] nt
	global_load_dwordx2 v[58:59], v170, s[98:99] offset:512 nt
	global_load_dwordx2 v[60:61], v170, s[98:99] offset:1024 nt
	global_load_dwordx2 v[62:63], v170, s[98:99] offset:1536 nt
	global_load_dwordx2 v[72:73], v171, s[98:99]
	global_load_dwordx2 v[74:75], v171, s[98:99] offset:512
	global_load_dwordx2 v[76:77], v171, s[98:99] offset:1024
	global_load_dwordx2 v[78:79], v171, s[98:99] offset:1536
	v_add_u32_e32 v170, 0x400000, v170
	v_add_u32_e32 v171, 0x400000, v171
	v_add_u32_e32 v172, 0x2000, v172
	global_load_dword v90, v172, s[98:99]
	global_load_dwordx2 v[64:65], v170, s[98:99] nt
	global_load_dwordx2 v[66:67], v170, s[98:99] offset:512 nt
	global_load_dwordx2 v[68:69], v170, s[98:99] offset:1024 nt
	global_load_dwordx2 v[70:71], v170, s[98:99] offset:1536 nt
	global_load_dwordx2 v[80:81], v171, s[98:99]
	global_load_dwordx2 v[82:83], v171, s[98:99] offset:512
	global_load_dwordx2 v[84:85], v171, s[98:99] offset:1024
	global_load_dwordx2 v[86:87], v171, s[98:99] offset:1536
	v_add_u32_e32 v170, 0x400000, v170
	v_add_u32_e32 v171, 0x400000, v171
	v_add_u32_e32 v172, 0x2000, v172
	s_waitcnt vmcnt(31)
	v_lshlrev_b32_e32 v96, 16, v20
	v_and_b32_e32 v97, 0xffff0000, v20
	v_lshlrev_b32_e32 v98, 16, v21
	v_and_b32_e32 v99, 0xffff0000, v21
	v_lshlrev_b32_e32 v100, 16, v22
	v_and_b32_e32 v101, 0xffff0000, v22
	v_lshlrev_b32_e32 v102, 16, v23
	v_and_b32_e32 v103, 0xffff0000, v23
	v_lshlrev_b32_e32 v104, 16, v24
	v_and_b32_e32 v105, 0xffff0000, v24
	v_lshlrev_b32_e32 v106, 16, v25
	v_and_b32_e32 v107, 0xffff0000, v25
	v_lshlrev_b32_e32 v108, 16, v26
	v_and_b32_e32 v109, 0xffff0000, v26
	v_lshlrev_b32_e32 v110, 16, v27
	v_and_b32_e32 v111, 0xffff0000, v27
	v_pk_mul_f32 v[128:129], v[96:97], v[96:97]
	v_pk_fma_f32 v[128:129], v[98:99], v[98:99], v[128:129]
	v_pk_fma_f32 v[128:129], v[100:101], v[100:101], v[128:129]
	v_pk_fma_f32 v[128:129], v[102:103], v[102:103], v[128:129]
	v_pk_fma_f32 v[128:129], v[104:105], v[104:105], v[128:129]
	v_pk_fma_f32 v[128:129], v[106:107], v[106:107], v[128:129]
	v_pk_fma_f32 v[128:129], v[108:109], v[108:109], v[128:129]
	v_pk_fma_f32 v[128:129], v[110:111], v[110:111], v[128:129]
	s_nop 0
	v_add_f32_e32 v128, v128, v129
	s_waitcnt vmcnt(22)
	v_lshlrev_b32_e32 v112, 16, v28
	v_and_b32_e32 v113, 0xffff0000, v28
	v_lshlrev_b32_e32 v114, 16, v29
	v_and_b32_e32 v115, 0xffff0000, v29
	v_lshlrev_b32_e32 v116, 16, v30
	v_and_b32_e32 v117, 0xffff0000, v30
	v_lshlrev_b32_e32 v118, 16, v31
	v_and_b32_e32 v119, 0xffff0000, v31
	v_lshlrev_b32_e32 v120, 16, v32
	v_and_b32_e32 v121, 0xffff0000, v32
	v_lshlrev_b32_e32 v122, 16, v33
	v_and_b32_e32 v123, 0xffff0000, v33
	v_lshlrev_b32_e32 v124, 16, v34
	v_and_b32_e32 v125, 0xffff0000, v34
	v_lshlrev_b32_e32 v126, 16, v35
	v_and_b32_e32 v127, 0xffff0000, v35
	v_pk_mul_f32 v[130:131], v[112:113], v[112:113]
	v_pk_fma_f32 v[130:131], v[114:115], v[114:115], v[130:131]
	v_pk_fma_f32 v[130:131], v[116:117], v[116:117], v[130:131]
	v_pk_fma_f32 v[130:131], v[118:119], v[118:119], v[130:131]
	v_pk_fma_f32 v[130:131], v[120:121], v[120:121], v[130:131]
	v_pk_fma_f32 v[130:131], v[122:123], v[122:123], v[130:131]
	v_pk_fma_f32 v[130:131], v[124:125], v[124:125], v[130:131]
	v_pk_fma_f32 v[130:131], v[126:127], v[126:127], v[130:131]
	s_nop 0
	v_add_f32_e32 v130, v130, v131
	s_nop 1
	v_add_f32_dpp v128, v128, v128 quad_perm:[1,0,3,2] row_mask:0xf bank_mask:0xf
	v_add_f32_dpp v130, v130, v130 quad_perm:[1,0,3,2] row_mask:0xf bank_mask:0xf
	s_nop 0
	v_add_f32_dpp v128, v128, v128 quad_perm:[2,3,0,1] row_mask:0xf bank_mask:0xf
	v_add_f32_dpp v130, v130, v130 quad_perm:[2,3,0,1] row_mask:0xf bank_mask:0xf
	s_nop 0
	v_add_f32_dpp v128, v128, v128 row_half_mirror row_mask:0xf bank_mask:0xf
	v_add_f32_dpp v130, v130, v130 row_half_mirror row_mask:0xf bank_mask:0xf
	s_nop 0
	v_add_f32_dpp v128, v128, v128 row_mirror row_mask:0xf bank_mask:0xf
	v_add_f32_dpp v130, v130, v130 row_mirror row_mask:0xf bank_mask:0xf
	s_nop 0
	ds_bpermute_b32 v136, v187, v128
	ds_bpermute_b32 v137, v187, v130
	s_waitcnt lgkmcnt(0)
;     __device__ __forceinline__ float* out() const { return (float*)karg_in(33); }
; __device__ __forceinline__ float ssq4(v4f v) { return (v.x * v.x + v.y * v.y) + (v.z * v.z + v.w * v.w); }
; template <int R, bool BASE_F32, bool OUT_F32>
; __device__ __forceinline__ void rows_res(const Ctx& C, int m0, int stride, int mx, const float* gpost, float scale, int lane) {
;     ...
;     for (int r = 0; r < R; ++r) r1[r] = rsqrtf(wave_sum(r1[r]) * (1.f / DM) + EPS) * scale;
; #pragma unroll
;     for (int j = 0; j < 4; ++j) { const v4f gp = ld4_f32(gpost + 4 * lane + 256 * j);
; #pragma unroll
;         for (int r = 0; r < R; ++r) d[r][j] = b[r][j] + d[r][j] * r1[r] * gp; }
;     if (OUT_F32) { float* Y = C.out();
; #pragma unroll
;         for (int r = 0; r < R; ++r)
; #pragma unroll
;             for (int j = 0; j < 4; ++j) if (ok[r]) *(v4f*)(Y + (size_t)mr[r] * DM + 4 * lane + 256 * j) = d[r][j];
;     } else { float* rs = C.RS(); float t[R];
; #pragma unroll
;         for (int r = 0; r < R; ++r) { float s = 0.f;
; #pragma unroll
;             for (int j = 0; j < 4; ++j) s += ssq4(d[r][j]);
;             t[r] = s; }
; #pragma unroll
;         for (int r = 0; r < R; ++r) t[r] = wave_sum(t[r]) * (1.f / DM) + EPS;
	v_add_f32_e32 v128, v128, v136
	v_add_f32_e32 v130, v130, v137
	ds_bpermute_b32 v136, v188, v128
	ds_bpermute_b32 v137, v188, v130
	s_waitcnt lgkmcnt(0)
	v_add_f32_e32 v128, v128, v136
	v_add_f32_e32 v130, v130, v137
	v_fmamk_f32 v128, v128, 0x3a800000, v138
	v_fmamk_f32 v130, v130, 0x3a800000, v138
	s_nop 0
	v_rsq_f32_e32 v128, v128
	v_rsq_f32_e32 v130, v130
	s_nop 1
	s_waitcnt vmcnt(18)
	v_pk_mul_f32 v[96:97], v[128:129], v[96:97] op_sel_hi:[0,1]
	v_pk_mul_f32 v[98:99], v[128:129], v[98:99] op_sel_hi:[0,1]
	v_pk_mul_f32 v[100:101], v[128:129], v[100:101] op_sel_hi:[0,1]
	v_pk_mul_f32 v[102:103], v[128:129], v[102:103] op_sel_hi:[0,1]
	v_pk_mul_f32 v[104:105], v[128:129], v[104:105] op_sel_hi:[0,1]
	v_pk_mul_f32 v[106:107], v[128:129], v[106:107] op_sel_hi:[0,1]
	v_pk_mul_f32 v[108:109], v[128:129], v[108:109] op_sel_hi:[0,1]
	v_pk_mul_f32 v[110:111], v[128:129], v[110:111] op_sel_hi:[0,1]
	v_pk_mul_f32 v[96:97], v[96:97], v[192:193]
	v_pk_mul_f32 v[98:99], v[98:99], v[194:195]
	v_pk_mul_f32 v[100:101], v[100:101], v[196:197]
	v_pk_mul_f32 v[102:103], v[102:103], v[198:199]
	v_pk_mul_f32 v[104:105], v[104:105], v[200:201]
	v_pk_mul_f32 v[106:107], v[106:107], v[202:203]
	v_pk_mul_f32 v[108:109], v[108:109], v[204:205]
	v_pk_mul_f32 v[110:111], v[110:111], v[206:207]
	v_lshlrev_b32_e32 v20, 16, v36
	v_and_b32_e32 v21, 0xffff0000, v36
	v_lshlrev_b32_e32 v22, 16, v37
	v_and_b32_e32 v23, 0xffff0000, v37
	v_lshlrev_b32_e32 v24, 16, v38
	v_and_b32_e32 v25, 0xffff0000, v38
	v_lshlrev_b32_e32 v26, 16, v39
	v_and_b32_e32 v27, 0xffff0000, v39
	v_pk_fma_f32 v[96:97], v[52:53], v[20:21], v[96:97] op_sel_hi:[0,1,1]
	v_pk_fma_f32 v[98:99], v[52:53], v[22:23], v[98:99] op_sel_hi:[0,1,1]
	v_pk_fma_f32 v[100:101], v[52:53], v[24:25], v[100:101] op_sel_hi:[0,1,1]
	v_pk_fma_f32 v[102:103], v[52:53], v[26:27], v[102:103] op_sel_hi:[0,1,1]
	v_lshlrev_b32_e32 v20, 16, v40
	v_and_b32_e32 v21, 0xffff0000, v40
	v_lshlrev_b32_e32 v22, 16, v41
	v_and_b32_e32 v23, 0xffff0000, v41
	v_lshlrev_b32_e32 v24, 16, v42
	v_and_b32_e32 v25, 0xffff0000, v42
	v_lshlrev_b32_e32 v26, 16, v43
	v_and_b32_e32 v27, 0xffff0000, v43
	v_pk_fma_f32 v[104:105], v[52:53], v[20:21], v[104:105] op_sel_hi:[0,1,1]
	v_pk_fma_f32 v[106:107], v[52:53], v[22:23], v[106:107] op_sel_hi:[0,1,1]
	v_pk_fma_f32 v[108:109], v[52:53], v[24:25], v[108:109] op_sel_hi:[0,1,1]
	v_pk_fma_f32 v[110:111], v[52:53], v[26:27], v[110:111] op_sel_hi:[0,1,1]
	v_pk_mul_f32 v[132:133], v[96:97], v[96:97]
	v_pk_fma_f32 v[132:133], v[98:99], v[98:99], v[132:133]
	v_pk_fma_f32 v[132:133], v[100:101], v[100:101], v[132:133]
	v_pk_fma_f32 v[132:133], v[102:103], v[102:103], v[132:133]
	v_pk_fma_f32 v[132:133], v[104:105], v[104:105], v[132:133]
	v_pk_fma_f32 v[132:133], v[106:107], v[106:107], v[132:133]
	v_pk_fma_f32 v[132:133], v[108:109], v[108:109], v[132:133]
	v_pk_fma_f32 v[132:133], v[110:111], v[110:111], v[132:133]
	s_nop 0
	v_add_f32_e32 v132, v132, v133
	v_pk_mul_f32 v[112:113], v[130:131], v[112:113] op_sel_hi:[0,1]
	v_pk_mul_f32 v[114:115], v[130:131], v[114:115] op_sel_hi:[0,1]
	v_pk_mul_f32 v[116:117], v[130:131], v[116:117] op_sel_hi:[0,1]
	v_pk_mul_f32 v[118:119], v[130:131], v[118:119] op_sel_hi:[0,1]
	v_pk_mul_f32 v[120:121], v[130:131], v[120:121] op_sel_hi:[0,1]
	v_pk_mul_f32 v[122:123], v[130:131], v[122:123] op_sel_hi:[0,1]
	v_pk_mul_f32 v[124:125], v[130:131], v[124:125] op_sel_hi:[0,1]
	v_pk_mul_f32 v[126:127], v[130:131], v[126:127] op_sel_hi:[0,1]
	v_pk_mul_f32 v[112:113], v[112:113], v[192:193]
	v_pk_mul_f32 v[114:115], v[114:115], v[194:195]
	v_pk_mul_f32 v[116:117], v[116:117], v[196:197]
	v_pk_mul_f32 v[118:119], v[118:119], v[198:199]
	v_pk_mul_f32 v[120:121], v[120:121], v[200:201]
	v_pk_mul_f32 v[122:123], v[122:123], v[202:203]
	v_pk_mul_f32 v[124:125], v[124:125], v[204:205]
	v_pk_mul_f32 v[126:127], v[126:127], v[206:207]
	v_lshlrev_b32_e32 v28, 16, v44
	v_and_b32_e32 v29, 0xffff0000, v44
	v_lshlrev_b32_e32 v30, 16, v45
	v_and_b32_e32 v31, 0xffff0000, v45
	v_lshlrev_b32_e32 v32, 16, v46
	v_and_b32_e32 v33, 0xffff0000, v46
	v_lshlrev_b32_e32 v34, 16, v47
	v_and_b32_e32 v35, 0xffff0000, v47
	v_pk_fma_f32 v[112:113], v[54:55], v[28:29], v[112:113] op_sel_hi:[0,1,1]
	v_pk_fma_f32 v[114:115], v[54:55], v[30:31], v[114:115] op_sel_hi:[0,1,1]
	v_pk_fma_f32 v[116:117], v[54:55], v[32:33], v[116:117] op_sel_hi:[0,1,1]
	v_pk_fma_f32 v[118:119], v[54:55], v[34:35], v[118:119] op_sel_hi:[0,1,1]
	v_lshlrev_b32_e32 v28, 16, v48
	v_and_b32_e32 v29, 0xffff0000, v48
	v_lshlrev_b32_e32 v30, 16, v49
	v_and_b32_e32 v31, 0xffff0000, v49
	v_lshlrev_b32_e32 v32, 16, v50
	v_and_b32_e32 v33, 0xffff0000, v50
	v_lshlrev_b32_e32 v34, 16, v51
	v_and_b32_e32 v35, 0xffff0000, v51
	v_pk_fma_f32 v[120:121], v[54:55], v[28:29], v[120:121] op_sel_hi:[0,1,1]
	v_pk_fma_f32 v[122:123], v[54:55], v[30:31], v[122:123] op_sel_hi:[0,1,1]
	v_pk_fma_f32 v[124:125], v[54:55], v[32:33], v[124:125] op_sel_hi:[0,1,1]
	v_pk_fma_f32 v[126:127], v[54:55], v[34:35], v[126:127] op_sel_hi:[0,1,1]
	v_pk_mul_f32 v[134:135], v[112:113], v[112:113]
	v_pk_fma_f32 v[134:135], v[114:115], v[114:115], v[134:135]
	v_pk_fma_f32 v[134:135], v[116:117], v[116:117], v[134:135]
	v_pk_fma_f32 v[134:135], v[118:119], v[118:119], v[134:135]
	v_pk_fma_f32 v[134:135], v[120:121], v[120:121], v[134:135]
	v_pk_fma_f32 v[134:135], v[122:123], v[122:123], v[134:135]
	v_pk_fma_f32 v[134:135], v[124:125], v[124:125], v[134:135]
	v_pk_fma_f32 v[134:135], v[126:127], v[126:127], v[134:135]
	s_nop 0
	v_add_f32_e32 v134, v134, v135
	s_nop 1
	v_add_f32_dpp v132, v132, v132 quad_perm:[1,0,3,2] row_mask:0xf bank_mask:0xf
	v_add_f32_dpp v134, v134, v134 quad_perm:[1,0,3,2] row_mask:0xf bank_mask:0xf
	s_nop 0
	v_add_f32_dpp v132, v132, v132 quad_perm:[2,3,0,1] row_mask:0xf bank_mask:0xf
	v_add_f32_dpp v134, v134, v134 quad_perm:[2,3,0,1] row_mask:0xf bank_mask:0xf
	s_nop 0
	v_add_f32_dpp v132, v132, v132 row_half_mirror row_mask:0xf bank_mask:0xf
	v_add_f32_dpp v134, v134, v134 row_half_mirror row_mask:0xf bank_mask:0xf
	s_nop 0
	v_add_f32_dpp v132, v132, v132 row_mirror row_mask:0xf bank_mask:0xf
	v_add_f32_dpp v134, v134, v134 row_mirror row_mask:0xf bank_mask:0xf
	s_nop 0
	ds_bpermute_b32 v136, v187, v132
	ds_bpermute_b32 v137, v187, v134
	s_waitcnt lgkmcnt(0)
; __device__ __forceinline__ const float* xrow_ptr(const Ctx& C, int row) { return row < MPROMPT ? C.in(0) + (size_t)row * DM : C.in(1) + (size_t)(row - MPROMPT) * DM; }
; __device__ __forceinline__ v4f ld4_bf16(const bf16* p) { const v2u w = *(const v2u*)p; return (v4f){bf_lo(w.x), bf_hi(w.x), bf_lo(w.y), bf_hi(w.y)}; }
; __device__ __forceinline__ void st4_bf16(bf16* p, v4f o) { v2u w; w.x = cvt_pk_nv(o.x, o.y); w.y = cvt_pk_nv(o.z, o.w); *(v2u*)p = w; }
; __device__ __forceinline__ float ssq4(v4f v) { return (v.x * v.x + v.y * v.y) + (v.z * v.z + v.w * v.w); }
; template <int R, bool BASE_F32, bool OUT_F32>
; __device__ __forceinline__ void rows_res(const Ctx& C, int m0, int stride, int mx, const float* gpost, float scale, int lane) {
;     ...
;     for (int r = 0; r < R; ++r) { mr[r] = (r == 4) ? mx : m0 + r * stride; ok[r] = (r == 4) ? (mx < M) : (mr[r] < MPROMPT); const int mm = ok[r] ? mr[r] : 0;
; #pragma unroll
;         for (int j = 0; j < 4; ++j) d[r][j] = ld4_bf16(D + (size_t)mm * DM + 4 * lane + 256 * j);
;         if (BASE_F32) { const float* x = xrow_ptr(C, mm);
; #pragma unroll
;             for (int j = 0; j < 4; ++j) b[r][j] = ld4_f32(x + 4 * lane + 256 * j);
;         } else { const float inv = C.RS()[mm];
; #pragma unroll
;             for (int j = 0; j < 4; ++j) b[r][j] = ld4_bf16(XN + (size_t)mm * DM + 4 * lane + 256 * j) * inv;
;         } }
; #pragma unroll
;     for (int r = 0; r < R; ++r) { float s = 0.f;
; #pragma unroll
;         for (int j = 0; j < 4; ++j) s += ssq4(d[r][j]);
;         r1[r] = s; }
;     ...
;             for (int j = 0; j < 4; ++j) s += ssq4(d[r][j]);
;             t[r] = s; }
; #pragma unroll
;         for (int r = 0; r < R; ++r) t[r] = wave_sum(t[r]) * (1.f / DM) + EPS;
; #pragma unroll
;         for (int r = 0; r < R; ++r) { const float rstd = rsqrtf(t[r]);
; #pragma unroll
;             for (int j = 0; j < 4; ++j) if (ok[r]) st4_bf16(XN + (size_t)mr[r] * DM + 4 * lane + 256 * j, d[r][j] * rstd);
;             if (lane == 0 && ok[r]) rs[mr[r]] = sqrtf(t[r]); }
	v_add_f32_e32 v132, v132, v136
	v_add_f32_e32 v134, v134, v137
	ds_bpermute_b32 v136, v188, v132
	ds_bpermute_b32 v137, v188, v134
	s_waitcnt lgkmcnt(0)
	v_add_f32_e32 v132, v132, v136
	v_add_f32_e32 v134, v134, v137
	v_fmamk_f32 v164, v132, 0x3a800000, v138
	v_fmamk_f32 v167, v134, 0x3a800000, v138
	s_nop 0
	v_rsq_f32_e32 v132, v164
	v_rsq_f32_e32 v134, v167
	v_sqrt_f32_e32 v165, v164
	v_sqrt_f32_e32 v168, v167
	s_nop 1
	v_pk_mul_f32 v[140:141], v[96:97], v[132:133] op_sel_hi:[1,0]
	v_cvt_pk_bf16_f32 v148, v140, v141
	v_pk_mul_f32 v[142:143], v[98:99], v[132:133] op_sel_hi:[1,0]
	v_cvt_pk_bf16_f32 v149, v142, v143
	v_pk_mul_f32 v[144:145], v[100:101], v[132:133] op_sel_hi:[1,0]
	v_cvt_pk_bf16_f32 v150, v144, v145
	v_pk_mul_f32 v[146:147], v[102:103], v[132:133] op_sel_hi:[1,0]
	v_cvt_pk_bf16_f32 v151, v146, v147
	v_pk_mul_f32 v[140:141], v[104:105], v[132:133] op_sel_hi:[1,0]
	v_cvt_pk_bf16_f32 v152, v140, v141
	v_pk_mul_f32 v[142:143], v[106:107], v[132:133] op_sel_hi:[1,0]
	v_cvt_pk_bf16_f32 v153, v142, v143
	v_pk_mul_f32 v[144:145], v[108:109], v[132:133] op_sel_hi:[1,0]
	v_cvt_pk_bf16_f32 v154, v144, v145
	v_pk_mul_f32 v[146:147], v[110:111], v[132:133] op_sel_hi:[1,0]
	v_cvt_pk_bf16_f32 v155, v146, v147
	global_store_dwordx2 v173, v[148:149], s[98:99]
	global_store_dwordx2 v173, v[150:151], s[98:99] offset:512
	global_store_dwordx2 v173, v[152:153], s[98:99] offset:1024
	global_store_dwordx2 v173, v[154:155], s[98:99] offset:1536
	v_add_u32_e32 v173, 0x400000, v173
	v_pk_mul_f32 v[140:141], v[112:113], v[134:135] op_sel_hi:[1,0]
	v_cvt_pk_bf16_f32 v156, v140, v141
	v_pk_mul_f32 v[142:143], v[114:115], v[134:135] op_sel_hi:[1,0]
	v_cvt_pk_bf16_f32 v157, v142, v143
	v_pk_mul_f32 v[144:145], v[116:117], v[134:135] op_sel_hi:[1,0]
	v_cvt_pk_bf16_f32 v158, v144, v145
	v_pk_mul_f32 v[146:147], v[118:119], v[134:135] op_sel_hi:[1,0]
	v_cvt_pk_bf16_f32 v159, v146, v147
	v_pk_mul_f32 v[140:141], v[120:121], v[134:135] op_sel_hi:[1,0]
	v_cvt_pk_bf16_f32 v160, v140, v141
	v_pk_mul_f32 v[142:143], v[122:123], v[134:135] op_sel_hi:[1,0]
	v_cvt_pk_bf16_f32 v161, v142, v143
	v_pk_mul_f32 v[144:145], v[124:125], v[134:135] op_sel_hi:[1,0]
	v_cvt_pk_bf16_f32 v162, v144, v145
	v_pk_mul_f32 v[146:147], v[126:127], v[134:135] op_sel_hi:[1,0]
	v_cvt_pk_bf16_f32 v163, v146, v147
	global_store_dwordx2 v173, v[156:157], s[98:99]
	global_store_dwordx2 v173, v[158:159], s[98:99] offset:512
	global_store_dwordx2 v173, v[160:161], s[98:99] offset:1024
	global_store_dwordx2 v173, v[162:163], s[98:99] offset:1536
	v_add_u32_e32 v173, 0x400000, v173
	v_add_u32_e32 v166, -1, v165
	v_fma_f32 v140, -v166, v165, v164
	v_cmp_ge_f32_e32 vcc, 0, v140
	v_add_u32_e32 v141, 1, v165
	v_cndmask_b32_e32 v166, v165, v166, vcc
	v_fma_f32 v140, -v141, v165, v164
	v_cmp_lt_f32_e32 vcc, 0, v140
	s_nop 1
	v_cndmask_b32_e32 v165, v166, v141, vcc
	v_add_u32_e32 v169, -1, v168
	v_fma_f32 v142, -v169, v168, v167
	v_cmp_ge_f32_e32 vcc, 0, v142
	v_add_u32_e32 v143, 1, v168
	v_cndmask_b32_e32 v169, v168, v169, vcc
	v_fma_f32 v142, -v143, v168, v167
	v_cmp_lt_f32_e32 vcc, 0, v142
	s_nop 1
	v_cndmask_b32_e32 v168, v169, v143, vcc
	s_mov_b64 exec, 1
	global_store_dword v174, v165, s[98:99]
	v_add_u32_e32 v174, 0x2000, v174
	global_store_dword v174, v168, s[98:99]
	v_add_u32_e32 v174, 0x2000, v174
	s_mov_b64 exec, -1
	global_load_dword v52, v172, s[98:99]
	global_load_dwordx2 v[20:21], v170, s[98:99] nt
	global_load_dwordx2 v[22:23], v170, s[98:99] offset:512 nt
	global_load_dwordx2 v[24:25], v170, s[98:99] offset:1024 nt
	global_load_dwordx2 v[26:27], v170, s[98:99] offset:1536 nt
	global_load_dwordx2 v[36:37], v171, s[98:99]
	global_load_dwordx2 v[38:39], v171, s[98:99] offset:512
	global_load_dwordx2 v[40:41], v171, s[98:99] offset:1024
	global_load_dwordx2 v[42:43], v171, s[98:99] offset:1536
	v_add_u32_e32 v170, 0x400000, v170
	v_add_u32_e32 v171, 0x400000, v171
	v_add_u32_e32 v172, 0x2000, v172
	global_load_dword v54, v172, s[98:99]
	global_load_dwordx2 v[28:29], v170, s[98:99] nt
	global_load_dwordx2 v[30:31], v170, s[98:99] offset:512 nt
	global_load_dwordx2 v[32:33], v170, s[98:99] offset:1024 nt
	global_load_dwordx2 v[34:35], v170, s[98:99] offset:1536 nt
	global_load_dwordx2 v[44:45], v171, s[98:99]
	global_load_dwordx2 v[46:47], v171, s[98:99] offset:512
	global_load_dwordx2 v[48:49], v171, s[98:99] offset:1024
	global_load_dwordx2 v[50:51], v171, s[98:99] offset:1536
	v_add_u32_e32 v170, 0x400000, v170
	v_add_u32_e32 v171, 0x400000, v171
	v_add_u32_e32 v172, 0x2000, v172
	s_waitcnt vmcnt(41)
	v_lshlrev_b32_e32 v96, 16, v56
	v_and_b32_e32 v97, 0xffff0000, v56
	v_lshlrev_b32_e32 v98, 16, v57
	v_and_b32_e32 v99, 0xffff0000, v57
	v_lshlrev_b32_e32 v100, 16, v58
	v_and_b32_e32 v101, 0xffff0000, v58
	v_lshlrev_b32_e32 v102, 16, v59
	v_and_b32_e32 v103, 0xffff0000, v59
	v_lshlrev_b32_e32 v104, 16, v60
	v_and_b32_e32 v105, 0xffff0000, v60
	v_lshlrev_b32_e32 v106, 16, v61
	v_and_b32_e32 v107, 0xffff0000, v61
	v_lshlrev_b32_e32 v108, 16, v62
	v_and_b32_e32 v109, 0xffff0000, v62
	v_lshlrev_b32_e32 v110, 16, v63
	v_and_b32_e32 v111, 0xffff0000, v63
	v_pk_mul_f32 v[128:129], v[96:97], v[96:97]
	v_pk_fma_f32 v[128:129], v[98:99], v[98:99], v[128:129]
	v_pk_fma_f32 v[128:129], v[100:101], v[100:101], v[128:129]
	v_pk_fma_f32 v[128:129], v[102:103], v[102:103], v[128:129]
	v_pk_fma_f32 v[128:129], v[104:105], v[104:105], v[128:129]
	v_pk_fma_f32 v[128:129], v[106:107], v[106:107], v[128:129]
	v_pk_fma_f32 v[128:129], v[108:109], v[108:109], v[128:129]
	v_pk_fma_f32 v[128:129], v[110:111], v[110:111], v[128:129]
	s_nop 0
	v_add_f32_e32 v128, v128, v129
	s_waitcnt vmcnt(32)
; __device__ __forceinline__ float ssq4(v4f v) { return (v.x * v.x + v.y * v.y) + (v.z * v.z + v.w * v.w); }
; template <int R, bool BASE_F32, bool OUT_F32>
; __device__ __forceinline__ void rows_res(const Ctx& C, int m0, int stride, int mx, const float* gpost, float scale, int lane) {
;     ...
;     for (int r = 0; r < R; ++r) { float s = 0.f;
; #pragma unroll
;         for (int j = 0; j < 4; ++j) s += ssq4(d[r][j]);
;         r1[r] = s; }
; #pragma unroll
;     for (int r = 0; r < R; ++r) r1[r] = rsqrtf(wave_sum(r1[r]) * (1.f / DM) + EPS) * scale;
; #pragma unroll
;     for (int j = 0; j < 4; ++j) { const v4f gp = ld4_f32(gpost + 4 * lane + 256 * j);
; #pragma unroll
;         for (int r = 0; r < R; ++r) d[r][j] = b[r][j] + d[r][j] * r1[r] * gp; }
	v_lshlrev_b32_e32 v112, 16, v64
	v_and_b32_e32 v113, 0xffff0000, v64
	v_lshlrev_b32_e32 v114, 16, v65
	v_and_b32_e32 v115, 0xffff0000, v65
	v_lshlrev_b32_e32 v116, 16, v66
	v_and_b32_e32 v117, 0xffff0000, v66
	v_lshlrev_b32_e32 v118, 16, v67
	v_and_b32_e32 v119, 0xffff0000, v67
	v_lshlrev_b32_e32 v120, 16, v68
	v_and_b32_e32 v121, 0xffff0000, v68
	v_lshlrev_b32_e32 v122, 16, v69
	v_and_b32_e32 v123, 0xffff0000, v69
	v_lshlrev_b32_e32 v124, 16, v70
	v_and_b32_e32 v125, 0xffff0000, v70
	v_lshlrev_b32_e32 v126, 16, v71
	v_and_b32_e32 v127, 0xffff0000, v71
	v_pk_mul_f32 v[130:131], v[112:113], v[112:113]
	v_pk_fma_f32 v[130:131], v[114:115], v[114:115], v[130:131]
	v_pk_fma_f32 v[130:131], v[116:117], v[116:117], v[130:131]
	v_pk_fma_f32 v[130:131], v[118:119], v[118:119], v[130:131]
	v_pk_fma_f32 v[130:131], v[120:121], v[120:121], v[130:131]
	v_pk_fma_f32 v[130:131], v[122:123], v[122:123], v[130:131]
	v_pk_fma_f32 v[130:131], v[124:125], v[124:125], v[130:131]
	v_pk_fma_f32 v[130:131], v[126:127], v[126:127], v[130:131]
	s_nop 0
	v_add_f32_e32 v130, v130, v131
	s_nop 1
	v_add_f32_dpp v128, v128, v128 quad_perm:[1,0,3,2] row_mask:0xf bank_mask:0xf
	v_add_f32_dpp v130, v130, v130 quad_perm:[1,0,3,2] row_mask:0xf bank_mask:0xf
	s_nop 0
	v_add_f32_dpp v128, v128, v128 quad_perm:[2,3,0,1] row_mask:0xf bank_mask:0xf
	v_add_f32_dpp v130, v130, v130 quad_perm:[2,3,0,1] row_mask:0xf bank_mask:0xf
	s_nop 0
	v_add_f32_dpp v128, v128, v128 row_half_mirror row_mask:0xf bank_mask:0xf
	v_add_f32_dpp v130, v130, v130 row_half_mirror row_mask:0xf bank_mask:0xf
	s_nop 0
	v_add_f32_dpp v128, v128, v128 row_mirror row_mask:0xf bank_mask:0xf
	v_add_f32_dpp v130, v130, v130 row_mirror row_mask:0xf bank_mask:0xf
	s_nop 0
	ds_bpermute_b32 v136, v187, v128
	ds_bpermute_b32 v137, v187, v130
	s_waitcnt lgkmcnt(0)
	v_add_f32_e32 v128, v128, v136
	v_add_f32_e32 v130, v130, v137
	ds_bpermute_b32 v136, v188, v128
	ds_bpermute_b32 v137, v188, v130
	s_waitcnt lgkmcnt(0)
	v_add_f32_e32 v128, v128, v136
	v_add_f32_e32 v130, v130, v137
	v_fmamk_f32 v128, v128, 0x3a800000, v138
	v_fmamk_f32 v130, v130, 0x3a800000, v138
	s_nop 0
	v_rsq_f32_e32 v128, v128
	v_rsq_f32_e32 v130, v130
	s_nop 1
	s_waitcnt vmcnt(28)
	v_pk_mul_f32 v[96:97], v[128:129], v[96:97] op_sel_hi:[0,1]
	v_pk_mul_f32 v[98:99], v[128:129], v[98:99] op_sel_hi:[0,1]
	v_pk_mul_f32 v[100:101], v[128:129], v[100:101] op_sel_hi:[0,1]
	v_pk_mul_f32 v[102:103], v[128:129], v[102:103] op_sel_hi:[0,1]
	v_pk_mul_f32 v[104:105], v[128:129], v[104:105] op_sel_hi:[0,1]
	v_pk_mul_f32 v[106:107], v[128:129], v[106:107] op_sel_hi:[0,1]
	v_pk_mul_f32 v[108:109], v[128:129], v[108:109] op_sel_hi:[0,1]
	v_pk_mul_f32 v[110:111], v[128:129], v[110:111] op_sel_hi:[0,1]
	v_pk_mul_f32 v[96:97], v[96:97], v[192:193]
	v_pk_mul_f32 v[98:99], v[98:99], v[194:195]
	v_pk_mul_f32 v[100:101], v[100:101], v[196:197]
	v_pk_mul_f32 v[102:103], v[102:103], v[198:199]
	v_pk_mul_f32 v[104:105], v[104:105], v[200:201]
	v_pk_mul_f32 v[106:107], v[106:107], v[202:203]
	v_pk_mul_f32 v[108:109], v[108:109], v[204:205]
	v_pk_mul_f32 v[110:111], v[110:111], v[206:207]
	v_lshlrev_b32_e32 v56, 16, v72
	v_and_b32_e32 v57, 0xffff0000, v72
	v_lshlrev_b32_e32 v58, 16, v73
	v_and_b32_e32 v59, 0xffff0000, v73
	v_lshlrev_b32_e32 v60, 16, v74
	v_and_b32_e32 v61, 0xffff0000, v74
	v_lshlrev_b32_e32 v62, 16, v75
	v_and_b32_e32 v63, 0xffff0000, v75
	v_pk_fma_f32 v[96:97], v[88:89], v[56:57], v[96:97] op_sel_hi:[0,1,1]
	v_pk_fma_f32 v[98:99], v[88:89], v[58:59], v[98:99] op_sel_hi:[0,1,1]
	v_pk_fma_f32 v[100:101], v[88:89], v[60:61], v[100:101] op_sel_hi:[0,1,1]
	v_pk_fma_f32 v[102:103], v[88:89], v[62:63], v[102:103] op_sel_hi:[0,1,1]
	v_lshlrev_b32_e32 v56, 16, v76
	v_and_b32_e32 v57, 0xffff0000, v76
	v_lshlrev_b32_e32 v58, 16, v77
	v_and_b32_e32 v59, 0xffff0000, v77
	v_lshlrev_b32_e32 v60, 16, v78
	v_and_b32_e32 v61, 0xffff0000, v78
	v_lshlrev_b32_e32 v62, 16, v79
	v_and_b32_e32 v63, 0xffff0000, v79
	v_pk_fma_f32 v[104:105], v[88:89], v[56:57], v[104:105] op_sel_hi:[0,1,1]
	v_pk_fma_f32 v[106:107], v[88:89], v[58:59], v[106:107] op_sel_hi:[0,1,1]
	v_pk_fma_f32 v[108:109], v[88:89], v[60:61], v[108:109] op_sel_hi:[0,1,1]
	v_pk_fma_f32 v[110:111], v[88:89], v[62:63], v[110:111] op_sel_hi:[0,1,1]
	v_pk_mul_f32 v[132:133], v[96:97], v[96:97]
	v_pk_fma_f32 v[132:133], v[98:99], v[98:99], v[132:133]
	v_pk_fma_f32 v[132:133], v[100:101], v[100:101], v[132:133]
	v_pk_fma_f32 v[132:133], v[102:103], v[102:103], v[132:133]
	v_pk_fma_f32 v[132:133], v[104:105], v[104:105], v[132:133]
	v_pk_fma_f32 v[132:133], v[106:107], v[106:107], v[132:133]
	v_pk_fma_f32 v[132:133], v[108:109], v[108:109], v[132:133]
	v_pk_fma_f32 v[132:133], v[110:111], v[110:111], v[132:133]
	s_nop 0
	v_add_f32_e32 v132, v132, v133
	v_pk_mul_f32 v[112:113], v[130:131], v[112:113] op_sel_hi:[0,1]
	v_pk_mul_f32 v[114:115], v[130:131], v[114:115] op_sel_hi:[0,1]
	v_pk_mul_f32 v[116:117], v[130:131], v[116:117] op_sel_hi:[0,1]
	v_pk_mul_f32 v[118:119], v[130:131], v[118:119] op_sel_hi:[0,1]
	v_pk_mul_f32 v[120:121], v[130:131], v[120:121] op_sel_hi:[0,1]
	v_pk_mul_f32 v[122:123], v[130:131], v[122:123] op_sel_hi:[0,1]
	v_pk_mul_f32 v[124:125], v[130:131], v[124:125] op_sel_hi:[0,1]
	v_pk_mul_f32 v[126:127], v[130:131], v[126:127] op_sel_hi:[0,1]
	v_pk_mul_f32 v[112:113], v[112:113], v[192:193]
	v_pk_mul_f32 v[114:115], v[114:115], v[194:195]
	v_pk_mul_f32 v[116:117], v[116:117], v[196:197]
	v_pk_mul_f32 v[118:119], v[118:119], v[198:199]
	v_pk_mul_f32 v[120:121], v[120:121], v[200:201]
	v_pk_mul_f32 v[122:123], v[122:123], v[202:203]
	v_pk_mul_f32 v[124:125], v[124:125], v[204:205]
	v_pk_mul_f32 v[126:127], v[126:127], v[206:207]
;     __device__ __forceinline__ float* out() const { return (float*)karg_in(33); }
; __device__ __forceinline__ const float* xrow_ptr(const Ctx& C, int row) { return row < MPROMPT ? C.in(0) + (size_t)row * DM : C.in(1) + (size_t)(row - MPROMPT) * DM; }
; __device__ __forceinline__ v4f ld4_bf16(const bf16* p) { const v2u w = *(const v2u*)p; return (v4f){bf_lo(w.x), bf_hi(w.x), bf_lo(w.y), bf_hi(w.y)}; }
; __device__ __forceinline__ void st4_bf16(bf16* p, v4f o) { v2u w; w.x = cvt_pk_nv(o.x, o.y); w.y = cvt_pk_nv(o.z, o.w); *(v2u*)p = w; }
; __device__ __forceinline__ float ssq4(v4f v) { return (v.x * v.x + v.y * v.y) + (v.z * v.z + v.w * v.w); }
; template <int R, bool BASE_F32, bool OUT_F32>
; __device__ __forceinline__ void rows_res(const Ctx& C, int m0, int stride, int mx, const float* gpost, float scale, int lane) {
;     ...
;     for (int r = 0; r < R; ++r) { mr[r] = (r == 4) ? mx : m0 + r * stride; ok[r] = (r == 4) ? (mx < M) : (mr[r] < MPROMPT); const int mm = ok[r] ? mr[r] : 0;
; #pragma unroll
;         for (int j = 0; j < 4; ++j) d[r][j] = ld4_bf16(D + (size_t)mm * DM + 4 * lane + 256 * j);
;         if (BASE_F32) { const float* x = xrow_ptr(C, mm);
; #pragma unroll
;             for (int j = 0; j < 4; ++j) b[r][j] = ld4_f32(x + 4 * lane + 256 * j);
;         } else { const float inv = C.RS()[mm];
; #pragma unroll
;             for (int j = 0; j < 4; ++j) b[r][j] = ld4_bf16(XN + (size_t)mm * DM + 4 * lane + 256 * j) * inv;
;         } }
;     ...
;         for (int r = 0; r < R; ++r) d[r][j] = b[r][j] + d[r][j] * r1[r] * gp; }
;     if (OUT_F32) { float* Y = C.out();
; #pragma unroll
;         for (int r = 0; r < R; ++r)
; #pragma unroll
;             for (int j = 0; j < 4; ++j) if (ok[r]) *(v4f*)(Y + (size_t)mr[r] * DM + 4 * lane + 256 * j) = d[r][j];
;     } else { float* rs = C.RS(); float t[R];
; #pragma unroll
;         for (int r = 0; r < R; ++r) { float s = 0.f;
; #pragma unroll
;             for (int j = 0; j < 4; ++j) s += ssq4(d[r][j]);
;             t[r] = s; }
; #pragma unroll
;         for (int r = 0; r < R; ++r) t[r] = wave_sum(t[r]) * (1.f / DM) + EPS;
; #pragma unroll
;         for (int r = 0; r < R; ++r) { const float rstd = rsqrtf(t[r]);
; #pragma unroll
;             for (int j = 0; j < 4; ++j) if (ok[r]) st4_bf16(XN + (size_t)mr[r] * DM + 4 * lane + 256 * j, d[r][j] * rstd);
;             if (lane == 0 && ok[r]) rs[mr[r]] = sqrtf(t[r]); }
	v_lshlrev_b32_e32 v64, 16, v80
	v_and_b32_e32 v65, 0xffff0000, v80
	v_lshlrev_b32_e32 v66, 16, v81
	v_and_b32_e32 v67, 0xffff0000, v81
	v_lshlrev_b32_e32 v68, 16, v82
	v_and_b32_e32 v69, 0xffff0000, v82
	v_lshlrev_b32_e32 v70, 16, v83
	v_and_b32_e32 v71, 0xffff0000, v83
	v_pk_fma_f32 v[112:113], v[90:91], v[64:65], v[112:113] op_sel_hi:[0,1,1]
	v_pk_fma_f32 v[114:115], v[90:91], v[66:67], v[114:115] op_sel_hi:[0,1,1]
	v_pk_fma_f32 v[116:117], v[90:91], v[68:69], v[116:117] op_sel_hi:[0,1,1]
	v_pk_fma_f32 v[118:119], v[90:91], v[70:71], v[118:119] op_sel_hi:[0,1,1]
	v_lshlrev_b32_e32 v64, 16, v84
	v_and_b32_e32 v65, 0xffff0000, v84
	v_lshlrev_b32_e32 v66, 16, v85
	v_and_b32_e32 v67, 0xffff0000, v85
	v_lshlrev_b32_e32 v68, 16, v86
	v_and_b32_e32 v69, 0xffff0000, v86
	v_lshlrev_b32_e32 v70, 16, v87
	v_and_b32_e32 v71, 0xffff0000, v87
	v_pk_fma_f32 v[120:121], v[90:91], v[64:65], v[120:121] op_sel_hi:[0,1,1]
	v_pk_fma_f32 v[122:123], v[90:91], v[66:67], v[122:123] op_sel_hi:[0,1,1]
	v_pk_fma_f32 v[124:125], v[90:91], v[68:69], v[124:125] op_sel_hi:[0,1,1]
	v_pk_fma_f32 v[126:127], v[90:91], v[70:71], v[126:127] op_sel_hi:[0,1,1]
	v_pk_mul_f32 v[134:135], v[112:113], v[112:113]
	v_pk_fma_f32 v[134:135], v[114:115], v[114:115], v[134:135]
	v_pk_fma_f32 v[134:135], v[116:117], v[116:117], v[134:135]
	v_pk_fma_f32 v[134:135], v[118:119], v[118:119], v[134:135]
	v_pk_fma_f32 v[134:135], v[120:121], v[120:121], v[134:135]
	v_pk_fma_f32 v[134:135], v[122:123], v[122:123], v[134:135]
	v_pk_fma_f32 v[134:135], v[124:125], v[124:125], v[134:135]
	v_pk_fma_f32 v[134:135], v[126:127], v[126:127], v[134:135]
	s_nop 0
	v_add_f32_e32 v134, v134, v135
	s_nop 1
	v_add_f32_dpp v132, v132, v132 quad_perm:[1,0,3,2] row_mask:0xf bank_mask:0xf
	v_add_f32_dpp v134, v134, v134 quad_perm:[1,0,3,2] row_mask:0xf bank_mask:0xf
	s_nop 0
	v_add_f32_dpp v132, v132, v132 quad_perm:[2,3,0,1] row_mask:0xf bank_mask:0xf
	v_add_f32_dpp v134, v134, v134 quad_perm:[2,3,0,1] row_mask:0xf bank_mask:0xf
	s_nop 0
	v_add_f32_dpp v132, v132, v132 row_half_mirror row_mask:0xf bank_mask:0xf
	v_add_f32_dpp v134, v134, v134 row_half_mirror row_mask:0xf bank_mask:0xf
	s_nop 0
	v_add_f32_dpp v132, v132, v132 row_mirror row_mask:0xf bank_mask:0xf
	v_add_f32_dpp v134, v134, v134 row_mirror row_mask:0xf bank_mask:0xf
	s_nop 0
	ds_bpermute_b32 v136, v187, v132
	ds_bpermute_b32 v137, v187, v134
	s_waitcnt lgkmcnt(0)
	v_add_f32_e32 v132, v132, v136
	v_add_f32_e32 v134, v134, v137
	ds_bpermute_b32 v136, v188, v132
	ds_bpermute_b32 v137, v188, v134
	s_waitcnt lgkmcnt(0)
	v_add_f32_e32 v132, v132, v136
	v_add_f32_e32 v134, v134, v137
	v_fmamk_f32 v164, v132, 0x3a800000, v138
	v_fmamk_f32 v167, v134, 0x3a800000, v138
	s_nop 0
	v_rsq_f32_e32 v132, v164
	v_rsq_f32_e32 v134, v167
	v_sqrt_f32_e32 v165, v164
	v_sqrt_f32_e32 v168, v167
	s_nop 1
	v_pk_mul_f32 v[140:141], v[96:97], v[132:133] op_sel_hi:[1,0]
	v_cvt_pk_bf16_f32 v148, v140, v141
	v_pk_mul_f32 v[142:143], v[98:99], v[132:133] op_sel_hi:[1,0]
	v_cvt_pk_bf16_f32 v149, v142, v143
	v_pk_mul_f32 v[144:145], v[100:101], v[132:133] op_sel_hi:[1,0]
	v_cvt_pk_bf16_f32 v150, v144, v145
	v_pk_mul_f32 v[146:147], v[102:103], v[132:133] op_sel_hi:[1,0]
	v_cvt_pk_bf16_f32 v151, v146, v147
	v_pk_mul_f32 v[140:141], v[104:105], v[132:133] op_sel_hi:[1,0]
	v_cvt_pk_bf16_f32 v152, v140, v141
	v_pk_mul_f32 v[142:143], v[106:107], v[132:133] op_sel_hi:[1,0]
	v_cvt_pk_bf16_f32 v153, v142, v143
	v_pk_mul_f32 v[144:145], v[108:109], v[132:133] op_sel_hi:[1,0]
	v_cvt_pk_bf16_f32 v154, v144, v145
	v_pk_mul_f32 v[146:147], v[110:111], v[132:133] op_sel_hi:[1,0]
	v_cvt_pk_bf16_f32 v155, v146, v147
	global_store_dwordx2 v173, v[148:149], s[98:99]
	global_store_dwordx2 v173, v[150:151], s[98:99] offset:512
	global_store_dwordx2 v173, v[152:153], s[98:99] offset:1024
	global_store_dwordx2 v173, v[154:155], s[98:99] offset:1536
	v_add_u32_e32 v173, 0x400000, v173
	v_pk_mul_f32 v[140:141], v[112:113], v[134:135] op_sel_hi:[1,0]
	v_cvt_pk_bf16_f32 v156, v140, v141
	v_pk_mul_f32 v[142:143], v[114:115], v[134:135] op_sel_hi:[1,0]
	v_cvt_pk_bf16_f32 v157, v142, v143
	v_pk_mul_f32 v[144:145], v[116:117], v[134:135] op_sel_hi:[1,0]
	v_cvt_pk_bf16_f32 v158, v144, v145
	v_pk_mul_f32 v[146:147], v[118:119], v[134:135] op_sel_hi:[1,0]
	v_cvt_pk_bf16_f32 v159, v146, v147
	v_pk_mul_f32 v[140:141], v[120:121], v[134:135] op_sel_hi:[1,0]
	v_cvt_pk_bf16_f32 v160, v140, v141
	v_pk_mul_f32 v[142:143], v[122:123], v[134:135] op_sel_hi:[1,0]
	v_cvt_pk_bf16_f32 v161, v142, v143
	v_pk_mul_f32 v[144:145], v[124:125], v[134:135] op_sel_hi:[1,0]
	v_cvt_pk_bf16_f32 v162, v144, v145
	v_pk_mul_f32 v[146:147], v[126:127], v[134:135] op_sel_hi:[1,0]
	v_cvt_pk_bf16_f32 v163, v146, v147
	global_store_dwordx2 v173, v[156:157], s[98:99]
	global_store_dwordx2 v173, v[158:159], s[98:99] offset:512
	global_store_dwordx2 v173, v[160:161], s[98:99] offset:1024
	global_store_dwordx2 v173, v[162:163], s[98:99] offset:1536
	v_add_u32_e32 v173, 0x400000, v173
	v_add_u32_e32 v166, -1, v165
	v_fma_f32 v140, -v166, v165, v164
	v_cmp_ge_f32_e32 vcc, 0, v140
	v_add_u32_e32 v141, 1, v165
	v_cndmask_b32_e32 v166, v165, v166, vcc
	v_fma_f32 v140, -v141, v165, v164
	v_cmp_lt_f32_e32 vcc, 0, v140
	s_nop 1
	v_cndmask_b32_e32 v165, v166, v141, vcc
	v_add_u32_e32 v169, -1, v168
	v_fma_f32 v142, -v169, v168, v167
	v_cmp_ge_f32_e32 vcc, 0, v142
	v_add_u32_e32 v143, 1, v168
	v_cndmask_b32_e32 v169, v168, v169, vcc
	v_fma_f32 v142, -v143, v168, v167
	v_cmp_lt_f32_e32 vcc, 0, v142
	s_nop 1
	v_cndmask_b32_e32 v168, v169, v143, vcc
	s_mov_b64 exec, 1
	global_store_dword v174, v165, s[98:99]
	v_add_u32_e32 v174, 0x2000, v174
	global_store_dword v174, v168, s[98:99]
	v_add_u32_e32 v174, 0x2000, v174
	s_mov_b64 exec, -1
	global_load_dword v88, v172, s[98:99]
	global_load_dwordx2 v[56:57], v170, s[98:99] nt
	global_load_dwordx2 v[58:59], v170, s[98:99] offset:512 nt
	global_load_dwordx2 v[60:61], v170, s[98:99] offset:1024 nt
	global_load_dwordx2 v[62:63], v170, s[98:99] offset:1536 nt
	global_load_dwordx2 v[72:73], v171, s[98:99]
	global_load_dwordx2 v[74:75], v171, s[98:99] offset:512
	global_load_dwordx2 v[76:77], v171, s[98:99] offset:1024
	global_load_dwordx2 v[78:79], v171, s[98:99] offset:1536
	v_add_u32_e32 v170, 0x400000, v170
	v_add_u32_e32 v171, 0x400000, v171
	v_add_u32_e32 v172, 0x2000, v172
	global_load_dword v90, v172, s[98:99]
	global_load_dwordx2 v[64:65], v170, s[98:99] nt
	global_load_dwordx2 v[66:67], v170, s[98:99] offset:512 nt
	global_load_dwordx2 v[68:69], v170, s[98:99] offset:1024 nt
	global_load_dwordx2 v[70:71], v170, s[98:99] offset:1536 nt
	global_load_dwordx2 v[80:81], v171, s[98:99]
	global_load_dwordx2 v[82:83], v171, s[98:99] offset:512
	global_load_dwordx2 v[84:85], v171, s[98:99] offset:1024
	global_load_dwordx2 v[86:87], v171, s[98:99] offset:1536
	v_add_u32_e32 v170, 0x400000, v170
	v_add_u32_e32 v171, 0x400000, v171
	v_add_u32_e32 v172, 0x2000, v172
	s_waitcnt vmcnt(41)
; __device__ __forceinline__ float ssq4(v4f v) { return (v.x * v.x + v.y * v.y) + (v.z * v.z + v.w * v.w); }
; template <int R, bool BASE_F32, bool OUT_F32>
; __device__ __forceinline__ void rows_res(const Ctx& C, int m0, int stride, int mx, const float* gpost, float scale, int lane) {
;     ...
;     for (int r = 0; r < R; ++r) { float s = 0.f;
; #pragma unroll
;         for (int j = 0; j < 4; ++j) s += ssq4(d[r][j]);
;         r1[r] = s; }
; #pragma unroll
;     for (int r = 0; r < R; ++r) r1[r] = rsqrtf(wave_sum(r1[r]) * (1.f / DM) + EPS) * scale;
; #pragma unroll
;     for (int j = 0; j < 4; ++j) { const v4f gp = ld4_f32(gpost + 4 * lane + 256 * j);
; #pragma unroll
;         for (int r = 0; r < R; ++r) d[r][j] = b[r][j] + d[r][j] * r1[r] * gp; }
	v_lshlrev_b32_e32 v96, 16, v20
	v_and_b32_e32 v97, 0xffff0000, v20
	v_lshlrev_b32_e32 v98, 16, v21
	v_and_b32_e32 v99, 0xffff0000, v21
	v_lshlrev_b32_e32 v100, 16, v22
	v_and_b32_e32 v101, 0xffff0000, v22
	v_lshlrev_b32_e32 v102, 16, v23
	v_and_b32_e32 v103, 0xffff0000, v23
	v_lshlrev_b32_e32 v104, 16, v24
	v_and_b32_e32 v105, 0xffff0000, v24
	v_lshlrev_b32_e32 v106, 16, v25
	v_and_b32_e32 v107, 0xffff0000, v25
	v_lshlrev_b32_e32 v108, 16, v26
	v_and_b32_e32 v109, 0xffff0000, v26
	v_lshlrev_b32_e32 v110, 16, v27
	v_and_b32_e32 v111, 0xffff0000, v27
	v_pk_mul_f32 v[128:129], v[96:97], v[96:97]
	v_pk_fma_f32 v[128:129], v[98:99], v[98:99], v[128:129]
	v_pk_fma_f32 v[128:129], v[100:101], v[100:101], v[128:129]
	v_pk_fma_f32 v[128:129], v[102:103], v[102:103], v[128:129]
	v_pk_fma_f32 v[128:129], v[104:105], v[104:105], v[128:129]
	v_pk_fma_f32 v[128:129], v[106:107], v[106:107], v[128:129]
	v_pk_fma_f32 v[128:129], v[108:109], v[108:109], v[128:129]
	v_pk_fma_f32 v[128:129], v[110:111], v[110:111], v[128:129]
	s_nop 0
	v_add_f32_e32 v128, v128, v129
	s_waitcnt vmcnt(32)
	v_lshlrev_b32_e32 v112, 16, v28
	v_and_b32_e32 v113, 0xffff0000, v28
	v_lshlrev_b32_e32 v114, 16, v29
	v_and_b32_e32 v115, 0xffff0000, v29
	v_lshlrev_b32_e32 v116, 16, v30
	v_and_b32_e32 v117, 0xffff0000, v30
	v_lshlrev_b32_e32 v118, 16, v31
	v_and_b32_e32 v119, 0xffff0000, v31
	v_lshlrev_b32_e32 v120, 16, v32
	v_and_b32_e32 v121, 0xffff0000, v32
	v_lshlrev_b32_e32 v122, 16, v33
	v_and_b32_e32 v123, 0xffff0000, v33
	v_lshlrev_b32_e32 v124, 16, v34
	v_and_b32_e32 v125, 0xffff0000, v34
	v_lshlrev_b32_e32 v126, 16, v35
	v_and_b32_e32 v127, 0xffff0000, v35
	v_pk_mul_f32 v[130:131], v[112:113], v[112:113]
	v_pk_fma_f32 v[130:131], v[114:115], v[114:115], v[130:131]
	v_pk_fma_f32 v[130:131], v[116:117], v[116:117], v[130:131]
	v_pk_fma_f32 v[130:131], v[118:119], v[118:119], v[130:131]
	v_pk_fma_f32 v[130:131], v[120:121], v[120:121], v[130:131]
	v_pk_fma_f32 v[130:131], v[122:123], v[122:123], v[130:131]
	v_pk_fma_f32 v[130:131], v[124:125], v[124:125], v[130:131]
	v_pk_fma_f32 v[130:131], v[126:127], v[126:127], v[130:131]
	s_nop 0
	v_add_f32_e32 v130, v130, v131
	s_nop 1
	v_add_f32_dpp v128, v128, v128 quad_perm:[1,0,3,2] row_mask:0xf bank_mask:0xf
	v_add_f32_dpp v130, v130, v130 quad_perm:[1,0,3,2] row_mask:0xf bank_mask:0xf
	s_nop 0
	v_add_f32_dpp v128, v128, v128 quad_perm:[2,3,0,1] row_mask:0xf bank_mask:0xf
	v_add_f32_dpp v130, v130, v130 quad_perm:[2,3,0,1] row_mask:0xf bank_mask:0xf
	s_nop 0
	v_add_f32_dpp v128, v128, v128 row_half_mirror row_mask:0xf bank_mask:0xf
	v_add_f32_dpp v130, v130, v130 row_half_mirror row_mask:0xf bank_mask:0xf
	s_nop 0
	v_add_f32_dpp v128, v128, v128 row_mirror row_mask:0xf bank_mask:0xf
	v_add_f32_dpp v130, v130, v130 row_mirror row_mask:0xf bank_mask:0xf
	s_nop 0
	ds_bpermute_b32 v136, v187, v128
	ds_bpermute_b32 v137, v187, v130
	s_waitcnt lgkmcnt(0)
	v_add_f32_e32 v128, v128, v136
	v_add_f32_e32 v130, v130, v137
	ds_bpermute_b32 v136, v188, v128
	ds_bpermute_b32 v137, v188, v130
	s_waitcnt lgkmcnt(0)
	v_add_f32_e32 v128, v128, v136
	v_add_f32_e32 v130, v130, v137
	v_fmamk_f32 v128, v128, 0x3a800000, v138
	v_fmamk_f32 v130, v130, 0x3a800000, v138
	s_nop 0
	v_rsq_f32_e32 v128, v128
	v_rsq_f32_e32 v130, v130
	s_nop 1
	s_waitcnt vmcnt(28)
	v_pk_mul_f32 v[96:97], v[128:129], v[96:97] op_sel_hi:[0,1]
	v_pk_mul_f32 v[98:99], v[128:129], v[98:99] op_sel_hi:[0,1]
	v_pk_mul_f32 v[100:101], v[128:129], v[100:101] op_sel_hi:[0,1]
	v_pk_mul_f32 v[102:103], v[128:129], v[102:103] op_sel_hi:[0,1]
	v_pk_mul_f32 v[104:105], v[128:129], v[104:105] op_sel_hi:[0,1]
	v_pk_mul_f32 v[106:107], v[128:129], v[106:107] op_sel_hi:[0,1]
	v_pk_mul_f32 v[108:109], v[128:129], v[108:109] op_sel_hi:[0,1]
	v_pk_mul_f32 v[110:111], v[128:129], v[110:111] op_sel_hi:[0,1]
	v_pk_mul_f32 v[96:97], v[96:97], v[192:193]
	v_pk_mul_f32 v[98:99], v[98:99], v[194:195]
	v_pk_mul_f32 v[100:101], v[100:101], v[196:197]
	v_pk_mul_f32 v[102:103], v[102:103], v[198:199]
	v_pk_mul_f32 v[104:105], v[104:105], v[200:201]
	v_pk_mul_f32 v[106:107], v[106:107], v[202:203]
	v_pk_mul_f32 v[108:109], v[108:109], v[204:205]
	v_pk_mul_f32 v[110:111], v[110:111], v[206:207]
	v_lshlrev_b32_e32 v20, 16, v36
	v_and_b32_e32 v21, 0xffff0000, v36
	v_lshlrev_b32_e32 v22, 16, v37
	v_and_b32_e32 v23, 0xffff0000, v37
	v_lshlrev_b32_e32 v24, 16, v38
	v_and_b32_e32 v25, 0xffff0000, v38
	v_lshlrev_b32_e32 v26, 16, v39
	v_and_b32_e32 v27, 0xffff0000, v39
	v_pk_fma_f32 v[96:97], v[52:53], v[20:21], v[96:97] op_sel_hi:[0,1,1]
	v_pk_fma_f32 v[98:99], v[52:53], v[22:23], v[98:99] op_sel_hi:[0,1,1]
	v_pk_fma_f32 v[100:101], v[52:53], v[24:25], v[100:101] op_sel_hi:[0,1,1]
	v_pk_fma_f32 v[102:103], v[52:53], v[26:27], v[102:103] op_sel_hi:[0,1,1]
	v_lshlrev_b32_e32 v20, 16, v40
	v_and_b32_e32 v21, 0xffff0000, v40
	v_lshlrev_b32_e32 v22, 16, v41
	v_and_b32_e32 v23, 0xffff0000, v41
	v_lshlrev_b32_e32 v24, 16, v42
	v_and_b32_e32 v25, 0xffff0000, v42
	v_lshlrev_b32_e32 v26, 16, v43
	v_and_b32_e32 v27, 0xffff0000, v43
	v_pk_fma_f32 v[104:105], v[52:53], v[20:21], v[104:105] op_sel_hi:[0,1,1]
	v_pk_fma_f32 v[106:107], v[52:53], v[22:23], v[106:107] op_sel_hi:[0,1,1]
	v_pk_fma_f32 v[108:109], v[52:53], v[24:25], v[108:109] op_sel_hi:[0,1,1]
	v_pk_fma_f32 v[110:111], v[52:53], v[26:27], v[110:111] op_sel_hi:[0,1,1]
	v_pk_mul_f32 v[132:133], v[96:97], v[96:97]
	v_pk_fma_f32 v[132:133], v[98:99], v[98:99], v[132:133]
	v_pk_fma_f32 v[132:133], v[100:101], v[100:101], v[132:133]
	v_pk_fma_f32 v[132:133], v[102:103], v[102:103], v[132:133]
	v_pk_fma_f32 v[132:133], v[104:105], v[104:105], v[132:133]
;     __device__ __forceinline__ float* out() const { return (float*)karg_in(33); }
; __device__ __forceinline__ void st4_bf16(bf16* p, v4f o) { v2u w; w.x = cvt_pk_nv(o.x, o.y); w.y = cvt_pk_nv(o.z, o.w); *(v2u*)p = w; }
; __device__ __forceinline__ float ssq4(v4f v) { return (v.x * v.x + v.y * v.y) + (v.z * v.z + v.w * v.w); }
; template <int R, bool BASE_F32, bool OUT_F32>
; __device__ __forceinline__ void rows_res(const Ctx& C, int m0, int stride, int mx, const float* gpost, float scale, int lane) {
;     ...
;         for (int r = 0; r < R; ++r) d[r][j] = b[r][j] + d[r][j] * r1[r] * gp; }
;     if (OUT_F32) { float* Y = C.out();
; #pragma unroll
;         for (int r = 0; r < R; ++r)
; #pragma unroll
;             for (int j = 0; j < 4; ++j) if (ok[r]) *(v4f*)(Y + (size_t)mr[r] * DM + 4 * lane + 256 * j) = d[r][j];
;     } else { float* rs = C.RS(); float t[R];
; #pragma unroll
;         for (int r = 0; r < R; ++r) { float s = 0.f;
; #pragma unroll
;             for (int j = 0; j < 4; ++j) s += ssq4(d[r][j]);
;             t[r] = s; }
; #pragma unroll
;         for (int r = 0; r < R; ++r) t[r] = wave_sum(t[r]) * (1.f / DM) + EPS;
; #pragma unroll
;         for (int r = 0; r < R; ++r) { const float rstd = rsqrtf(t[r]);
; #pragma unroll
;             for (int j = 0; j < 4; ++j) if (ok[r]) st4_bf16(XN + (size_t)mr[r] * DM + 4 * lane + 256 * j, d[r][j] * rstd);
	v_pk_fma_f32 v[132:133], v[106:107], v[106:107], v[132:133]
	v_pk_fma_f32 v[132:133], v[108:109], v[108:109], v[132:133]
	v_pk_fma_f32 v[132:133], v[110:111], v[110:111], v[132:133]
	s_nop 0
	v_add_f32_e32 v132, v132, v133
	v_pk_mul_f32 v[112:113], v[130:131], v[112:113] op_sel_hi:[0,1]
	v_pk_mul_f32 v[114:115], v[130:131], v[114:115] op_sel_hi:[0,1]
	v_pk_mul_f32 v[116:117], v[130:131], v[116:117] op_sel_hi:[0,1]
	v_pk_mul_f32 v[118:119], v[130:131], v[118:119] op_sel_hi:[0,1]
	v_pk_mul_f32 v[120:121], v[130:131], v[120:121] op_sel_hi:[0,1]
	v_pk_mul_f32 v[122:123], v[130:131], v[122:123] op_sel_hi:[0,1]
	v_pk_mul_f32 v[124:125], v[130:131], v[124:125] op_sel_hi:[0,1]
	v_pk_mul_f32 v[126:127], v[130:131], v[126:127] op_sel_hi:[0,1]
	v_pk_mul_f32 v[112:113], v[112:113], v[192:193]
	v_pk_mul_f32 v[114:115], v[114:115], v[194:195]
	v_pk_mul_f32 v[116:117], v[116:117], v[196:197]
	v_pk_mul_f32 v[118:119], v[118:119], v[198:199]
	v_pk_mul_f32 v[120:121], v[120:121], v[200:201]
	v_pk_mul_f32 v[122:123], v[122:123], v[202:203]
	v_pk_mul_f32 v[124:125], v[124:125], v[204:205]
	v_pk_mul_f32 v[126:127], v[126:127], v[206:207]
	v_lshlrev_b32_e32 v28, 16, v44
	v_and_b32_e32 v29, 0xffff0000, v44
	v_lshlrev_b32_e32 v30, 16, v45
	v_and_b32_e32 v31, 0xffff0000, v45
	v_lshlrev_b32_e32 v32, 16, v46
	v_and_b32_e32 v33, 0xffff0000, v46
	v_lshlrev_b32_e32 v34, 16, v47
	v_and_b32_e32 v35, 0xffff0000, v47
	v_pk_fma_f32 v[112:113], v[54:55], v[28:29], v[112:113] op_sel_hi:[0,1,1]
	v_pk_fma_f32 v[114:115], v[54:55], v[30:31], v[114:115] op_sel_hi:[0,1,1]
	v_pk_fma_f32 v[116:117], v[54:55], v[32:33], v[116:117] op_sel_hi:[0,1,1]
	v_pk_fma_f32 v[118:119], v[54:55], v[34:35], v[118:119] op_sel_hi:[0,1,1]
	v_lshlrev_b32_e32 v28, 16, v48
	v_and_b32_e32 v29, 0xffff0000, v48
	v_lshlrev_b32_e32 v30, 16, v49
	v_and_b32_e32 v31, 0xffff0000, v49
	v_lshlrev_b32_e32 v32, 16, v50
	v_and_b32_e32 v33, 0xffff0000, v50
	v_lshlrev_b32_e32 v34, 16, v51
	v_and_b32_e32 v35, 0xffff0000, v51
	v_pk_fma_f32 v[120:121], v[54:55], v[28:29], v[120:121] op_sel_hi:[0,1,1]
	v_pk_fma_f32 v[122:123], v[54:55], v[30:31], v[122:123] op_sel_hi:[0,1,1]
	v_pk_fma_f32 v[124:125], v[54:55], v[32:33], v[124:125] op_sel_hi:[0,1,1]
	v_pk_fma_f32 v[126:127], v[54:55], v[34:35], v[126:127] op_sel_hi:[0,1,1]
	v_pk_mul_f32 v[134:135], v[112:113], v[112:113]
	v_pk_fma_f32 v[134:135], v[114:115], v[114:115], v[134:135]
	v_pk_fma_f32 v[134:135], v[116:117], v[116:117], v[134:135]
	v_pk_fma_f32 v[134:135], v[118:119], v[118:119], v[134:135]
	v_pk_fma_f32 v[134:135], v[120:121], v[120:121], v[134:135]
	v_pk_fma_f32 v[134:135], v[122:123], v[122:123], v[134:135]
	v_pk_fma_f32 v[134:135], v[124:125], v[124:125], v[134:135]
	v_pk_fma_f32 v[134:135], v[126:127], v[126:127], v[134:135]
	s_nop 0
	v_add_f32_e32 v134, v134, v135
	s_nop 1
	v_add_f32_dpp v132, v132, v132 quad_perm:[1,0,3,2] row_mask:0xf bank_mask:0xf
	v_add_f32_dpp v134, v134, v134 quad_perm:[1,0,3,2] row_mask:0xf bank_mask:0xf
	s_nop 0
	v_add_f32_dpp v132, v132, v132 quad_perm:[2,3,0,1] row_mask:0xf bank_mask:0xf
	v_add_f32_dpp v134, v134, v134 quad_perm:[2,3,0,1] row_mask:0xf bank_mask:0xf
	s_nop 0
	v_add_f32_dpp v132, v132, v132 row_half_mirror row_mask:0xf bank_mask:0xf
	v_add_f32_dpp v134, v134, v134 row_half_mirror row_mask:0xf bank_mask:0xf
	s_nop 0
	v_add_f32_dpp v132, v132, v132 row_mirror row_mask:0xf bank_mask:0xf
	v_add_f32_dpp v134, v134, v134 row_mirror row_mask:0xf bank_mask:0xf
	s_nop 0
	ds_bpermute_b32 v136, v187, v132
	ds_bpermute_b32 v137, v187, v134
	s_waitcnt lgkmcnt(0)
	v_add_f32_e32 v132, v132, v136
	v_add_f32_e32 v134, v134, v137
	ds_bpermute_b32 v136, v188, v132
	ds_bpermute_b32 v137, v188, v134
	s_waitcnt lgkmcnt(0)
	v_add_f32_e32 v132, v132, v136
	v_add_f32_e32 v134, v134, v137
	v_fmamk_f32 v164, v132, 0x3a800000, v138
	v_fmamk_f32 v167, v134, 0x3a800000, v138
	s_nop 0
	v_rsq_f32_e32 v132, v164
	v_rsq_f32_e32 v134, v167
	v_sqrt_f32_e32 v165, v164
	v_sqrt_f32_e32 v168, v167
	s_nop 1
	v_pk_mul_f32 v[140:141], v[96:97], v[132:133] op_sel_hi:[1,0]
	v_cvt_pk_bf16_f32 v148, v140, v141
	v_pk_mul_f32 v[142:143], v[98:99], v[132:133] op_sel_hi:[1,0]
	v_cvt_pk_bf16_f32 v149, v142, v143
	v_pk_mul_f32 v[144:145], v[100:101], v[132:133] op_sel_hi:[1,0]
	v_cvt_pk_bf16_f32 v150, v144, v145
	v_pk_mul_f32 v[146:147], v[102:103], v[132:133] op_sel_hi:[1,0]
	v_cvt_pk_bf16_f32 v151, v146, v147
	v_pk_mul_f32 v[140:141], v[104:105], v[132:133] op_sel_hi:[1,0]
	v_cvt_pk_bf16_f32 v152, v140, v141
	v_pk_mul_f32 v[142:143], v[106:107], v[132:133] op_sel_hi:[1,0]
	v_cvt_pk_bf16_f32 v153, v142, v143
	v_pk_mul_f32 v[144:145], v[108:109], v[132:133] op_sel_hi:[1,0]
	v_cvt_pk_bf16_f32 v154, v144, v145
	v_pk_mul_f32 v[146:147], v[110:111], v[132:133] op_sel_hi:[1,0]
	v_cvt_pk_bf16_f32 v155, v146, v147
	global_store_dwordx2 v173, v[148:149], s[98:99]
	global_store_dwordx2 v173, v[150:151], s[98:99] offset:512
	global_store_dwordx2 v173, v[152:153], s[98:99] offset:1024
	global_store_dwordx2 v173, v[154:155], s[98:99] offset:1536
	v_add_u32_e32 v173, 0x400000, v173
	v_pk_mul_f32 v[140:141], v[112:113], v[134:135] op_sel_hi:[1,0]
	v_cvt_pk_bf16_f32 v156, v140, v141
	v_pk_mul_f32 v[142:143], v[114:115], v[134:135] op_sel_hi:[1,0]
	v_cvt_pk_bf16_f32 v157, v142, v143
	v_pk_mul_f32 v[144:145], v[116:117], v[134:135] op_sel_hi:[1,0]
	v_cvt_pk_bf16_f32 v158, v144, v145
	v_pk_mul_f32 v[146:147], v[118:119], v[134:135] op_sel_hi:[1,0]
	v_cvt_pk_bf16_f32 v159, v146, v147
	v_pk_mul_f32 v[140:141], v[120:121], v[134:135] op_sel_hi:[1,0]
	v_cvt_pk_bf16_f32 v160, v140, v141
	v_pk_mul_f32 v[142:143], v[122:123], v[134:135] op_sel_hi:[1,0]
	v_cvt_pk_bf16_f32 v161, v142, v143
; __device__ __forceinline__ const float* xrow_ptr(const Ctx& C, int row) { return row < MPROMPT ? C.in(0) + (size_t)row * DM : C.in(1) + (size_t)(row - MPROMPT) * DM; }
; __device__ __forceinline__ v4f ld4_bf16(const bf16* p) { const v2u w = *(const v2u*)p; return (v4f){bf_lo(w.x), bf_hi(w.x), bf_lo(w.y), bf_hi(w.y)}; }
; __device__ __forceinline__ void st4_bf16(bf16* p, v4f o) { v2u w; w.x = cvt_pk_nv(o.x, o.y); w.y = cvt_pk_nv(o.z, o.w); *(v2u*)p = w; }
; __device__ __forceinline__ float ssq4(v4f v) { return (v.x * v.x + v.y * v.y) + (v.z * v.z + v.w * v.w); }
; template <int R, bool BASE_F32, bool OUT_F32>
; __device__ __forceinline__ void rows_res(const Ctx& C, int m0, int stride, int mx, const float* gpost, float scale, int lane) {
;     ...
;     for (int r = 0; r < R; ++r) { mr[r] = (r == 4) ? mx : m0 + r * stride; ok[r] = (r == 4) ? (mx < M) : (mr[r] < MPROMPT); const int mm = ok[r] ? mr[r] : 0;
; #pragma unroll
;         for (int j = 0; j < 4; ++j) d[r][j] = ld4_bf16(D + (size_t)mm * DM + 4 * lane + 256 * j);
;         if (BASE_F32) { const float* x = xrow_ptr(C, mm);
; #pragma unroll
;             for (int j = 0; j < 4; ++j) b[r][j] = ld4_f32(x + 4 * lane + 256 * j);
;         } else { const float inv = C.RS()[mm];
; #pragma unroll
;             for (int j = 0; j < 4; ++j) b[r][j] = ld4_bf16(XN + (size_t)mm * DM + 4 * lane + 256 * j) * inv;
;         } }
; #pragma unroll
;     for (int r = 0; r < R; ++r) { float s = 0.f;
; #pragma unroll
;         for (int j = 0; j < 4; ++j) s += ssq4(d[r][j]);
;         r1[r] = s; }
; #pragma unroll
;     for (int r = 0; r < R; ++r) r1[r] = rsqrtf(wave_sum(r1[r]) * (1.f / DM) + EPS) * scale;
;     ...
;             for (int j = 0; j < 4; ++j) if (ok[r]) st4_bf16(XN + (size_t)mr[r] * DM + 4 * lane + 256 * j, d[r][j] * rstd);
;             if (lane == 0 && ok[r]) rs[mr[r]] = sqrtf(t[r]); }
	v_pk_mul_f32 v[144:145], v[124:125], v[134:135] op_sel_hi:[1,0]
	v_cvt_pk_bf16_f32 v162, v144, v145
	v_pk_mul_f32 v[146:147], v[126:127], v[134:135] op_sel_hi:[1,0]
	v_cvt_pk_bf16_f32 v163, v146, v147
	global_store_dwordx2 v173, v[156:157], s[98:99]
	global_store_dwordx2 v173, v[158:159], s[98:99] offset:512
	global_store_dwordx2 v173, v[160:161], s[98:99] offset:1024
	global_store_dwordx2 v173, v[162:163], s[98:99] offset:1536
	v_add_u32_e32 v173, 0x400000, v173
	v_add_u32_e32 v166, -1, v165
	v_fma_f32 v140, -v166, v165, v164
	v_cmp_ge_f32_e32 vcc, 0, v140
	v_add_u32_e32 v141, 1, v165
	v_cndmask_b32_e32 v166, v165, v166, vcc
	v_fma_f32 v140, -v141, v165, v164
	v_cmp_lt_f32_e32 vcc, 0, v140
	s_nop 1
	v_cndmask_b32_e32 v165, v166, v141, vcc
	v_add_u32_e32 v169, -1, v168
	v_fma_f32 v142, -v169, v168, v167
	v_cmp_ge_f32_e32 vcc, 0, v142
	v_add_u32_e32 v143, 1, v168
	v_cndmask_b32_e32 v169, v168, v169, vcc
	v_fma_f32 v142, -v143, v168, v167
	v_cmp_lt_f32_e32 vcc, 0, v142
	s_nop 1
	v_cndmask_b32_e32 v168, v169, v143, vcc
	s_mov_b64 exec, 1
	global_store_dword v174, v165, s[98:99]
	v_add_u32_e32 v174, 0x2000, v174
	global_store_dword v174, v168, s[98:99]
	v_add_u32_e32 v174, 0x2000, v174
	s_mov_b64 exec, -1
	global_load_dword v52, v172, s[98:99]
	global_load_dwordx2 v[20:21], v170, s[98:99] nt
	global_load_dwordx2 v[22:23], v170, s[98:99] offset:512 nt
	global_load_dwordx2 v[24:25], v170, s[98:99] offset:1024 nt
	global_load_dwordx2 v[26:27], v170, s[98:99] offset:1536 nt
	global_load_dwordx2 v[36:37], v171, s[98:99]
	global_load_dwordx2 v[38:39], v171, s[98:99] offset:512
	global_load_dwordx2 v[40:41], v171, s[98:99] offset:1024
	global_load_dwordx2 v[42:43], v171, s[98:99] offset:1536
	v_add_u32_e32 v170, 0x400000, v170
	v_add_u32_e32 v171, 0x400000, v171
	v_add_u32_e32 v172, 0x2000, v172
	global_load_dword v54, v172, s[98:99]
	global_load_dwordx2 v[28:29], v170, s[98:99] nt
	global_load_dwordx2 v[30:31], v170, s[98:99] offset:512 nt
	global_load_dwordx2 v[32:33], v170, s[98:99] offset:1024 nt
	global_load_dwordx2 v[34:35], v170, s[98:99] offset:1536 nt
	global_load_dwordx2 v[44:45], v171, s[98:99]
	global_load_dwordx2 v[46:47], v171, s[98:99] offset:512
	global_load_dwordx2 v[48:49], v171, s[98:99] offset:1024
	global_load_dwordx2 v[50:51], v171, s[98:99] offset:1536
	v_add_u32_e32 v170, 0x400000, v170
	v_add_u32_e32 v171, 0x400000, v171
	v_add_u32_e32 v172, 0x2000, v172
	s_waitcnt vmcnt(41)
	v_lshlrev_b32_e32 v96, 16, v56
	v_and_b32_e32 v97, 0xffff0000, v56
	v_lshlrev_b32_e32 v98, 16, v57
	v_and_b32_e32 v99, 0xffff0000, v57
	v_lshlrev_b32_e32 v100, 16, v58
	v_and_b32_e32 v101, 0xffff0000, v58
	v_lshlrev_b32_e32 v102, 16, v59
	v_and_b32_e32 v103, 0xffff0000, v59
	v_lshlrev_b32_e32 v104, 16, v60
	v_and_b32_e32 v105, 0xffff0000, v60
	v_lshlrev_b32_e32 v106, 16, v61
	v_and_b32_e32 v107, 0xffff0000, v61
	v_lshlrev_b32_e32 v108, 16, v62
	v_and_b32_e32 v109, 0xffff0000, v62
	v_lshlrev_b32_e32 v110, 16, v63
	v_and_b32_e32 v111, 0xffff0000, v63
	v_pk_mul_f32 v[128:129], v[96:97], v[96:97]
	v_pk_fma_f32 v[128:129], v[98:99], v[98:99], v[128:129]
	v_pk_fma_f32 v[128:129], v[100:101], v[100:101], v[128:129]
	v_pk_fma_f32 v[128:129], v[102:103], v[102:103], v[128:129]
	v_pk_fma_f32 v[128:129], v[104:105], v[104:105], v[128:129]
	v_pk_fma_f32 v[128:129], v[106:107], v[106:107], v[128:129]
	v_pk_fma_f32 v[128:129], v[108:109], v[108:109], v[128:129]
	v_pk_fma_f32 v[128:129], v[110:111], v[110:111], v[128:129]
	s_nop 0
	v_add_f32_e32 v128, v128, v129
	s_waitcnt vmcnt(32)
	v_lshlrev_b32_e32 v112, 16, v64
	v_and_b32_e32 v113, 0xffff0000, v64
	v_lshlrev_b32_e32 v114, 16, v65
	v_and_b32_e32 v115, 0xffff0000, v65
	v_lshlrev_b32_e32 v116, 16, v66
	v_and_b32_e32 v117, 0xffff0000, v66
	v_lshlrev_b32_e32 v118, 16, v67
	v_and_b32_e32 v119, 0xffff0000, v67
	v_lshlrev_b32_e32 v120, 16, v68
	v_and_b32_e32 v121, 0xffff0000, v68
	v_lshlrev_b32_e32 v122, 16, v69
	v_and_b32_e32 v123, 0xffff0000, v69
	v_lshlrev_b32_e32 v124, 16, v70
	v_and_b32_e32 v125, 0xffff0000, v70
	v_lshlrev_b32_e32 v126, 16, v71
	v_and_b32_e32 v127, 0xffff0000, v71
	v_pk_mul_f32 v[130:131], v[112:113], v[112:113]
	v_pk_fma_f32 v[130:131], v[114:115], v[114:115], v[130:131]
	v_pk_fma_f32 v[130:131], v[116:117], v[116:117], v[130:131]
	v_pk_fma_f32 v[130:131], v[118:119], v[118:119], v[130:131]
	v_pk_fma_f32 v[130:131], v[120:121], v[120:121], v[130:131]
	v_pk_fma_f32 v[130:131], v[122:123], v[122:123], v[130:131]
	v_pk_fma_f32 v[130:131], v[124:125], v[124:125], v[130:131]
	v_pk_fma_f32 v[130:131], v[126:127], v[126:127], v[130:131]
	s_nop 0
	v_add_f32_e32 v130, v130, v131
	s_nop 1
	v_add_f32_dpp v128, v128, v128 quad_perm:[1,0,3,2] row_mask:0xf bank_mask:0xf
	v_add_f32_dpp v130, v130, v130 quad_perm:[1,0,3,2] row_mask:0xf bank_mask:0xf
	s_nop 0
	v_add_f32_dpp v128, v128, v128 quad_perm:[2,3,0,1] row_mask:0xf bank_mask:0xf
	v_add_f32_dpp v130, v130, v130 quad_perm:[2,3,0,1] row_mask:0xf bank_mask:0xf
	s_nop 0
	v_add_f32_dpp v128, v128, v128 row_half_mirror row_mask:0xf bank_mask:0xf
	v_add_f32_dpp v130, v130, v130 row_half_mirror row_mask:0xf bank_mask:0xf
	s_nop 0
	v_add_f32_dpp v128, v128, v128 row_mirror row_mask:0xf bank_mask:0xf
	v_add_f32_dpp v130, v130, v130 row_mirror row_mask:0xf bank_mask:0xf
	s_nop 0
	ds_bpermute_b32 v136, v187, v128
	ds_bpermute_b32 v137, v187, v130
	s_waitcnt lgkmcnt(0)
	v_add_f32_e32 v128, v128, v136
	v_add_f32_e32 v130, v130, v137
	ds_bpermute_b32 v136, v188, v128
	ds_bpermute_b32 v137, v188, v130
	s_waitcnt lgkmcnt(0)
	v_add_f32_e32 v128, v128, v136
	v_add_f32_e32 v130, v130, v137
	v_fmamk_f32 v128, v128, 0x3a800000, v138
	v_fmamk_f32 v130, v130, 0x3a800000, v138
	s_nop 0
	v_rsq_f32_e32 v128, v128
	v_rsq_f32_e32 v130, v130
	s_nop 1
	s_waitcnt vmcnt(28)
;     __device__ __forceinline__ float* out() const { return (float*)karg_in(33); }
; __device__ __forceinline__ float ssq4(v4f v) { return (v.x * v.x + v.y * v.y) + (v.z * v.z + v.w * v.w); }
; template <int R, bool BASE_F32, bool OUT_F32>
; __device__ __forceinline__ void rows_res(const Ctx& C, int m0, int stride, int mx, const float* gpost, float scale, int lane) {
;     ...
;     for (int r = 0; r < R; ++r) r1[r] = rsqrtf(wave_sum(r1[r]) * (1.f / DM) + EPS) * scale;
; #pragma unroll
;     for (int j = 0; j < 4; ++j) { const v4f gp = ld4_f32(gpost + 4 * lane + 256 * j);
; #pragma unroll
;         for (int r = 0; r < R; ++r) d[r][j] = b[r][j] + d[r][j] * r1[r] * gp; }
;     if (OUT_F32) { float* Y = C.out();
; #pragma unroll
;         for (int r = 0; r < R; ++r)
; #pragma unroll
;             for (int j = 0; j < 4; ++j) if (ok[r]) *(v4f*)(Y + (size_t)mr[r] * DM + 4 * lane + 256 * j) = d[r][j];
;     } else { float* rs = C.RS(); float t[R];
; #pragma unroll
;         for (int r = 0; r < R; ++r) { float s = 0.f;
; #pragma unroll
;             for (int j = 0; j < 4; ++j) s += ssq4(d[r][j]);
;             t[r] = s; }
; #pragma unroll
;         for (int r = 0; r < R; ++r) t[r] = wave_sum(t[r]) * (1.f / DM) + EPS;
	v_pk_mul_f32 v[96:97], v[128:129], v[96:97] op_sel_hi:[0,1]
	v_pk_mul_f32 v[98:99], v[128:129], v[98:99] op_sel_hi:[0,1]
	v_pk_mul_f32 v[100:101], v[128:129], v[100:101] op_sel_hi:[0,1]
	v_pk_mul_f32 v[102:103], v[128:129], v[102:103] op_sel_hi:[0,1]
	v_pk_mul_f32 v[104:105], v[128:129], v[104:105] op_sel_hi:[0,1]
	v_pk_mul_f32 v[106:107], v[128:129], v[106:107] op_sel_hi:[0,1]
	v_pk_mul_f32 v[108:109], v[128:129], v[108:109] op_sel_hi:[0,1]
	v_pk_mul_f32 v[110:111], v[128:129], v[110:111] op_sel_hi:[0,1]
	v_pk_mul_f32 v[96:97], v[96:97], v[192:193]
	v_pk_mul_f32 v[98:99], v[98:99], v[194:195]
	v_pk_mul_f32 v[100:101], v[100:101], v[196:197]
	v_pk_mul_f32 v[102:103], v[102:103], v[198:199]
	v_pk_mul_f32 v[104:105], v[104:105], v[200:201]
	v_pk_mul_f32 v[106:107], v[106:107], v[202:203]
	v_pk_mul_f32 v[108:109], v[108:109], v[204:205]
	v_pk_mul_f32 v[110:111], v[110:111], v[206:207]
	v_lshlrev_b32_e32 v56, 16, v72
	v_and_b32_e32 v57, 0xffff0000, v72
	v_lshlrev_b32_e32 v58, 16, v73
	v_and_b32_e32 v59, 0xffff0000, v73
	v_lshlrev_b32_e32 v60, 16, v74
	v_and_b32_e32 v61, 0xffff0000, v74
	v_lshlrev_b32_e32 v62, 16, v75
	v_and_b32_e32 v63, 0xffff0000, v75
	v_pk_fma_f32 v[96:97], v[88:89], v[56:57], v[96:97] op_sel_hi:[0,1,1]
	v_pk_fma_f32 v[98:99], v[88:89], v[58:59], v[98:99] op_sel_hi:[0,1,1]
	v_pk_fma_f32 v[100:101], v[88:89], v[60:61], v[100:101] op_sel_hi:[0,1,1]
	v_pk_fma_f32 v[102:103], v[88:89], v[62:63], v[102:103] op_sel_hi:[0,1,1]
	v_lshlrev_b32_e32 v56, 16, v76
	v_and_b32_e32 v57, 0xffff0000, v76
	v_lshlrev_b32_e32 v58, 16, v77
	v_and_b32_e32 v59, 0xffff0000, v77
	v_lshlrev_b32_e32 v60, 16, v78
	v_and_b32_e32 v61, 0xffff0000, v78
	v_lshlrev_b32_e32 v62, 16, v79
	v_and_b32_e32 v63, 0xffff0000, v79
	v_pk_fma_f32 v[104:105], v[88:89], v[56:57], v[104:105] op_sel_hi:[0,1,1]
	v_pk_fma_f32 v[106:107], v[88:89], v[58:59], v[106:107] op_sel_hi:[0,1,1]
	v_pk_fma_f32 v[108:109], v[88:89], v[60:61], v[108:109] op_sel_hi:[0,1,1]
	v_pk_fma_f32 v[110:111], v[88:89], v[62:63], v[110:111] op_sel_hi:[0,1,1]
	v_pk_mul_f32 v[132:133], v[96:97], v[96:97]
	v_pk_fma_f32 v[132:133], v[98:99], v[98:99], v[132:133]
	v_pk_fma_f32 v[132:133], v[100:101], v[100:101], v[132:133]
	v_pk_fma_f32 v[132:133], v[102:103], v[102:103], v[132:133]
	v_pk_fma_f32 v[132:133], v[104:105], v[104:105], v[132:133]
	v_pk_fma_f32 v[132:133], v[106:107], v[106:107], v[132:133]
	v_pk_fma_f32 v[132:133], v[108:109], v[108:109], v[132:133]
	v_pk_fma_f32 v[132:133], v[110:111], v[110:111], v[132:133]
	s_nop 0
	v_add_f32_e32 v132, v132, v133
	v_pk_mul_f32 v[112:113], v[130:131], v[112:113] op_sel_hi:[0,1]
	v_pk_mul_f32 v[114:115], v[130:131], v[114:115] op_sel_hi:[0,1]
	v_pk_mul_f32 v[116:117], v[130:131], v[116:117] op_sel_hi:[0,1]
	v_pk_mul_f32 v[118:119], v[130:131], v[118:119] op_sel_hi:[0,1]
	v_pk_mul_f32 v[120:121], v[130:131], v[120:121] op_sel_hi:[0,1]
	v_pk_mul_f32 v[122:123], v[130:131], v[122:123] op_sel_hi:[0,1]
	v_pk_mul_f32 v[124:125], v[130:131], v[124:125] op_sel_hi:[0,1]
	v_pk_mul_f32 v[126:127], v[130:131], v[126:127] op_sel_hi:[0,1]
	v_pk_mul_f32 v[112:113], v[112:113], v[192:193]
	v_pk_mul_f32 v[114:115], v[114:115], v[194:195]
	v_pk_mul_f32 v[116:117], v[116:117], v[196:197]
	v_pk_mul_f32 v[118:119], v[118:119], v[198:199]
	v_pk_mul_f32 v[120:121], v[120:121], v[200:201]
	v_pk_mul_f32 v[122:123], v[122:123], v[202:203]
	v_pk_mul_f32 v[124:125], v[124:125], v[204:205]
	v_pk_mul_f32 v[126:127], v[126:127], v[206:207]
	v_lshlrev_b32_e32 v64, 16, v80
	v_and_b32_e32 v65, 0xffff0000, v80
	v_lshlrev_b32_e32 v66, 16, v81
	v_and_b32_e32 v67, 0xffff0000, v81
	v_lshlrev_b32_e32 v68, 16, v82
	v_and_b32_e32 v69, 0xffff0000, v82
	v_lshlrev_b32_e32 v70, 16, v83
	v_and_b32_e32 v71, 0xffff0000, v83
	v_pk_fma_f32 v[112:113], v[90:91], v[64:65], v[112:113] op_sel_hi:[0,1,1]
	v_pk_fma_f32 v[114:115], v[90:91], v[66:67], v[114:115] op_sel_hi:[0,1,1]
	v_pk_fma_f32 v[116:117], v[90:91], v[68:69], v[116:117] op_sel_hi:[0,1,1]
	v_pk_fma_f32 v[118:119], v[90:91], v[70:71], v[118:119] op_sel_hi:[0,1,1]
	v_lshlrev_b32_e32 v64, 16, v84
	v_and_b32_e32 v65, 0xffff0000, v84
	v_lshlrev_b32_e32 v66, 16, v85
	v_and_b32_e32 v67, 0xffff0000, v85
	v_lshlrev_b32_e32 v68, 16, v86
	v_and_b32_e32 v69, 0xffff0000, v86
	v_lshlrev_b32_e32 v70, 16, v87
	v_and_b32_e32 v71, 0xffff0000, v87
	v_pk_fma_f32 v[120:121], v[90:91], v[64:65], v[120:121] op_sel_hi:[0,1,1]
	v_pk_fma_f32 v[122:123], v[90:91], v[66:67], v[122:123] op_sel_hi:[0,1,1]
	v_pk_fma_f32 v[124:125], v[90:91], v[68:69], v[124:125] op_sel_hi:[0,1,1]
	v_pk_fma_f32 v[126:127], v[90:91], v[70:71], v[126:127] op_sel_hi:[0,1,1]
	v_pk_mul_f32 v[134:135], v[112:113], v[112:113]
	v_pk_fma_f32 v[134:135], v[114:115], v[114:115], v[134:135]
	v_pk_fma_f32 v[134:135], v[116:117], v[116:117], v[134:135]
	v_pk_fma_f32 v[134:135], v[118:119], v[118:119], v[134:135]
	v_pk_fma_f32 v[134:135], v[120:121], v[120:121], v[134:135]
	v_pk_fma_f32 v[134:135], v[122:123], v[122:123], v[134:135]
	v_pk_fma_f32 v[134:135], v[124:125], v[124:125], v[134:135]
	v_pk_fma_f32 v[134:135], v[126:127], v[126:127], v[134:135]
	s_nop 0
	v_add_f32_e32 v134, v134, v135
	s_nop 1
	v_add_f32_dpp v132, v132, v132 quad_perm:[1,0,3,2] row_mask:0xf bank_mask:0xf
	v_add_f32_dpp v134, v134, v134 quad_perm:[1,0,3,2] row_mask:0xf bank_mask:0xf
	s_nop 0
	v_add_f32_dpp v132, v132, v132 quad_perm:[2,3,0,1] row_mask:0xf bank_mask:0xf
	v_add_f32_dpp v134, v134, v134 quad_perm:[2,3,0,1] row_mask:0xf bank_mask:0xf
	s_nop 0
	v_add_f32_dpp v132, v132, v132 row_half_mirror row_mask:0xf bank_mask:0xf
	v_add_f32_dpp v134, v134, v134 row_half_mirror row_mask:0xf bank_mask:0xf
	s_nop 0
	v_add_f32_dpp v132, v132, v132 row_mirror row_mask:0xf bank_mask:0xf
	v_add_f32_dpp v134, v134, v134 row_mirror row_mask:0xf bank_mask:0xf
	s_nop 0
	ds_bpermute_b32 v136, v187, v132
	ds_bpermute_b32 v137, v187, v134
	s_waitcnt lgkmcnt(0)
; __device__ __forceinline__ const float* xrow_ptr(const Ctx& C, int row) { return row < MPROMPT ? C.in(0) + (size_t)row * DM : C.in(1) + (size_t)(row - MPROMPT) * DM; }
; __device__ __forceinline__ v4f ld4_bf16(const bf16* p) { const v2u w = *(const v2u*)p; return (v4f){bf_lo(w.x), bf_hi(w.x), bf_lo(w.y), bf_hi(w.y)}; }
; __device__ __forceinline__ void st4_bf16(bf16* p, v4f o) { v2u w; w.x = cvt_pk_nv(o.x, o.y); w.y = cvt_pk_nv(o.z, o.w); *(v2u*)p = w; }
; __device__ __forceinline__ float ssq4(v4f v) { return (v.x * v.x + v.y * v.y) + (v.z * v.z + v.w * v.w); }
; template <int R, bool BASE_F32, bool OUT_F32>
; __device__ __forceinline__ void rows_res(const Ctx& C, int m0, int stride, int mx, const float* gpost, float scale, int lane) {
;     ...
;     for (int r = 0; r < R; ++r) { mr[r] = (r == 4) ? mx : m0 + r * stride; ok[r] = (r == 4) ? (mx < M) : (mr[r] < MPROMPT); const int mm = ok[r] ? mr[r] : 0;
; #pragma unroll
;         for (int j = 0; j < 4; ++j) d[r][j] = ld4_bf16(D + (size_t)mm * DM + 4 * lane + 256 * j);
;         if (BASE_F32) { const float* x = xrow_ptr(C, mm);
; #pragma unroll
;             for (int j = 0; j < 4; ++j) b[r][j] = ld4_f32(x + 4 * lane + 256 * j);
;         } else { const float inv = C.RS()[mm];
; #pragma unroll
;             for (int j = 0; j < 4; ++j) b[r][j] = ld4_bf16(XN + (size_t)mm * DM + 4 * lane + 256 * j) * inv;
;         } }
; #pragma unroll
;     for (int r = 0; r < R; ++r) { float s = 0.f;
; #pragma unroll
;         for (int j = 0; j < 4; ++j) s += ssq4(d[r][j]);
;         r1[r] = s; }
;     ...
;             for (int j = 0; j < 4; ++j) s += ssq4(d[r][j]);
;             t[r] = s; }
; #pragma unroll
;         for (int r = 0; r < R; ++r) t[r] = wave_sum(t[r]) * (1.f / DM) + EPS;
; #pragma unroll
;         for (int r = 0; r < R; ++r) { const float rstd = rsqrtf(t[r]);
; #pragma unroll
;             for (int j = 0; j < 4; ++j) if (ok[r]) st4_bf16(XN + (size_t)mr[r] * DM + 4 * lane + 256 * j, d[r][j] * rstd);
;             if (lane == 0 && ok[r]) rs[mr[r]] = sqrtf(t[r]); }
	v_add_f32_e32 v132, v132, v136
	v_add_f32_e32 v134, v134, v137
	ds_bpermute_b32 v136, v188, v132
	ds_bpermute_b32 v137, v188, v134
	s_waitcnt lgkmcnt(0)
	v_add_f32_e32 v132, v132, v136
	v_add_f32_e32 v134, v134, v137
	v_fmamk_f32 v164, v132, 0x3a800000, v138
	v_fmamk_f32 v167, v134, 0x3a800000, v138
	s_nop 0
	v_rsq_f32_e32 v132, v164
	v_rsq_f32_e32 v134, v167
	v_sqrt_f32_e32 v165, v164
	v_sqrt_f32_e32 v168, v167
	s_nop 1
	v_pk_mul_f32 v[140:141], v[96:97], v[132:133] op_sel_hi:[1,0]
	v_cvt_pk_bf16_f32 v148, v140, v141
	v_pk_mul_f32 v[142:143], v[98:99], v[132:133] op_sel_hi:[1,0]
	v_cvt_pk_bf16_f32 v149, v142, v143
	v_pk_mul_f32 v[144:145], v[100:101], v[132:133] op_sel_hi:[1,0]
	v_cvt_pk_bf16_f32 v150, v144, v145
	v_pk_mul_f32 v[146:147], v[102:103], v[132:133] op_sel_hi:[1,0]
	v_cvt_pk_bf16_f32 v151, v146, v147
	v_pk_mul_f32 v[140:141], v[104:105], v[132:133] op_sel_hi:[1,0]
	v_cvt_pk_bf16_f32 v152, v140, v141
	v_pk_mul_f32 v[142:143], v[106:107], v[132:133] op_sel_hi:[1,0]
	v_cvt_pk_bf16_f32 v153, v142, v143
	v_pk_mul_f32 v[144:145], v[108:109], v[132:133] op_sel_hi:[1,0]
	v_cvt_pk_bf16_f32 v154, v144, v145
	v_pk_mul_f32 v[146:147], v[110:111], v[132:133] op_sel_hi:[1,0]
	v_cvt_pk_bf16_f32 v155, v146, v147
	global_store_dwordx2 v173, v[148:149], s[98:99]
	global_store_dwordx2 v173, v[150:151], s[98:99] offset:512
	global_store_dwordx2 v173, v[152:153], s[98:99] offset:1024
	global_store_dwordx2 v173, v[154:155], s[98:99] offset:1536
	v_add_u32_e32 v173, 0x400000, v173
	v_pk_mul_f32 v[140:141], v[112:113], v[134:135] op_sel_hi:[1,0]
	v_cvt_pk_bf16_f32 v156, v140, v141
	v_pk_mul_f32 v[142:143], v[114:115], v[134:135] op_sel_hi:[1,0]
	v_cvt_pk_bf16_f32 v157, v142, v143
	v_pk_mul_f32 v[144:145], v[116:117], v[134:135] op_sel_hi:[1,0]
	v_cvt_pk_bf16_f32 v158, v144, v145
	v_pk_mul_f32 v[146:147], v[118:119], v[134:135] op_sel_hi:[1,0]
	v_cvt_pk_bf16_f32 v159, v146, v147
	v_pk_mul_f32 v[140:141], v[120:121], v[134:135] op_sel_hi:[1,0]
	v_cvt_pk_bf16_f32 v160, v140, v141
	v_pk_mul_f32 v[142:143], v[122:123], v[134:135] op_sel_hi:[1,0]
	v_cvt_pk_bf16_f32 v161, v142, v143
	v_pk_mul_f32 v[144:145], v[124:125], v[134:135] op_sel_hi:[1,0]
	v_cvt_pk_bf16_f32 v162, v144, v145
	v_pk_mul_f32 v[146:147], v[126:127], v[134:135] op_sel_hi:[1,0]
	v_cvt_pk_bf16_f32 v163, v146, v147
	global_store_dwordx2 v173, v[156:157], s[98:99]
	global_store_dwordx2 v173, v[158:159], s[98:99] offset:512
	global_store_dwordx2 v173, v[160:161], s[98:99] offset:1024
	global_store_dwordx2 v173, v[162:163], s[98:99] offset:1536
	v_add_u32_e32 v173, 0x400000, v173
	v_add_u32_e32 v166, -1, v165
	v_fma_f32 v140, -v166, v165, v164
	v_cmp_ge_f32_e32 vcc, 0, v140
	v_add_u32_e32 v141, 1, v165
	v_cndmask_b32_e32 v166, v165, v166, vcc
	v_fma_f32 v140, -v141, v165, v164
	v_cmp_lt_f32_e32 vcc, 0, v140
	s_nop 1
	v_cndmask_b32_e32 v165, v166, v141, vcc
	v_add_u32_e32 v169, -1, v168
	v_fma_f32 v142, -v169, v168, v167
	v_cmp_ge_f32_e32 vcc, 0, v142
	v_add_u32_e32 v143, 1, v168
	v_cndmask_b32_e32 v169, v168, v169, vcc
	v_fma_f32 v142, -v143, v168, v167
	v_cmp_lt_f32_e32 vcc, 0, v142
	s_nop 1
	v_cndmask_b32_e32 v168, v169, v143, vcc
	s_mov_b64 exec, 1
	global_store_dword v174, v165, s[98:99]
	v_add_u32_e32 v174, 0x2000, v174
	global_store_dword v174, v168, s[98:99]
	v_add_u32_e32 v174, 0x2000, v174
	s_mov_b64 exec, -1
	global_load_dword v88, v172, s[98:99]
	global_load_dwordx2 v[56:57], v170, s[98:99] nt
	global_load_dwordx2 v[58:59], v170, s[98:99] offset:512 nt
	global_load_dwordx2 v[60:61], v170, s[98:99] offset:1024 nt
	global_load_dwordx2 v[62:63], v170, s[98:99] offset:1536 nt
	global_load_dwordx2 v[72:73], v171, s[98:99]
	global_load_dwordx2 v[74:75], v171, s[98:99] offset:512
	global_load_dwordx2 v[76:77], v171, s[98:99] offset:1024
	global_load_dwordx2 v[78:79], v171, s[98:99] offset:1536
	v_add_u32_e32 v170, 0x400000, v170
	v_add_u32_e32 v171, 0x400000, v171
	v_add_u32_e32 v172, 0x2000, v172
	global_load_dword v90, v172, s[98:99]
	global_load_dwordx2 v[64:65], v170, s[98:99] nt
	global_load_dwordx2 v[66:67], v170, s[98:99] offset:512 nt
	global_load_dwordx2 v[68:69], v170, s[98:99] offset:1024 nt
	global_load_dwordx2 v[70:71], v170, s[98:99] offset:1536 nt
	global_load_dwordx2 v[80:81], v171, s[98:99]
	global_load_dwordx2 v[82:83], v171, s[98:99] offset:512
	global_load_dwordx2 v[84:85], v171, s[98:99] offset:1024
	global_load_dwordx2 v[86:87], v171, s[98:99] offset:1536
	v_add_u32_e32 v170, 0x400000, v170
	v_add_u32_e32 v171, 0x400000, v171
	v_add_u32_e32 v172, 0x2000, v172
	s_waitcnt vmcnt(41)
	v_lshlrev_b32_e32 v96, 16, v20
	v_and_b32_e32 v97, 0xffff0000, v20
	v_lshlrev_b32_e32 v98, 16, v21
	v_and_b32_e32 v99, 0xffff0000, v21
	v_lshlrev_b32_e32 v100, 16, v22
	v_and_b32_e32 v101, 0xffff0000, v22
	v_lshlrev_b32_e32 v102, 16, v23
	v_and_b32_e32 v103, 0xffff0000, v23
	v_lshlrev_b32_e32 v104, 16, v24
	v_and_b32_e32 v105, 0xffff0000, v24
	v_lshlrev_b32_e32 v106, 16, v25
	v_and_b32_e32 v107, 0xffff0000, v25
	v_lshlrev_b32_e32 v108, 16, v26
	v_and_b32_e32 v109, 0xffff0000, v26
	v_lshlrev_b32_e32 v110, 16, v27
	v_and_b32_e32 v111, 0xffff0000, v27
	v_pk_mul_f32 v[128:129], v[96:97], v[96:97]
	v_pk_fma_f32 v[128:129], v[98:99], v[98:99], v[128:129]
	v_pk_fma_f32 v[128:129], v[100:101], v[100:101], v[128:129]
	v_pk_fma_f32 v[128:129], v[102:103], v[102:103], v[128:129]
	v_pk_fma_f32 v[128:129], v[104:105], v[104:105], v[128:129]
	v_pk_fma_f32 v[128:129], v[106:107], v[106:107], v[128:129]
	v_pk_fma_f32 v[128:129], v[108:109], v[108:109], v[128:129]
	v_pk_fma_f32 v[128:129], v[110:111], v[110:111], v[128:129]
	s_nop 0
	v_add_f32_e32 v128, v128, v129
	s_waitcnt vmcnt(32)
; __device__ __forceinline__ v4f ld4_bf16(const bf16* p) { const v2u w = *(const v2u*)p; return (v4f){bf_lo(w.x), bf_hi(w.x), bf_lo(w.y), bf_hi(w.y)}; }
; __device__ __forceinline__ float ssq4(v4f v) { return (v.x * v.x + v.y * v.y) + (v.z * v.z + v.w * v.w); }
; template <int R, bool BASE_F32, bool OUT_F32>
; __device__ __forceinline__ void rows_res(const Ctx& C, int m0, int stride, int mx, const float* gpost, float scale, int lane) {
;     ...
;             for (int j = 0; j < 4; ++j) b[r][j] = ld4_bf16(XN + (size_t)mm * DM + 4 * lane + 256 * j) * inv;
;         } }
; #pragma unroll
;     for (int r = 0; r < R; ++r) { float s = 0.f;
; #pragma unroll
;         for (int j = 0; j < 4; ++j) s += ssq4(d[r][j]);
;         r1[r] = s; }
; #pragma unroll
;     for (int r = 0; r < R; ++r) r1[r] = rsqrtf(wave_sum(r1[r]) * (1.f / DM) + EPS) * scale;
; #pragma unroll
;     for (int j = 0; j < 4; ++j) { const v4f gp = ld4_f32(gpost + 4 * lane + 256 * j);
; #pragma unroll
;         for (int r = 0; r < R; ++r) d[r][j] = b[r][j] + d[r][j] * r1[r] * gp; }
	v_lshlrev_b32_e32 v112, 16, v28
	v_and_b32_e32 v113, 0xffff0000, v28
	v_lshlrev_b32_e32 v114, 16, v29
	v_and_b32_e32 v115, 0xffff0000, v29
	v_lshlrev_b32_e32 v116, 16, v30
	v_and_b32_e32 v117, 0xffff0000, v30
	v_lshlrev_b32_e32 v118, 16, v31
	v_and_b32_e32 v119, 0xffff0000, v31
	v_lshlrev_b32_e32 v120, 16, v32
	v_and_b32_e32 v121, 0xffff0000, v32
	v_lshlrev_b32_e32 v122, 16, v33
	v_and_b32_e32 v123, 0xffff0000, v33
	v_lshlrev_b32_e32 v124, 16, v34
	v_and_b32_e32 v125, 0xffff0000, v34
	v_lshlrev_b32_e32 v126, 16, v35
	v_and_b32_e32 v127, 0xffff0000, v35
	v_pk_mul_f32 v[130:131], v[112:113], v[112:113]
	v_pk_fma_f32 v[130:131], v[114:115], v[114:115], v[130:131]
	v_pk_fma_f32 v[130:131], v[116:117], v[116:117], v[130:131]
	v_pk_fma_f32 v[130:131], v[118:119], v[118:119], v[130:131]
	v_pk_fma_f32 v[130:131], v[120:121], v[120:121], v[130:131]
	v_pk_fma_f32 v[130:131], v[122:123], v[122:123], v[130:131]
	v_pk_fma_f32 v[130:131], v[124:125], v[124:125], v[130:131]
	v_pk_fma_f32 v[130:131], v[126:127], v[126:127], v[130:131]
	s_nop 0
	v_add_f32_e32 v130, v130, v131
	s_nop 1
	v_add_f32_dpp v128, v128, v128 quad_perm:[1,0,3,2] row_mask:0xf bank_mask:0xf
	v_add_f32_dpp v130, v130, v130 quad_perm:[1,0,3,2] row_mask:0xf bank_mask:0xf
	s_nop 0
	v_add_f32_dpp v128, v128, v128 quad_perm:[2,3,0,1] row_mask:0xf bank_mask:0xf
	v_add_f32_dpp v130, v130, v130 quad_perm:[2,3,0,1] row_mask:0xf bank_mask:0xf
	s_nop 0
	v_add_f32_dpp v128, v128, v128 row_half_mirror row_mask:0xf bank_mask:0xf
	v_add_f32_dpp v130, v130, v130 row_half_mirror row_mask:0xf bank_mask:0xf
	s_nop 0
	v_add_f32_dpp v128, v128, v128 row_mirror row_mask:0xf bank_mask:0xf
	v_add_f32_dpp v130, v130, v130 row_mirror row_mask:0xf bank_mask:0xf
	s_nop 0
	ds_bpermute_b32 v136, v187, v128
	ds_bpermute_b32 v137, v187, v130
	s_waitcnt lgkmcnt(0)
	v_add_f32_e32 v128, v128, v136
	v_add_f32_e32 v130, v130, v137
	ds_bpermute_b32 v136, v188, v128
	ds_bpermute_b32 v137, v188, v130
	s_waitcnt lgkmcnt(0)
	v_add_f32_e32 v128, v128, v136
	v_add_f32_e32 v130, v130, v137
	v_fmamk_f32 v128, v128, 0x3a800000, v138
	v_fmamk_f32 v130, v130, 0x3a800000, v138
	s_nop 0
	v_rsq_f32_e32 v128, v128
	v_rsq_f32_e32 v130, v130
	s_nop 1
	s_waitcnt vmcnt(28)
	v_pk_mul_f32 v[96:97], v[128:129], v[96:97] op_sel_hi:[0,1]
	v_pk_mul_f32 v[98:99], v[128:129], v[98:99] op_sel_hi:[0,1]
	v_pk_mul_f32 v[100:101], v[128:129], v[100:101] op_sel_hi:[0,1]
	v_pk_mul_f32 v[102:103], v[128:129], v[102:103] op_sel_hi:[0,1]
	v_pk_mul_f32 v[104:105], v[128:129], v[104:105] op_sel_hi:[0,1]
	v_pk_mul_f32 v[106:107], v[128:129], v[106:107] op_sel_hi:[0,1]
	v_pk_mul_f32 v[108:109], v[128:129], v[108:109] op_sel_hi:[0,1]
	v_pk_mul_f32 v[110:111], v[128:129], v[110:111] op_sel_hi:[0,1]
	v_pk_mul_f32 v[96:97], v[96:97], v[192:193]
	v_pk_mul_f32 v[98:99], v[98:99], v[194:195]
	v_pk_mul_f32 v[100:101], v[100:101], v[196:197]
	v_pk_mul_f32 v[102:103], v[102:103], v[198:199]
	v_pk_mul_f32 v[104:105], v[104:105], v[200:201]
	v_pk_mul_f32 v[106:107], v[106:107], v[202:203]
	v_pk_mul_f32 v[108:109], v[108:109], v[204:205]
	v_pk_mul_f32 v[110:111], v[110:111], v[206:207]
	v_lshlrev_b32_e32 v20, 16, v36
	v_and_b32_e32 v21, 0xffff0000, v36
	v_lshlrev_b32_e32 v22, 16, v37
	v_and_b32_e32 v23, 0xffff0000, v37
	v_lshlrev_b32_e32 v24, 16, v38
	v_and_b32_e32 v25, 0xffff0000, v38
	v_lshlrev_b32_e32 v26, 16, v39
	v_and_b32_e32 v27, 0xffff0000, v39
	v_pk_fma_f32 v[96:97], v[52:53], v[20:21], v[96:97] op_sel_hi:[0,1,1]
	v_pk_fma_f32 v[98:99], v[52:53], v[22:23], v[98:99] op_sel_hi:[0,1,1]
	v_pk_fma_f32 v[100:101], v[52:53], v[24:25], v[100:101] op_sel_hi:[0,1,1]
	v_pk_fma_f32 v[102:103], v[52:53], v[26:27], v[102:103] op_sel_hi:[0,1,1]
	v_lshlrev_b32_e32 v20, 16, v40
	v_and_b32_e32 v21, 0xffff0000, v40
	v_lshlrev_b32_e32 v22, 16, v41
	v_and_b32_e32 v23, 0xffff0000, v41
	v_lshlrev_b32_e32 v24, 16, v42
	v_and_b32_e32 v25, 0xffff0000, v42
	v_lshlrev_b32_e32 v26, 16, v43
	v_and_b32_e32 v27, 0xffff0000, v43
	v_pk_fma_f32 v[104:105], v[52:53], v[20:21], v[104:105] op_sel_hi:[0,1,1]
	v_pk_fma_f32 v[106:107], v[52:53], v[22:23], v[106:107] op_sel_hi:[0,1,1]
	v_pk_fma_f32 v[108:109], v[52:53], v[24:25], v[108:109] op_sel_hi:[0,1,1]
	v_pk_fma_f32 v[110:111], v[52:53], v[26:27], v[110:111] op_sel_hi:[0,1,1]
	v_pk_mul_f32 v[132:133], v[96:97], v[96:97]
	v_pk_fma_f32 v[132:133], v[98:99], v[98:99], v[132:133]
	v_pk_fma_f32 v[132:133], v[100:101], v[100:101], v[132:133]
	v_pk_fma_f32 v[132:133], v[102:103], v[102:103], v[132:133]
	v_pk_fma_f32 v[132:133], v[104:105], v[104:105], v[132:133]
	v_pk_fma_f32 v[132:133], v[106:107], v[106:107], v[132:133]
	v_pk_fma_f32 v[132:133], v[108:109], v[108:109], v[132:133]
	v_pk_fma_f32 v[132:133], v[110:111], v[110:111], v[132:133]
	s_nop 0
	v_add_f32_e32 v132, v132, v133
	v_pk_mul_f32 v[112:113], v[130:131], v[112:113] op_sel_hi:[0,1]
	v_pk_mul_f32 v[114:115], v[130:131], v[114:115] op_sel_hi:[0,1]
	v_pk_mul_f32 v[116:117], v[130:131], v[116:117] op_sel_hi:[0,1]
	v_pk_mul_f32 v[118:119], v[130:131], v[118:119] op_sel_hi:[0,1]
	v_pk_mul_f32 v[120:121], v[130:131], v[120:121] op_sel_hi:[0,1]
	v_pk_mul_f32 v[122:123], v[130:131], v[122:123] op_sel_hi:[0,1]
	v_pk_mul_f32 v[124:125], v[130:131], v[124:125] op_sel_hi:[0,1]
	v_pk_mul_f32 v[126:127], v[130:131], v[126:127] op_sel_hi:[0,1]
	v_pk_mul_f32 v[112:113], v[112:113], v[192:193]
	v_pk_mul_f32 v[114:115], v[114:115], v[194:195]
	v_pk_mul_f32 v[116:117], v[116:117], v[196:197]
	v_pk_mul_f32 v[118:119], v[118:119], v[198:199]
	v_pk_mul_f32 v[120:121], v[120:121], v[200:201]
	v_pk_mul_f32 v[122:123], v[122:123], v[202:203]
	v_pk_mul_f32 v[124:125], v[124:125], v[204:205]
	v_pk_mul_f32 v[126:127], v[126:127], v[206:207]
;     __device__ __forceinline__ float* out() const { return (float*)karg_in(33); }
; __device__ __forceinline__ void st4_bf16(bf16* p, v4f o) { v2u w; w.x = cvt_pk_nv(o.x, o.y); w.y = cvt_pk_nv(o.z, o.w); *(v2u*)p = w; }
; __device__ __forceinline__ float ssq4(v4f v) { return (v.x * v.x + v.y * v.y) + (v.z * v.z + v.w * v.w); }
; template <int R, bool BASE_F32, bool OUT_F32>
; __device__ __forceinline__ void rows_res(const Ctx& C, int m0, int stride, int mx, const float* gpost, float scale, int lane) {
;     ...
;     for (int j = 0; j < 4; ++j) { const v4f gp = ld4_f32(gpost + 4 * lane + 256 * j);
; #pragma unroll
;         for (int r = 0; r < R; ++r) d[r][j] = b[r][j] + d[r][j] * r1[r] * gp; }
;     if (OUT_F32) { float* Y = C.out();
; #pragma unroll
;         for (int r = 0; r < R; ++r)
; #pragma unroll
;             for (int j = 0; j < 4; ++j) if (ok[r]) *(v4f*)(Y + (size_t)mr[r] * DM + 4 * lane + 256 * j) = d[r][j];
;     } else { float* rs = C.RS(); float t[R];
; #pragma unroll
;         for (int r = 0; r < R; ++r) { float s = 0.f;
; #pragma unroll
;             for (int j = 0; j < 4; ++j) s += ssq4(d[r][j]);
;             t[r] = s; }
; #pragma unroll
;         for (int r = 0; r < R; ++r) t[r] = wave_sum(t[r]) * (1.f / DM) + EPS;
; #pragma unroll
;         for (int r = 0; r < R; ++r) { const float rstd = rsqrtf(t[r]);
; #pragma unroll
;             for (int j = 0; j < 4; ++j) if (ok[r]) st4_bf16(XN + (size_t)mr[r] * DM + 4 * lane + 256 * j, d[r][j] * rstd);
;             if (lane == 0 && ok[r]) rs[mr[r]] = sqrtf(t[r]); }
	v_lshlrev_b32_e32 v28, 16, v44
	v_and_b32_e32 v29, 0xffff0000, v44
	v_lshlrev_b32_e32 v30, 16, v45
	v_and_b32_e32 v31, 0xffff0000, v45
	v_lshlrev_b32_e32 v32, 16, v46
	v_and_b32_e32 v33, 0xffff0000, v46
	v_lshlrev_b32_e32 v34, 16, v47
	v_and_b32_e32 v35, 0xffff0000, v47
	v_pk_fma_f32 v[112:113], v[54:55], v[28:29], v[112:113] op_sel_hi:[0,1,1]
	v_pk_fma_f32 v[114:115], v[54:55], v[30:31], v[114:115] op_sel_hi:[0,1,1]
	v_pk_fma_f32 v[116:117], v[54:55], v[32:33], v[116:117] op_sel_hi:[0,1,1]
	v_pk_fma_f32 v[118:119], v[54:55], v[34:35], v[118:119] op_sel_hi:[0,1,1]
	v_lshlrev_b32_e32 v28, 16, v48
	v_and_b32_e32 v29, 0xffff0000, v48
	v_lshlrev_b32_e32 v30, 16, v49
	v_and_b32_e32 v31, 0xffff0000, v49
	v_lshlrev_b32_e32 v32, 16, v50
	v_and_b32_e32 v33, 0xffff0000, v50
	v_lshlrev_b32_e32 v34, 16, v51
	v_and_b32_e32 v35, 0xffff0000, v51
	v_pk_fma_f32 v[120:121], v[54:55], v[28:29], v[120:121] op_sel_hi:[0,1,1]
	v_pk_fma_f32 v[122:123], v[54:55], v[30:31], v[122:123] op_sel_hi:[0,1,1]
	v_pk_fma_f32 v[124:125], v[54:55], v[32:33], v[124:125] op_sel_hi:[0,1,1]
	v_pk_fma_f32 v[126:127], v[54:55], v[34:35], v[126:127] op_sel_hi:[0,1,1]
	v_pk_mul_f32 v[134:135], v[112:113], v[112:113]
	v_pk_fma_f32 v[134:135], v[114:115], v[114:115], v[134:135]
	v_pk_fma_f32 v[134:135], v[116:117], v[116:117], v[134:135]
	v_pk_fma_f32 v[134:135], v[118:119], v[118:119], v[134:135]
	v_pk_fma_f32 v[134:135], v[120:121], v[120:121], v[134:135]
	v_pk_fma_f32 v[134:135], v[122:123], v[122:123], v[134:135]
	v_pk_fma_f32 v[134:135], v[124:125], v[124:125], v[134:135]
	v_pk_fma_f32 v[134:135], v[126:127], v[126:127], v[134:135]
	s_nop 0
	v_add_f32_e32 v134, v134, v135
	s_nop 1
	v_add_f32_dpp v132, v132, v132 quad_perm:[1,0,3,2] row_mask:0xf bank_mask:0xf
	v_add_f32_dpp v134, v134, v134 quad_perm:[1,0,3,2] row_mask:0xf bank_mask:0xf
	s_nop 0
	v_add_f32_dpp v132, v132, v132 quad_perm:[2,3,0,1] row_mask:0xf bank_mask:0xf
	v_add_f32_dpp v134, v134, v134 quad_perm:[2,3,0,1] row_mask:0xf bank_mask:0xf
	s_nop 0
	v_add_f32_dpp v132, v132, v132 row_half_mirror row_mask:0xf bank_mask:0xf
	v_add_f32_dpp v134, v134, v134 row_half_mirror row_mask:0xf bank_mask:0xf
	s_nop 0
	v_add_f32_dpp v132, v132, v132 row_mirror row_mask:0xf bank_mask:0xf
	v_add_f32_dpp v134, v134, v134 row_mirror row_mask:0xf bank_mask:0xf
	s_nop 0
	ds_bpermute_b32 v136, v187, v132
	ds_bpermute_b32 v137, v187, v134
	s_waitcnt lgkmcnt(0)
	v_add_f32_e32 v132, v132, v136
	v_add_f32_e32 v134, v134, v137
	ds_bpermute_b32 v136, v188, v132
	ds_bpermute_b32 v137, v188, v134
	s_waitcnt lgkmcnt(0)
	v_add_f32_e32 v132, v132, v136
	v_add_f32_e32 v134, v134, v137
	v_fmamk_f32 v164, v132, 0x3a800000, v138
	v_fmamk_f32 v167, v134, 0x3a800000, v138
	s_nop 0
	v_rsq_f32_e32 v132, v164
	v_rsq_f32_e32 v134, v167
	v_sqrt_f32_e32 v165, v164
	v_sqrt_f32_e32 v168, v167
	s_nop 1
	v_pk_mul_f32 v[140:141], v[96:97], v[132:133] op_sel_hi:[1,0]
	v_cvt_pk_bf16_f32 v148, v140, v141
	v_pk_mul_f32 v[142:143], v[98:99], v[132:133] op_sel_hi:[1,0]
	v_cvt_pk_bf16_f32 v149, v142, v143
	v_pk_mul_f32 v[144:145], v[100:101], v[132:133] op_sel_hi:[1,0]
	v_cvt_pk_bf16_f32 v150, v144, v145
	v_pk_mul_f32 v[146:147], v[102:103], v[132:133] op_sel_hi:[1,0]
	v_cvt_pk_bf16_f32 v151, v146, v147
	v_pk_mul_f32 v[140:141], v[104:105], v[132:133] op_sel_hi:[1,0]
	v_cvt_pk_bf16_f32 v152, v140, v141
	v_pk_mul_f32 v[142:143], v[106:107], v[132:133] op_sel_hi:[1,0]
	v_cvt_pk_bf16_f32 v153, v142, v143
	v_pk_mul_f32 v[144:145], v[108:109], v[132:133] op_sel_hi:[1,0]
	v_cvt_pk_bf16_f32 v154, v144, v145
	v_pk_mul_f32 v[146:147], v[110:111], v[132:133] op_sel_hi:[1,0]
	v_cvt_pk_bf16_f32 v155, v146, v147
	global_store_dwordx2 v173, v[148:149], s[98:99]
	global_store_dwordx2 v173, v[150:151], s[98:99] offset:512
	global_store_dwordx2 v173, v[152:153], s[98:99] offset:1024
	global_store_dwordx2 v173, v[154:155], s[98:99] offset:1536
	v_add_u32_e32 v173, 0x400000, v173
	v_pk_mul_f32 v[140:141], v[112:113], v[134:135] op_sel_hi:[1,0]
	v_cvt_pk_bf16_f32 v156, v140, v141
	v_pk_mul_f32 v[142:143], v[114:115], v[134:135] op_sel_hi:[1,0]
	v_cvt_pk_bf16_f32 v157, v142, v143
	v_pk_mul_f32 v[144:145], v[116:117], v[134:135] op_sel_hi:[1,0]
	v_cvt_pk_bf16_f32 v158, v144, v145
	v_pk_mul_f32 v[146:147], v[118:119], v[134:135] op_sel_hi:[1,0]
	v_cvt_pk_bf16_f32 v159, v146, v147
	v_pk_mul_f32 v[140:141], v[120:121], v[134:135] op_sel_hi:[1,0]
	v_cvt_pk_bf16_f32 v160, v140, v141
	v_pk_mul_f32 v[142:143], v[122:123], v[134:135] op_sel_hi:[1,0]
	v_cvt_pk_bf16_f32 v161, v142, v143
	v_pk_mul_f32 v[144:145], v[124:125], v[134:135] op_sel_hi:[1,0]
	v_cvt_pk_bf16_f32 v162, v144, v145
	v_pk_mul_f32 v[146:147], v[126:127], v[134:135] op_sel_hi:[1,0]
	v_cvt_pk_bf16_f32 v163, v146, v147
	global_store_dwordx2 v173, v[156:157], s[98:99]
	global_store_dwordx2 v173, v[158:159], s[98:99] offset:512
	global_store_dwordx2 v173, v[160:161], s[98:99] offset:1024
	global_store_dwordx2 v173, v[162:163], s[98:99] offset:1536
	v_add_u32_e32 v173, 0x400000, v173
	v_add_u32_e32 v166, -1, v165
	v_fma_f32 v140, -v166, v165, v164
	v_cmp_ge_f32_e32 vcc, 0, v140
	v_add_u32_e32 v141, 1, v165
	v_cndmask_b32_e32 v166, v165, v166, vcc
	v_fma_f32 v140, -v141, v165, v164
	v_cmp_lt_f32_e32 vcc, 0, v140
	s_nop 1
	v_cndmask_b32_e32 v165, v166, v141, vcc
	v_add_u32_e32 v169, -1, v168
	v_fma_f32 v142, -v169, v168, v167
	v_cmp_ge_f32_e32 vcc, 0, v142
	v_add_u32_e32 v143, 1, v168
	v_cndmask_b32_e32 v169, v168, v169, vcc
	v_fma_f32 v142, -v143, v168, v167
	v_cmp_lt_f32_e32 vcc, 0, v142
	s_nop 1
	v_cndmask_b32_e32 v168, v169, v143, vcc
	s_mov_b64 exec, 1
	global_store_dword v174, v165, s[98:99]
	v_add_u32_e32 v174, 0x2000, v174
	global_store_dword v174, v168, s[98:99]
	v_add_u32_e32 v174, 0x2000, v174
	s_mov_b64 exec, -1
	s_waitcnt vmcnt(23)
; __device__ __forceinline__ v4f ld4_bf16(const bf16* p) { const v2u w = *(const v2u*)p; return (v4f){bf_lo(w.x), bf_hi(w.x), bf_lo(w.y), bf_hi(w.y)}; }
; __device__ __forceinline__ float ssq4(v4f v) { return (v.x * v.x + v.y * v.y) + (v.z * v.z + v.w * v.w); }
; template <int R, bool BASE_F32, bool OUT_F32>
; __device__ __forceinline__ void rows_res(const Ctx& C, int m0, int stride, int mx, const float* gpost, float scale, int lane) {
;     ...
;             for (int j = 0; j < 4; ++j) b[r][j] = ld4_bf16(XN + (size_t)mm * DM + 4 * lane + 256 * j) * inv;
;         } }
; #pragma unroll
;     for (int r = 0; r < R; ++r) { float s = 0.f;
; #pragma unroll
;         for (int j = 0; j < 4; ++j) s += ssq4(d[r][j]);
;         r1[r] = s; }
; #pragma unroll
;     for (int r = 0; r < R; ++r) r1[r] = rsqrtf(wave_sum(r1[r]) * (1.f / DM) + EPS) * scale;
; #pragma unroll
;     for (int j = 0; j < 4; ++j) { const v4f gp = ld4_f32(gpost + 4 * lane + 256 * j);
; #pragma unroll
;         for (int r = 0; r < R; ++r) d[r][j] = b[r][j] + d[r][j] * r1[r] * gp; }
	v_lshlrev_b32_e32 v96, 16, v56
	v_and_b32_e32 v97, 0xffff0000, v56
	v_lshlrev_b32_e32 v98, 16, v57
	v_and_b32_e32 v99, 0xffff0000, v57
	v_lshlrev_b32_e32 v100, 16, v58
	v_and_b32_e32 v101, 0xffff0000, v58
	v_lshlrev_b32_e32 v102, 16, v59
	v_and_b32_e32 v103, 0xffff0000, v59
	v_lshlrev_b32_e32 v104, 16, v60
	v_and_b32_e32 v105, 0xffff0000, v60
	v_lshlrev_b32_e32 v106, 16, v61
	v_and_b32_e32 v107, 0xffff0000, v61
	v_lshlrev_b32_e32 v108, 16, v62
	v_and_b32_e32 v109, 0xffff0000, v62
	v_lshlrev_b32_e32 v110, 16, v63
	v_and_b32_e32 v111, 0xffff0000, v63
	v_pk_mul_f32 v[128:129], v[96:97], v[96:97]
	v_pk_fma_f32 v[128:129], v[98:99], v[98:99], v[128:129]
	v_pk_fma_f32 v[128:129], v[100:101], v[100:101], v[128:129]
	v_pk_fma_f32 v[128:129], v[102:103], v[102:103], v[128:129]
	v_pk_fma_f32 v[128:129], v[104:105], v[104:105], v[128:129]
	v_pk_fma_f32 v[128:129], v[106:107], v[106:107], v[128:129]
	v_pk_fma_f32 v[128:129], v[108:109], v[108:109], v[128:129]
	v_pk_fma_f32 v[128:129], v[110:111], v[110:111], v[128:129]
	s_nop 0
	v_add_f32_e32 v128, v128, v129
	s_waitcnt vmcnt(14)
	v_lshlrev_b32_e32 v112, 16, v64
	v_and_b32_e32 v113, 0xffff0000, v64
	v_lshlrev_b32_e32 v114, 16, v65
	v_and_b32_e32 v115, 0xffff0000, v65
	v_lshlrev_b32_e32 v116, 16, v66
	v_and_b32_e32 v117, 0xffff0000, v66
	v_lshlrev_b32_e32 v118, 16, v67
	v_and_b32_e32 v119, 0xffff0000, v67
	v_lshlrev_b32_e32 v120, 16, v68
	v_and_b32_e32 v121, 0xffff0000, v68
	v_lshlrev_b32_e32 v122, 16, v69
	v_and_b32_e32 v123, 0xffff0000, v69
	v_lshlrev_b32_e32 v124, 16, v70
	v_and_b32_e32 v125, 0xffff0000, v70
	v_lshlrev_b32_e32 v126, 16, v71
	v_and_b32_e32 v127, 0xffff0000, v71
	v_pk_mul_f32 v[130:131], v[112:113], v[112:113]
	v_pk_fma_f32 v[130:131], v[114:115], v[114:115], v[130:131]
	v_pk_fma_f32 v[130:131], v[116:117], v[116:117], v[130:131]
	v_pk_fma_f32 v[130:131], v[118:119], v[118:119], v[130:131]
	v_pk_fma_f32 v[130:131], v[120:121], v[120:121], v[130:131]
	v_pk_fma_f32 v[130:131], v[122:123], v[122:123], v[130:131]
	v_pk_fma_f32 v[130:131], v[124:125], v[124:125], v[130:131]
	v_pk_fma_f32 v[130:131], v[126:127], v[126:127], v[130:131]
	s_nop 0
	v_add_f32_e32 v130, v130, v131
	s_nop 1
	v_add_f32_dpp v128, v128, v128 quad_perm:[1,0,3,2] row_mask:0xf bank_mask:0xf
	v_add_f32_dpp v130, v130, v130 quad_perm:[1,0,3,2] row_mask:0xf bank_mask:0xf
	s_nop 0
	v_add_f32_dpp v128, v128, v128 quad_perm:[2,3,0,1] row_mask:0xf bank_mask:0xf
	v_add_f32_dpp v130, v130, v130 quad_perm:[2,3,0,1] row_mask:0xf bank_mask:0xf
	s_nop 0
	v_add_f32_dpp v128, v128, v128 row_half_mirror row_mask:0xf bank_mask:0xf
	v_add_f32_dpp v130, v130, v130 row_half_mirror row_mask:0xf bank_mask:0xf
	s_nop 0
	v_add_f32_dpp v128, v128, v128 row_mirror row_mask:0xf bank_mask:0xf
	v_add_f32_dpp v130, v130, v130 row_mirror row_mask:0xf bank_mask:0xf
	s_nop 0
	ds_bpermute_b32 v136, v187, v128
	ds_bpermute_b32 v137, v187, v130
	s_waitcnt lgkmcnt(0)
	v_add_f32_e32 v128, v128, v136
	v_add_f32_e32 v130, v130, v137
	ds_bpermute_b32 v136, v188, v128
	ds_bpermute_b32 v137, v188, v130
	s_waitcnt lgkmcnt(0)
	v_add_f32_e32 v128, v128, v136
	v_add_f32_e32 v130, v130, v137
	v_fmamk_f32 v128, v128, 0x3a800000, v138
	v_fmamk_f32 v130, v130, 0x3a800000, v138
	s_nop 0
	v_rsq_f32_e32 v128, v128
	v_rsq_f32_e32 v130, v130
	s_nop 1
	s_waitcnt vmcnt(10)
	v_pk_mul_f32 v[96:97], v[128:129], v[96:97] op_sel_hi:[0,1]
	v_pk_mul_f32 v[98:99], v[128:129], v[98:99] op_sel_hi:[0,1]
	v_pk_mul_f32 v[100:101], v[128:129], v[100:101] op_sel_hi:[0,1]
	v_pk_mul_f32 v[102:103], v[128:129], v[102:103] op_sel_hi:[0,1]
	v_pk_mul_f32 v[104:105], v[128:129], v[104:105] op_sel_hi:[0,1]
	v_pk_mul_f32 v[106:107], v[128:129], v[106:107] op_sel_hi:[0,1]
	v_pk_mul_f32 v[108:109], v[128:129], v[108:109] op_sel_hi:[0,1]
	v_pk_mul_f32 v[110:111], v[128:129], v[110:111] op_sel_hi:[0,1]
	v_pk_mul_f32 v[96:97], v[96:97], v[192:193]
	v_pk_mul_f32 v[98:99], v[98:99], v[194:195]
	v_pk_mul_f32 v[100:101], v[100:101], v[196:197]
	v_pk_mul_f32 v[102:103], v[102:103], v[198:199]
	v_pk_mul_f32 v[104:105], v[104:105], v[200:201]
	v_pk_mul_f32 v[106:107], v[106:107], v[202:203]
	v_pk_mul_f32 v[108:109], v[108:109], v[204:205]
	v_pk_mul_f32 v[110:111], v[110:111], v[206:207]
	v_lshlrev_b32_e32 v56, 16, v72
	v_and_b32_e32 v57, 0xffff0000, v72
	v_lshlrev_b32_e32 v58, 16, v73
	v_and_b32_e32 v59, 0xffff0000, v73
	v_lshlrev_b32_e32 v60, 16, v74
	v_and_b32_e32 v61, 0xffff0000, v74
	v_lshlrev_b32_e32 v62, 16, v75
	v_and_b32_e32 v63, 0xffff0000, v75
	v_pk_fma_f32 v[96:97], v[88:89], v[56:57], v[96:97] op_sel_hi:[0,1,1]
	v_pk_fma_f32 v[98:99], v[88:89], v[58:59], v[98:99] op_sel_hi:[0,1,1]
	v_pk_fma_f32 v[100:101], v[88:89], v[60:61], v[100:101] op_sel_hi:[0,1,1]
	v_pk_fma_f32 v[102:103], v[88:89], v[62:63], v[102:103] op_sel_hi:[0,1,1]
	v_lshlrev_b32_e32 v56, 16, v76
	v_and_b32_e32 v57, 0xffff0000, v76
	v_lshlrev_b32_e32 v58, 16, v77
	v_and_b32_e32 v59, 0xffff0000, v77
	v_lshlrev_b32_e32 v60, 16, v78
	v_and_b32_e32 v61, 0xffff0000, v78
	v_lshlrev_b32_e32 v62, 16, v79
	v_and_b32_e32 v63, 0xffff0000, v79
	v_pk_fma_f32 v[104:105], v[88:89], v[56:57], v[104:105] op_sel_hi:[0,1,1]
	v_pk_fma_f32 v[106:107], v[88:89], v[58:59], v[106:107] op_sel_hi:[0,1,1]
	v_pk_fma_f32 v[108:109], v[88:89], v[60:61], v[108:109] op_sel_hi:[0,1,1]
	v_pk_fma_f32 v[110:111], v[88:89], v[62:63], v[110:111] op_sel_hi:[0,1,1]
	v_pk_mul_f32 v[132:133], v[96:97], v[96:97]
	v_pk_fma_f32 v[132:133], v[98:99], v[98:99], v[132:133]
	v_pk_fma_f32 v[132:133], v[100:101], v[100:101], v[132:133]
	v_pk_fma_f32 v[132:133], v[102:103], v[102:103], v[132:133]
	v_pk_fma_f32 v[132:133], v[104:105], v[104:105], v[132:133]
;     __device__ __forceinline__ float* out() const { return (float*)karg_in(33); }
; __device__ __forceinline__ void st4_bf16(bf16* p, v4f o) { v2u w; w.x = cvt_pk_nv(o.x, o.y); w.y = cvt_pk_nv(o.z, o.w); *(v2u*)p = w; }
; __device__ __forceinline__ float ssq4(v4f v) { return (v.x * v.x + v.y * v.y) + (v.z * v.z + v.w * v.w); }
; template <int R, bool BASE_F32, bool OUT_F32>
; __device__ __forceinline__ void rows_res(const Ctx& C, int m0, int stride, int mx, const float* gpost, float scale, int lane) {
;     ...
;     for (int j = 0; j < 4; ++j) { const v4f gp = ld4_f32(gpost + 4 * lane + 256 * j);
; #pragma unroll
;         for (int r = 0; r < R; ++r) d[r][j] = b[r][j] + d[r][j] * r1[r] * gp; }
;     if (OUT_F32) { float* Y = C.out();
; #pragma unroll
;         for (int r = 0; r < R; ++r)
; #pragma unroll
;             for (int j = 0; j < 4; ++j) if (ok[r]) *(v4f*)(Y + (size_t)mr[r] * DM + 4 * lane + 256 * j) = d[r][j];
;     } else { float* rs = C.RS(); float t[R];
; #pragma unroll
;         for (int r = 0; r < R; ++r) { float s = 0.f;
; #pragma unroll
;             for (int j = 0; j < 4; ++j) s += ssq4(d[r][j]);
;             t[r] = s; }
; #pragma unroll
;         for (int r = 0; r < R; ++r) t[r] = wave_sum(t[r]) * (1.f / DM) + EPS;
; #pragma unroll
;         for (int r = 0; r < R; ++r) { const float rstd = rsqrtf(t[r]);
; #pragma unroll
;             for (int j = 0; j < 4; ++j) if (ok[r]) st4_bf16(XN + (size_t)mr[r] * DM + 4 * lane + 256 * j, d[r][j] * rstd);
;             if (lane == 0 && ok[r]) rs[mr[r]] = sqrtf(t[r]); }
	v_pk_fma_f32 v[132:133], v[106:107], v[106:107], v[132:133]
	v_pk_fma_f32 v[132:133], v[108:109], v[108:109], v[132:133]
	v_pk_fma_f32 v[132:133], v[110:111], v[110:111], v[132:133]
	s_nop 0
	v_add_f32_e32 v132, v132, v133
	v_pk_mul_f32 v[112:113], v[130:131], v[112:113] op_sel_hi:[0,1]
	v_pk_mul_f32 v[114:115], v[130:131], v[114:115] op_sel_hi:[0,1]
	v_pk_mul_f32 v[116:117], v[130:131], v[116:117] op_sel_hi:[0,1]
	v_pk_mul_f32 v[118:119], v[130:131], v[118:119] op_sel_hi:[0,1]
	v_pk_mul_f32 v[120:121], v[130:131], v[120:121] op_sel_hi:[0,1]
	v_pk_mul_f32 v[122:123], v[130:131], v[122:123] op_sel_hi:[0,1]
	v_pk_mul_f32 v[124:125], v[130:131], v[124:125] op_sel_hi:[0,1]
	v_pk_mul_f32 v[126:127], v[130:131], v[126:127] op_sel_hi:[0,1]
	v_pk_mul_f32 v[112:113], v[112:113], v[192:193]
	v_pk_mul_f32 v[114:115], v[114:115], v[194:195]
	v_pk_mul_f32 v[116:117], v[116:117], v[196:197]
	v_pk_mul_f32 v[118:119], v[118:119], v[198:199]
	v_pk_mul_f32 v[120:121], v[120:121], v[200:201]
	v_pk_mul_f32 v[122:123], v[122:123], v[202:203]
	v_pk_mul_f32 v[124:125], v[124:125], v[204:205]
	v_pk_mul_f32 v[126:127], v[126:127], v[206:207]
	v_lshlrev_b32_e32 v64, 16, v80
	v_and_b32_e32 v65, 0xffff0000, v80
	v_lshlrev_b32_e32 v66, 16, v81
	v_and_b32_e32 v67, 0xffff0000, v81
	v_lshlrev_b32_e32 v68, 16, v82
	v_and_b32_e32 v69, 0xffff0000, v82
	v_lshlrev_b32_e32 v70, 16, v83
	v_and_b32_e32 v71, 0xffff0000, v83
	v_pk_fma_f32 v[112:113], v[90:91], v[64:65], v[112:113] op_sel_hi:[0,1,1]
	v_pk_fma_f32 v[114:115], v[90:91], v[66:67], v[114:115] op_sel_hi:[0,1,1]
	v_pk_fma_f32 v[116:117], v[90:91], v[68:69], v[116:117] op_sel_hi:[0,1,1]
	v_pk_fma_f32 v[118:119], v[90:91], v[70:71], v[118:119] op_sel_hi:[0,1,1]
	v_lshlrev_b32_e32 v64, 16, v84
	v_and_b32_e32 v65, 0xffff0000, v84
	v_lshlrev_b32_e32 v66, 16, v85
	v_and_b32_e32 v67, 0xffff0000, v85
	v_lshlrev_b32_e32 v68, 16, v86
	v_and_b32_e32 v69, 0xffff0000, v86
	v_lshlrev_b32_e32 v70, 16, v87
	v_and_b32_e32 v71, 0xffff0000, v87
	v_pk_fma_f32 v[120:121], v[90:91], v[64:65], v[120:121] op_sel_hi:[0,1,1]
	v_pk_fma_f32 v[122:123], v[90:91], v[66:67], v[122:123] op_sel_hi:[0,1,1]
	v_pk_fma_f32 v[124:125], v[90:91], v[68:69], v[124:125] op_sel_hi:[0,1,1]
	v_pk_fma_f32 v[126:127], v[90:91], v[70:71], v[126:127] op_sel_hi:[0,1,1]
	v_pk_mul_f32 v[134:135], v[112:113], v[112:113]
	v_pk_fma_f32 v[134:135], v[114:115], v[114:115], v[134:135]
	v_pk_fma_f32 v[134:135], v[116:117], v[116:117], v[134:135]
	v_pk_fma_f32 v[134:135], v[118:119], v[118:119], v[134:135]
	v_pk_fma_f32 v[134:135], v[120:121], v[120:121], v[134:135]
	v_pk_fma_f32 v[134:135], v[122:123], v[122:123], v[134:135]
	v_pk_fma_f32 v[134:135], v[124:125], v[124:125], v[134:135]
	v_pk_fma_f32 v[134:135], v[126:127], v[126:127], v[134:135]
	s_nop 0
	v_add_f32_e32 v134, v134, v135
	s_nop 1
	v_add_f32_dpp v132, v132, v132 quad_perm:[1,0,3,2] row_mask:0xf bank_mask:0xf
	v_add_f32_dpp v134, v134, v134 quad_perm:[1,0,3,2] row_mask:0xf bank_mask:0xf
	s_nop 0
	v_add_f32_dpp v132, v132, v132 quad_perm:[2,3,0,1] row_mask:0xf bank_mask:0xf
	v_add_f32_dpp v134, v134, v134 quad_perm:[2,3,0,1] row_mask:0xf bank_mask:0xf
	s_nop 0
	v_add_f32_dpp v132, v132, v132 row_half_mirror row_mask:0xf bank_mask:0xf
	v_add_f32_dpp v134, v134, v134 row_half_mirror row_mask:0xf bank_mask:0xf
	s_nop 0
	v_add_f32_dpp v132, v132, v132 row_mirror row_mask:0xf bank_mask:0xf
	v_add_f32_dpp v134, v134, v134 row_mirror row_mask:0xf bank_mask:0xf
	s_nop 0
	ds_bpermute_b32 v136, v187, v132
	ds_bpermute_b32 v137, v187, v134
	s_waitcnt lgkmcnt(0)
	v_add_f32_e32 v132, v132, v136
	v_add_f32_e32 v134, v134, v137
	ds_bpermute_b32 v136, v188, v132
	ds_bpermute_b32 v137, v188, v134
	s_waitcnt lgkmcnt(0)
	v_add_f32_e32 v132, v132, v136
	v_add_f32_e32 v134, v134, v137
	v_fmamk_f32 v164, v132, 0x3a800000, v138
	v_fmamk_f32 v167, v134, 0x3a800000, v138
	s_nop 0
	v_rsq_f32_e32 v132, v164
	v_rsq_f32_e32 v134, v167
	v_sqrt_f32_e32 v165, v164
	v_sqrt_f32_e32 v168, v167
	s_nop 1
	v_pk_mul_f32 v[140:141], v[96:97], v[132:133] op_sel_hi:[1,0]
	v_cvt_pk_bf16_f32 v148, v140, v141
	v_pk_mul_f32 v[142:143], v[98:99], v[132:133] op_sel_hi:[1,0]
	v_cvt_pk_bf16_f32 v149, v142, v143
	v_pk_mul_f32 v[144:145], v[100:101], v[132:133] op_sel_hi:[1,0]
	v_cvt_pk_bf16_f32 v150, v144, v145
	v_pk_mul_f32 v[146:147], v[102:103], v[132:133] op_sel_hi:[1,0]
	v_cvt_pk_bf16_f32 v151, v146, v147
	v_pk_mul_f32 v[140:141], v[104:105], v[132:133] op_sel_hi:[1,0]
	v_cvt_pk_bf16_f32 v152, v140, v141
	v_pk_mul_f32 v[142:143], v[106:107], v[132:133] op_sel_hi:[1,0]
	v_cvt_pk_bf16_f32 v153, v142, v143
	v_pk_mul_f32 v[144:145], v[108:109], v[132:133] op_sel_hi:[1,0]
	v_cvt_pk_bf16_f32 v154, v144, v145
	v_pk_mul_f32 v[146:147], v[110:111], v[132:133] op_sel_hi:[1,0]
	v_cvt_pk_bf16_f32 v155, v146, v147
	global_store_dwordx2 v173, v[148:149], s[98:99]
	global_store_dwordx2 v173, v[150:151], s[98:99] offset:512
	global_store_dwordx2 v173, v[152:153], s[98:99] offset:1024
	global_store_dwordx2 v173, v[154:155], s[98:99] offset:1536
	v_add_u32_e32 v173, 0x400000, v173
	v_pk_mul_f32 v[140:141], v[112:113], v[134:135] op_sel_hi:[1,0]
	v_cvt_pk_bf16_f32 v156, v140, v141
	v_pk_mul_f32 v[142:143], v[114:115], v[134:135] op_sel_hi:[1,0]
	v_cvt_pk_bf16_f32 v157, v142, v143
	v_pk_mul_f32 v[144:145], v[116:117], v[134:135] op_sel_hi:[1,0]
	v_cvt_pk_bf16_f32 v158, v144, v145
	v_pk_mul_f32 v[146:147], v[118:119], v[134:135] op_sel_hi:[1,0]
	v_cvt_pk_bf16_f32 v159, v146, v147
	v_pk_mul_f32 v[140:141], v[120:121], v[134:135] op_sel_hi:[1,0]
	v_cvt_pk_bf16_f32 v160, v140, v141
	v_pk_mul_f32 v[142:143], v[122:123], v[134:135] op_sel_hi:[1,0]
	v_cvt_pk_bf16_f32 v161, v142, v143
	v_pk_mul_f32 v[144:145], v[124:125], v[134:135] op_sel_hi:[1,0]
	v_cvt_pk_bf16_f32 v162, v144, v145
	v_pk_mul_f32 v[146:147], v[126:127], v[134:135] op_sel_hi:[1,0]
	v_cvt_pk_bf16_f32 v163, v146, v147
	global_store_dwordx2 v173, v[156:157], s[98:99]
	global_store_dwordx2 v173, v[158:159], s[98:99] offset:512
	global_store_dwordx2 v173, v[160:161], s[98:99] offset:1024
	global_store_dwordx2 v173, v[162:163], s[98:99] offset:1536
	v_add_u32_e32 v173, 0x400000, v173
	v_add_u32_e32 v166, -1, v165
	v_fma_f32 v140, -v166, v165, v164
	v_cmp_ge_f32_e32 vcc, 0, v140
	v_add_u32_e32 v141, 1, v165
	v_cndmask_b32_e32 v166, v165, v166, vcc
	v_fma_f32 v140, -v141, v165, v164
	v_cmp_lt_f32_e32 vcc, 0, v140
	s_nop 1
	v_cndmask_b32_e32 v165, v166, v141, vcc
	v_add_u32_e32 v169, -1, v168
	v_fma_f32 v142, -v169, v168, v167
	v_cmp_ge_f32_e32 vcc, 0, v142
	v_add_u32_e32 v143, 1, v168
	v_cndmask_b32_e32 v169, v168, v169, vcc
	v_fma_f32 v142, -v143, v168, v167
	v_cmp_lt_f32_e32 vcc, 0, v142
	s_nop 1
	v_cndmask_b32_e32 v168, v169, v143, vcc
	s_mov_b64 exec, 1
	global_store_dword v174, v165, s[98:99]
	v_add_u32_e32 v174, 0x2000, v174
	global_store_dword v174, v168, s[98:99]
	v_add_u32_e32 v174, 0x2000, v174
	s_mov_b64 exec, -1
	s_branch .LBB0_1013
; __device__ __forceinline__ const float* xrow_ptr(const Ctx& C, int row) { return row < MPROMPT ? C.in(0) + (size_t)row * DM : C.in(1) + (size_t)(row - MPROMPT) * DM; }
; __device__ __forceinline__ v4f ld4_bf16(const bf16* p) { const v2u w = *(const v2u*)p; return (v4f){bf_lo(w.x), bf_hi(w.x), bf_lo(w.y), bf_hi(w.y)}; }
; __device__ __forceinline__ float ssq4(v4f v) { return (v.x * v.x + v.y * v.y) + (v.z * v.z + v.w * v.w); }
; template <int R, bool BASE_F32, bool OUT_F32>
; __device__ __forceinline__ void rows_res(const Ctx& C, int m0, int stride, int mx, const float* gpost, float scale, int lane) {
;     ...
;     const bf16* D = C.D(); bf16* XN = C.XN();
; #pragma unroll
;     for (int r = 0; r < R; ++r) { mr[r] = (r == 4) ? mx : m0 + r * stride; ok[r] = (r == 4) ? (mx < M) : (mr[r] < MPROMPT); const int mm = ok[r] ? mr[r] : 0;
; #pragma unroll
;         for (int j = 0; j < 4; ++j) d[r][j] = ld4_bf16(D + (size_t)mm * DM + 4 * lane + 256 * j);
;         if (BASE_F32) { const float* x = xrow_ptr(C, mm);
; #pragma unroll
;             for (int j = 0; j < 4; ++j) b[r][j] = ld4_f32(x + 4 * lane + 256 * j);
;         } else { const float inv = C.RS()[mm];
; #pragma unroll
;             for (int j = 0; j < 4; ++j) b[r][j] = ld4_bf16(XN + (size_t)mm * DM + 4 * lane + 256 * j) * inv;
;         } }
; #pragma unroll
;     for (int r = 0; r < R; ++r) { float s = 0.f;
; #pragma unroll
;         for (int j = 0; j < 4; ++j) s += ssq4(d[r][j]);
;         r1[r] = s; }
; #pragma unroll
;     for (int r = 0; r < R; ++r) r1[r] = rsqrtf(wave_sum(r1[r]) * (1.f / DM) + EPS) * scale;
	v_mov_b32_e32 v3, v1
	s_mov_b32 s0, 0x358637bd
	s_waitcnt lgkmcnt(0)
	v_lshl_add_u64 v[4:5], s[16:17], 0, v[2:3]
	s_mov_b64 s[18:19], 0x7100000
	s_mov_b64 s[20:21], 0x3000000
	v_mov_b32_e32 v3, 0x2a80000
	s_mov_b32 s22, 0x3a800000
	v_mov_b64_e32 v[6:7], s[0:1]
	s_mov_b32 s42, 0x800000
	v_mov_b32_e32 v41, 0x358637bd
	s_mov_b32 s43, 0xf800000
	v_mov_b32_e32 v148, 0x260
	s_mov_b32 s24, s23
	v_readlane_b32 s56, v232, 5
	s_branch .LBB0_997

;     __device__ __forceinline__ const float* in(int i) const { return karg_in(i); }
; __device__ __forceinline__ const float* xrow_ptr(const Ctx& C, int row) { return row < MPROMPT ? C.in(0) + (size_t)row * DM : C.in(1) + (size_t)(row - MPROMPT) * DM; }
; __device__ __forceinline__ v4f ld4_bf16(const bf16* p) { const v2u w = *(const v2u*)p; return (v4f){bf_lo(w.x), bf_hi(w.x), bf_lo(w.y), bf_hi(w.y)}; }
; __device__ __forceinline__ float ssq4(v4f v) { return (v.x * v.x + v.y * v.y) + (v.z * v.z + v.w * v.w); }
; #define FTID const int ftid_ = fresh_tid()
; template <int R, bool BASE_F32, bool OUT_F32>
; __device__ __forceinline__ void rows_res(const Ctx& C, int m0, int stride, int mx, const float* gpost, float scale, int lane) {
;     ...
;     for (int r = 0; r < R; ++r) { mr[r] = (r == 4) ? mx : m0 + r * stride; ok[r] = (r == 4) ? (mx < M) : (mr[r] < MPROMPT); const int mm = ok[r] ? mr[r] : 0;
; #pragma unroll
;         for (int j = 0; j < 4; ++j) d[r][j] = ld4_bf16(D + (size_t)mm * DM + 4 * lane + 256 * j);
;         if (BASE_F32) { const float* x = xrow_ptr(C, mm);
; #pragma unroll
;             for (int j = 0; j < 4; ++j) b[r][j] = ld4_f32(x + 4 * lane + 256 * j);
;         } else { const float inv = C.RS()[mm];
; #pragma unroll
;             for (int j = 0; j < 4; ++j) b[r][j] = ld4_bf16(XN + (size_t)mm * DM + 4 * lane + 256 * j) * inv;
;         } }
; #pragma unroll
;     for (int r = 0; r < R; ++r) { float s = 0.f;
; #pragma unroll
;         for (int j = 0; j < 4; ++j) s += ssq4(d[r][j]);
;         r1[r] = s; }
; __global__ void __launch_bounds__(NTHREADS, 2) fwd_kernel(Args args) {
;     ...
;     { FTID; const float* gp = C.in(32); { const int gw_ = GWV, ngw_ = NGWV, nit = (MPROMPT + 4 * ngw_ - 1) / (4 * ngw_);
;       for (int it = 0; it < nit - 1; ++it) rows_res<4, false, true>(C, gw_ + 4 * it * ngw_, ngw_, M, gp, 0.5f, LANE);
.LBB0_1272:
	s_or_b64 exec, exec, s[4:5]
	s_mov_b64 s[0:1], s[80:81]
	s_waitcnt lgkmcnt(0)
	s_barrier
	s_load_dwordx2 s[8:9], s[0:1], 0x100
	v_readfirstlane_b32 s0, v182
	v_lshlrev_b32_e32 v0, 2, v182
	s_ashr_i32 s26, s0, 6
	v_readlane_b32 s0, v232, 0
	v_and_b32_e32 v0, 0xfc, v0
	s_add_i32 s15, s26, s0
	v_mov_b32_e32 v17, 0
	s_and_b64 vcc, exec, s[6:7]
	v_lshlrev_b32_e32 v16, 2, v0
	v_lshlrev_b32_e32 v18, 1, v0
	s_load_dwordx2 s[98:99], s[80:81], 0x110
	s_load_dwordx2 s[100:101], s[80:81], 0x100
	v_and_b32_e32 v176, 63, v182
	v_lshlrev_b32_e32 v170, 3, v176
	s_lshl_b32 vcc_lo, s15, 11
	v_add_u32_e32 v170, vcc_lo, v170
	v_add_u32_e32 v171, 0x3000000, v170
	v_add_u32_e32 v170, 0x7100000, v170
	v_mov_b32_e32 v173, v171
	s_lshl_b32 vcc_lo, s15, 2
	v_mov_b32_e32 v172, 0x2a80000
	v_add_u32_e32 v172, vcc_lo, v172
	v_mov_b32_e32 v174, v172
	s_lshl_b32 vcc_lo, s15, 12
	v_lshlrev_b32_e32 v175, 4, v176
	v_add_u32_e32 v175, vcc_lo, v175
	v_lshlrev_b32_e32 v176, 4, v176
	v_mov_b32_e32 v138, 0x358637bd
	s_waitcnt lgkmcnt(0)
	global_load_dwordx4 v[192:195], v176, s[100:101]
	global_load_dwordx4 v[196:199], v176, s[100:101] offset:1024
	global_load_dwordx4 v[200:203], v176, s[100:101] offset:2048
	global_load_dwordx4 v[204:207], v176, s[100:101] offset:3072
	s_load_dwordx2 s[100:101], s[80:81], 0x108
	global_load_dword v52, v172, s[98:99]
	global_load_dwordx2 v[20:21], v170, s[98:99] nt
	global_load_dwordx2 v[22:23], v170, s[98:99] offset:512 nt
	global_load_dwordx2 v[24:25], v170, s[98:99] offset:1024 nt
	global_load_dwordx2 v[26:27], v170, s[98:99] offset:1536 nt
	global_load_dwordx2 v[36:37], v171, s[98:99] nt
	global_load_dwordx2 v[38:39], v171, s[98:99] offset:512 nt
	global_load_dwordx2 v[40:41], v171, s[98:99] offset:1024 nt
	global_load_dwordx2 v[42:43], v171, s[98:99] offset:1536 nt
	v_add_u32_e32 v170, 0x400000, v170
	v_add_u32_e32 v171, 0x400000, v171
	v_add_u32_e32 v172, 0x2000, v172
	global_load_dword v54, v172, s[98:99]
	global_load_dwordx2 v[28:29], v170, s[98:99] nt
	global_load_dwordx2 v[30:31], v170, s[98:99] offset:512 nt
	global_load_dwordx2 v[32:33], v170, s[98:99] offset:1024 nt
	global_load_dwordx2 v[34:35], v170, s[98:99] offset:1536 nt
	global_load_dwordx2 v[44:45], v171, s[98:99] nt
	global_load_dwordx2 v[46:47], v171, s[98:99] offset:512 nt
	global_load_dwordx2 v[48:49], v171, s[98:99] offset:1024 nt
	global_load_dwordx2 v[50:51], v171, s[98:99] offset:1536 nt
	v_add_u32_e32 v170, 0x400000, v170
	v_add_u32_e32 v171, 0x400000, v171
	v_add_u32_e32 v172, 0x2000, v172
	global_load_dword v88, v172, s[98:99]
	global_load_dwordx2 v[56:57], v170, s[98:99] nt
	global_load_dwordx2 v[58:59], v170, s[98:99] offset:512 nt
	global_load_dwordx2 v[60:61], v170, s[98:99] offset:1024 nt
	global_load_dwordx2 v[62:63], v170, s[98:99] offset:1536 nt
	global_load_dwordx2 v[72:73], v171, s[98:99] nt
	global_load_dwordx2 v[74:75], v171, s[98:99] offset:512 nt
	global_load_dwordx2 v[76:77], v171, s[98:99] offset:1024 nt
	global_load_dwordx2 v[78:79], v171, s[98:99] offset:1536 nt
	v_add_u32_e32 v170, 0x400000, v170
	v_add_u32_e32 v171, 0x400000, v171
	v_add_u32_e32 v172, 0x2000, v172
	global_load_dword v90, v172, s[98:99]
	global_load_dwordx2 v[64:65], v170, s[98:99] nt
	global_load_dwordx2 v[66:67], v170, s[98:99] offset:512 nt
	global_load_dwordx2 v[68:69], v170, s[98:99] offset:1024 nt
	global_load_dwordx2 v[70:71], v170, s[98:99] offset:1536 nt
	global_load_dwordx2 v[80:81], v171, s[98:99] nt
	global_load_dwordx2 v[82:83], v171, s[98:99] offset:512 nt
	global_load_dwordx2 v[84:85], v171, s[98:99] offset:1024 nt
	global_load_dwordx2 v[86:87], v171, s[98:99] offset:1536 nt
	v_add_u32_e32 v170, 0x400000, v170
	v_add_u32_e32 v171, 0x400000, v171
	v_add_u32_e32 v172, 0x2000, v172
	s_waitcnt vmcnt(31)
	v_lshlrev_b32_e32 v96, 16, v20
	v_and_b32_e32 v97, 0xffff0000, v20
	v_lshlrev_b32_e32 v98, 16, v21
	v_and_b32_e32 v99, 0xffff0000, v21
	v_lshlrev_b32_e32 v100, 16, v22
	v_and_b32_e32 v101, 0xffff0000, v22
	v_lshlrev_b32_e32 v102, 16, v23
	v_and_b32_e32 v103, 0xffff0000, v23
	v_lshlrev_b32_e32 v104, 16, v24
	v_and_b32_e32 v105, 0xffff0000, v24
	v_lshlrev_b32_e32 v106, 16, v25
	v_and_b32_e32 v107, 0xffff0000, v25
	v_lshlrev_b32_e32 v108, 16, v26
	v_and_b32_e32 v109, 0xffff0000, v26
	v_lshlrev_b32_e32 v110, 16, v27
	v_and_b32_e32 v111, 0xffff0000, v27
	v_pk_mul_f32 v[128:129], v[96:97], v[96:97]
	v_pk_fma_f32 v[128:129], v[98:99], v[98:99], v[128:129]
	v_pk_fma_f32 v[128:129], v[100:101], v[100:101], v[128:129]
	v_pk_fma_f32 v[128:129], v[102:103], v[102:103], v[128:129]
	v_pk_fma_f32 v[128:129], v[104:105], v[104:105], v[128:129]
	v_pk_fma_f32 v[128:129], v[106:107], v[106:107], v[128:129]
	v_pk_fma_f32 v[128:129], v[108:109], v[108:109], v[128:129]
	v_pk_fma_f32 v[128:129], v[110:111], v[110:111], v[128:129]
	s_nop 0
	v_add_f32_e32 v128, v128, v129
	s_waitcnt vmcnt(22)
;     __device__ __forceinline__ float* out() const { return (float*)karg_in(33); }
; template <int R, bool BASE_F32, bool OUT_F32>
; __device__ __forceinline__ void rows_res(const Ctx& C, int m0, int stride, int mx, const float* gpost, float scale, int lane) {
;     ...
;     for (int r = 0; r < R; ++r) r1[r] = rsqrtf(wave_sum(r1[r]) * (1.f / DM) + EPS) * scale;
; #pragma unroll
;     for (int j = 0; j < 4; ++j) { const v4f gp = ld4_f32(gpost + 4 * lane + 256 * j);
; #pragma unroll
;         for (int r = 0; r < R; ++r) d[r][j] = b[r][j] + d[r][j] * r1[r] * gp; }
;     if (OUT_F32) { float* Y = C.out();
; #pragma unroll
;         for (int r = 0; r < R; ++r)
; #pragma unroll
;             for (int j = 0; j < 4; ++j) if (ok[r]) *(v4f*)(Y + (size_t)mr[r] * DM + 4 * lane + 256 * j) = d[r][j];
	v_lshlrev_b32_e32 v112, 16, v28
	v_and_b32_e32 v113, 0xffff0000, v28
	v_lshlrev_b32_e32 v114, 16, v29
	v_and_b32_e32 v115, 0xffff0000, v29
	v_lshlrev_b32_e32 v116, 16, v30
	v_and_b32_e32 v117, 0xffff0000, v30
	v_lshlrev_b32_e32 v118, 16, v31
	v_and_b32_e32 v119, 0xffff0000, v31
	v_lshlrev_b32_e32 v120, 16, v32
	v_and_b32_e32 v121, 0xffff0000, v32
	v_lshlrev_b32_e32 v122, 16, v33
	v_and_b32_e32 v123, 0xffff0000, v33
	v_lshlrev_b32_e32 v124, 16, v34
	v_and_b32_e32 v125, 0xffff0000, v34
	v_lshlrev_b32_e32 v126, 16, v35
	v_and_b32_e32 v127, 0xffff0000, v35
	v_pk_mul_f32 v[130:131], v[112:113], v[112:113]
	v_pk_fma_f32 v[130:131], v[114:115], v[114:115], v[130:131]
	v_pk_fma_f32 v[130:131], v[116:117], v[116:117], v[130:131]
	v_pk_fma_f32 v[130:131], v[118:119], v[118:119], v[130:131]
	v_pk_fma_f32 v[130:131], v[120:121], v[120:121], v[130:131]
	v_pk_fma_f32 v[130:131], v[122:123], v[122:123], v[130:131]
	v_pk_fma_f32 v[130:131], v[124:125], v[124:125], v[130:131]
	v_pk_fma_f32 v[130:131], v[126:127], v[126:127], v[130:131]
	s_nop 0
	v_add_f32_e32 v130, v130, v131
	s_nop 1
	v_add_f32_dpp v128, v128, v128 quad_perm:[1,0,3,2] row_mask:0xf bank_mask:0xf
	v_add_f32_dpp v130, v130, v130 quad_perm:[1,0,3,2] row_mask:0xf bank_mask:0xf
	s_nop 0
	v_add_f32_dpp v128, v128, v128 quad_perm:[2,3,0,1] row_mask:0xf bank_mask:0xf
	v_add_f32_dpp v130, v130, v130 quad_perm:[2,3,0,1] row_mask:0xf bank_mask:0xf
	s_nop 0
	v_add_f32_dpp v128, v128, v128 row_half_mirror row_mask:0xf bank_mask:0xf
	v_add_f32_dpp v130, v130, v130 row_half_mirror row_mask:0xf bank_mask:0xf
	s_nop 0
	v_add_f32_dpp v128, v128, v128 row_mirror row_mask:0xf bank_mask:0xf
	v_add_f32_dpp v130, v130, v130 row_mirror row_mask:0xf bank_mask:0xf
	s_nop 0
	ds_bpermute_b32 v136, v187, v128
	ds_bpermute_b32 v137, v187, v130
	s_waitcnt lgkmcnt(0)
	v_add_f32_e32 v128, v128, v136
	v_add_f32_e32 v130, v130, v137
	ds_bpermute_b32 v136, v188, v128
	ds_bpermute_b32 v137, v188, v130
	s_waitcnt lgkmcnt(0)
	v_add_f32_e32 v128, v128, v136
	v_add_f32_e32 v130, v130, v137
	v_fmamk_f32 v128, v128, 0x3a800000, v138
	v_fmamk_f32 v130, v130, 0x3a800000, v138
	s_nop 0
	v_rsq_f32_e32 v128, v128
	v_rsq_f32_e32 v130, v130
	s_nop 1
	v_mul_f32_e32 v128, 0.5, v128
	v_mul_f32_e32 v130, 0.5, v130
	s_waitcnt vmcnt(18)
	v_pk_mul_f32 v[96:97], v[128:129], v[96:97] op_sel_hi:[0,1]
	v_pk_mul_f32 v[98:99], v[128:129], v[98:99] op_sel_hi:[0,1]
	v_pk_mul_f32 v[100:101], v[128:129], v[100:101] op_sel_hi:[0,1]
	v_pk_mul_f32 v[102:103], v[128:129], v[102:103] op_sel_hi:[0,1]
	v_pk_mul_f32 v[104:105], v[128:129], v[104:105] op_sel_hi:[0,1]
	v_pk_mul_f32 v[106:107], v[128:129], v[106:107] op_sel_hi:[0,1]
	v_pk_mul_f32 v[108:109], v[128:129], v[108:109] op_sel_hi:[0,1]
	v_pk_mul_f32 v[110:111], v[128:129], v[110:111] op_sel_hi:[0,1]
	v_pk_mul_f32 v[96:97], v[96:97], v[192:193]
	v_pk_mul_f32 v[98:99], v[98:99], v[194:195]
	v_pk_mul_f32 v[100:101], v[100:101], v[196:197]
	v_pk_mul_f32 v[102:103], v[102:103], v[198:199]
	v_pk_mul_f32 v[104:105], v[104:105], v[200:201]
	v_pk_mul_f32 v[106:107], v[106:107], v[202:203]
	v_pk_mul_f32 v[108:109], v[108:109], v[204:205]
	v_pk_mul_f32 v[110:111], v[110:111], v[206:207]
	v_lshlrev_b32_e32 v20, 16, v36
	v_and_b32_e32 v21, 0xffff0000, v36
	v_lshlrev_b32_e32 v22, 16, v37
	v_and_b32_e32 v23, 0xffff0000, v37
	v_lshlrev_b32_e32 v24, 16, v38
	v_and_b32_e32 v25, 0xffff0000, v38
	v_lshlrev_b32_e32 v26, 16, v39
	v_and_b32_e32 v27, 0xffff0000, v39
	v_pk_fma_f32 v[96:97], v[52:53], v[20:21], v[96:97] op_sel_hi:[0,1,1]
	v_pk_fma_f32 v[98:99], v[52:53], v[22:23], v[98:99] op_sel_hi:[0,1,1]
	v_pk_fma_f32 v[100:101], v[52:53], v[24:25], v[100:101] op_sel_hi:[0,1,1]
	v_pk_fma_f32 v[102:103], v[52:53], v[26:27], v[102:103] op_sel_hi:[0,1,1]
	v_lshlrev_b32_e32 v20, 16, v40
	v_and_b32_e32 v21, 0xffff0000, v40
	v_lshlrev_b32_e32 v22, 16, v41
	v_and_b32_e32 v23, 0xffff0000, v41
	v_lshlrev_b32_e32 v24, 16, v42
	v_and_b32_e32 v25, 0xffff0000, v42
	v_lshlrev_b32_e32 v26, 16, v43
	v_and_b32_e32 v27, 0xffff0000, v43
	v_pk_fma_f32 v[104:105], v[52:53], v[20:21], v[104:105] op_sel_hi:[0,1,1]
	v_pk_fma_f32 v[106:107], v[52:53], v[22:23], v[106:107] op_sel_hi:[0,1,1]
	v_pk_fma_f32 v[108:109], v[52:53], v[24:25], v[108:109] op_sel_hi:[0,1,1]
	v_pk_fma_f32 v[110:111], v[52:53], v[26:27], v[110:111] op_sel_hi:[0,1,1]
	global_store_dwordx4 v175, v[96:99], s[100:101] nt
	global_store_dwordx4 v175, v[100:103], s[100:101] offset:1024 nt
	global_store_dwordx4 v175, v[104:107], s[100:101] offset:2048 nt
	global_store_dwordx4 v175, v[108:111], s[100:101] offset:3072 nt
	v_add_u32_e32 v175, 0x800000, v175
	v_pk_mul_f32 v[112:113], v[130:131], v[112:113] op_sel_hi:[0,1]
	v_pk_mul_f32 v[114:115], v[130:131], v[114:115] op_sel_hi:[0,1]
	v_pk_mul_f32 v[116:117], v[130:131], v[116:117] op_sel_hi:[0,1]
	v_pk_mul_f32 v[118:119], v[130:131], v[118:119] op_sel_hi:[0,1]
	v_pk_mul_f32 v[120:121], v[130:131], v[120:121] op_sel_hi:[0,1]
	v_pk_mul_f32 v[122:123], v[130:131], v[122:123] op_sel_hi:[0,1]
	v_pk_mul_f32 v[124:125], v[130:131], v[124:125] op_sel_hi:[0,1]
	v_pk_mul_f32 v[126:127], v[130:131], v[126:127] op_sel_hi:[0,1]
	v_pk_mul_f32 v[112:113], v[112:113], v[192:193]
	v_pk_mul_f32 v[114:115], v[114:115], v[194:195]
	v_pk_mul_f32 v[116:117], v[116:117], v[196:197]
	v_pk_mul_f32 v[118:119], v[118:119], v[198:199]
	v_pk_mul_f32 v[120:121], v[120:121], v[200:201]
	v_pk_mul_f32 v[122:123], v[122:123], v[202:203]
	v_pk_mul_f32 v[124:125], v[124:125], v[204:205]
	v_pk_mul_f32 v[126:127], v[126:127], v[206:207]
	v_lshlrev_b32_e32 v28, 16, v44
	v_and_b32_e32 v29, 0xffff0000, v44
	v_lshlrev_b32_e32 v30, 16, v45
	v_and_b32_e32 v31, 0xffff0000, v45
;     __device__ __forceinline__ float* out() const { return (float*)karg_in(33); }
; __device__ __forceinline__ const float* xrow_ptr(const Ctx& C, int row) { return row < MPROMPT ? C.in(0) + (size_t)row * DM : C.in(1) + (size_t)(row - MPROMPT) * DM; }
; __device__ __forceinline__ v4f ld4_bf16(const bf16* p) { const v2u w = *(const v2u*)p; return (v4f){bf_lo(w.x), bf_hi(w.x), bf_lo(w.y), bf_hi(w.y)}; }
; __device__ __forceinline__ float ssq4(v4f v) { return (v.x * v.x + v.y * v.y) + (v.z * v.z + v.w * v.w); }
; template <int R, bool BASE_F32, bool OUT_F32>
; __device__ __forceinline__ void rows_res(const Ctx& C, int m0, int stride, int mx, const float* gpost, float scale, int lane) {
;     ...
;     for (int r = 0; r < R; ++r) { mr[r] = (r == 4) ? mx : m0 + r * stride; ok[r] = (r == 4) ? (mx < M) : (mr[r] < MPROMPT); const int mm = ok[r] ? mr[r] : 0;
; #pragma unroll
;         for (int j = 0; j < 4; ++j) d[r][j] = ld4_bf16(D + (size_t)mm * DM + 4 * lane + 256 * j);
;         if (BASE_F32) { const float* x = xrow_ptr(C, mm);
; #pragma unroll
;             for (int j = 0; j < 4; ++j) b[r][j] = ld4_f32(x + 4 * lane + 256 * j);
;         } else { const float inv = C.RS()[mm];
; #pragma unroll
;             for (int j = 0; j < 4; ++j) b[r][j] = ld4_bf16(XN + (size_t)mm * DM + 4 * lane + 256 * j) * inv;
;         } }
; #pragma unroll
;     for (int r = 0; r < R; ++r) { float s = 0.f;
; #pragma unroll
;         for (int j = 0; j < 4; ++j) s += ssq4(d[r][j]);
;         r1[r] = s; }
; #pragma unroll
;     for (int r = 0; r < R; ++r) r1[r] = rsqrtf(wave_sum(r1[r]) * (1.f / DM) + EPS) * scale;
; #pragma unroll
;     for (int j = 0; j < 4; ++j) { const v4f gp = ld4_f32(gpost + 4 * lane + 256 * j);
; #pragma unroll
;         for (int r = 0; r < R; ++r) d[r][j] = b[r][j] + d[r][j] * r1[r] * gp; }
;     if (OUT_F32) { float* Y = C.out();
; #pragma unroll
;         for (int r = 0; r < R; ++r)
; #pragma unroll
;             for (int j = 0; j < 4; ++j) if (ok[r]) *(v4f*)(Y + (size_t)mr[r] * DM + 4 * lane + 256 * j) = d[r][j];
	v_lshlrev_b32_e32 v32, 16, v46
	v_and_b32_e32 v33, 0xffff0000, v46
	v_lshlrev_b32_e32 v34, 16, v47
	v_and_b32_e32 v35, 0xffff0000, v47
	v_pk_fma_f32 v[112:113], v[54:55], v[28:29], v[112:113] op_sel_hi:[0,1,1]
	v_pk_fma_f32 v[114:115], v[54:55], v[30:31], v[114:115] op_sel_hi:[0,1,1]
	v_pk_fma_f32 v[116:117], v[54:55], v[32:33], v[116:117] op_sel_hi:[0,1,1]
	v_pk_fma_f32 v[118:119], v[54:55], v[34:35], v[118:119] op_sel_hi:[0,1,1]
	v_lshlrev_b32_e32 v28, 16, v48
	v_and_b32_e32 v29, 0xffff0000, v48
	v_lshlrev_b32_e32 v30, 16, v49
	v_and_b32_e32 v31, 0xffff0000, v49
	v_lshlrev_b32_e32 v32, 16, v50
	v_and_b32_e32 v33, 0xffff0000, v50
	v_lshlrev_b32_e32 v34, 16, v51
	v_and_b32_e32 v35, 0xffff0000, v51
	v_pk_fma_f32 v[120:121], v[54:55], v[28:29], v[120:121] op_sel_hi:[0,1,1]
	v_pk_fma_f32 v[122:123], v[54:55], v[30:31], v[122:123] op_sel_hi:[0,1,1]
	v_pk_fma_f32 v[124:125], v[54:55], v[32:33], v[124:125] op_sel_hi:[0,1,1]
	v_pk_fma_f32 v[126:127], v[54:55], v[34:35], v[126:127] op_sel_hi:[0,1,1]
	global_store_dwordx4 v175, v[112:115], s[100:101] nt
	global_store_dwordx4 v175, v[116:119], s[100:101] offset:1024 nt
	global_store_dwordx4 v175, v[120:123], s[100:101] offset:2048 nt
	global_store_dwordx4 v175, v[124:127], s[100:101] offset:3072 nt
	v_add_u32_e32 v175, 0x800000, v175
	global_load_dword v52, v172, s[98:99]
	global_load_dwordx2 v[20:21], v170, s[98:99] nt
	global_load_dwordx2 v[22:23], v170, s[98:99] offset:512 nt
	global_load_dwordx2 v[24:25], v170, s[98:99] offset:1024 nt
	global_load_dwordx2 v[26:27], v170, s[98:99] offset:1536 nt
	global_load_dwordx2 v[36:37], v171, s[98:99] nt
	global_load_dwordx2 v[38:39], v171, s[98:99] offset:512 nt
	global_load_dwordx2 v[40:41], v171, s[98:99] offset:1024 nt
	global_load_dwordx2 v[42:43], v171, s[98:99] offset:1536 nt
	v_add_u32_e32 v170, 0x400000, v170
	v_add_u32_e32 v171, 0x400000, v171
	v_add_u32_e32 v172, 0x2000, v172
	global_load_dword v54, v172, s[98:99]
	global_load_dwordx2 v[28:29], v170, s[98:99] nt
	global_load_dwordx2 v[30:31], v170, s[98:99] offset:512 nt
	global_load_dwordx2 v[32:33], v170, s[98:99] offset:1024 nt
	global_load_dwordx2 v[34:35], v170, s[98:99] offset:1536 nt
	global_load_dwordx2 v[44:45], v171, s[98:99] nt
	global_load_dwordx2 v[46:47], v171, s[98:99] offset:512 nt
	global_load_dwordx2 v[48:49], v171, s[98:99] offset:1024 nt
	global_load_dwordx2 v[50:51], v171, s[98:99] offset:1536 nt
	v_add_u32_e32 v170, 0x400000, v170
	v_add_u32_e32 v171, 0x400000, v171
	v_add_u32_e32 v172, 0x2000, v172
	s_waitcnt vmcnt(39)
	v_lshlrev_b32_e32 v96, 16, v56
	v_and_b32_e32 v97, 0xffff0000, v56
	v_lshlrev_b32_e32 v98, 16, v57
	v_and_b32_e32 v99, 0xffff0000, v57
	v_lshlrev_b32_e32 v100, 16, v58
	v_and_b32_e32 v101, 0xffff0000, v58
	v_lshlrev_b32_e32 v102, 16, v59
	v_and_b32_e32 v103, 0xffff0000, v59
	v_lshlrev_b32_e32 v104, 16, v60
	v_and_b32_e32 v105, 0xffff0000, v60
	v_lshlrev_b32_e32 v106, 16, v61
	v_and_b32_e32 v107, 0xffff0000, v61
	v_lshlrev_b32_e32 v108, 16, v62
	v_and_b32_e32 v109, 0xffff0000, v62
	v_lshlrev_b32_e32 v110, 16, v63
	v_and_b32_e32 v111, 0xffff0000, v63
	v_pk_mul_f32 v[128:129], v[96:97], v[96:97]
	v_pk_fma_f32 v[128:129], v[98:99], v[98:99], v[128:129]
	v_pk_fma_f32 v[128:129], v[100:101], v[100:101], v[128:129]
	v_pk_fma_f32 v[128:129], v[102:103], v[102:103], v[128:129]
	v_pk_fma_f32 v[128:129], v[104:105], v[104:105], v[128:129]
	v_pk_fma_f32 v[128:129], v[106:107], v[106:107], v[128:129]
	v_pk_fma_f32 v[128:129], v[108:109], v[108:109], v[128:129]
	v_pk_fma_f32 v[128:129], v[110:111], v[110:111], v[128:129]
	s_nop 0
	v_add_f32_e32 v128, v128, v129
	s_waitcnt vmcnt(30)
	v_lshlrev_b32_e32 v112, 16, v64
	v_and_b32_e32 v113, 0xffff0000, v64
	v_lshlrev_b32_e32 v114, 16, v65
	v_and_b32_e32 v115, 0xffff0000, v65
	v_lshlrev_b32_e32 v116, 16, v66
	v_and_b32_e32 v117, 0xffff0000, v66
	v_lshlrev_b32_e32 v118, 16, v67
	v_and_b32_e32 v119, 0xffff0000, v67
	v_lshlrev_b32_e32 v120, 16, v68
	v_and_b32_e32 v121, 0xffff0000, v68
	v_lshlrev_b32_e32 v122, 16, v69
	v_and_b32_e32 v123, 0xffff0000, v69
	v_lshlrev_b32_e32 v124, 16, v70
	v_and_b32_e32 v125, 0xffff0000, v70
	v_lshlrev_b32_e32 v126, 16, v71
	v_and_b32_e32 v127, 0xffff0000, v71
	v_pk_mul_f32 v[130:131], v[112:113], v[112:113]
	v_pk_fma_f32 v[130:131], v[114:115], v[114:115], v[130:131]
	v_pk_fma_f32 v[130:131], v[116:117], v[116:117], v[130:131]
	v_pk_fma_f32 v[130:131], v[118:119], v[118:119], v[130:131]
	v_pk_fma_f32 v[130:131], v[120:121], v[120:121], v[130:131]
	v_pk_fma_f32 v[130:131], v[122:123], v[122:123], v[130:131]
	v_pk_fma_f32 v[130:131], v[124:125], v[124:125], v[130:131]
	v_pk_fma_f32 v[130:131], v[126:127], v[126:127], v[130:131]
	s_nop 0
	v_add_f32_e32 v130, v130, v131
	s_nop 1
	v_add_f32_dpp v128, v128, v128 quad_perm:[1,0,3,2] row_mask:0xf bank_mask:0xf
	v_add_f32_dpp v130, v130, v130 quad_perm:[1,0,3,2] row_mask:0xf bank_mask:0xf
	s_nop 0
	v_add_f32_dpp v128, v128, v128 quad_perm:[2,3,0,1] row_mask:0xf bank_mask:0xf
	v_add_f32_dpp v130, v130, v130 quad_perm:[2,3,0,1] row_mask:0xf bank_mask:0xf
	s_nop 0
	v_add_f32_dpp v128, v128, v128 row_half_mirror row_mask:0xf bank_mask:0xf
	v_add_f32_dpp v130, v130, v130 row_half_mirror row_mask:0xf bank_mask:0xf
	s_nop 0
	v_add_f32_dpp v128, v128, v128 row_mirror row_mask:0xf bank_mask:0xf
	v_add_f32_dpp v130, v130, v130 row_mirror row_mask:0xf bank_mask:0xf
	s_nop 0
	ds_bpermute_b32 v136, v187, v128
	ds_bpermute_b32 v137, v187, v130
	s_waitcnt lgkmcnt(0)
	v_add_f32_e32 v128, v128, v136
	v_add_f32_e32 v130, v130, v137
	ds_bpermute_b32 v136, v188, v128
	ds_bpermute_b32 v137, v188, v130
	s_waitcnt lgkmcnt(0)
;     __device__ __forceinline__ float* out() const { return (float*)karg_in(33); }
; __device__ __forceinline__ const float* xrow_ptr(const Ctx& C, int row) { return row < MPROMPT ? C.in(0) + (size_t)row * DM : C.in(1) + (size_t)(row - MPROMPT) * DM; }
; __device__ __forceinline__ v4f ld4_bf16(const bf16* p) { const v2u w = *(const v2u*)p; return (v4f){bf_lo(w.x), bf_hi(w.x), bf_lo(w.y), bf_hi(w.y)}; }
; __device__ __forceinline__ float ssq4(v4f v) { return (v.x * v.x + v.y * v.y) + (v.z * v.z + v.w * v.w); }
; template <int R, bool BASE_F32, bool OUT_F32>
; __device__ __forceinline__ void rows_res(const Ctx& C, int m0, int stride, int mx, const float* gpost, float scale, int lane) {
;     ...
;     for (int r = 0; r < R; ++r) { mr[r] = (r == 4) ? mx : m0 + r * stride; ok[r] = (r == 4) ? (mx < M) : (mr[r] < MPROMPT); const int mm = ok[r] ? mr[r] : 0;
; #pragma unroll
;         for (int j = 0; j < 4; ++j) d[r][j] = ld4_bf16(D + (size_t)mm * DM + 4 * lane + 256 * j);
;         if (BASE_F32) { const float* x = xrow_ptr(C, mm);
; #pragma unroll
;             for (int j = 0; j < 4; ++j) b[r][j] = ld4_f32(x + 4 * lane + 256 * j);
;         } else { const float inv = C.RS()[mm];
; #pragma unroll
;             for (int j = 0; j < 4; ++j) b[r][j] = ld4_bf16(XN + (size_t)mm * DM + 4 * lane + 256 * j) * inv;
;         } }
; #pragma unroll
;     for (int r = 0; r < R; ++r) { float s = 0.f;
; #pragma unroll
;         for (int j = 0; j < 4; ++j) s += ssq4(d[r][j]);
;         r1[r] = s; }
; #pragma unroll
;     for (int r = 0; r < R; ++r) r1[r] = rsqrtf(wave_sum(r1[r]) * (1.f / DM) + EPS) * scale;
; #pragma unroll
;     for (int j = 0; j < 4; ++j) { const v4f gp = ld4_f32(gpost + 4 * lane + 256 * j);
; #pragma unroll
;         for (int r = 0; r < R; ++r) d[r][j] = b[r][j] + d[r][j] * r1[r] * gp; }
;     if (OUT_F32) { float* Y = C.out();
; #pragma unroll
;         for (int r = 0; r < R; ++r)
; #pragma unroll
;             for (int j = 0; j < 4; ++j) if (ok[r]) *(v4f*)(Y + (size_t)mr[r] * DM + 4 * lane + 256 * j) = d[r][j];
	v_add_f32_e32 v128, v128, v136
	v_add_f32_e32 v130, v130, v137
	v_fmamk_f32 v128, v128, 0x3a800000, v138
	v_fmamk_f32 v130, v130, 0x3a800000, v138
	s_nop 0
	v_rsq_f32_e32 v128, v128
	v_rsq_f32_e32 v130, v130
	s_nop 1
	v_mul_f32_e32 v128, 0.5, v128
	v_mul_f32_e32 v130, 0.5, v130
	s_waitcnt vmcnt(26)
	v_pk_mul_f32 v[96:97], v[128:129], v[96:97] op_sel_hi:[0,1]
	v_pk_mul_f32 v[98:99], v[128:129], v[98:99] op_sel_hi:[0,1]
	v_pk_mul_f32 v[100:101], v[128:129], v[100:101] op_sel_hi:[0,1]
	v_pk_mul_f32 v[102:103], v[128:129], v[102:103] op_sel_hi:[0,1]
	v_pk_mul_f32 v[104:105], v[128:129], v[104:105] op_sel_hi:[0,1]
	v_pk_mul_f32 v[106:107], v[128:129], v[106:107] op_sel_hi:[0,1]
	v_pk_mul_f32 v[108:109], v[128:129], v[108:109] op_sel_hi:[0,1]
	v_pk_mul_f32 v[110:111], v[128:129], v[110:111] op_sel_hi:[0,1]
	v_pk_mul_f32 v[96:97], v[96:97], v[192:193]
	v_pk_mul_f32 v[98:99], v[98:99], v[194:195]
	v_pk_mul_f32 v[100:101], v[100:101], v[196:197]
	v_pk_mul_f32 v[102:103], v[102:103], v[198:199]
	v_pk_mul_f32 v[104:105], v[104:105], v[200:201]
	v_pk_mul_f32 v[106:107], v[106:107], v[202:203]
	v_pk_mul_f32 v[108:109], v[108:109], v[204:205]
	v_pk_mul_f32 v[110:111], v[110:111], v[206:207]
	v_lshlrev_b32_e32 v56, 16, v72
	v_and_b32_e32 v57, 0xffff0000, v72
	v_lshlrev_b32_e32 v58, 16, v73
	v_and_b32_e32 v59, 0xffff0000, v73
	v_lshlrev_b32_e32 v60, 16, v74
	v_and_b32_e32 v61, 0xffff0000, v74
	v_lshlrev_b32_e32 v62, 16, v75
	v_and_b32_e32 v63, 0xffff0000, v75
	v_pk_fma_f32 v[96:97], v[88:89], v[56:57], v[96:97] op_sel_hi:[0,1,1]
	v_pk_fma_f32 v[98:99], v[88:89], v[58:59], v[98:99] op_sel_hi:[0,1,1]
	v_pk_fma_f32 v[100:101], v[88:89], v[60:61], v[100:101] op_sel_hi:[0,1,1]
	v_pk_fma_f32 v[102:103], v[88:89], v[62:63], v[102:103] op_sel_hi:[0,1,1]
	v_lshlrev_b32_e32 v56, 16, v76
	v_and_b32_e32 v57, 0xffff0000, v76
	v_lshlrev_b32_e32 v58, 16, v77
	v_and_b32_e32 v59, 0xffff0000, v77
	v_lshlrev_b32_e32 v60, 16, v78
	v_and_b32_e32 v61, 0xffff0000, v78
	v_lshlrev_b32_e32 v62, 16, v79
	v_and_b32_e32 v63, 0xffff0000, v79
	v_pk_fma_f32 v[104:105], v[88:89], v[56:57], v[104:105] op_sel_hi:[0,1,1]
	v_pk_fma_f32 v[106:107], v[88:89], v[58:59], v[106:107] op_sel_hi:[0,1,1]
	v_pk_fma_f32 v[108:109], v[88:89], v[60:61], v[108:109] op_sel_hi:[0,1,1]
	v_pk_fma_f32 v[110:111], v[88:89], v[62:63], v[110:111] op_sel_hi:[0,1,1]
	global_store_dwordx4 v175, v[96:99], s[100:101] nt
	global_store_dwordx4 v175, v[100:103], s[100:101] offset:1024 nt
	global_store_dwordx4 v175, v[104:107], s[100:101] offset:2048 nt
	global_store_dwordx4 v175, v[108:111], s[100:101] offset:3072 nt
	v_add_u32_e32 v175, 0x800000, v175
	v_pk_mul_f32 v[112:113], v[130:131], v[112:113] op_sel_hi:[0,1]
	v_pk_mul_f32 v[114:115], v[130:131], v[114:115] op_sel_hi:[0,1]
	v_pk_mul_f32 v[116:117], v[130:131], v[116:117] op_sel_hi:[0,1]
	v_pk_mul_f32 v[118:119], v[130:131], v[118:119] op_sel_hi:[0,1]
	v_pk_mul_f32 v[120:121], v[130:131], v[120:121] op_sel_hi:[0,1]
	v_pk_mul_f32 v[122:123], v[130:131], v[122:123] op_sel_hi:[0,1]
	v_pk_mul_f32 v[124:125], v[130:131], v[124:125] op_sel_hi:[0,1]
	v_pk_mul_f32 v[126:127], v[130:131], v[126:127] op_sel_hi:[0,1]
	v_pk_mul_f32 v[112:113], v[112:113], v[192:193]
	v_pk_mul_f32 v[114:115], v[114:115], v[194:195]
	v_pk_mul_f32 v[116:117], v[116:117], v[196:197]
	v_pk_mul_f32 v[118:119], v[118:119], v[198:199]
	v_pk_mul_f32 v[120:121], v[120:121], v[200:201]
	v_pk_mul_f32 v[122:123], v[122:123], v[202:203]
	v_pk_mul_f32 v[124:125], v[124:125], v[204:205]
	v_pk_mul_f32 v[126:127], v[126:127], v[206:207]
	v_lshlrev_b32_e32 v64, 16, v80
	v_and_b32_e32 v65, 0xffff0000, v80
	v_lshlrev_b32_e32 v66, 16, v81
	v_and_b32_e32 v67, 0xffff0000, v81
	v_lshlrev_b32_e32 v68, 16, v82
	v_and_b32_e32 v69, 0xffff0000, v82
	v_lshlrev_b32_e32 v70, 16, v83
	v_and_b32_e32 v71, 0xffff0000, v83
	v_pk_fma_f32 v[112:113], v[90:91], v[64:65], v[112:113] op_sel_hi:[0,1,1]
	v_pk_fma_f32 v[114:115], v[90:91], v[66:67], v[114:115] op_sel_hi:[0,1,1]
	v_pk_fma_f32 v[116:117], v[90:91], v[68:69], v[116:117] op_sel_hi:[0,1,1]
	v_pk_fma_f32 v[118:119], v[90:91], v[70:71], v[118:119] op_sel_hi:[0,1,1]
	v_lshlrev_b32_e32 v64, 16, v84
	v_and_b32_e32 v65, 0xffff0000, v84
	v_lshlrev_b32_e32 v66, 16, v85
	v_and_b32_e32 v67, 0xffff0000, v85
	v_lshlrev_b32_e32 v68, 16, v86
	v_and_b32_e32 v69, 0xffff0000, v86
	v_lshlrev_b32_e32 v70, 16, v87
	v_and_b32_e32 v71, 0xffff0000, v87
	v_pk_fma_f32 v[120:121], v[90:91], v[64:65], v[120:121] op_sel_hi:[0,1,1]
	v_pk_fma_f32 v[122:123], v[90:91], v[66:67], v[122:123] op_sel_hi:[0,1,1]
	v_pk_fma_f32 v[124:125], v[90:91], v[68:69], v[124:125] op_sel_hi:[0,1,1]
	v_pk_fma_f32 v[126:127], v[90:91], v[70:71], v[126:127] op_sel_hi:[0,1,1]
	global_store_dwordx4 v175, v[112:115], s[100:101] nt
	global_store_dwordx4 v175, v[116:119], s[100:101] offset:1024 nt
	global_store_dwordx4 v175, v[120:123], s[100:101] offset:2048 nt
	global_store_dwordx4 v175, v[124:127], s[100:101] offset:3072 nt
	v_add_u32_e32 v175, 0x800000, v175
	global_load_dword v88, v172, s[98:99]
	global_load_dwordx2 v[56:57], v170, s[98:99] nt
	global_load_dwordx2 v[58:59], v170, s[98:99] offset:512 nt
	global_load_dwordx2 v[60:61], v170, s[98:99] offset:1024 nt
	global_load_dwordx2 v[62:63], v170, s[98:99] offset:1536 nt
	global_load_dwordx2 v[72:73], v171, s[98:99] nt
	global_load_dwordx2 v[74:75], v171, s[98:99] offset:512 nt
	global_load_dwordx2 v[76:77], v171, s[98:99] offset:1024 nt
	global_load_dwordx2 v[78:79], v171, s[98:99] offset:1536 nt
	v_add_u32_e32 v170, 0x400000, v170
	v_add_u32_e32 v171, 0x400000, v171
	v_add_u32_e32 v172, 0x2000, v172
	global_load_dword v90, v172, s[98:99]
	global_load_dwordx2 v[64:65], v170, s[98:99] nt
	global_load_dwordx2 v[66:67], v170, s[98:99] offset:512 nt
	global_load_dwordx2 v[68:69], v170, s[98:99] offset:1024 nt
	global_load_dwordx2 v[70:71], v170, s[98:99] offset:1536 nt
	global_load_dwordx2 v[80:81], v171, s[98:99] nt
	global_load_dwordx2 v[82:83], v171, s[98:99] offset:512 nt
	global_load_dwordx2 v[84:85], v171, s[98:99] offset:1024 nt
	global_load_dwordx2 v[86:87], v171, s[98:99] offset:1536 nt
	v_add_u32_e32 v170, 0x400000, v170
	v_add_u32_e32 v171, 0x400000, v171
	v_add_u32_e32 v172, 0x2000, v172
	s_waitcnt vmcnt(39)
;     __device__ __forceinline__ float* out() const { return (float*)karg_in(33); }
; __device__ __forceinline__ float ssq4(v4f v) { return (v.x * v.x + v.y * v.y) + (v.z * v.z + v.w * v.w); }
; template <int R, bool BASE_F32, bool OUT_F32>
; __device__ __forceinline__ void rows_res(const Ctx& C, int m0, int stride, int mx, const float* gpost, float scale, int lane) {
;     ...
;     for (int r = 0; r < R; ++r) { float s = 0.f;
; #pragma unroll
;         for (int j = 0; j < 4; ++j) s += ssq4(d[r][j]);
;         r1[r] = s; }
; #pragma unroll
;     for (int r = 0; r < R; ++r) r1[r] = rsqrtf(wave_sum(r1[r]) * (1.f / DM) + EPS) * scale;
; #pragma unroll
;     for (int j = 0; j < 4; ++j) { const v4f gp = ld4_f32(gpost + 4 * lane + 256 * j);
; #pragma unroll
;         for (int r = 0; r < R; ++r) d[r][j] = b[r][j] + d[r][j] * r1[r] * gp; }
;     if (OUT_F32) { float* Y = C.out();
; #pragma unroll
;         for (int r = 0; r < R; ++r)
; #pragma unroll
;             for (int j = 0; j < 4; ++j) if (ok[r]) *(v4f*)(Y + (size_t)mr[r] * DM + 4 * lane + 256 * j) = d[r][j];
	v_lshlrev_b32_e32 v96, 16, v20
	v_and_b32_e32 v97, 0xffff0000, v20
	v_lshlrev_b32_e32 v98, 16, v21
	v_and_b32_e32 v99, 0xffff0000, v21
	v_lshlrev_b32_e32 v100, 16, v22
	v_and_b32_e32 v101, 0xffff0000, v22
	v_lshlrev_b32_e32 v102, 16, v23
	v_and_b32_e32 v103, 0xffff0000, v23
	v_lshlrev_b32_e32 v104, 16, v24
	v_and_b32_e32 v105, 0xffff0000, v24
	v_lshlrev_b32_e32 v106, 16, v25
	v_and_b32_e32 v107, 0xffff0000, v25
	v_lshlrev_b32_e32 v108, 16, v26
	v_and_b32_e32 v109, 0xffff0000, v26
	v_lshlrev_b32_e32 v110, 16, v27
	v_and_b32_e32 v111, 0xffff0000, v27
	v_pk_mul_f32 v[128:129], v[96:97], v[96:97]
	v_pk_fma_f32 v[128:129], v[98:99], v[98:99], v[128:129]
	v_pk_fma_f32 v[128:129], v[100:101], v[100:101], v[128:129]
	v_pk_fma_f32 v[128:129], v[102:103], v[102:103], v[128:129]
	v_pk_fma_f32 v[128:129], v[104:105], v[104:105], v[128:129]
	v_pk_fma_f32 v[128:129], v[106:107], v[106:107], v[128:129]
	v_pk_fma_f32 v[128:129], v[108:109], v[108:109], v[128:129]
	v_pk_fma_f32 v[128:129], v[110:111], v[110:111], v[128:129]
	s_nop 0
	v_add_f32_e32 v128, v128, v129
	s_waitcnt vmcnt(30)
	v_lshlrev_b32_e32 v112, 16, v28
	v_and_b32_e32 v113, 0xffff0000, v28
	v_lshlrev_b32_e32 v114, 16, v29
	v_and_b32_e32 v115, 0xffff0000, v29
	v_lshlrev_b32_e32 v116, 16, v30
	v_and_b32_e32 v117, 0xffff0000, v30
	v_lshlrev_b32_e32 v118, 16, v31
	v_and_b32_e32 v119, 0xffff0000, v31
	v_lshlrev_b32_e32 v120, 16, v32
	v_and_b32_e32 v121, 0xffff0000, v32
	v_lshlrev_b32_e32 v122, 16, v33
	v_and_b32_e32 v123, 0xffff0000, v33
	v_lshlrev_b32_e32 v124, 16, v34
	v_and_b32_e32 v125, 0xffff0000, v34
	v_lshlrev_b32_e32 v126, 16, v35
	v_and_b32_e32 v127, 0xffff0000, v35
	v_pk_mul_f32 v[130:131], v[112:113], v[112:113]
	v_pk_fma_f32 v[130:131], v[114:115], v[114:115], v[130:131]
	v_pk_fma_f32 v[130:131], v[116:117], v[116:117], v[130:131]
	v_pk_fma_f32 v[130:131], v[118:119], v[118:119], v[130:131]
	v_pk_fma_f32 v[130:131], v[120:121], v[120:121], v[130:131]
	v_pk_fma_f32 v[130:131], v[122:123], v[122:123], v[130:131]
	v_pk_fma_f32 v[130:131], v[124:125], v[124:125], v[130:131]
	v_pk_fma_f32 v[130:131], v[126:127], v[126:127], v[130:131]
	s_nop 0
	v_add_f32_e32 v130, v130, v131
	s_nop 1
	v_add_f32_dpp v128, v128, v128 quad_perm:[1,0,3,2] row_mask:0xf bank_mask:0xf
	v_add_f32_dpp v130, v130, v130 quad_perm:[1,0,3,2] row_mask:0xf bank_mask:0xf
	s_nop 0
	v_add_f32_dpp v128, v128, v128 quad_perm:[2,3,0,1] row_mask:0xf bank_mask:0xf
	v_add_f32_dpp v130, v130, v130 quad_perm:[2,3,0,1] row_mask:0xf bank_mask:0xf
	s_nop 0
	v_add_f32_dpp v128, v128, v128 row_half_mirror row_mask:0xf bank_mask:0xf
	v_add_f32_dpp v130, v130, v130 row_half_mirror row_mask:0xf bank_mask:0xf
	s_nop 0
	v_add_f32_dpp v128, v128, v128 row_mirror row_mask:0xf bank_mask:0xf
	v_add_f32_dpp v130, v130, v130 row_mirror row_mask:0xf bank_mask:0xf
	s_nop 0
	ds_bpermute_b32 v136, v187, v128
	ds_bpermute_b32 v137, v187, v130
	s_waitcnt lgkmcnt(0)
	v_add_f32_e32 v128, v128, v136
	v_add_f32_e32 v130, v130, v137
	ds_bpermute_b32 v136, v188, v128
	ds_bpermute_b32 v137, v188, v130
	s_waitcnt lgkmcnt(0)
	v_add_f32_e32 v128, v128, v136
	v_add_f32_e32 v130, v130, v137
	v_fmamk_f32 v128, v128, 0x3a800000, v138
	v_fmamk_f32 v130, v130, 0x3a800000, v138
	s_nop 0
	v_rsq_f32_e32 v128, v128
	v_rsq_f32_e32 v130, v130
	s_nop 1
	v_mul_f32_e32 v128, 0.5, v128
	v_mul_f32_e32 v130, 0.5, v130
	s_waitcnt vmcnt(26)
	v_pk_mul_f32 v[96:97], v[128:129], v[96:97] op_sel_hi:[0,1]
	v_pk_mul_f32 v[98:99], v[128:129], v[98:99] op_sel_hi:[0,1]
	v_pk_mul_f32 v[100:101], v[128:129], v[100:101] op_sel_hi:[0,1]
	v_pk_mul_f32 v[102:103], v[128:129], v[102:103] op_sel_hi:[0,1]
	v_pk_mul_f32 v[104:105], v[128:129], v[104:105] op_sel_hi:[0,1]
	v_pk_mul_f32 v[106:107], v[128:129], v[106:107] op_sel_hi:[0,1]
	v_pk_mul_f32 v[108:109], v[128:129], v[108:109] op_sel_hi:[0,1]
	v_pk_mul_f32 v[110:111], v[128:129], v[110:111] op_sel_hi:[0,1]
	v_pk_mul_f32 v[96:97], v[96:97], v[192:193]
	v_pk_mul_f32 v[98:99], v[98:99], v[194:195]
	v_pk_mul_f32 v[100:101], v[100:101], v[196:197]
	v_pk_mul_f32 v[102:103], v[102:103], v[198:199]
	v_pk_mul_f32 v[104:105], v[104:105], v[200:201]
	v_pk_mul_f32 v[106:107], v[106:107], v[202:203]
	v_pk_mul_f32 v[108:109], v[108:109], v[204:205]
	v_pk_mul_f32 v[110:111], v[110:111], v[206:207]
	v_lshlrev_b32_e32 v20, 16, v36
	v_and_b32_e32 v21, 0xffff0000, v36
	v_lshlrev_b32_e32 v22, 16, v37
	v_and_b32_e32 v23, 0xffff0000, v37
	v_lshlrev_b32_e32 v24, 16, v38
	v_and_b32_e32 v25, 0xffff0000, v38
	v_lshlrev_b32_e32 v26, 16, v39
	v_and_b32_e32 v27, 0xffff0000, v39
	v_pk_fma_f32 v[96:97], v[52:53], v[20:21], v[96:97] op_sel_hi:[0,1,1]
	v_pk_fma_f32 v[98:99], v[52:53], v[22:23], v[98:99] op_sel_hi:[0,1,1]
	v_pk_fma_f32 v[100:101], v[52:53], v[24:25], v[100:101] op_sel_hi:[0,1,1]
	v_pk_fma_f32 v[102:103], v[52:53], v[26:27], v[102:103] op_sel_hi:[0,1,1]
	v_lshlrev_b32_e32 v20, 16, v40
	v_and_b32_e32 v21, 0xffff0000, v40
	v_lshlrev_b32_e32 v22, 16, v41
	v_and_b32_e32 v23, 0xffff0000, v41
	v_lshlrev_b32_e32 v24, 16, v42
	v_and_b32_e32 v25, 0xffff0000, v42
	v_lshlrev_b32_e32 v26, 16, v43
	v_and_b32_e32 v27, 0xffff0000, v43
	v_pk_fma_f32 v[104:105], v[52:53], v[20:21], v[104:105] op_sel_hi:[0,1,1]
	v_pk_fma_f32 v[106:107], v[52:53], v[22:23], v[106:107] op_sel_hi:[0,1,1]
	v_pk_fma_f32 v[108:109], v[52:53], v[24:25], v[108:109] op_sel_hi:[0,1,1]
	v_pk_fma_f32 v[110:111], v[52:53], v[26:27], v[110:111] op_sel_hi:[0,1,1]
	global_store_dwordx4 v175, v[96:99], s[100:101] nt
	global_store_dwordx4 v175, v[100:103], s[100:101] offset:1024 nt
	global_store_dwordx4 v175, v[104:107], s[100:101] offset:2048 nt
	global_store_dwordx4 v175, v[108:111], s[100:101] offset:3072 nt
;     __device__ __forceinline__ float* out() const { return (float*)karg_in(33); }
; __device__ __forceinline__ const float* xrow_ptr(const Ctx& C, int row) { return row < MPROMPT ? C.in(0) + (size_t)row * DM : C.in(1) + (size_t)(row - MPROMPT) * DM; }
; __device__ __forceinline__ v4f ld4_bf16(const bf16* p) { const v2u w = *(const v2u*)p; return (v4f){bf_lo(w.x), bf_hi(w.x), bf_lo(w.y), bf_hi(w.y)}; }
; __device__ __forceinline__ float ssq4(v4f v) { return (v.x * v.x + v.y * v.y) + (v.z * v.z + v.w * v.w); }
; template <int R, bool BASE_F32, bool OUT_F32>
; __device__ __forceinline__ void rows_res(const Ctx& C, int m0, int stride, int mx, const float* gpost, float scale, int lane) {
;     ...
;     for (int r = 0; r < R; ++r) { mr[r] = (r == 4) ? mx : m0 + r * stride; ok[r] = (r == 4) ? (mx < M) : (mr[r] < MPROMPT); const int mm = ok[r] ? mr[r] : 0;
; #pragma unroll
;         for (int j = 0; j < 4; ++j) d[r][j] = ld4_bf16(D + (size_t)mm * DM + 4 * lane + 256 * j);
;         if (BASE_F32) { const float* x = xrow_ptr(C, mm);
; #pragma unroll
;             for (int j = 0; j < 4; ++j) b[r][j] = ld4_f32(x + 4 * lane + 256 * j);
;         } else { const float inv = C.RS()[mm];
; #pragma unroll
;             for (int j = 0; j < 4; ++j) b[r][j] = ld4_bf16(XN + (size_t)mm * DM + 4 * lane + 256 * j) * inv;
;         } }
; #pragma unroll
;     for (int r = 0; r < R; ++r) { float s = 0.f;
; #pragma unroll
;         for (int j = 0; j < 4; ++j) s += ssq4(d[r][j]);
;         r1[r] = s; }
; #pragma unroll
;     for (int r = 0; r < R; ++r) r1[r] = rsqrtf(wave_sum(r1[r]) * (1.f / DM) + EPS) * scale;
; #pragma unroll
;     for (int j = 0; j < 4; ++j) { const v4f gp = ld4_f32(gpost + 4 * lane + 256 * j);
; #pragma unroll
;         for (int r = 0; r < R; ++r) d[r][j] = b[r][j] + d[r][j] * r1[r] * gp; }
;     if (OUT_F32) { float* Y = C.out();
; #pragma unroll
;         for (int r = 0; r < R; ++r)
; #pragma unroll
;             for (int j = 0; j < 4; ++j) if (ok[r]) *(v4f*)(Y + (size_t)mr[r] * DM + 4 * lane + 256 * j) = d[r][j];
	v_add_u32_e32 v175, 0x800000, v175
	v_pk_mul_f32 v[112:113], v[130:131], v[112:113] op_sel_hi:[0,1]
	v_pk_mul_f32 v[114:115], v[130:131], v[114:115] op_sel_hi:[0,1]
	v_pk_mul_f32 v[116:117], v[130:131], v[116:117] op_sel_hi:[0,1]
	v_pk_mul_f32 v[118:119], v[130:131], v[118:119] op_sel_hi:[0,1]
	v_pk_mul_f32 v[120:121], v[130:131], v[120:121] op_sel_hi:[0,1]
	v_pk_mul_f32 v[122:123], v[130:131], v[122:123] op_sel_hi:[0,1]
	v_pk_mul_f32 v[124:125], v[130:131], v[124:125] op_sel_hi:[0,1]
	v_pk_mul_f32 v[126:127], v[130:131], v[126:127] op_sel_hi:[0,1]
	v_pk_mul_f32 v[112:113], v[112:113], v[192:193]
	v_pk_mul_f32 v[114:115], v[114:115], v[194:195]
	v_pk_mul_f32 v[116:117], v[116:117], v[196:197]
	v_pk_mul_f32 v[118:119], v[118:119], v[198:199]
	v_pk_mul_f32 v[120:121], v[120:121], v[200:201]
	v_pk_mul_f32 v[122:123], v[122:123], v[202:203]
	v_pk_mul_f32 v[124:125], v[124:125], v[204:205]
	v_pk_mul_f32 v[126:127], v[126:127], v[206:207]
	v_lshlrev_b32_e32 v28, 16, v44
	v_and_b32_e32 v29, 0xffff0000, v44
	v_lshlrev_b32_e32 v30, 16, v45
	v_and_b32_e32 v31, 0xffff0000, v45
	v_lshlrev_b32_e32 v32, 16, v46
	v_and_b32_e32 v33, 0xffff0000, v46
	v_lshlrev_b32_e32 v34, 16, v47
	v_and_b32_e32 v35, 0xffff0000, v47
	v_pk_fma_f32 v[112:113], v[54:55], v[28:29], v[112:113] op_sel_hi:[0,1,1]
	v_pk_fma_f32 v[114:115], v[54:55], v[30:31], v[114:115] op_sel_hi:[0,1,1]
	v_pk_fma_f32 v[116:117], v[54:55], v[32:33], v[116:117] op_sel_hi:[0,1,1]
	v_pk_fma_f32 v[118:119], v[54:55], v[34:35], v[118:119] op_sel_hi:[0,1,1]
	v_lshlrev_b32_e32 v28, 16, v48
	v_and_b32_e32 v29, 0xffff0000, v48
	v_lshlrev_b32_e32 v30, 16, v49
	v_and_b32_e32 v31, 0xffff0000, v49
	v_lshlrev_b32_e32 v32, 16, v50
	v_and_b32_e32 v33, 0xffff0000, v50
	v_lshlrev_b32_e32 v34, 16, v51
	v_and_b32_e32 v35, 0xffff0000, v51
	v_pk_fma_f32 v[120:121], v[54:55], v[28:29], v[120:121] op_sel_hi:[0,1,1]
	v_pk_fma_f32 v[122:123], v[54:55], v[30:31], v[122:123] op_sel_hi:[0,1,1]
	v_pk_fma_f32 v[124:125], v[54:55], v[32:33], v[124:125] op_sel_hi:[0,1,1]
	v_pk_fma_f32 v[126:127], v[54:55], v[34:35], v[126:127] op_sel_hi:[0,1,1]
	global_store_dwordx4 v175, v[112:115], s[100:101] nt
	global_store_dwordx4 v175, v[116:119], s[100:101] offset:1024 nt
	global_store_dwordx4 v175, v[120:123], s[100:101] offset:2048 nt
	global_store_dwordx4 v175, v[124:127], s[100:101] offset:3072 nt
	v_add_u32_e32 v175, 0x800000, v175
	global_load_dword v52, v172, s[98:99]
	global_load_dwordx2 v[20:21], v170, s[98:99] nt
	global_load_dwordx2 v[22:23], v170, s[98:99] offset:512 nt
	global_load_dwordx2 v[24:25], v170, s[98:99] offset:1024 nt
	global_load_dwordx2 v[26:27], v170, s[98:99] offset:1536 nt
	global_load_dwordx2 v[36:37], v171, s[98:99] nt
	global_load_dwordx2 v[38:39], v171, s[98:99] offset:512 nt
	global_load_dwordx2 v[40:41], v171, s[98:99] offset:1024 nt
	global_load_dwordx2 v[42:43], v171, s[98:99] offset:1536 nt
	v_add_u32_e32 v170, 0x400000, v170
	v_add_u32_e32 v171, 0x400000, v171
	v_add_u32_e32 v172, 0x2000, v172
	global_load_dword v54, v172, s[98:99]
	global_load_dwordx2 v[28:29], v170, s[98:99] nt
	global_load_dwordx2 v[30:31], v170, s[98:99] offset:512 nt
	global_load_dwordx2 v[32:33], v170, s[98:99] offset:1024 nt
	global_load_dwordx2 v[34:35], v170, s[98:99] offset:1536 nt
	global_load_dwordx2 v[44:45], v171, s[98:99] nt
	global_load_dwordx2 v[46:47], v171, s[98:99] offset:512 nt
	global_load_dwordx2 v[48:49], v171, s[98:99] offset:1024 nt
	global_load_dwordx2 v[50:51], v171, s[98:99] offset:1536 nt
	v_add_u32_e32 v170, 0x400000, v170
	v_add_u32_e32 v171, 0x400000, v171
	v_add_u32_e32 v172, 0x2000, v172
	s_waitcnt vmcnt(39)
	v_lshlrev_b32_e32 v96, 16, v56
	v_and_b32_e32 v97, 0xffff0000, v56
	v_lshlrev_b32_e32 v98, 16, v57
	v_and_b32_e32 v99, 0xffff0000, v57
	v_lshlrev_b32_e32 v100, 16, v58
	v_and_b32_e32 v101, 0xffff0000, v58
	v_lshlrev_b32_e32 v102, 16, v59
	v_and_b32_e32 v103, 0xffff0000, v59
	v_lshlrev_b32_e32 v104, 16, v60
	v_and_b32_e32 v105, 0xffff0000, v60
	v_lshlrev_b32_e32 v106, 16, v61
	v_and_b32_e32 v107, 0xffff0000, v61
	v_lshlrev_b32_e32 v108, 16, v62
	v_and_b32_e32 v109, 0xffff0000, v62
	v_lshlrev_b32_e32 v110, 16, v63
	v_and_b32_e32 v111, 0xffff0000, v63
	v_pk_mul_f32 v[128:129], v[96:97], v[96:97]
	v_pk_fma_f32 v[128:129], v[98:99], v[98:99], v[128:129]
	v_pk_fma_f32 v[128:129], v[100:101], v[100:101], v[128:129]
	v_pk_fma_f32 v[128:129], v[102:103], v[102:103], v[128:129]
	v_pk_fma_f32 v[128:129], v[104:105], v[104:105], v[128:129]
	v_pk_fma_f32 v[128:129], v[106:107], v[106:107], v[128:129]
	v_pk_fma_f32 v[128:129], v[108:109], v[108:109], v[128:129]
	v_pk_fma_f32 v[128:129], v[110:111], v[110:111], v[128:129]
	s_nop 0
	v_add_f32_e32 v128, v128, v129
	s_waitcnt vmcnt(30)
	v_lshlrev_b32_e32 v112, 16, v64
	v_and_b32_e32 v113, 0xffff0000, v64
	v_lshlrev_b32_e32 v114, 16, v65
	v_and_b32_e32 v115, 0xffff0000, v65
	v_lshlrev_b32_e32 v116, 16, v66
	v_and_b32_e32 v117, 0xffff0000, v66
	v_lshlrev_b32_e32 v118, 16, v67
	v_and_b32_e32 v119, 0xffff0000, v67
	v_lshlrev_b32_e32 v120, 16, v68
	v_and_b32_e32 v121, 0xffff0000, v68
	v_lshlrev_b32_e32 v122, 16, v69
	v_and_b32_e32 v123, 0xffff0000, v69
	v_lshlrev_b32_e32 v124, 16, v70
	v_and_b32_e32 v125, 0xffff0000, v70
	v_lshlrev_b32_e32 v126, 16, v71
	v_and_b32_e32 v127, 0xffff0000, v71
	v_pk_mul_f32 v[130:131], v[112:113], v[112:113]
	v_pk_fma_f32 v[130:131], v[114:115], v[114:115], v[130:131]
	v_pk_fma_f32 v[130:131], v[116:117], v[116:117], v[130:131]
	v_pk_fma_f32 v[130:131], v[118:119], v[118:119], v[130:131]
	v_pk_fma_f32 v[130:131], v[120:121], v[120:121], v[130:131]
	v_pk_fma_f32 v[130:131], v[122:123], v[122:123], v[130:131]
	v_pk_fma_f32 v[130:131], v[124:125], v[124:125], v[130:131]
	v_pk_fma_f32 v[130:131], v[126:127], v[126:127], v[130:131]
	s_nop 0
	v_add_f32_e32 v130, v130, v131
	s_nop 1
	v_add_f32_dpp v128, v128, v128 quad_perm:[1,0,3,2] row_mask:0xf bank_mask:0xf
	v_add_f32_dpp v130, v130, v130 quad_perm:[1,0,3,2] row_mask:0xf bank_mask:0xf
	s_nop 0
	v_add_f32_dpp v128, v128, v128 quad_perm:[2,3,0,1] row_mask:0xf bank_mask:0xf
	v_add_f32_dpp v130, v130, v130 quad_perm:[2,3,0,1] row_mask:0xf bank_mask:0xf
	s_nop 0
	v_add_f32_dpp v128, v128, v128 row_half_mirror row_mask:0xf bank_mask:0xf
	v_add_f32_dpp v130, v130, v130 row_half_mirror row_mask:0xf bank_mask:0xf
	s_nop 0
	v_add_f32_dpp v128, v128, v128 row_mirror row_mask:0xf bank_mask:0xf
	v_add_f32_dpp v130, v130, v130 row_mirror row_mask:0xf bank_mask:0xf
	s_nop 0
	ds_bpermute_b32 v136, v187, v128
	ds_bpermute_b32 v137, v187, v130
	s_waitcnt lgkmcnt(0)
;     __device__ __forceinline__ float* out() const { return (float*)karg_in(33); }
; __device__ __forceinline__ const float* xrow_ptr(const Ctx& C, int row) { return row < MPROMPT ? C.in(0) + (size_t)row * DM : C.in(1) + (size_t)(row - MPROMPT) * DM; }
; __device__ __forceinline__ v4f ld4_bf16(const bf16* p) { const v2u w = *(const v2u*)p; return (v4f){bf_lo(w.x), bf_hi(w.x), bf_lo(w.y), bf_hi(w.y)}; }
; __device__ __forceinline__ float ssq4(v4f v) { return (v.x * v.x + v.y * v.y) + (v.z * v.z + v.w * v.w); }
; template <int R, bool BASE_F32, bool OUT_F32>
; __device__ __forceinline__ void rows_res(const Ctx& C, int m0, int stride, int mx, const float* gpost, float scale, int lane) {
;     ...
;     for (int r = 0; r < R; ++r) { mr[r] = (r == 4) ? mx : m0 + r * stride; ok[r] = (r == 4) ? (mx < M) : (mr[r] < MPROMPT); const int mm = ok[r] ? mr[r] : 0;
; #pragma unroll
;         for (int j = 0; j < 4; ++j) d[r][j] = ld4_bf16(D + (size_t)mm * DM + 4 * lane + 256 * j);
;         if (BASE_F32) { const float* x = xrow_ptr(C, mm);
; #pragma unroll
;             for (int j = 0; j < 4; ++j) b[r][j] = ld4_f32(x + 4 * lane + 256 * j);
;         } else { const float inv = C.RS()[mm];
; #pragma unroll
;             for (int j = 0; j < 4; ++j) b[r][j] = ld4_bf16(XN + (size_t)mm * DM + 4 * lane + 256 * j) * inv;
;         } }
; #pragma unroll
;     for (int r = 0; r < R; ++r) { float s = 0.f;
; #pragma unroll
;         for (int j = 0; j < 4; ++j) s += ssq4(d[r][j]);
;         r1[r] = s; }
; #pragma unroll
;     for (int r = 0; r < R; ++r) r1[r] = rsqrtf(wave_sum(r1[r]) * (1.f / DM) + EPS) * scale;
; #pragma unroll
;     for (int j = 0; j < 4; ++j) { const v4f gp = ld4_f32(gpost + 4 * lane + 256 * j);
; #pragma unroll
;         for (int r = 0; r < R; ++r) d[r][j] = b[r][j] + d[r][j] * r1[r] * gp; }
;     if (OUT_F32) { float* Y = C.out();
; #pragma unroll
;         for (int r = 0; r < R; ++r)
; #pragma unroll
;             for (int j = 0; j < 4; ++j) if (ok[r]) *(v4f*)(Y + (size_t)mr[r] * DM + 4 * lane + 256 * j) = d[r][j];
	v_add_f32_e32 v128, v128, v136
	v_add_f32_e32 v130, v130, v137
	ds_bpermute_b32 v136, v188, v128
	ds_bpermute_b32 v137, v188, v130
	s_waitcnt lgkmcnt(0)
	v_add_f32_e32 v128, v128, v136
	v_add_f32_e32 v130, v130, v137
	v_fmamk_f32 v128, v128, 0x3a800000, v138
	v_fmamk_f32 v130, v130, 0x3a800000, v138
	s_nop 0
	v_rsq_f32_e32 v128, v128
	v_rsq_f32_e32 v130, v130
	s_nop 1
	v_mul_f32_e32 v128, 0.5, v128
	v_mul_f32_e32 v130, 0.5, v130
	s_waitcnt vmcnt(26)
	v_pk_mul_f32 v[96:97], v[128:129], v[96:97] op_sel_hi:[0,1]
	v_pk_mul_f32 v[98:99], v[128:129], v[98:99] op_sel_hi:[0,1]
	v_pk_mul_f32 v[100:101], v[128:129], v[100:101] op_sel_hi:[0,1]
	v_pk_mul_f32 v[102:103], v[128:129], v[102:103] op_sel_hi:[0,1]
	v_pk_mul_f32 v[104:105], v[128:129], v[104:105] op_sel_hi:[0,1]
	v_pk_mul_f32 v[106:107], v[128:129], v[106:107] op_sel_hi:[0,1]
	v_pk_mul_f32 v[108:109], v[128:129], v[108:109] op_sel_hi:[0,1]
	v_pk_mul_f32 v[110:111], v[128:129], v[110:111] op_sel_hi:[0,1]
	v_pk_mul_f32 v[96:97], v[96:97], v[192:193]
	v_pk_mul_f32 v[98:99], v[98:99], v[194:195]
	v_pk_mul_f32 v[100:101], v[100:101], v[196:197]
	v_pk_mul_f32 v[102:103], v[102:103], v[198:199]
	v_pk_mul_f32 v[104:105], v[104:105], v[200:201]
	v_pk_mul_f32 v[106:107], v[106:107], v[202:203]
	v_pk_mul_f32 v[108:109], v[108:109], v[204:205]
	v_pk_mul_f32 v[110:111], v[110:111], v[206:207]
	v_lshlrev_b32_e32 v56, 16, v72
	v_and_b32_e32 v57, 0xffff0000, v72
	v_lshlrev_b32_e32 v58, 16, v73
	v_and_b32_e32 v59, 0xffff0000, v73
	v_lshlrev_b32_e32 v60, 16, v74
	v_and_b32_e32 v61, 0xffff0000, v74
	v_lshlrev_b32_e32 v62, 16, v75
	v_and_b32_e32 v63, 0xffff0000, v75
	v_pk_fma_f32 v[96:97], v[88:89], v[56:57], v[96:97] op_sel_hi:[0,1,1]
	v_pk_fma_f32 v[98:99], v[88:89], v[58:59], v[98:99] op_sel_hi:[0,1,1]
	v_pk_fma_f32 v[100:101], v[88:89], v[60:61], v[100:101] op_sel_hi:[0,1,1]
	v_pk_fma_f32 v[102:103], v[88:89], v[62:63], v[102:103] op_sel_hi:[0,1,1]
	v_lshlrev_b32_e32 v56, 16, v76
	v_and_b32_e32 v57, 0xffff0000, v76
	v_lshlrev_b32_e32 v58, 16, v77
	v_and_b32_e32 v59, 0xffff0000, v77
	v_lshlrev_b32_e32 v60, 16, v78
	v_and_b32_e32 v61, 0xffff0000, v78
	v_lshlrev_b32_e32 v62, 16, v79
	v_and_b32_e32 v63, 0xffff0000, v79
	v_pk_fma_f32 v[104:105], v[88:89], v[56:57], v[104:105] op_sel_hi:[0,1,1]
	v_pk_fma_f32 v[106:107], v[88:89], v[58:59], v[106:107] op_sel_hi:[0,1,1]
	v_pk_fma_f32 v[108:109], v[88:89], v[60:61], v[108:109] op_sel_hi:[0,1,1]
	v_pk_fma_f32 v[110:111], v[88:89], v[62:63], v[110:111] op_sel_hi:[0,1,1]
	global_store_dwordx4 v175, v[96:99], s[100:101] nt
	global_store_dwordx4 v175, v[100:103], s[100:101] offset:1024 nt
	global_store_dwordx4 v175, v[104:107], s[100:101] offset:2048 nt
	global_store_dwordx4 v175, v[108:111], s[100:101] offset:3072 nt
	v_add_u32_e32 v175, 0x800000, v175
	v_pk_mul_f32 v[112:113], v[130:131], v[112:113] op_sel_hi:[0,1]
	v_pk_mul_f32 v[114:115], v[130:131], v[114:115] op_sel_hi:[0,1]
	v_pk_mul_f32 v[116:117], v[130:131], v[116:117] op_sel_hi:[0,1]
	v_pk_mul_f32 v[118:119], v[130:131], v[118:119] op_sel_hi:[0,1]
	v_pk_mul_f32 v[120:121], v[130:131], v[120:121] op_sel_hi:[0,1]
	v_pk_mul_f32 v[122:123], v[130:131], v[122:123] op_sel_hi:[0,1]
	v_pk_mul_f32 v[124:125], v[130:131], v[124:125] op_sel_hi:[0,1]
	v_pk_mul_f32 v[126:127], v[130:131], v[126:127] op_sel_hi:[0,1]
	v_pk_mul_f32 v[112:113], v[112:113], v[192:193]
	v_pk_mul_f32 v[114:115], v[114:115], v[194:195]
	v_pk_mul_f32 v[116:117], v[116:117], v[196:197]
	v_pk_mul_f32 v[118:119], v[118:119], v[198:199]
	v_pk_mul_f32 v[120:121], v[120:121], v[200:201]
	v_pk_mul_f32 v[122:123], v[122:123], v[202:203]
	v_pk_mul_f32 v[124:125], v[124:125], v[204:205]
	v_pk_mul_f32 v[126:127], v[126:127], v[206:207]
	v_lshlrev_b32_e32 v64, 16, v80
	v_and_b32_e32 v65, 0xffff0000, v80
	v_lshlrev_b32_e32 v66, 16, v81
	v_and_b32_e32 v67, 0xffff0000, v81
	v_lshlrev_b32_e32 v68, 16, v82
	v_and_b32_e32 v69, 0xffff0000, v82
	v_lshlrev_b32_e32 v70, 16, v83
	v_and_b32_e32 v71, 0xffff0000, v83
	v_pk_fma_f32 v[112:113], v[90:91], v[64:65], v[112:113] op_sel_hi:[0,1,1]
	v_pk_fma_f32 v[114:115], v[90:91], v[66:67], v[114:115] op_sel_hi:[0,1,1]
	v_pk_fma_f32 v[116:117], v[90:91], v[68:69], v[116:117] op_sel_hi:[0,1,1]
	v_pk_fma_f32 v[118:119], v[90:91], v[70:71], v[118:119] op_sel_hi:[0,1,1]
	v_lshlrev_b32_e32 v64, 16, v84
	v_and_b32_e32 v65, 0xffff0000, v84
	v_lshlrev_b32_e32 v66, 16, v85
	v_and_b32_e32 v67, 0xffff0000, v85
	v_lshlrev_b32_e32 v68, 16, v86
	v_and_b32_e32 v69, 0xffff0000, v86
	v_lshlrev_b32_e32 v70, 16, v87
	v_and_b32_e32 v71, 0xffff0000, v87
	v_pk_fma_f32 v[120:121], v[90:91], v[64:65], v[120:121] op_sel_hi:[0,1,1]
	v_pk_fma_f32 v[122:123], v[90:91], v[66:67], v[122:123] op_sel_hi:[0,1,1]
	v_pk_fma_f32 v[124:125], v[90:91], v[68:69], v[124:125] op_sel_hi:[0,1,1]
	v_pk_fma_f32 v[126:127], v[90:91], v[70:71], v[126:127] op_sel_hi:[0,1,1]
	global_store_dwordx4 v175, v[112:115], s[100:101] nt
	global_store_dwordx4 v175, v[116:119], s[100:101] offset:1024 nt
	global_store_dwordx4 v175, v[120:123], s[100:101] offset:2048 nt
	global_store_dwordx4 v175, v[124:127], s[100:101] offset:3072 nt
	v_add_u32_e32 v175, 0x800000, v175
	global_load_dword v88, v172, s[98:99]
	global_load_dwordx2 v[56:57], v170, s[98:99] nt
	global_load_dwordx2 v[58:59], v170, s[98:99] offset:512 nt
	global_load_dwordx2 v[60:61], v170, s[98:99] offset:1024 nt
	global_load_dwordx2 v[62:63], v170, s[98:99] offset:1536 nt
	global_load_dwordx2 v[72:73], v171, s[98:99] nt
	global_load_dwordx2 v[74:75], v171, s[98:99] offset:512 nt
	global_load_dwordx2 v[76:77], v171, s[98:99] offset:1024 nt
	global_load_dwordx2 v[78:79], v171, s[98:99] offset:1536 nt
	v_add_u32_e32 v170, 0x400000, v170
	v_add_u32_e32 v171, 0x400000, v171
	v_add_u32_e32 v172, 0x2000, v172
	global_load_dword v90, v172, s[98:99]
	global_load_dwordx2 v[64:65], v170, s[98:99] nt
	global_load_dwordx2 v[66:67], v170, s[98:99] offset:512 nt
	global_load_dwordx2 v[68:69], v170, s[98:99] offset:1024 nt
	global_load_dwordx2 v[70:71], v170, s[98:99] offset:1536 nt
	global_load_dwordx2 v[80:81], v171, s[98:99] nt
	global_load_dwordx2 v[82:83], v171, s[98:99] offset:512 nt
	global_load_dwordx2 v[84:85], v171, s[98:99] offset:1024 nt
	global_load_dwordx2 v[86:87], v171, s[98:99] offset:1536 nt
	v_add_u32_e32 v170, 0x400000, v170
	v_add_u32_e32 v171, 0x400000, v171
	v_add_u32_e32 v172, 0x2000, v172
	s_waitcnt vmcnt(39)
;     __device__ __forceinline__ float* out() const { return (float*)karg_in(33); }
; __device__ __forceinline__ float ssq4(v4f v) { return (v.x * v.x + v.y * v.y) + (v.z * v.z + v.w * v.w); }
; template <int R, bool BASE_F32, bool OUT_F32>
; __device__ __forceinline__ void rows_res(const Ctx& C, int m0, int stride, int mx, const float* gpost, float scale, int lane) {
;     ...
;     for (int r = 0; r < R; ++r) { float s = 0.f;
; #pragma unroll
;         for (int j = 0; j < 4; ++j) s += ssq4(d[r][j]);
;         r1[r] = s; }
; #pragma unroll
;     for (int r = 0; r < R; ++r) r1[r] = rsqrtf(wave_sum(r1[r]) * (1.f / DM) + EPS) * scale;
; #pragma unroll
;     for (int j = 0; j < 4; ++j) { const v4f gp = ld4_f32(gpost + 4 * lane + 256 * j);
; #pragma unroll
;         for (int r = 0; r < R; ++r) d[r][j] = b[r][j] + d[r][j] * r1[r] * gp; }
;     if (OUT_F32) { float* Y = C.out();
; #pragma unroll
;         for (int r = 0; r < R; ++r)
; #pragma unroll
;             for (int j = 0; j < 4; ++j) if (ok[r]) *(v4f*)(Y + (size_t)mr[r] * DM + 4 * lane + 256 * j) = d[r][j];
	v_lshlrev_b32_e32 v96, 16, v20
	v_and_b32_e32 v97, 0xffff0000, v20
	v_lshlrev_b32_e32 v98, 16, v21
	v_and_b32_e32 v99, 0xffff0000, v21
	v_lshlrev_b32_e32 v100, 16, v22
	v_and_b32_e32 v101, 0xffff0000, v22
	v_lshlrev_b32_e32 v102, 16, v23
	v_and_b32_e32 v103, 0xffff0000, v23
	v_lshlrev_b32_e32 v104, 16, v24
	v_and_b32_e32 v105, 0xffff0000, v24
	v_lshlrev_b32_e32 v106, 16, v25
	v_and_b32_e32 v107, 0xffff0000, v25
	v_lshlrev_b32_e32 v108, 16, v26
	v_and_b32_e32 v109, 0xffff0000, v26
	v_lshlrev_b32_e32 v110, 16, v27
	v_and_b32_e32 v111, 0xffff0000, v27
	v_pk_mul_f32 v[128:129], v[96:97], v[96:97]
	v_pk_fma_f32 v[128:129], v[98:99], v[98:99], v[128:129]
	v_pk_fma_f32 v[128:129], v[100:101], v[100:101], v[128:129]
	v_pk_fma_f32 v[128:129], v[102:103], v[102:103], v[128:129]
	v_pk_fma_f32 v[128:129], v[104:105], v[104:105], v[128:129]
	v_pk_fma_f32 v[128:129], v[106:107], v[106:107], v[128:129]
	v_pk_fma_f32 v[128:129], v[108:109], v[108:109], v[128:129]
	v_pk_fma_f32 v[128:129], v[110:111], v[110:111], v[128:129]
	s_nop 0
	v_add_f32_e32 v128, v128, v129
	s_waitcnt vmcnt(30)
	v_lshlrev_b32_e32 v112, 16, v28
	v_and_b32_e32 v113, 0xffff0000, v28
	v_lshlrev_b32_e32 v114, 16, v29
	v_and_b32_e32 v115, 0xffff0000, v29
	v_lshlrev_b32_e32 v116, 16, v30
	v_and_b32_e32 v117, 0xffff0000, v30
	v_lshlrev_b32_e32 v118, 16, v31
	v_and_b32_e32 v119, 0xffff0000, v31
	v_lshlrev_b32_e32 v120, 16, v32
	v_and_b32_e32 v121, 0xffff0000, v32
	v_lshlrev_b32_e32 v122, 16, v33
	v_and_b32_e32 v123, 0xffff0000, v33
	v_lshlrev_b32_e32 v124, 16, v34
	v_and_b32_e32 v125, 0xffff0000, v34
	v_lshlrev_b32_e32 v126, 16, v35
	v_and_b32_e32 v127, 0xffff0000, v35
	v_pk_mul_f32 v[130:131], v[112:113], v[112:113]
	v_pk_fma_f32 v[130:131], v[114:115], v[114:115], v[130:131]
	v_pk_fma_f32 v[130:131], v[116:117], v[116:117], v[130:131]
	v_pk_fma_f32 v[130:131], v[118:119], v[118:119], v[130:131]
	v_pk_fma_f32 v[130:131], v[120:121], v[120:121], v[130:131]
	v_pk_fma_f32 v[130:131], v[122:123], v[122:123], v[130:131]
	v_pk_fma_f32 v[130:131], v[124:125], v[124:125], v[130:131]
	v_pk_fma_f32 v[130:131], v[126:127], v[126:127], v[130:131]
	s_nop 0
	v_add_f32_e32 v130, v130, v131
	s_nop 1
	v_add_f32_dpp v128, v128, v128 quad_perm:[1,0,3,2] row_mask:0xf bank_mask:0xf
	v_add_f32_dpp v130, v130, v130 quad_perm:[1,0,3,2] row_mask:0xf bank_mask:0xf
	s_nop 0
	v_add_f32_dpp v128, v128, v128 quad_perm:[2,3,0,1] row_mask:0xf bank_mask:0xf
	v_add_f32_dpp v130, v130, v130 quad_perm:[2,3,0,1] row_mask:0xf bank_mask:0xf
	s_nop 0
	v_add_f32_dpp v128, v128, v128 row_half_mirror row_mask:0xf bank_mask:0xf
	v_add_f32_dpp v130, v130, v130 row_half_mirror row_mask:0xf bank_mask:0xf
	s_nop 0
	v_add_f32_dpp v128, v128, v128 row_mirror row_mask:0xf bank_mask:0xf
	v_add_f32_dpp v130, v130, v130 row_mirror row_mask:0xf bank_mask:0xf
	s_nop 0
	ds_bpermute_b32 v136, v187, v128
	ds_bpermute_b32 v137, v187, v130
	s_waitcnt lgkmcnt(0)
	v_add_f32_e32 v128, v128, v136
	v_add_f32_e32 v130, v130, v137
	ds_bpermute_b32 v136, v188, v128
	ds_bpermute_b32 v137, v188, v130
	s_waitcnt lgkmcnt(0)
	v_add_f32_e32 v128, v128, v136
	v_add_f32_e32 v130, v130, v137
	v_fmamk_f32 v128, v128, 0x3a800000, v138
	v_fmamk_f32 v130, v130, 0x3a800000, v138
	s_nop 0
	v_rsq_f32_e32 v128, v128
	v_rsq_f32_e32 v130, v130
	s_nop 1
	v_mul_f32_e32 v128, 0.5, v128
	v_mul_f32_e32 v130, 0.5, v130
	s_waitcnt vmcnt(26)
	v_pk_mul_f32 v[96:97], v[128:129], v[96:97] op_sel_hi:[0,1]
	v_pk_mul_f32 v[98:99], v[128:129], v[98:99] op_sel_hi:[0,1]
	v_pk_mul_f32 v[100:101], v[128:129], v[100:101] op_sel_hi:[0,1]
	v_pk_mul_f32 v[102:103], v[128:129], v[102:103] op_sel_hi:[0,1]
	v_pk_mul_f32 v[104:105], v[128:129], v[104:105] op_sel_hi:[0,1]
	v_pk_mul_f32 v[106:107], v[128:129], v[106:107] op_sel_hi:[0,1]
	v_pk_mul_f32 v[108:109], v[128:129], v[108:109] op_sel_hi:[0,1]
	v_pk_mul_f32 v[110:111], v[128:129], v[110:111] op_sel_hi:[0,1]
	v_pk_mul_f32 v[96:97], v[96:97], v[192:193]
	v_pk_mul_f32 v[98:99], v[98:99], v[194:195]
	v_pk_mul_f32 v[100:101], v[100:101], v[196:197]
	v_pk_mul_f32 v[102:103], v[102:103], v[198:199]
	v_pk_mul_f32 v[104:105], v[104:105], v[200:201]
	v_pk_mul_f32 v[106:107], v[106:107], v[202:203]
	v_pk_mul_f32 v[108:109], v[108:109], v[204:205]
	v_pk_mul_f32 v[110:111], v[110:111], v[206:207]
	v_lshlrev_b32_e32 v20, 16, v36
	v_and_b32_e32 v21, 0xffff0000, v36
	v_lshlrev_b32_e32 v22, 16, v37
	v_and_b32_e32 v23, 0xffff0000, v37
	v_lshlrev_b32_e32 v24, 16, v38
	v_and_b32_e32 v25, 0xffff0000, v38
	v_lshlrev_b32_e32 v26, 16, v39
	v_and_b32_e32 v27, 0xffff0000, v39
	v_pk_fma_f32 v[96:97], v[52:53], v[20:21], v[96:97] op_sel_hi:[0,1,1]
	v_pk_fma_f32 v[98:99], v[52:53], v[22:23], v[98:99] op_sel_hi:[0,1,1]
	v_pk_fma_f32 v[100:101], v[52:53], v[24:25], v[100:101] op_sel_hi:[0,1,1]
	v_pk_fma_f32 v[102:103], v[52:53], v[26:27], v[102:103] op_sel_hi:[0,1,1]
	v_lshlrev_b32_e32 v20, 16, v40
	v_and_b32_e32 v21, 0xffff0000, v40
	v_lshlrev_b32_e32 v22, 16, v41
	v_and_b32_e32 v23, 0xffff0000, v41
	v_lshlrev_b32_e32 v24, 16, v42
	v_and_b32_e32 v25, 0xffff0000, v42
	v_lshlrev_b32_e32 v26, 16, v43
	v_and_b32_e32 v27, 0xffff0000, v43
	v_pk_fma_f32 v[104:105], v[52:53], v[20:21], v[104:105] op_sel_hi:[0,1,1]
	v_pk_fma_f32 v[106:107], v[52:53], v[22:23], v[106:107] op_sel_hi:[0,1,1]
	v_pk_fma_f32 v[108:109], v[52:53], v[24:25], v[108:109] op_sel_hi:[0,1,1]
	v_pk_fma_f32 v[110:111], v[52:53], v[26:27], v[110:111] op_sel_hi:[0,1,1]
	global_store_dwordx4 v175, v[96:99], s[100:101] nt
	global_store_dwordx4 v175, v[100:103], s[100:101] offset:1024 nt
	global_store_dwordx4 v175, v[104:107], s[100:101] offset:2048 nt
	global_store_dwordx4 v175, v[108:111], s[100:101] offset:3072 nt
;     __device__ __forceinline__ float* out() const { return (float*)karg_in(33); }
; __device__ __forceinline__ float ssq4(v4f v) { return (v.x * v.x + v.y * v.y) + (v.z * v.z + v.w * v.w); }
; template <int R, bool BASE_F32, bool OUT_F32>
; __device__ __forceinline__ void rows_res(const Ctx& C, int m0, int stride, int mx, const float* gpost, float scale, int lane) {
;     ...
;     for (int r = 0; r < R; ++r) { float s = 0.f;
; #pragma unroll
;         for (int j = 0; j < 4; ++j) s += ssq4(d[r][j]);
;         r1[r] = s; }
; #pragma unroll
;     for (int r = 0; r < R; ++r) r1[r] = rsqrtf(wave_sum(r1[r]) * (1.f / DM) + EPS) * scale;
; #pragma unroll
;     for (int j = 0; j < 4; ++j) { const v4f gp = ld4_f32(gpost + 4 * lane + 256 * j);
; #pragma unroll
;         for (int r = 0; r < R; ++r) d[r][j] = b[r][j] + d[r][j] * r1[r] * gp; }
;     if (OUT_F32) { float* Y = C.out();
; #pragma unroll
;         for (int r = 0; r < R; ++r)
; #pragma unroll
;             for (int j = 0; j < 4; ++j) if (ok[r]) *(v4f*)(Y + (size_t)mr[r] * DM + 4 * lane + 256 * j) = d[r][j];
	v_add_u32_e32 v175, 0x800000, v175
	v_pk_mul_f32 v[112:113], v[130:131], v[112:113] op_sel_hi:[0,1]
	v_pk_mul_f32 v[114:115], v[130:131], v[114:115] op_sel_hi:[0,1]
	v_pk_mul_f32 v[116:117], v[130:131], v[116:117] op_sel_hi:[0,1]
	v_pk_mul_f32 v[118:119], v[130:131], v[118:119] op_sel_hi:[0,1]
	v_pk_mul_f32 v[120:121], v[130:131], v[120:121] op_sel_hi:[0,1]
	v_pk_mul_f32 v[122:123], v[130:131], v[122:123] op_sel_hi:[0,1]
	v_pk_mul_f32 v[124:125], v[130:131], v[124:125] op_sel_hi:[0,1]
	v_pk_mul_f32 v[126:127], v[130:131], v[126:127] op_sel_hi:[0,1]
	v_pk_mul_f32 v[112:113], v[112:113], v[192:193]
	v_pk_mul_f32 v[114:115], v[114:115], v[194:195]
	v_pk_mul_f32 v[116:117], v[116:117], v[196:197]
	v_pk_mul_f32 v[118:119], v[118:119], v[198:199]
	v_pk_mul_f32 v[120:121], v[120:121], v[200:201]
	v_pk_mul_f32 v[122:123], v[122:123], v[202:203]
	v_pk_mul_f32 v[124:125], v[124:125], v[204:205]
	v_pk_mul_f32 v[126:127], v[126:127], v[206:207]
	v_lshlrev_b32_e32 v28, 16, v44
	v_and_b32_e32 v29, 0xffff0000, v44
	v_lshlrev_b32_e32 v30, 16, v45
	v_and_b32_e32 v31, 0xffff0000, v45
	v_lshlrev_b32_e32 v32, 16, v46
	v_and_b32_e32 v33, 0xffff0000, v46
	v_lshlrev_b32_e32 v34, 16, v47
	v_and_b32_e32 v35, 0xffff0000, v47
	v_pk_fma_f32 v[112:113], v[54:55], v[28:29], v[112:113] op_sel_hi:[0,1,1]
	v_pk_fma_f32 v[114:115], v[54:55], v[30:31], v[114:115] op_sel_hi:[0,1,1]
	v_pk_fma_f32 v[116:117], v[54:55], v[32:33], v[116:117] op_sel_hi:[0,1,1]
	v_pk_fma_f32 v[118:119], v[54:55], v[34:35], v[118:119] op_sel_hi:[0,1,1]
	v_lshlrev_b32_e32 v28, 16, v48
	v_and_b32_e32 v29, 0xffff0000, v48
	v_lshlrev_b32_e32 v30, 16, v49
	v_and_b32_e32 v31, 0xffff0000, v49
	v_lshlrev_b32_e32 v32, 16, v50
	v_and_b32_e32 v33, 0xffff0000, v50
	v_lshlrev_b32_e32 v34, 16, v51
	v_and_b32_e32 v35, 0xffff0000, v51
	v_pk_fma_f32 v[120:121], v[54:55], v[28:29], v[120:121] op_sel_hi:[0,1,1]
	v_pk_fma_f32 v[122:123], v[54:55], v[30:31], v[122:123] op_sel_hi:[0,1,1]
	v_pk_fma_f32 v[124:125], v[54:55], v[32:33], v[124:125] op_sel_hi:[0,1,1]
	v_pk_fma_f32 v[126:127], v[54:55], v[34:35], v[126:127] op_sel_hi:[0,1,1]
	global_store_dwordx4 v175, v[112:115], s[100:101] nt
	global_store_dwordx4 v175, v[116:119], s[100:101] offset:1024 nt
	global_store_dwordx4 v175, v[120:123], s[100:101] offset:2048 nt
	global_store_dwordx4 v175, v[124:127], s[100:101] offset:3072 nt
	v_add_u32_e32 v175, 0x800000, v175
	s_waitcnt vmcnt(21)
	v_lshlrev_b32_e32 v96, 16, v56
	v_and_b32_e32 v97, 0xffff0000, v56
	v_lshlrev_b32_e32 v98, 16, v57
	v_and_b32_e32 v99, 0xffff0000, v57
	v_lshlrev_b32_e32 v100, 16, v58
	v_and_b32_e32 v101, 0xffff0000, v58
	v_lshlrev_b32_e32 v102, 16, v59
	v_and_b32_e32 v103, 0xffff0000, v59
	v_lshlrev_b32_e32 v104, 16, v60
	v_and_b32_e32 v105, 0xffff0000, v60
	v_lshlrev_b32_e32 v106, 16, v61
	v_and_b32_e32 v107, 0xffff0000, v61
	v_lshlrev_b32_e32 v108, 16, v62
	v_and_b32_e32 v109, 0xffff0000, v62
	v_lshlrev_b32_e32 v110, 16, v63
	v_and_b32_e32 v111, 0xffff0000, v63
	v_pk_mul_f32 v[128:129], v[96:97], v[96:97]
	v_pk_fma_f32 v[128:129], v[98:99], v[98:99], v[128:129]
	v_pk_fma_f32 v[128:129], v[100:101], v[100:101], v[128:129]
	v_pk_fma_f32 v[128:129], v[102:103], v[102:103], v[128:129]
	v_pk_fma_f32 v[128:129], v[104:105], v[104:105], v[128:129]
	v_pk_fma_f32 v[128:129], v[106:107], v[106:107], v[128:129]
	v_pk_fma_f32 v[128:129], v[108:109], v[108:109], v[128:129]
	v_pk_fma_f32 v[128:129], v[110:111], v[110:111], v[128:129]
	s_nop 0
	v_add_f32_e32 v128, v128, v129
	s_waitcnt vmcnt(12)
	v_lshlrev_b32_e32 v112, 16, v64
	v_and_b32_e32 v113, 0xffff0000, v64
	v_lshlrev_b32_e32 v114, 16, v65
	v_and_b32_e32 v115, 0xffff0000, v65
	v_lshlrev_b32_e32 v116, 16, v66
	v_and_b32_e32 v117, 0xffff0000, v66
	v_lshlrev_b32_e32 v118, 16, v67
	v_and_b32_e32 v119, 0xffff0000, v67
	v_lshlrev_b32_e32 v120, 16, v68
	v_and_b32_e32 v121, 0xffff0000, v68
	v_lshlrev_b32_e32 v122, 16, v69
	v_and_b32_e32 v123, 0xffff0000, v69
	v_lshlrev_b32_e32 v124, 16, v70
	v_and_b32_e32 v125, 0xffff0000, v70
	v_lshlrev_b32_e32 v126, 16, v71
	v_and_b32_e32 v127, 0xffff0000, v71
	v_pk_mul_f32 v[130:131], v[112:113], v[112:113]
	v_pk_fma_f32 v[130:131], v[114:115], v[114:115], v[130:131]
	v_pk_fma_f32 v[130:131], v[116:117], v[116:117], v[130:131]
	v_pk_fma_f32 v[130:131], v[118:119], v[118:119], v[130:131]
	v_pk_fma_f32 v[130:131], v[120:121], v[120:121], v[130:131]
	v_pk_fma_f32 v[130:131], v[122:123], v[122:123], v[130:131]
	v_pk_fma_f32 v[130:131], v[124:125], v[124:125], v[130:131]
	v_pk_fma_f32 v[130:131], v[126:127], v[126:127], v[130:131]
	s_nop 0
	v_add_f32_e32 v130, v130, v131
	s_nop 1
	v_add_f32_dpp v128, v128, v128 quad_perm:[1,0,3,2] row_mask:0xf bank_mask:0xf
	v_add_f32_dpp v130, v130, v130 quad_perm:[1,0,3,2] row_mask:0xf bank_mask:0xf
	s_nop 0
	v_add_f32_dpp v128, v128, v128 quad_perm:[2,3,0,1] row_mask:0xf bank_mask:0xf
	v_add_f32_dpp v130, v130, v130 quad_perm:[2,3,0,1] row_mask:0xf bank_mask:0xf
	s_nop 0
	v_add_f32_dpp v128, v128, v128 row_half_mirror row_mask:0xf bank_mask:0xf
	v_add_f32_dpp v130, v130, v130 row_half_mirror row_mask:0xf bank_mask:0xf
	s_nop 0
	v_add_f32_dpp v128, v128, v128 row_mirror row_mask:0xf bank_mask:0xf
	v_add_f32_dpp v130, v130, v130 row_mirror row_mask:0xf bank_mask:0xf
	s_nop 0
	ds_bpermute_b32 v136, v187, v128
	ds_bpermute_b32 v137, v187, v130
	s_waitcnt lgkmcnt(0)
;     __device__ __forceinline__ const float* in(int i) const { return karg_in(i); }
;     __device__ __forceinline__ float* out() const { return (float*)karg_in(33); }
; #define FTID const int ftid_ = fresh_tid()
; template <int R, bool BASE_F32, bool OUT_F32>
; __device__ __forceinline__ void rows_res(const Ctx& C, int m0, int stride, int mx, const float* gpost, float scale, int lane) {
;     ...
;     for (int r = 0; r < R; ++r) r1[r] = rsqrtf(wave_sum(r1[r]) * (1.f / DM) + EPS) * scale;
; #pragma unroll
;     for (int j = 0; j < 4; ++j) { const v4f gp = ld4_f32(gpost + 4 * lane + 256 * j);
; #pragma unroll
;         for (int r = 0; r < R; ++r) d[r][j] = b[r][j] + d[r][j] * r1[r] * gp; }
;     if (OUT_F32) { float* Y = C.out();
; #pragma unroll
;         for (int r = 0; r < R; ++r)
; #pragma unroll
;             for (int j = 0; j < 4; ++j) if (ok[r]) *(v4f*)(Y + (size_t)mr[r] * DM + 4 * lane + 256 * j) = d[r][j];
; __global__ void __launch_bounds__(NTHREADS, 2) fwd_kernel(Args args) {
;     ...
;     { FTID; const float* gp = C.in(32); { const int gw_ = GWV, ngw_ = NGWV, nit = (MPROMPT + 4 * ngw_ - 1) / (4 * ngw_);
;       for (int it = 0; it < nit - 1; ++it) rows_res<4, false, true>(C, gw_ + 4 * it * ngw_, ngw_, M, gp, 0.5f, LANE);
;       rows_res<5, false, true>(C, gw_ + 4 * (nit - 1) * ngw_, ngw_, MPROMPT + gw_, gp, 0.5f, LANE);
;       for (int ms = MPROMPT + gw_ + ngw_; ms < M; ms += ngw_) rows_res<5, false, true>(C, MPROMPT, ngw_, ms, gp, 0.5f, LANE); } }
	v_add_f32_e32 v128, v128, v136
	v_add_f32_e32 v130, v130, v137
	ds_bpermute_b32 v136, v188, v128
	ds_bpermute_b32 v137, v188, v130
	s_waitcnt lgkmcnt(0)
	v_add_f32_e32 v128, v128, v136
	v_add_f32_e32 v130, v130, v137
	v_fmamk_f32 v128, v128, 0x3a800000, v138
	v_fmamk_f32 v130, v130, 0x3a800000, v138
	s_nop 0
	v_rsq_f32_e32 v128, v128
	v_rsq_f32_e32 v130, v130
	s_nop 1
	v_mul_f32_e32 v128, 0.5, v128
	v_mul_f32_e32 v130, 0.5, v130
	s_waitcnt vmcnt(8)
	v_pk_mul_f32 v[96:97], v[128:129], v[96:97] op_sel_hi:[0,1]
	v_pk_mul_f32 v[98:99], v[128:129], v[98:99] op_sel_hi:[0,1]
	v_pk_mul_f32 v[100:101], v[128:129], v[100:101] op_sel_hi:[0,1]
	v_pk_mul_f32 v[102:103], v[128:129], v[102:103] op_sel_hi:[0,1]
	v_pk_mul_f32 v[104:105], v[128:129], v[104:105] op_sel_hi:[0,1]
	v_pk_mul_f32 v[106:107], v[128:129], v[106:107] op_sel_hi:[0,1]
	v_pk_mul_f32 v[108:109], v[128:129], v[108:109] op_sel_hi:[0,1]
	v_pk_mul_f32 v[110:111], v[128:129], v[110:111] op_sel_hi:[0,1]
	v_pk_mul_f32 v[96:97], v[96:97], v[192:193]
	v_pk_mul_f32 v[98:99], v[98:99], v[194:195]
	v_pk_mul_f32 v[100:101], v[100:101], v[196:197]
	v_pk_mul_f32 v[102:103], v[102:103], v[198:199]
	v_pk_mul_f32 v[104:105], v[104:105], v[200:201]
	v_pk_mul_f32 v[106:107], v[106:107], v[202:203]
	v_pk_mul_f32 v[108:109], v[108:109], v[204:205]
	v_pk_mul_f32 v[110:111], v[110:111], v[206:207]
	v_lshlrev_b32_e32 v56, 16, v72
	v_and_b32_e32 v57, 0xffff0000, v72
	v_lshlrev_b32_e32 v58, 16, v73
	v_and_b32_e32 v59, 0xffff0000, v73
	v_lshlrev_b32_e32 v60, 16, v74
	v_and_b32_e32 v61, 0xffff0000, v74
	v_lshlrev_b32_e32 v62, 16, v75
	v_and_b32_e32 v63, 0xffff0000, v75
	v_pk_fma_f32 v[96:97], v[88:89], v[56:57], v[96:97] op_sel_hi:[0,1,1]
	v_pk_fma_f32 v[98:99], v[88:89], v[58:59], v[98:99] op_sel_hi:[0,1,1]
	v_pk_fma_f32 v[100:101], v[88:89], v[60:61], v[100:101] op_sel_hi:[0,1,1]
	v_pk_fma_f32 v[102:103], v[88:89], v[62:63], v[102:103] op_sel_hi:[0,1,1]
	v_lshlrev_b32_e32 v56, 16, v76
	v_and_b32_e32 v57, 0xffff0000, v76
	v_lshlrev_b32_e32 v58, 16, v77
	v_and_b32_e32 v59, 0xffff0000, v77
	v_lshlrev_b32_e32 v60, 16, v78
	v_and_b32_e32 v61, 0xffff0000, v78
	v_lshlrev_b32_e32 v62, 16, v79
	v_and_b32_e32 v63, 0xffff0000, v79
	v_pk_fma_f32 v[104:105], v[88:89], v[56:57], v[104:105] op_sel_hi:[0,1,1]
	v_pk_fma_f32 v[106:107], v[88:89], v[58:59], v[106:107] op_sel_hi:[0,1,1]
	v_pk_fma_f32 v[108:109], v[88:89], v[60:61], v[108:109] op_sel_hi:[0,1,1]
	v_pk_fma_f32 v[110:111], v[88:89], v[62:63], v[110:111] op_sel_hi:[0,1,1]
	global_store_dwordx4 v175, v[96:99], s[100:101] nt
	global_store_dwordx4 v175, v[100:103], s[100:101] offset:1024 nt
	global_store_dwordx4 v175, v[104:107], s[100:101] offset:2048 nt
	global_store_dwordx4 v175, v[108:111], s[100:101] offset:3072 nt
	v_add_u32_e32 v175, 0x800000, v175
	v_pk_mul_f32 v[112:113], v[130:131], v[112:113] op_sel_hi:[0,1]
	v_pk_mul_f32 v[114:115], v[130:131], v[114:115] op_sel_hi:[0,1]
	v_pk_mul_f32 v[116:117], v[130:131], v[116:117] op_sel_hi:[0,1]
	v_pk_mul_f32 v[118:119], v[130:131], v[118:119] op_sel_hi:[0,1]
	v_pk_mul_f32 v[120:121], v[130:131], v[120:121] op_sel_hi:[0,1]
	v_pk_mul_f32 v[122:123], v[130:131], v[122:123] op_sel_hi:[0,1]
	v_pk_mul_f32 v[124:125], v[130:131], v[124:125] op_sel_hi:[0,1]
	v_pk_mul_f32 v[126:127], v[130:131], v[126:127] op_sel_hi:[0,1]
	v_pk_mul_f32 v[112:113], v[112:113], v[192:193]
	v_pk_mul_f32 v[114:115], v[114:115], v[194:195]
	v_pk_mul_f32 v[116:117], v[116:117], v[196:197]
	v_pk_mul_f32 v[118:119], v[118:119], v[198:199]
	v_pk_mul_f32 v[120:121], v[120:121], v[200:201]
	v_pk_mul_f32 v[122:123], v[122:123], v[202:203]
	v_pk_mul_f32 v[124:125], v[124:125], v[204:205]
	v_pk_mul_f32 v[126:127], v[126:127], v[206:207]
	v_lshlrev_b32_e32 v64, 16, v80
	v_and_b32_e32 v65, 0xffff0000, v80
	v_lshlrev_b32_e32 v66, 16, v81
	v_and_b32_e32 v67, 0xffff0000, v81
	v_lshlrev_b32_e32 v68, 16, v82
	v_and_b32_e32 v69, 0xffff0000, v82
	v_lshlrev_b32_e32 v70, 16, v83
	v_and_b32_e32 v71, 0xffff0000, v83
	v_pk_fma_f32 v[112:113], v[90:91], v[64:65], v[112:113] op_sel_hi:[0,1,1]
	v_pk_fma_f32 v[114:115], v[90:91], v[66:67], v[114:115] op_sel_hi:[0,1,1]
	v_pk_fma_f32 v[116:117], v[90:91], v[68:69], v[116:117] op_sel_hi:[0,1,1]
	v_pk_fma_f32 v[118:119], v[90:91], v[70:71], v[118:119] op_sel_hi:[0,1,1]
	v_lshlrev_b32_e32 v64, 16, v84
	v_and_b32_e32 v65, 0xffff0000, v84
	v_lshlrev_b32_e32 v66, 16, v85
	v_and_b32_e32 v67, 0xffff0000, v85
	v_lshlrev_b32_e32 v68, 16, v86
	v_and_b32_e32 v69, 0xffff0000, v86
	v_lshlrev_b32_e32 v70, 16, v87
	v_and_b32_e32 v71, 0xffff0000, v87
	v_pk_fma_f32 v[120:121], v[90:91], v[64:65], v[120:121] op_sel_hi:[0,1,1]
	v_pk_fma_f32 v[122:123], v[90:91], v[66:67], v[122:123] op_sel_hi:[0,1,1]
	v_pk_fma_f32 v[124:125], v[90:91], v[68:69], v[124:125] op_sel_hi:[0,1,1]
	v_pk_fma_f32 v[126:127], v[90:91], v[70:71], v[126:127] op_sel_hi:[0,1,1]
	global_store_dwordx4 v175, v[112:115], s[100:101] nt
	global_store_dwordx4 v175, v[116:119], s[100:101] offset:1024 nt
	global_store_dwordx4 v175, v[120:123], s[100:101] offset:2048 nt
	global_store_dwordx4 v175, v[124:127], s[100:101] offset:3072 nt
	v_add_u32_e32 v175, 0x800000, v175
	s_branch .LBB0_1283
	s_waitcnt lgkmcnt(0)
	v_lshl_add_u64 v[20:21], s[8:9], 0, v[16:17]
	v_mov_b32_e32 v19, v17
	s_mov_b64 s[10:11], 0x7100000
	s_mov_b64 s[12:13], 0x3000000
	v_mov_b32_e32 v23, 0x2a80000
	v_mov_b32_e32 v22, 0x358637bd
	s_mov_b32 s14, 0x3a800000
	s_mov_b32 s27, 0x800000
	s_mov_b32 s16, s15
	s_branch .LBB0_1275
